# speedup vs baseline: 1.0568x; 1.0071x over previous
; DI unsigned pk2(float lo, float hi) { const f32x2_t v = {lo, hi}; const bf16x2_t b = __builtin_convertvector(v, bf16x2_t); return __builtin_bit_cast(unsigned, b); }
; DI float lo16(unsigned w) { return __uint_as_float(w << 16); }
; DI float hi16(unsigned w) { return __uint_as_float(w & 0xffff0000u); }
; DI void gatenorm_pass(const Args& a, int G, const int tid) {
;     ...
;         for (int q = 0; q < 4; ++q) { const int m = m0 + q * NGW; if (m < R) {
; #pragma unroll
;             for (int g = 0; g < 2; ++g) { yw[q][g] = *((const u32x4*)(MIX + (size_t)m * LDMIX + 512 + g * 512) + lane); zw[q][g] = *((const u32x4*)(HIN + (size_t)m * LDH + C_Z + g * 512) + lane); } } }
; #pragma unroll
;         for (int q = 0; q < 4; ++q) { const int m = m0 + q * NGW; if (m < R) {
; #pragma unroll
;             for (int g = 0; g < 2; ++g) {
;                 float v[8]; float s = 0.f;
; #pragma unroll
;                 for (int e = 0; e < 4; ++e) { const float z0 = lo16(zw[q][g][e]), z1 = hi16(zw[q][g][e]); v[2 * e] = lo16(yw[q][g][e]) * z0 * __frcp_rn(1.0f + __expf(-z0)); v[2 * e + 1] = hi16(yw[q][g][e]) * z1 * __frcp_rn(1.0f + __expf(-z1)); s += v[2 * e] * v[2 * e] + v[2 * e + 1] * v[2 * e + 1]; }
;                 s = wave_sum(s); const float r = rsqrtf(s * (1.0f / 512.0f) + EPS);
;                 u32x4 w;
; #pragma unroll
;                 for (int e = 0; e < 4; ++e) w[e] = pk2(v[2 * e] * r, v[2 * e + 1] * r);
;                 *((u32x4*)(MIX + (size_t)m * LDMIX + 512 + g * 512) + lane) = w;
.LBB0_103:
	s_or_b64 exec, exec, s[4:5]
	s_waitcnt vmcnt(1)
	v_lshlrev_b32_e32 v70, 16, v63
	v_and_b32_e32 v71, 0xffff0000, v63
	v_mul_f32_e32 v63, 0xbfb8aa3b, v70
	v_lshlrev_b32_e32 v74, 16, v59
	v_and_b32_e32 v75, 0xffff0000, v59
	v_mul_f32_e32 v59, 0xbfb8aa3b, v71
	v_exp_f32_e32 v72, v63
	v_exp_f32_e32 v73, v59
	v_pk_mul_f32 v[74:75], v[74:75], v[70:71]
	v_and_b32_e32 v85, 0xffff0000, v57
	v_and_b32_e32 v87, 0xffff0000, v51
	v_pk_add_f32 v[70:71], v[72:73], 1.0 op_sel_hi:[1,0]
	v_and_b32_e32 v89, 0xffff0000, v49
	v_rcp_f32_e32 v71, v71
	v_lshlrev_b32_e32 v72, 16, v62
	v_and_b32_e32 v73, 0xffff0000, v62
	v_rcp_f32_e32 v70, v70
	v_mul_f32_e32 v59, 0xbfb8aa3b, v72
	v_mul_f32_e32 v63, 0xbfb8aa3b, v73
	v_exp_f32_e32 v62, v59
	v_exp_f32_e32 v63, v63
	v_pk_mul_f32 v[70:71], v[74:75], v[70:71]
	v_lshlrev_b32_e32 v74, 16, v58
	v_and_b32_e32 v75, 0xffff0000, v58
	v_pk_add_f32 v[62:63], v[62:63], 1.0 op_sel_hi:[1,0]
	v_pk_mul_f32 v[58:59], v[74:75], v[72:73]
	v_rcp_f32_e32 v63, v63
	v_rcp_f32_e32 v62, v62
	s_nop 0
	v_pk_mul_f32 v[58:59], v[58:59], v[62:63]
	v_mov_b32_e32 v62, v70
	v_mov_b32_e32 v63, v58
	v_pk_mul_f32 v[62:63], v[62:63], v[62:63]
	v_mov_b32_e32 v72, v71
	v_mov_b32_e32 v73, v59
	v_pk_fma_f32 v[62:63], v[72:73], v[72:73], v[62:63]
	v_lshlrev_b32_e32 v72, 16, v61
	v_and_b32_e32 v73, 0xffff0000, v61
	v_mul_f32_e32 v61, 0xbfb8aa3b, v72
	v_lshlrev_b32_e32 v84, 16, v57
	v_mul_f32_e32 v57, 0xbfb8aa3b, v73
	v_exp_f32_e32 v74, v61
	v_exp_f32_e32 v75, v57
	v_pk_mul_f32 v[84:85], v[84:85], v[72:73]
	v_pk_add_f32 v[72:73], v[74:75], 1.0 op_sel_hi:[1,0]
	v_rcp_f32_e32 v73, v73
	v_lshlrev_b32_e32 v74, 16, v60
	v_and_b32_e32 v75, 0xffff0000, v60
	v_rcp_f32_e32 v72, v72
	v_mul_f32_e32 v57, 0xbfb8aa3b, v74
	v_mul_f32_e32 v61, 0xbfb8aa3b, v75
	v_exp_f32_e32 v60, v57
	v_exp_f32_e32 v61, v61
	v_pk_mul_f32 v[72:73], v[84:85], v[72:73]
	v_lshlrev_b32_e32 v84, 16, v56
	v_and_b32_e32 v85, 0xffff0000, v56
	v_pk_add_f32 v[60:61], v[60:61], 1.0 op_sel_hi:[1,0]
	v_pk_mul_f32 v[56:57], v[84:85], v[74:75]
	v_rcp_f32_e32 v61, v61
	v_rcp_f32_e32 v60, v60
	s_nop 0
	v_pk_mul_f32 v[56:57], v[56:57], v[60:61]
	v_mov_b32_e32 v61, v72
	v_mov_b32_e32 v60, v56
	v_pk_mul_f32 v[60:61], v[60:61], v[60:61]
	v_mov_b32_e32 v74, v57
	v_mov_b32_e32 v75, v73
	v_pk_fma_f32 v[60:61], v[74:75], v[74:75], v[60:61]
	s_waitcnt vmcnt(0)
	v_lshlrev_b32_e32 v74, 16, v55
	v_and_b32_e32 v75, 0xffff0000, v55
	v_mul_f32_e32 v55, 0xbfb8aa3b, v74
	v_lshlrev_b32_e32 v86, 16, v51
	v_mul_f32_e32 v51, 0xbfb8aa3b, v75
	v_exp_f32_e32 v84, v55
	v_exp_f32_e32 v85, v51
	v_pk_mul_f32 v[86:87], v[86:87], v[74:75]
	v_pk_add_f32 v[74:75], v[84:85], 1.0 op_sel_hi:[1,0]
	v_rcp_f32_e32 v75, v75
	v_lshlrev_b32_e32 v84, 16, v54
	v_and_b32_e32 v85, 0xffff0000, v54
	v_rcp_f32_e32 v74, v74
	v_mul_f32_e32 v51, 0xbfb8aa3b, v84
	v_mul_f32_e32 v55, 0xbfb8aa3b, v85
	v_exp_f32_e32 v54, v51
	v_exp_f32_e32 v55, v55
	v_pk_mul_f32 v[74:75], v[86:87], v[74:75]
	v_lshlrev_b32_e32 v86, 16, v50
	v_and_b32_e32 v87, 0xffff0000, v50
	v_pk_add_f32 v[54:55], v[54:55], 1.0 op_sel_hi:[1,0]
	v_pk_mul_f32 v[50:51], v[86:87], v[84:85]
	v_rcp_f32_e32 v55, v55
	v_rcp_f32_e32 v54, v54
	s_nop 0
	v_pk_mul_f32 v[50:51], v[50:51], v[54:55]
	v_mov_b32_e32 v54, v74
	v_mov_b32_e32 v55, v50
	v_pk_mul_f32 v[54:55], v[54:55], v[54:55]
	v_mov_b32_e32 v84, v75
	v_mov_b32_e32 v85, v51
	v_pk_fma_f32 v[54:55], v[84:85], v[84:85], v[54:55]
	v_lshlrev_b32_e32 v84, 16, v53
	v_and_b32_e32 v85, 0xffff0000, v53
	v_mul_f32_e32 v53, 0xbfb8aa3b, v84
	v_lshlrev_b32_e32 v88, 16, v49
	v_mul_f32_e32 v49, 0xbfb8aa3b, v85
	v_exp_f32_e32 v86, v53
	v_exp_f32_e32 v87, v49
	v_pk_mul_f32 v[88:89], v[88:89], v[84:85]
	v_pk_add_f32 v[84:85], v[86:87], 1.0 op_sel_hi:[1,0]
	v_rcp_f32_e32 v85, v85
	v_lshlrev_b32_e32 v86, 16, v52
	v_and_b32_e32 v87, 0xffff0000, v52
	v_rcp_f32_e32 v84, v84
	v_mul_f32_e32 v49, 0xbfb8aa3b, v86
	v_mul_f32_e32 v53, 0xbfb8aa3b, v87
	v_exp_f32_e32 v52, v49
	v_exp_f32_e32 v53, v53
	v_pk_mul_f32 v[84:85], v[88:89], v[84:85]
	v_lshlrev_b32_e32 v88, 16, v48
	v_and_b32_e32 v89, 0xffff0000, v48
	v_pk_add_f32 v[52:53], v[52:53], 1.0 op_sel_hi:[1,0]
	v_pk_mul_f32 v[48:49], v[88:89], v[86:87]
	v_rcp_f32_e32 v53, v53
	v_div_scale_f32 v86, s[4:5], v52, v52, 1.0
	v_rcp_f32_e32 v87, v86
	s_mov_b32 s4, 0x3b000000
	v_fma_f32 v88, -v86, v87, 1.0
	v_fmac_f32_e32 v87, v88, v87
	v_div_scale_f32 v88, vcc, 1.0, v52, 1.0
	v_mul_f32_e32 v89, v88, v87
	v_fma_f32 v90, -v86, v89, v88
	v_fmac_f32_e32 v89, v90, v87
	v_fma_f32 v86, -v86, v89, v88
	v_div_fmas_f32 v86, v86, v87, v89
	v_div_fixup_f32 v52, v86, v52, 1.0
	v_pk_mul_f32 v[48:49], v[48:49], v[52:53]
	v_mov_b32_e32 v53, v84
	v_mov_b32_e32 v52, v48
	v_pk_mul_f32 v[52:53], v[52:53], v[52:53]
	v_mov_b32_e32 v86, v49
	v_mov_b32_e32 v87, v85
	v_pk_fma_f32 v[52:53], v[86:87], v[86:87], v[52:53]
	v_mov_b32_e32 v87, v60
	v_mov_b32_e32 v86, v52
	v_mov_b32_e32 v60, v53
	v_pk_add_f32 v[52:53], v[86:87], v[60:61]
	v_mov_b32_e32 v60, v55
	v_mov_b32_e32 v61, v63
	v_pk_add_f32 v[52:53], v[60:61], v[52:53]
	v_mov_b32_e32 v55, v62
	v_pk_add_f32 v[52:53], v[54:55], v[52:53]
	ds_bpermute_b32 v55, v65, v53
	ds_bpermute_b32 v54, v65, v52
	s_waitcnt lgkmcnt(0)
	v_pk_add_f32 v[52:53], v[52:53], v[54:55]
	ds_bpermute_b32 v55, v76, v53
	ds_bpermute_b32 v54, v76, v52
	s_waitcnt lgkmcnt(0)
	v_pk_add_f32 v[52:53], v[52:53], v[54:55]
	ds_bpermute_b32 v55, v77, v53
	ds_bpermute_b32 v54, v77, v52
	s_waitcnt lgkmcnt(0)
	v_pk_add_f32 v[52:53], v[52:53], v[54:55]
	ds_bpermute_b32 v55, v78, v53
	ds_bpermute_b32 v54, v78, v52
	s_waitcnt lgkmcnt(0)
	v_pk_add_f32 v[52:53], v[52:53], v[54:55]
	ds_bpermute_b32 v55, v79, v53
	ds_bpermute_b32 v54, v79, v52
	s_waitcnt lgkmcnt(0)
; DI unsigned pk2(float lo, float hi) { const f32x2_t v = {lo, hi}; const bf16x2_t b = __builtin_convertvector(v, bf16x2_t); return __builtin_bit_cast(unsigned, b); }
; DI float lo16(unsigned w) { return __uint_as_float(w << 16); }
; DI float hi16(unsigned w) { return __uint_as_float(w & 0xffff0000u); }
; DI void gatenorm_pass(const Args& a, int G, const int tid) {
;     ...
;         for (int q = 0; q < 4; ++q) { const int m = m0 + q * NGW; if (m < R) {
; #pragma unroll
;             for (int g = 0; g < 2; ++g) {
;                 float v[8]; float s = 0.f;
; #pragma unroll
;                 for (int e = 0; e < 4; ++e) { const float z0 = lo16(zw[q][g][e]), z1 = hi16(zw[q][g][e]); v[2 * e] = lo16(yw[q][g][e]) * z0 * __frcp_rn(1.0f + __expf(-z0)); v[2 * e + 1] = hi16(yw[q][g][e]) * z1 * __frcp_rn(1.0f + __expf(-z1)); s += v[2 * e] * v[2 * e] + v[2 * e + 1] * v[2 * e + 1]; }
;                 s = wave_sum(s); const float r = rsqrtf(s * (1.0f / 512.0f) + EPS);
;                 u32x4 w;
; #pragma unroll
;                 for (int e = 0; e < 4; ++e) w[e] = pk2(v[2 * e] * r, v[2 * e + 1] * r);
;                 *((u32x4*)(MIX + (size_t)m * LDMIX + 512 + g * 512) + lane) = w;
;             } } }
	v_pk_add_f32 v[52:53], v[52:53], v[54:55]
	ds_bpermute_b32 v55, v80, v53
	ds_bpermute_b32 v54, v80, v52
	s_waitcnt lgkmcnt(0)
	v_pk_add_f32 v[52:53], v[52:53], v[54:55]
	v_pk_fma_f32 v[60:61], v[52:53], s[4:5], v[176:177] op_sel_hi:[1,0,0]
	v_mul_f32_e32 v52, 0x4b800000, v61
	v_cmp_gt_f32_e64 s[46:47], s39, v61
	v_cmp_gt_f32_e32 vcc, s39, v60
	s_nop 0
	v_cndmask_b32_e64 v52, v61, v52, s[46:47]
	v_rsq_f32_e32 v52, v52
	s_nop 0
	v_mul_f32_e32 v53, 0x45800000, v52
	v_cndmask_b32_e64 v62, v52, v53, s[46:47]
	v_pk_mul_f32 v[52:53], v[56:57], v[62:63] op_sel_hi:[1,0]
	v_pk_mul_f32 v[54:55], v[72:73], v[62:63] op_sel_hi:[1,0]
	v_cvt_pk_bf16_f32 v52, v52, v53
	v_cvt_pk_bf16_f32 v53, v54, v55
	v_pk_mul_f32 v[54:55], v[58:59], v[62:63] op_sel_hi:[1,0]
	v_pk_mul_f32 v[56:57], v[70:71], v[62:63] op_sel_hi:[1,0]
	v_cvt_pk_bf16_f32 v54, v54, v55
	v_cvt_pk_bf16_f32 v55, v56, v57
	global_store_dwordx4 v[68:69], v[52:55], off offset:1024
	s_nop 1
	v_mul_f32_e32 v52, 0x4b800000, v60
	v_cndmask_b32_e32 v52, v60, v52, vcc
	v_rsq_f32_e32 v52, v52
	s_nop 0
	v_mul_f32_e32 v53, 0x45800000, v52
	v_cndmask_b32_e32 v52, v52, v53, vcc
	v_pk_mul_f32 v[48:49], v[48:49], v[52:53] op_sel_hi:[1,0]
	v_pk_mul_f32 v[54:55], v[84:85], v[52:53] op_sel_hi:[1,0]
	v_pk_mul_f32 v[50:51], v[50:51], v[52:53] op_sel_hi:[1,0]
	v_pk_mul_f32 v[52:53], v[74:75], v[52:53] op_sel_hi:[1,0]
	v_cvt_pk_bf16_f32 v48, v48, v49
	v_cvt_pk_bf16_f32 v49, v54, v55
	v_cvt_pk_bf16_f32 v50, v50, v51
	v_cvt_pk_bf16_f32 v51, v52, v53
	global_store_dwordx4 v[68:69], v[48:51], off offset:2048
	s_and_saveexec_b64 s[4:5], s[44:45]
	s_cbranch_execz .LBB0_106
	v_lshlrev_b32_e32 v48, 16, v39
	v_and_b32_e32 v49, 0xffff0000, v39
	v_mul_f32_e32 v50, 0xbfb8aa3b, v48
	v_mul_f32_e32 v51, 0xbfb8aa3b, v49
	v_exp_f32_e32 v50, v50
	v_exp_f32_e32 v51, v51
	v_lshlrev_b32_e32 v52, 16, v7
	v_and_b32_e32 v53, 0xffff0000, v7
	v_pk_mul_f32 v[48:49], v[52:53], v[48:49]
	v_pk_add_f32 v[50:51], v[50:51], 1.0 op_sel_hi:[1,0]
	v_rcp_f32_e32 v51, v51
	v_lshlrev_b32_e32 v52, 16, v38
	v_and_b32_e32 v53, 0xffff0000, v38
	v_mul_f32_e32 v54, 0xbfb8aa3b, v52
	v_mul_f32_e32 v55, 0xbfb8aa3b, v53
	v_exp_f32_e32 v54, v54
	v_exp_f32_e32 v55, v55
	v_rcp_f32_e32 v50, v50
	s_nop 0
	v_pk_mul_f32 v[48:49], v[48:49], v[50:51]
	v_pk_add_f32 v[50:51], v[54:55], 1.0 op_sel_hi:[1,0]
	v_lshlrev_b32_e32 v54, 16, v6
	v_and_b32_e32 v55, 0xffff0000, v6
	v_pk_mul_f32 v[52:53], v[54:55], v[52:53]
	v_rcp_f32_e32 v51, v51
	v_rcp_f32_e32 v50, v50
	v_lshlrev_b32_e32 v54, 16, v37
	v_and_b32_e32 v55, 0xffff0000, v37
	v_mul_f32_e32 v56, 0xbfb8aa3b, v54
	v_mul_f32_e32 v57, 0xbfb8aa3b, v55
	v_exp_f32_e32 v56, v56
	v_exp_f32_e32 v57, v57
	v_pk_mul_f32 v[50:51], v[52:53], v[50:51]
	v_mov_b32_e32 v52, v48
	v_mov_b32_e32 v53, v50
	v_pk_add_f32 v[56:57], v[56:57], 1.0 op_sel_hi:[1,0]
	v_pk_mul_f32 v[52:53], v[52:53], v[52:53]
	v_mov_b32_e32 v58, v49
	v_mov_b32_e32 v59, v51
	v_pk_fma_f32 v[52:53], v[58:59], v[58:59], v[52:53]
	v_lshlrev_b32_e32 v58, 16, v5
	v_and_b32_e32 v59, 0xffff0000, v5
	v_pk_mul_f32 v[54:55], v[58:59], v[54:55]
	v_rcp_f32_e32 v57, v57
	v_lshlrev_b32_e32 v58, 16, v36
	v_and_b32_e32 v59, 0xffff0000, v36
	v_mul_f32_e32 v60, 0xbfb8aa3b, v58
	v_mul_f32_e32 v61, 0xbfb8aa3b, v59
	v_exp_f32_e32 v60, v60
	v_exp_f32_e32 v61, v61
	v_rcp_f32_e32 v56, v56
	s_nop 0
	v_pk_mul_f32 v[54:55], v[54:55], v[56:57]
	v_pk_add_f32 v[56:57], v[60:61], 1.0 op_sel_hi:[1,0]
	v_lshlrev_b32_e32 v60, 16, v4
	v_and_b32_e32 v61, 0xffff0000, v4
	v_pk_mul_f32 v[58:59], v[60:61], v[58:59]
	v_mov_b32_e32 v69, v55
	v_rcp_f32_e32 v57, v57
	v_rcp_f32_e32 v56, v56
	v_lshlrev_b32_e32 v60, 16, v35
	v_and_b32_e32 v61, 0xffff0000, v35
	v_mul_f32_e32 v62, 0xbfb8aa3b, v60
	v_mul_f32_e32 v63, 0xbfb8aa3b, v61
	v_exp_f32_e32 v62, v62
	v_exp_f32_e32 v63, v63
	v_pk_mul_f32 v[56:57], v[58:59], v[56:57]
	v_mov_b32_e32 v59, v54
	v_mov_b32_e32 v58, v56
	v_pk_mul_f32 v[58:59], v[58:59], v[58:59]
	v_mov_b32_e32 v68, v57
	v_pk_fma_f32 v[68:69], v[68:69], v[68:69], v[58:59]
	v_pk_add_f32 v[58:59], v[62:63], 1.0 op_sel_hi:[1,0]
	v_lshlrev_b32_e32 v62, 16, v19
	v_and_b32_e32 v63, 0xffff0000, v19
	v_pk_mul_f32 v[60:61], v[62:63], v[60:61]
	v_rcp_f32_e32 v59, v59
	v_lshlrev_b32_e32 v62, 16, v34
	v_and_b32_e32 v63, 0xffff0000, v34
	v_mul_f32_e32 v70, 0xbfb8aa3b, v62
	v_mul_f32_e32 v71, 0xbfb8aa3b, v63
	v_exp_f32_e32 v70, v70
	v_exp_f32_e32 v71, v71
	v_rcp_f32_e32 v58, v58
	s_nop 0
	v_pk_mul_f32 v[58:59], v[60:61], v[58:59]
	v_pk_add_f32 v[60:61], v[70:71], 1.0 op_sel_hi:[1,0]
	v_lshlrev_b32_e32 v70, 16, v18
	v_and_b32_e32 v71, 0xffff0000, v18
	v_pk_mul_f32 v[62:63], v[70:71], v[62:63]
	v_rcp_f32_e32 v61, v61
	v_rcp_f32_e32 v60, v60
	v_lshlrev_b32_e32 v70, 16, v33
	v_and_b32_e32 v71, 0xffff0000, v33
	v_mul_f32_e32 v72, 0xbfb8aa3b, v70
	v_mul_f32_e32 v73, 0xbfb8aa3b, v71
	v_exp_f32_e32 v72, v72
	v_exp_f32_e32 v73, v73
	v_pk_mul_f32 v[60:61], v[62:63], v[60:61]
	v_mov_b32_e32 v62, v58
	v_mov_b32_e32 v63, v60
	v_pk_add_f32 v[72:73], v[72:73], 1.0 op_sel_hi:[1,0]
	v_pk_mul_f32 v[62:63], v[62:63], v[62:63]
	v_mov_b32_e32 v74, v59
	v_mov_b32_e32 v75, v61
	v_pk_fma_f32 v[62:63], v[74:75], v[74:75], v[62:63]
	v_lshlrev_b32_e32 v74, 16, v17
	v_and_b32_e32 v75, 0xffff0000, v17
	v_pk_mul_f32 v[70:71], v[74:75], v[70:71]
	v_rcp_f32_e32 v73, v73
	v_lshlrev_b32_e32 v74, 16, v32
	v_and_b32_e32 v75, 0xffff0000, v32
	v_mul_f32_e32 v84, 0xbfb8aa3b, v74
	v_mul_f32_e32 v85, 0xbfb8aa3b, v75
	v_exp_f32_e32 v84, v84
	v_exp_f32_e32 v85, v85
	v_rcp_f32_e32 v72, v72
	s_nop 0
	v_pk_mul_f32 v[70:71], v[70:71], v[72:73]
	v_pk_add_f32 v[72:73], v[84:85], 1.0 op_sel_hi:[1,0]
	v_lshlrev_b32_e32 v84, 16, v16
	v_and_b32_e32 v85, 0xffff0000, v16
	v_pk_mul_f32 v[74:75], v[84:85], v[74:75]
	v_div_scale_f32 v86, s[6:7], v72, v72, 1.0
	v_rcp_f32_e32 v88, v86
	v_rcp_f32_e32 v73, v73
	s_mov_b32 s6, 0x3b000000
	v_fma_f32 v84, -v86, v88, 1.0
	v_fmac_f32_e32 v88, v84, v88
	v_div_scale_f32 v84, vcc, 1.0, v72, 1.0
	v_mul_f32_e32 v85, v84, v88
	v_fma_f32 v87, -v86, v85, v84
	v_fmac_f32_e32 v85, v87, v88
	v_fma_f32 v84, -v86, v85, v84
	v_div_fmas_f32 v84, v84, v88, v85
	v_div_fixup_f32 v72, v84, v72, 1.0
	v_pk_mul_f32 v[72:73], v[74:75], v[72:73]
	v_mov_b32_e32 v75, v70
	v_mov_b32_e32 v74, v72
	v_pk_mul_f32 v[74:75], v[74:75], v[74:75]
	v_mov_b32_e32 v84, v73
	v_mov_b32_e32 v85, v71
	v_pk_fma_f32 v[74:75], v[84:85], v[84:85], v[74:75]
	v_mov_b32_e32 v85, v68
	v_mov_b32_e32 v84, v74
	v_mov_b32_e32 v68, v75
	v_pk_add_f32 v[68:69], v[84:85], v[68:69]
	v_mov_b32_e32 v74, v63
	v_mov_b32_e32 v75, v53
	v_pk_add_f32 v[68:69], v[74:75], v[68:69]
	v_mov_b32_e32 v63, v52
	v_pk_add_f32 v[52:53], v[62:63], v[68:69]
	ds_bpermute_b32 v63, v65, v53
	ds_bpermute_b32 v62, v65, v52
	s_waitcnt lgkmcnt(0)
; DI unsigned pk2(float lo, float hi) { const f32x2_t v = {lo, hi}; const bf16x2_t b = __builtin_convertvector(v, bf16x2_t); return __builtin_bit_cast(unsigned, b); }
; DI float lo16(unsigned w) { return __uint_as_float(w << 16); }
; DI float hi16(unsigned w) { return __uint_as_float(w & 0xffff0000u); }
; DI void gatenorm_pass(const Args& a, int G, const int tid) {
;     ...
;         for (int q = 0; q < 4; ++q) { const int m = m0 + q * NGW; if (m < R) {
; #pragma unroll
;             for (int g = 0; g < 2; ++g) {
;                 float v[8]; float s = 0.f;
; #pragma unroll
;                 for (int e = 0; e < 4; ++e) { const float z0 = lo16(zw[q][g][e]), z1 = hi16(zw[q][g][e]); v[2 * e] = lo16(yw[q][g][e]) * z0 * __frcp_rn(1.0f + __expf(-z0)); v[2 * e + 1] = hi16(yw[q][g][e]) * z1 * __frcp_rn(1.0f + __expf(-z1)); s += v[2 * e] * v[2 * e] + v[2 * e + 1] * v[2 * e + 1]; }
;                 s = wave_sum(s); const float r = rsqrtf(s * (1.0f / 512.0f) + EPS);
;                 u32x4 w;
; #pragma unroll
;                 for (int e = 0; e < 4; ++e) w[e] = pk2(v[2 * e] * r, v[2 * e + 1] * r);
;                 *((u32x4*)(MIX + (size_t)m * LDMIX + 512 + g * 512) + lane) = w;
;             } } }
	v_pk_add_f32 v[52:53], v[52:53], v[62:63]
	ds_bpermute_b32 v63, v76, v53
	ds_bpermute_b32 v62, v76, v52
	s_waitcnt lgkmcnt(0)
	v_pk_add_f32 v[52:53], v[52:53], v[62:63]
	ds_bpermute_b32 v63, v77, v53
	ds_bpermute_b32 v62, v77, v52
	s_waitcnt lgkmcnt(0)
	v_pk_add_f32 v[52:53], v[52:53], v[62:63]
	ds_bpermute_b32 v63, v78, v53
	ds_bpermute_b32 v62, v78, v52
	s_waitcnt lgkmcnt(0)
	v_pk_add_f32 v[52:53], v[52:53], v[62:63]
	ds_bpermute_b32 v63, v79, v53
	ds_bpermute_b32 v62, v79, v52
	s_waitcnt lgkmcnt(0)
	v_pk_add_f32 v[52:53], v[52:53], v[62:63]
	ds_bpermute_b32 v63, v80, v53
	ds_bpermute_b32 v62, v80, v52
	s_waitcnt lgkmcnt(0)
	v_pk_add_f32 v[52:53], v[52:53], v[62:63]
	v_pk_fma_f32 v[62:63], v[52:53], s[6:7], v[176:177] op_sel_hi:[1,0,0]
	v_mad_i64_i32 v[68:69], s[6:7], v81, s27, v[66:67]
	v_mul_f32_e32 v52, 0x4b800000, v63
	v_cmp_gt_f32_e32 vcc, s39, v63
	s_nop 1
	v_cndmask_b32_e32 v52, v63, v52, vcc
	v_rsq_f32_e32 v52, v52
	s_nop 0
	v_mul_f32_e32 v53, 0x45800000, v52
	v_cndmask_b32_e32 v74, v52, v53, vcc
	v_pk_mul_f32 v[52:53], v[56:57], v[74:75] op_sel_hi:[1,0]
	v_pk_mul_f32 v[54:55], v[54:55], v[74:75] op_sel_hi:[1,0]
	v_pk_mul_f32 v[50:51], v[50:51], v[74:75] op_sel_hi:[1,0]
	v_cvt_pk_bf16_f32 v52, v52, v53
	v_cvt_pk_bf16_f32 v53, v54, v55
	v_cvt_pk_bf16_f32 v54, v50, v51
	v_mul_f32_e32 v50, 0x4b800000, v62
	v_cmp_gt_f32_e32 vcc, s39, v62
	v_pk_mul_f32 v[48:49], v[48:49], v[74:75] op_sel_hi:[1,0]
	s_nop 0
	v_cndmask_b32_e32 v50, v62, v50, vcc
	v_rsq_f32_e32 v50, v50
	v_cvt_pk_bf16_f32 v55, v48, v49
	global_store_dwordx4 v[68:69], v[52:55], off offset:1024
	v_mul_f32_e32 v48, 0x45800000, v50
	s_nop 0
	v_cndmask_b32_e32 v52, v50, v48, vcc
	v_pk_mul_f32 v[48:49], v[72:73], v[52:53] op_sel_hi:[1,0]
	v_pk_mul_f32 v[50:51], v[70:71], v[52:53] op_sel_hi:[1,0]
	v_cvt_pk_bf16_f32 v48, v48, v49
	v_cvt_pk_bf16_f32 v49, v50, v51
	v_pk_mul_f32 v[50:51], v[60:61], v[52:53] op_sel_hi:[1,0]
	v_pk_mul_f32 v[52:53], v[58:59], v[52:53] op_sel_hi:[1,0]
	v_cvt_pk_bf16_f32 v50, v50, v51
	v_cvt_pk_bf16_f32 v51, v52, v53
	global_store_dwordx4 v[68:69], v[48:51], off offset:2048
	s_or_b64 exec, exec, s[4:5]
	s_and_saveexec_b64 s[4:5], s[42:43]
	s_cbranch_execnz .LBB0_107

; DI unsigned pk2(float lo, float hi) { const f32x2_t v = {lo, hi}; const bf16x2_t b = __builtin_convertvector(v, bf16x2_t); return __builtin_bit_cast(unsigned, b); }
; DI float lo16(unsigned w) { return __uint_as_float(w << 16); }
; DI float hi16(unsigned w) { return __uint_as_float(w & 0xffff0000u); }
; DI void gatenorm_pass(const Args& a, int G, const int tid) {
;     ...
;         for (int q = 0; q < 4; ++q) { const int m = m0 + q * NGW; if (m < R) {
; #pragma unroll
;             for (int g = 0; g < 2; ++g) {
;                 float v[8]; float s = 0.f;
; #pragma unroll
;                 for (int e = 0; e < 4; ++e) { const float z0 = lo16(zw[q][g][e]), z1 = hi16(zw[q][g][e]); v[2 * e] = lo16(yw[q][g][e]) * z0 * __frcp_rn(1.0f + __expf(-z0)); v[2 * e + 1] = hi16(yw[q][g][e]) * z1 * __frcp_rn(1.0f + __expf(-z1)); s += v[2 * e] * v[2 * e] + v[2 * e + 1] * v[2 * e + 1]; }
;                 s = wave_sum(s); const float r = rsqrtf(s * (1.0f / 512.0f) + EPS);
;                 u32x4 w;
; #pragma unroll
;                 for (int e = 0; e < 4; ++e) w[e] = pk2(v[2 * e] * r, v[2 * e + 1] * r);
;                 *((u32x4*)(MIX + (size_t)m * LDMIX + 512 + g * 512) + lane) = w;
;             } } }
.LBB0_107:
	v_lshlrev_b32_e32 v48, 16, v47
	v_and_b32_e32 v49, 0xffff0000, v47
	v_mul_f32_e32 v50, 0xbfb8aa3b, v48
	v_mul_f32_e32 v51, 0xbfb8aa3b, v49
	v_exp_f32_e32 v50, v50
	v_exp_f32_e32 v51, v51
	v_lshlrev_b32_e32 v52, 16, v11
	v_and_b32_e32 v53, 0xffff0000, v11
	v_pk_mul_f32 v[48:49], v[52:53], v[48:49]
	v_pk_add_f32 v[50:51], v[50:51], 1.0 op_sel_hi:[1,0]
	v_rcp_f32_e32 v51, v51
	v_lshlrev_b32_e32 v52, 16, v46
	v_and_b32_e32 v53, 0xffff0000, v46
	v_mul_f32_e32 v54, 0xbfb8aa3b, v52
	v_mul_f32_e32 v55, 0xbfb8aa3b, v53
	v_exp_f32_e32 v54, v54
	v_exp_f32_e32 v55, v55
	v_rcp_f32_e32 v50, v50
	s_nop 0
	v_pk_mul_f32 v[48:49], v[48:49], v[50:51]
	v_pk_add_f32 v[50:51], v[54:55], 1.0 op_sel_hi:[1,0]
	v_lshlrev_b32_e32 v54, 16, v10
	v_and_b32_e32 v55, 0xffff0000, v10
	v_pk_mul_f32 v[52:53], v[54:55], v[52:53]
	v_rcp_f32_e32 v51, v51
	v_rcp_f32_e32 v50, v50
	v_lshlrev_b32_e32 v54, 16, v45
	v_and_b32_e32 v55, 0xffff0000, v45
	v_mul_f32_e32 v56, 0xbfb8aa3b, v54
	v_mul_f32_e32 v57, 0xbfb8aa3b, v55
	v_exp_f32_e32 v56, v56
	v_exp_f32_e32 v57, v57
	v_pk_mul_f32 v[50:51], v[52:53], v[50:51]
	v_mov_b32_e32 v52, v48
	v_mov_b32_e32 v53, v50
	v_pk_add_f32 v[56:57], v[56:57], 1.0 op_sel_hi:[1,0]
	v_pk_mul_f32 v[52:53], v[52:53], v[52:53]
	v_mov_b32_e32 v58, v49
	v_mov_b32_e32 v59, v51
	v_pk_fma_f32 v[52:53], v[58:59], v[58:59], v[52:53]
	v_lshlrev_b32_e32 v58, 16, v9
	v_and_b32_e32 v59, 0xffff0000, v9
	v_pk_mul_f32 v[54:55], v[58:59], v[54:55]
	v_rcp_f32_e32 v57, v57
	v_lshlrev_b32_e32 v58, 16, v44
	v_and_b32_e32 v59, 0xffff0000, v44
	v_mul_f32_e32 v60, 0xbfb8aa3b, v58
	v_mul_f32_e32 v61, 0xbfb8aa3b, v59
	v_exp_f32_e32 v60, v60
	v_exp_f32_e32 v61, v61
	v_rcp_f32_e32 v56, v56
	s_nop 0
	v_pk_mul_f32 v[54:55], v[54:55], v[56:57]
	v_pk_add_f32 v[56:57], v[60:61], 1.0 op_sel_hi:[1,0]
	v_lshlrev_b32_e32 v60, 16, v8
	v_and_b32_e32 v61, 0xffff0000, v8
	v_pk_mul_f32 v[58:59], v[60:61], v[58:59]
	v_mov_b32_e32 v69, v55
	v_rcp_f32_e32 v57, v57
	v_rcp_f32_e32 v56, v56
	v_lshlrev_b32_e32 v60, 16, v43
	v_and_b32_e32 v61, 0xffff0000, v43
	v_mul_f32_e32 v62, 0xbfb8aa3b, v60
	v_mul_f32_e32 v63, 0xbfb8aa3b, v61
	v_exp_f32_e32 v62, v62
	v_exp_f32_e32 v63, v63
	v_pk_mul_f32 v[56:57], v[58:59], v[56:57]
	v_mov_b32_e32 v59, v54
	v_mov_b32_e32 v58, v56
	v_pk_mul_f32 v[58:59], v[58:59], v[58:59]
	v_mov_b32_e32 v68, v57
	v_pk_fma_f32 v[68:69], v[68:69], v[68:69], v[58:59]
	v_pk_add_f32 v[58:59], v[62:63], 1.0 op_sel_hi:[1,0]
	v_lshlrev_b32_e32 v62, 16, v23
	v_and_b32_e32 v63, 0xffff0000, v23
	v_pk_mul_f32 v[60:61], v[62:63], v[60:61]
	v_rcp_f32_e32 v59, v59
	v_lshlrev_b32_e32 v62, 16, v42
	v_and_b32_e32 v63, 0xffff0000, v42
	v_mul_f32_e32 v70, 0xbfb8aa3b, v62
	v_mul_f32_e32 v71, 0xbfb8aa3b, v63
	v_exp_f32_e32 v70, v70
	v_exp_f32_e32 v71, v71
	v_rcp_f32_e32 v58, v58
	s_nop 0
	v_pk_mul_f32 v[58:59], v[60:61], v[58:59]
	v_pk_add_f32 v[60:61], v[70:71], 1.0 op_sel_hi:[1,0]
	v_lshlrev_b32_e32 v70, 16, v22
	v_and_b32_e32 v71, 0xffff0000, v22
	v_pk_mul_f32 v[62:63], v[70:71], v[62:63]
	v_rcp_f32_e32 v61, v61
	v_rcp_f32_e32 v60, v60
	v_lshlrev_b32_e32 v70, 16, v41
	v_and_b32_e32 v71, 0xffff0000, v41
	v_mul_f32_e32 v72, 0xbfb8aa3b, v70
	v_mul_f32_e32 v73, 0xbfb8aa3b, v71
	v_exp_f32_e32 v72, v72
	v_exp_f32_e32 v73, v73
	v_pk_mul_f32 v[60:61], v[62:63], v[60:61]
	v_mov_b32_e32 v62, v58
	v_mov_b32_e32 v63, v60
	v_pk_add_f32 v[72:73], v[72:73], 1.0 op_sel_hi:[1,0]
	v_pk_mul_f32 v[62:63], v[62:63], v[62:63]
	v_mov_b32_e32 v74, v59
	v_mov_b32_e32 v75, v61
	v_pk_fma_f32 v[62:63], v[74:75], v[74:75], v[62:63]
	v_lshlrev_b32_e32 v74, 16, v21
	v_and_b32_e32 v75, 0xffff0000, v21
	v_pk_mul_f32 v[70:71], v[74:75], v[70:71]
	v_rcp_f32_e32 v73, v73
	v_lshlrev_b32_e32 v74, 16, v40
	v_and_b32_e32 v75, 0xffff0000, v40
	v_mul_f32_e32 v84, 0xbfb8aa3b, v74
	v_mul_f32_e32 v85, 0xbfb8aa3b, v75
	v_exp_f32_e32 v84, v84
	v_exp_f32_e32 v85, v85
	v_rcp_f32_e32 v72, v72
	s_nop 0
	v_pk_mul_f32 v[70:71], v[70:71], v[72:73]
	v_pk_add_f32 v[72:73], v[84:85], 1.0 op_sel_hi:[1,0]
	v_lshlrev_b32_e32 v84, 16, v20
	v_and_b32_e32 v85, 0xffff0000, v20
	v_pk_mul_f32 v[74:75], v[84:85], v[74:75]
	v_div_scale_f32 v86, s[6:7], v72, v72, 1.0
	v_rcp_f32_e32 v88, v86
	v_rcp_f32_e32 v73, v73
	s_mov_b32 s6, 0x3b000000
	v_fma_f32 v84, -v86, v88, 1.0
	v_fmac_f32_e32 v88, v84, v88
	v_div_scale_f32 v84, vcc, 1.0, v72, 1.0
	v_mul_f32_e32 v85, v84, v88
	v_fma_f32 v87, -v86, v85, v84
	v_fmac_f32_e32 v85, v87, v88
	v_fma_f32 v84, -v86, v85, v84
	v_div_fmas_f32 v84, v84, v88, v85
	v_div_fixup_f32 v72, v84, v72, 1.0
	v_pk_mul_f32 v[72:73], v[74:75], v[72:73]
	v_mov_b32_e32 v75, v70
	v_mov_b32_e32 v74, v72
	v_pk_mul_f32 v[74:75], v[74:75], v[74:75]
	v_mov_b32_e32 v84, v73
	v_mov_b32_e32 v85, v71
	v_pk_fma_f32 v[74:75], v[84:85], v[84:85], v[74:75]
	v_mov_b32_e32 v85, v68
	v_mov_b32_e32 v84, v74
	v_mov_b32_e32 v68, v75
	v_pk_add_f32 v[68:69], v[84:85], v[68:69]
	v_mov_b32_e32 v74, v63
	v_mov_b32_e32 v75, v53
	v_pk_add_f32 v[68:69], v[74:75], v[68:69]
	v_mov_b32_e32 v63, v52
	v_pk_add_f32 v[52:53], v[62:63], v[68:69]
	ds_bpermute_b32 v63, v65, v53
	ds_bpermute_b32 v62, v65, v52
	s_waitcnt lgkmcnt(0)
	v_pk_add_f32 v[52:53], v[52:53], v[62:63]
	ds_bpermute_b32 v63, v76, v53
	ds_bpermute_b32 v62, v76, v52
	s_waitcnt lgkmcnt(0)
	v_pk_add_f32 v[52:53], v[52:53], v[62:63]
	ds_bpermute_b32 v63, v77, v53
	ds_bpermute_b32 v62, v77, v52
	s_waitcnt lgkmcnt(0)
	v_pk_add_f32 v[52:53], v[52:53], v[62:63]
	ds_bpermute_b32 v63, v78, v53
	ds_bpermute_b32 v62, v78, v52
	s_waitcnt lgkmcnt(0)
	v_pk_add_f32 v[52:53], v[52:53], v[62:63]
	ds_bpermute_b32 v63, v79, v53
	ds_bpermute_b32 v62, v79, v52
	s_waitcnt lgkmcnt(0)
; DI unsigned pk2(float lo, float hi) { const f32x2_t v = {lo, hi}; const bf16x2_t b = __builtin_convertvector(v, bf16x2_t); return __builtin_bit_cast(unsigned, b); }
; DI float lo16(unsigned w) { return __uint_as_float(w << 16); }
; DI float hi16(unsigned w) { return __uint_as_float(w & 0xffff0000u); }
; DI void gatenorm_pass(const Args& a, int G, const int tid) {
;     ...
;         for (int q = 0; q < 4; ++q) { const int m = m0 + q * NGW; if (m < R) {
; #pragma unroll
;             for (int g = 0; g < 2; ++g) {
;                 float v[8]; float s = 0.f;
; #pragma unroll
;                 for (int e = 0; e < 4; ++e) { const float z0 = lo16(zw[q][g][e]), z1 = hi16(zw[q][g][e]); v[2 * e] = lo16(yw[q][g][e]) * z0 * __frcp_rn(1.0f + __expf(-z0)); v[2 * e + 1] = hi16(yw[q][g][e]) * z1 * __frcp_rn(1.0f + __expf(-z1)); s += v[2 * e] * v[2 * e] + v[2 * e + 1] * v[2 * e + 1]; }
;                 s = wave_sum(s); const float r = rsqrtf(s * (1.0f / 512.0f) + EPS);
;                 u32x4 w;
; #pragma unroll
;                 for (int e = 0; e < 4; ++e) w[e] = pk2(v[2 * e] * r, v[2 * e + 1] * r);
;                 *((u32x4*)(MIX + (size_t)m * LDMIX + 512 + g * 512) + lane) = w;
;             } } }
	v_pk_add_f32 v[52:53], v[52:53], v[62:63]
	ds_bpermute_b32 v63, v80, v53
	ds_bpermute_b32 v62, v80, v52
	s_waitcnt lgkmcnt(0)
	v_pk_add_f32 v[52:53], v[52:53], v[62:63]
	v_pk_fma_f32 v[62:63], v[52:53], s[6:7], v[176:177] op_sel_hi:[1,0,0]
	v_mad_i64_i32 v[68:69], s[6:7], v83, s27, v[66:67]
	v_mul_f32_e32 v52, 0x4b800000, v63
	v_cmp_gt_f32_e32 vcc, s39, v63
	s_nop 1
	v_cndmask_b32_e32 v52, v63, v52, vcc
	v_rsq_f32_e32 v52, v52
	s_nop 0
	v_mul_f32_e32 v53, 0x45800000, v52
	v_cndmask_b32_e32 v74, v52, v53, vcc
	v_pk_mul_f32 v[52:53], v[56:57], v[74:75] op_sel_hi:[1,0]
	v_pk_mul_f32 v[54:55], v[54:55], v[74:75] op_sel_hi:[1,0]
	v_pk_mul_f32 v[50:51], v[50:51], v[74:75] op_sel_hi:[1,0]
	v_cvt_pk_bf16_f32 v52, v52, v53
	v_cvt_pk_bf16_f32 v53, v54, v55
	v_cvt_pk_bf16_f32 v54, v50, v51
	v_mul_f32_e32 v50, 0x4b800000, v62
	v_cmp_gt_f32_e32 vcc, s39, v62
	v_pk_mul_f32 v[48:49], v[48:49], v[74:75] op_sel_hi:[1,0]
	s_nop 0
	v_cndmask_b32_e32 v50, v62, v50, vcc
	v_rsq_f32_e32 v50, v50
	v_cvt_pk_bf16_f32 v55, v48, v49
	global_store_dwordx4 v[68:69], v[52:55], off offset:1024
	v_mul_f32_e32 v48, 0x45800000, v50
	s_nop 0
	v_cndmask_b32_e32 v52, v50, v48, vcc
	v_pk_mul_f32 v[48:49], v[72:73], v[52:53] op_sel_hi:[1,0]
	v_pk_mul_f32 v[50:51], v[70:71], v[52:53] op_sel_hi:[1,0]
	v_cvt_pk_bf16_f32 v48, v48, v49
	v_cvt_pk_bf16_f32 v49, v50, v51
	v_pk_mul_f32 v[50:51], v[60:61], v[52:53] op_sel_hi:[1,0]
	v_pk_mul_f32 v[52:53], v[58:59], v[52:53] op_sel_hi:[1,0]
	v_cvt_pk_bf16_f32 v50, v50, v51
	v_cvt_pk_bf16_f32 v51, v52, v53
	global_store_dwordx4 v[68:69], v[48:51], off offset:2048
	s_or_b64 exec, exec, s[4:5]
	s_and_saveexec_b64 s[4:5], s[40:41]
	s_cbranch_execz .LBB0_96
.LBB0_108:
	v_lshlrev_b32_e32 v48, 16, v31
	v_and_b32_e32 v49, 0xffff0000, v31
	v_mul_f32_e32 v50, 0xbfb8aa3b, v48
	v_mul_f32_e32 v51, 0xbfb8aa3b, v49
	v_exp_f32_e32 v50, v50
	v_exp_f32_e32 v51, v51
	v_lshlrev_b32_e32 v52, 16, v3
	v_and_b32_e32 v53, 0xffff0000, v3
	v_pk_mul_f32 v[48:49], v[52:53], v[48:49]
	v_pk_add_f32 v[50:51], v[50:51], 1.0 op_sel_hi:[1,0]
	v_rcp_f32_e32 v51, v51
	v_lshlrev_b32_e32 v52, 16, v30
	v_and_b32_e32 v53, 0xffff0000, v30
	v_mul_f32_e32 v54, 0xbfb8aa3b, v52
	v_mul_f32_e32 v55, 0xbfb8aa3b, v53
	v_exp_f32_e32 v54, v54
	v_exp_f32_e32 v55, v55
	v_rcp_f32_e32 v50, v50
	s_nop 0
	v_pk_mul_f32 v[48:49], v[48:49], v[50:51]
	v_pk_add_f32 v[50:51], v[54:55], 1.0 op_sel_hi:[1,0]
	v_lshlrev_b32_e32 v54, 16, v2
	v_and_b32_e32 v55, 0xffff0000, v2
	v_pk_mul_f32 v[52:53], v[54:55], v[52:53]
	v_rcp_f32_e32 v51, v51
	v_rcp_f32_e32 v50, v50
	v_lshlrev_b32_e32 v54, 16, v29
	v_and_b32_e32 v55, 0xffff0000, v29
	v_mul_f32_e32 v56, 0xbfb8aa3b, v54
	v_mul_f32_e32 v57, 0xbfb8aa3b, v55
	v_exp_f32_e32 v56, v56
	v_exp_f32_e32 v57, v57
	v_pk_mul_f32 v[50:51], v[52:53], v[50:51]
	v_mov_b32_e32 v52, v48
	v_mov_b32_e32 v53, v50
	v_pk_add_f32 v[56:57], v[56:57], 1.0 op_sel_hi:[1,0]
	v_pk_mul_f32 v[52:53], v[52:53], v[52:53]
	v_mov_b32_e32 v58, v49
	v_mov_b32_e32 v59, v51
	v_pk_fma_f32 v[52:53], v[58:59], v[58:59], v[52:53]
	v_lshlrev_b32_e32 v58, 16, v1
	v_and_b32_e32 v59, 0xffff0000, v1
	v_pk_mul_f32 v[54:55], v[58:59], v[54:55]
	v_rcp_f32_e32 v57, v57
	v_lshlrev_b32_e32 v58, 16, v28
	v_and_b32_e32 v59, 0xffff0000, v28
	v_mul_f32_e32 v60, 0xbfb8aa3b, v58
	v_mul_f32_e32 v61, 0xbfb8aa3b, v59
	v_exp_f32_e32 v60, v60
	v_exp_f32_e32 v61, v61
	v_rcp_f32_e32 v56, v56
	s_nop 0
	v_pk_mul_f32 v[54:55], v[54:55], v[56:57]
	v_pk_add_f32 v[56:57], v[60:61], 1.0 op_sel_hi:[1,0]
	v_lshlrev_b32_e32 v60, 16, v0
	v_and_b32_e32 v61, 0xffff0000, v0
	v_pk_mul_f32 v[58:59], v[60:61], v[58:59]
	v_mov_b32_e32 v69, v55
	v_rcp_f32_e32 v57, v57
	v_rcp_f32_e32 v56, v56
	v_lshlrev_b32_e32 v60, 16, v27
	v_and_b32_e32 v61, 0xffff0000, v27
	v_mul_f32_e32 v62, 0xbfb8aa3b, v60
	v_mul_f32_e32 v63, 0xbfb8aa3b, v61
	v_exp_f32_e32 v62, v62
	v_exp_f32_e32 v63, v63
	v_pk_mul_f32 v[56:57], v[58:59], v[56:57]
	v_mov_b32_e32 v59, v54
	v_mov_b32_e32 v58, v56
	v_pk_mul_f32 v[58:59], v[58:59], v[58:59]
	v_mov_b32_e32 v68, v57
	v_pk_fma_f32 v[68:69], v[68:69], v[68:69], v[58:59]
	v_pk_add_f32 v[58:59], v[62:63], 1.0 op_sel_hi:[1,0]
	v_lshlrev_b32_e32 v62, 16, v15
	v_and_b32_e32 v63, 0xffff0000, v15
	v_pk_mul_f32 v[60:61], v[62:63], v[60:61]
	v_rcp_f32_e32 v59, v59
	v_lshlrev_b32_e32 v62, 16, v26
	v_and_b32_e32 v63, 0xffff0000, v26
	v_mul_f32_e32 v70, 0xbfb8aa3b, v62
	v_mul_f32_e32 v71, 0xbfb8aa3b, v63
	v_exp_f32_e32 v70, v70
	v_exp_f32_e32 v71, v71
	v_rcp_f32_e32 v58, v58
	s_nop 0
	v_pk_mul_f32 v[58:59], v[60:61], v[58:59]
	v_pk_add_f32 v[60:61], v[70:71], 1.0 op_sel_hi:[1,0]
	v_lshlrev_b32_e32 v70, 16, v14
	v_and_b32_e32 v71, 0xffff0000, v14
	v_pk_mul_f32 v[62:63], v[70:71], v[62:63]
	v_rcp_f32_e32 v61, v61
	v_rcp_f32_e32 v60, v60
	v_lshlrev_b32_e32 v70, 16, v25
	v_and_b32_e32 v71, 0xffff0000, v25
	v_mul_f32_e32 v72, 0xbfb8aa3b, v70
	v_mul_f32_e32 v73, 0xbfb8aa3b, v71
	v_exp_f32_e32 v72, v72
	v_exp_f32_e32 v73, v73
	v_pk_mul_f32 v[60:61], v[62:63], v[60:61]
	v_mov_b32_e32 v62, v58
	v_mov_b32_e32 v63, v60
	v_pk_add_f32 v[72:73], v[72:73], 1.0 op_sel_hi:[1,0]
	v_pk_mul_f32 v[62:63], v[62:63], v[62:63]
	v_mov_b32_e32 v74, v59
	v_mov_b32_e32 v75, v61
	v_pk_fma_f32 v[62:63], v[74:75], v[74:75], v[62:63]
	v_lshlrev_b32_e32 v74, 16, v13
	v_and_b32_e32 v75, 0xffff0000, v13
	v_pk_mul_f32 v[70:71], v[74:75], v[70:71]
	v_rcp_f32_e32 v73, v73
	v_lshlrev_b32_e32 v74, 16, v24
	v_and_b32_e32 v75, 0xffff0000, v24
	v_mul_f32_e32 v84, 0xbfb8aa3b, v74
	v_mul_f32_e32 v85, 0xbfb8aa3b, v75
	v_exp_f32_e32 v84, v84
	v_exp_f32_e32 v85, v85
	v_rcp_f32_e32 v72, v72
	s_nop 0
	v_pk_mul_f32 v[70:71], v[70:71], v[72:73]
	v_pk_add_f32 v[72:73], v[84:85], 1.0 op_sel_hi:[1,0]
	v_lshlrev_b32_e32 v84, 16, v12
	v_and_b32_e32 v85, 0xffff0000, v12
	v_pk_mul_f32 v[74:75], v[84:85], v[74:75]
	v_div_scale_f32 v84, s[6:7], v72, v72, 1.0
	v_rcp_f32_e32 v87, v84
	v_rcp_f32_e32 v73, v73
	s_mov_b32 s6, 0x3b000000
	v_fma_f32 v83, -v84, v87, 1.0
	v_fmac_f32_e32 v87, v83, v87
	v_div_scale_f32 v83, vcc, 1.0, v72, 1.0
	v_mul_f32_e32 v85, v83, v87
	v_fma_f32 v86, -v84, v85, v83
	v_fmac_f32_e32 v85, v86, v87
	v_fma_f32 v83, -v84, v85, v83
	v_div_fmas_f32 v83, v83, v87, v85
	v_div_fixup_f32 v72, v83, v72, 1.0
	v_pk_mul_f32 v[72:73], v[74:75], v[72:73]
	v_mov_b32_e32 v75, v70
	v_mov_b32_e32 v74, v72
	v_pk_mul_f32 v[74:75], v[74:75], v[74:75]
	v_mov_b32_e32 v84, v73
	v_mov_b32_e32 v85, v71
	v_pk_fma_f32 v[74:75], v[84:85], v[84:85], v[74:75]
	v_mov_b32_e32 v85, v68
	v_mov_b32_e32 v84, v74
	v_mov_b32_e32 v68, v75
	v_pk_add_f32 v[68:69], v[84:85], v[68:69]
	v_mov_b32_e32 v74, v63
	v_mov_b32_e32 v75, v53
	v_pk_add_f32 v[68:69], v[74:75], v[68:69]
	v_mov_b32_e32 v63, v52
	v_pk_add_f32 v[52:53], v[62:63], v[68:69]
	ds_bpermute_b32 v63, v65, v53
	ds_bpermute_b32 v62, v65, v52
	s_waitcnt lgkmcnt(0)
; DI unsigned pk2(float lo, float hi) { const f32x2_t v = {lo, hi}; const bf16x2_t b = __builtin_convertvector(v, bf16x2_t); return __builtin_bit_cast(unsigned, b); }
; DI float lo16(unsigned w) { return __uint_as_float(w << 16); }
; DI float hi16(unsigned w) { return __uint_as_float(w & 0xffff0000u); }
; DI void gatenorm_pass(const Args& a, int G, const int tid) {
;     ...
;         for (int q = 0; q < 4; ++q) { const int m = m0 + q * NGW; if (m < R) {
; #pragma unroll
;             for (int g = 0; g < 2; ++g) {
;                 float v[8]; float s = 0.f;
; #pragma unroll
;                 for (int e = 0; e < 4; ++e) { const float z0 = lo16(zw[q][g][e]), z1 = hi16(zw[q][g][e]); v[2 * e] = lo16(yw[q][g][e]) * z0 * __frcp_rn(1.0f + __expf(-z0)); v[2 * e + 1] = hi16(yw[q][g][e]) * z1 * __frcp_rn(1.0f + __expf(-z1)); s += v[2 * e] * v[2 * e] + v[2 * e + 1] * v[2 * e + 1]; }
;                 s = wave_sum(s); const float r = rsqrtf(s * (1.0f / 512.0f) + EPS);
;                 u32x4 w;
; #pragma unroll
;                 for (int e = 0; e < 4; ++e) w[e] = pk2(v[2 * e] * r, v[2 * e + 1] * r);
;                 *((u32x4*)(MIX + (size_t)m * LDMIX + 512 + g * 512) + lane) = w;
;             } } }
	v_pk_add_f32 v[52:53], v[52:53], v[62:63]
	ds_bpermute_b32 v63, v76, v53
	ds_bpermute_b32 v62, v76, v52
	s_waitcnt lgkmcnt(0)
	v_pk_add_f32 v[52:53], v[52:53], v[62:63]
	ds_bpermute_b32 v63, v77, v53
	ds_bpermute_b32 v62, v77, v52
	s_waitcnt lgkmcnt(0)
	v_pk_add_f32 v[52:53], v[52:53], v[62:63]
	ds_bpermute_b32 v63, v78, v53
	ds_bpermute_b32 v62, v78, v52
	s_waitcnt lgkmcnt(0)
	v_pk_add_f32 v[52:53], v[52:53], v[62:63]
	ds_bpermute_b32 v63, v79, v53
	ds_bpermute_b32 v62, v79, v52
	s_waitcnt lgkmcnt(0)
	v_pk_add_f32 v[52:53], v[52:53], v[62:63]
	ds_bpermute_b32 v63, v80, v53
	ds_bpermute_b32 v62, v80, v52
	s_waitcnt lgkmcnt(0)
	v_pk_add_f32 v[52:53], v[52:53], v[62:63]
	v_pk_fma_f32 v[62:63], v[52:53], s[6:7], v[176:177] op_sel_hi:[1,0,0]
	v_mad_i64_i32 v[68:69], s[6:7], v82, s27, v[66:67]
	v_mul_f32_e32 v52, 0x4b800000, v63
	v_cmp_gt_f32_e32 vcc, s39, v63
	s_nop 1
	v_cndmask_b32_e32 v52, v63, v52, vcc
	v_rsq_f32_e32 v52, v52
	s_nop 0
	v_mul_f32_e32 v53, 0x45800000, v52
	v_cndmask_b32_e32 v74, v52, v53, vcc
	v_pk_mul_f32 v[52:53], v[56:57], v[74:75] op_sel_hi:[1,0]
	v_pk_mul_f32 v[54:55], v[54:55], v[74:75] op_sel_hi:[1,0]
	v_pk_mul_f32 v[50:51], v[50:51], v[74:75] op_sel_hi:[1,0]
	v_cvt_pk_bf16_f32 v52, v52, v53
	v_cvt_pk_bf16_f32 v53, v54, v55
	v_cvt_pk_bf16_f32 v54, v50, v51
	v_mul_f32_e32 v50, 0x4b800000, v62
	v_cmp_gt_f32_e32 vcc, s39, v62
	v_pk_mul_f32 v[48:49], v[48:49], v[74:75] op_sel_hi:[1,0]
	s_nop 0
	v_cndmask_b32_e32 v50, v62, v50, vcc
	v_rsq_f32_e32 v50, v50
	v_cvt_pk_bf16_f32 v55, v48, v49
	global_store_dwordx4 v[68:69], v[52:55], off offset:1024
	v_mul_f32_e32 v48, 0x45800000, v50
	s_nop 0
	v_cndmask_b32_e32 v52, v50, v48, vcc
	v_pk_mul_f32 v[48:49], v[72:73], v[52:53] op_sel_hi:[1,0]
	v_pk_mul_f32 v[50:51], v[70:71], v[52:53] op_sel_hi:[1,0]
	v_cvt_pk_bf16_f32 v48, v48, v49
	v_cvt_pk_bf16_f32 v49, v50, v51
	v_pk_mul_f32 v[50:51], v[60:61], v[52:53] op_sel_hi:[1,0]
	v_pk_mul_f32 v[52:53], v[58:59], v[52:53] op_sel_hi:[1,0]
	v_cvt_pk_bf16_f32 v50, v50, v51
	v_cvt_pk_bf16_f32 v51, v52, v53
	global_store_dwordx4 v[68:69], v[48:51], off offset:2048
	s_branch .LBB0_96

; DI void attn_sample_unit(const Args& a, int b, int g, LAS unsigned char* lds, const int tid) {
;     ...
;     for (int k = sub; k < 144; k += 8) { float s = 0.f;
;         for (int d = 0; d < 64; ++d) s += Qf[qr * 65 + d] * Kf[k * 65 + d];
;         Pf[qr * 145 + k] = s; mx = fmaxf(mx, s); }
;     mx = fmaxf(mx, __shfl_xor(mx, 1)); mx = fmaxf(mx, __shfl_xor(mx, 2)); mx = fmaxf(mx, __shfl_xor(mx, 4)); mx = fmaxf(mx, sink);
;     float sum = 0.f;
;     for (int k = sub; k < 144; k += 8) { const float pv = __expf(Pf[qr * 145 + k] - mx); Pf[qr * 145 + k] = pv; sum += pv; }
;     sum += __shfl_xor(sum, 1); sum += __shfl_xor(sum, 2); sum += __shfl_xor(sum, 4);
;     const float inv = 1.0f / (sum + __expf(sink - mx));
.LBB0_137:
	ds_read2_b32 v[12:13], v3 offset1:1
	ds_read2_b32 v[14:15], v4 offset1:1
	v_add_u32_e32 v6, 8, v6
	v_max_f32_e32 v2, v2, v2
	v_cmp_lt_u32_e32 vcc, s37, v6
	s_or_b64 s[0:1], vcc, s[0:1]
	s_waitcnt lgkmcnt(0)
	v_fma_f32 v7, v12, v14, 0
	v_fmac_f32_e32 v7, v13, v15
	ds_read2_b32 v[12:13], v3 offset0:2 offset1:3
	ds_read2_b32 v[14:15], v4 offset0:2 offset1:3
	s_waitcnt lgkmcnt(0)
	v_fmac_f32_e32 v7, v12, v14
	v_fmac_f32_e32 v7, v13, v15
	ds_read2_b32 v[12:13], v3 offset0:4 offset1:5
	ds_read2_b32 v[14:15], v4 offset0:4 offset1:5
	s_waitcnt lgkmcnt(0)
	v_fmac_f32_e32 v7, v12, v14
	v_fmac_f32_e32 v7, v13, v15
	ds_read2_b32 v[12:13], v3 offset0:6 offset1:7
	ds_read2_b32 v[14:15], v4 offset0:6 offset1:7
	s_waitcnt lgkmcnt(0)
	v_fmac_f32_e32 v7, v12, v14
	v_fmac_f32_e32 v7, v13, v15
	ds_read2_b32 v[12:13], v3 offset0:8 offset1:9
	ds_read2_b32 v[14:15], v4 offset0:8 offset1:9
	s_waitcnt lgkmcnt(0)
	v_fmac_f32_e32 v7, v12, v14
	v_fmac_f32_e32 v7, v13, v15
	ds_read2_b32 v[12:13], v3 offset0:10 offset1:11
	ds_read2_b32 v[14:15], v4 offset0:10 offset1:11
	s_waitcnt lgkmcnt(0)
	v_fmac_f32_e32 v7, v12, v14
	v_fmac_f32_e32 v7, v13, v15
	ds_read2_b32 v[12:13], v3 offset0:12 offset1:13
	ds_read2_b32 v[14:15], v4 offset0:12 offset1:13
	s_waitcnt lgkmcnt(0)
	v_fmac_f32_e32 v7, v12, v14
	v_fmac_f32_e32 v7, v13, v15
	ds_read2_b32 v[12:13], v3 offset0:14 offset1:15
	ds_read2_b32 v[14:15], v4 offset0:14 offset1:15
	s_waitcnt lgkmcnt(0)
	v_fmac_f32_e32 v7, v12, v14
	v_fmac_f32_e32 v7, v13, v15
	ds_read2_b32 v[12:13], v3 offset0:16 offset1:17
	ds_read2_b32 v[14:15], v4 offset0:16 offset1:17
	s_waitcnt lgkmcnt(0)
	v_fmac_f32_e32 v7, v12, v14
	v_fmac_f32_e32 v7, v13, v15
	ds_read2_b32 v[12:13], v3 offset0:18 offset1:19
	ds_read2_b32 v[14:15], v4 offset0:18 offset1:19
	s_waitcnt lgkmcnt(0)
	v_fmac_f32_e32 v7, v12, v14
	v_fmac_f32_e32 v7, v13, v15
	ds_read2_b32 v[12:13], v3 offset0:20 offset1:21
	ds_read2_b32 v[14:15], v4 offset0:20 offset1:21
	s_waitcnt lgkmcnt(0)
	v_fmac_f32_e32 v7, v12, v14
	v_fmac_f32_e32 v7, v13, v15
	ds_read2_b32 v[12:13], v3 offset0:22 offset1:23
	ds_read2_b32 v[14:15], v4 offset0:22 offset1:23
	s_waitcnt lgkmcnt(0)
	v_fmac_f32_e32 v7, v12, v14
	v_fmac_f32_e32 v7, v13, v15
	ds_read2_b32 v[12:13], v3 offset0:24 offset1:25
	ds_read2_b32 v[14:15], v4 offset0:24 offset1:25
	s_waitcnt lgkmcnt(0)
	v_fmac_f32_e32 v7, v12, v14
	v_fmac_f32_e32 v7, v13, v15
	ds_read2_b32 v[12:13], v3 offset0:26 offset1:27
	ds_read2_b32 v[14:15], v4 offset0:26 offset1:27
	s_waitcnt lgkmcnt(0)
	v_fmac_f32_e32 v7, v12, v14
	v_fmac_f32_e32 v7, v13, v15
	ds_read2_b32 v[12:13], v3 offset0:28 offset1:29
	ds_read2_b32 v[14:15], v4 offset0:28 offset1:29
	s_waitcnt lgkmcnt(0)
	v_fmac_f32_e32 v7, v12, v14
	v_fmac_f32_e32 v7, v13, v15
	ds_read2_b32 v[12:13], v3 offset0:30 offset1:31
	ds_read2_b32 v[14:15], v4 offset0:30 offset1:31
	s_waitcnt lgkmcnt(0)
	v_fmac_f32_e32 v7, v12, v14
	v_fmac_f32_e32 v7, v13, v15
	ds_read2_b32 v[12:13], v3 offset0:32 offset1:33
	ds_read2_b32 v[14:15], v4 offset0:32 offset1:33
	s_waitcnt lgkmcnt(0)
	v_fmac_f32_e32 v7, v12, v14
	v_fmac_f32_e32 v7, v13, v15
	ds_read2_b32 v[12:13], v3 offset0:34 offset1:35
	ds_read2_b32 v[14:15], v4 offset0:34 offset1:35
	s_waitcnt lgkmcnt(0)
	v_fmac_f32_e32 v7, v12, v14
	v_fmac_f32_e32 v7, v13, v15
	ds_read2_b32 v[12:13], v3 offset0:36 offset1:37
	ds_read2_b32 v[14:15], v4 offset0:36 offset1:37
	s_waitcnt lgkmcnt(0)
	v_fmac_f32_e32 v7, v12, v14
	v_fmac_f32_e32 v7, v13, v15
	ds_read2_b32 v[12:13], v3 offset0:38 offset1:39
	ds_read2_b32 v[14:15], v4 offset0:38 offset1:39
	s_waitcnt lgkmcnt(0)
	v_fmac_f32_e32 v7, v12, v14
	v_fmac_f32_e32 v7, v13, v15
	ds_read2_b32 v[12:13], v3 offset0:40 offset1:41
	ds_read2_b32 v[14:15], v4 offset0:40 offset1:41
	s_waitcnt lgkmcnt(0)
	v_fmac_f32_e32 v7, v12, v14
	v_fmac_f32_e32 v7, v13, v15
	ds_read2_b32 v[12:13], v3 offset0:42 offset1:43
	ds_read2_b32 v[14:15], v4 offset0:42 offset1:43
	s_waitcnt lgkmcnt(0)
	v_fmac_f32_e32 v7, v12, v14
	v_fmac_f32_e32 v7, v13, v15
	ds_read2_b32 v[12:13], v3 offset0:44 offset1:45
	ds_read2_b32 v[14:15], v4 offset0:44 offset1:45
	s_waitcnt lgkmcnt(0)
	v_fmac_f32_e32 v7, v12, v14
	v_fmac_f32_e32 v7, v13, v15
	ds_read2_b32 v[12:13], v3 offset0:46 offset1:47
	ds_read2_b32 v[14:15], v4 offset0:46 offset1:47
	s_waitcnt lgkmcnt(0)
	v_fmac_f32_e32 v7, v12, v14
	v_fmac_f32_e32 v7, v13, v15
	ds_read2_b32 v[12:13], v3 offset0:48 offset1:49
	ds_read2_b32 v[14:15], v4 offset0:48 offset1:49
	s_waitcnt lgkmcnt(0)
	v_fmac_f32_e32 v7, v12, v14
	v_fmac_f32_e32 v7, v13, v15
	ds_read2_b32 v[12:13], v3 offset0:50 offset1:51
	ds_read2_b32 v[14:15], v4 offset0:50 offset1:51
	s_waitcnt lgkmcnt(0)
	v_fmac_f32_e32 v7, v12, v14
	v_fmac_f32_e32 v7, v13, v15
	ds_read2_b32 v[12:13], v3 offset0:52 offset1:53
	ds_read2_b32 v[14:15], v4 offset0:52 offset1:53
	s_waitcnt lgkmcnt(0)
	v_pk_mul_f32 v[12:13], v[12:13], v[14:15]
	v_add_f32_e32 v7, v7, v12
	v_add_f32_e32 v7, v7, v13
	ds_read2_b32 v[12:13], v3 offset0:54 offset1:55
	ds_read2_b32 v[14:15], v4 offset0:54 offset1:55
	s_waitcnt lgkmcnt(0)
	v_pk_mul_f32 v[12:13], v[12:13], v[14:15]
	v_add_f32_e32 v7, v7, v12
	v_add_f32_e32 v7, v7, v13
	ds_read2_b32 v[12:13], v3 offset0:56 offset1:57
	ds_read2_b32 v[14:15], v4 offset0:56 offset1:57
	s_waitcnt lgkmcnt(0)
	v_pk_mul_f32 v[12:13], v[12:13], v[14:15]
	v_add_f32_e32 v7, v7, v12
	v_add_f32_e32 v7, v7, v13
	ds_read2_b32 v[12:13], v3 offset0:58 offset1:59
	ds_read2_b32 v[14:15], v4 offset0:58 offset1:59
	s_waitcnt lgkmcnt(0)
	v_pk_mul_f32 v[12:13], v[12:13], v[14:15]
	v_add_f32_e32 v7, v7, v12
	v_add_f32_e32 v7, v7, v13
	ds_read2_b32 v[12:13], v3 offset0:60 offset1:61
	ds_read2_b32 v[14:15], v4 offset0:60 offset1:61
	s_waitcnt lgkmcnt(0)
	v_pk_mul_f32 v[12:13], v[12:13], v[14:15]
	v_add_f32_e32 v7, v7, v12
	v_add_f32_e32 v7, v7, v13
	ds_read2_b32 v[12:13], v3 offset0:62 offset1:63
	ds_read2_b32 v[14:15], v4 offset0:62 offset1:63
	v_add_u32_e32 v4, 0x820, v4
	s_waitcnt lgkmcnt(0)
	v_pk_mul_f32 v[12:13], v[12:13], v[14:15]
	v_add_f32_e32 v7, v7, v12
	v_add_f32_e32 v7, v7, v13
	ds_write_b32 v5, v7
	v_max_f32_e32 v2, v2, v7
	v_add_u32_e32 v5, 32, v5
	s_andn2_b64 exec, exec, s[0:1]
	s_cbranch_execnz .LBB0_137
	s_or_b64 exec, exec, s[0:1]
	v_and_b32_e32 v4, 64, v177
	v_xor_b32_e32 v3, 1, v177
	v_add_u32_e32 v4, 64, v4
	v_cmp_lt_i32_e32 vcc, v3, v4
	s_mov_b64 s[0:1], 0
	s_nop 0
	v_cndmask_b32_e32 v3, v177, v3, vcc
	v_lshlrev_b32_e32 v3, 2, v3
	ds_bpermute_b32 v5, v3, v2
	v_max_f32_e32 v2, v2, v2
	s_waitcnt lgkmcnt(0)
	v_max_f32_e32 v5, v5, v5
	v_max_f32_e32 v5, v2, v5
	v_xor_b32_e32 v2, 2, v177
	v_cmp_lt_i32_e32 vcc, v2, v4
	s_nop 1
	v_cndmask_b32_e32 v2, v177, v2, vcc
	v_lshlrev_b32_e32 v2, 2, v2
	ds_bpermute_b32 v6, v2, v5
	s_waitcnt lgkmcnt(0)
	v_max_f32_e32 v6, v6, v6
	v_max_f32_e32 v5, v5, v6
	v_xor_b32_e32 v6, 4, v177
	v_cmp_lt_i32_e32 vcc, v6, v4
	s_nop 1
	v_cndmask_b32_e32 v4, v177, v6, vcc
	v_lshlrev_b32_e32 v12, 2, v4
	ds_bpermute_b32 v4, v12, v5
	s_waitcnt vmcnt(0) lgkmcnt(0)
	v_max3_f32 v13, v5, v4, v10
	v_mov_b32_e32 v4, 0

; #define LAS __attribute__((address_space(3)))
; DI float lo16(unsigned w) { return __uint_as_float(w << 16); }
; DI float hi16(unsigned w) { return __uint_as_float(w & 0xffff0000u); }
; DI void ssd_unit(const Args& a, bool sample, int b, int hd, LAS unsigned char* lds, const int tid) {
;     ...
;             float acc[8];
;             { const f32x4 b0 = *(const f32x4*)(cb + ch), b1 = *(const f32x4*)(cb + ch + 4);
; #pragma unroll
;               for (int e = 0; e < 4; ++e) { acc[e] = b0[e]; acc[4 + e] = b1[e]; } }
; #pragma unroll
;             for (int jj = 0; jj < 4; ++jj) {
;                 const int ts = t - 3 + jj;
;                 float raw[8];
;                 if (ts >= 0) { const u32x4 w = *(const u32x4*)(HIN + (row0 + ts) * LDH + C_XBC + ch);
; #pragma unroll
;                     for (int e = 0; e < 4; ++e) { raw[2 * e] = lo16(w[e]); raw[2 * e + 1] = hi16(w[e]); } }
;                 else if (sample) { const float* cp = conv0 + ((size_t)b * 3 + (3 + ts)) * 1536 + ch; const f32x4 r0 = *(const f32x4*)cp, r1 = *(const f32x4*)(cp + 4);
; #pragma unroll
;                     for (int e = 0; e < 4; ++e) { raw[e] = r0[e]; raw[4 + e] = r1[e]; } }
;                 else {
; #pragma unroll
;                     for (int e = 0; e < 8; ++e) raw[e] = 0.f; }
;                 const f32x4 w0 = *(const f32x4*)(cw + jj * 1536 + ch), w1 = *(const f32x4*)(cw + jj * 1536 + ch + 4);
; #pragma unroll
;                 for (int e = 0; e < 4; ++e) { acc[e] += w0[e] * raw[e]; acc[4 + e] += w1[e] * raw[4 + e]; }
;             }
; #pragma unroll
;             for (int e = 0; e < 8; ++e) acc[e] = acc[e] * __frcp_rn(1.0f + __expf(-acc[e]));
;             *(LAS f32x4*)dst = (f32x4){acc[0], acc[1], acc[2], acc[3]}; *(LAS f32x4*)(dst + 4) = (f32x4){acc[4], acc[5], acc[6], acc[7]};
;         }
.LBB0_167:
	s_or_b64 exec, exec, s[8:9]
	s_waitcnt vmcnt(4)
	v_pk_fma_f32 v[24:25], v[28:29], v[40:41], v[24:25]
	v_pk_fma_f32 v[16:17], v[32:33], v[36:37], v[16:17]
	s_waitcnt vmcnt(3)
	v_pk_fma_f32 v[24:25], v[44:45], v[60:61], v[24:25]
	s_mov_b64 s[8:9], 0x4800
	s_waitcnt vmcnt(2)
	v_pk_fma_f32 v[16:17], v[48:49], v[56:57], v[16:17]
	s_waitcnt vmcnt(1)
	v_pk_fma_f32 v[32:33], v[64:65], v[76:77], v[24:25]
	v_lshl_add_u64 v[24:25], v[88:89], 0, s[8:9]
	s_movk_i32 s8, 0x4000
	v_pk_fma_f32 v[26:27], v[30:31], v[42:43], v[26:27]
	v_pk_fma_f32 v[18:19], v[34:35], v[38:39], v[18:19]
	s_waitcnt vmcnt(0)
	v_pk_fma_f32 v[30:31], v[68:69], v[72:73], v[16:17]
	v_add_co_u32_e32 v16, vcc, s8, v88
	v_pk_fma_f32 v[26:27], v[46:47], v[62:63], v[26:27]
	v_pk_fma_f32 v[18:19], v[50:51], v[58:59], v[18:19]
	v_addc_co_u32_e32 v17, vcc, 0, v89, vcc
	v_pk_fma_f32 v[34:35], v[66:67], v[78:79], v[26:27]
	v_pk_fma_f32 v[28:29], v[70:71], v[74:75], v[18:19]
	global_load_dwordx4 v[16:19], v[16:17], off offset:2048
	s_nop 0
	global_load_dwordx4 v[24:27], v[24:25], off offset:16
	v_add_u32_e32 v93, 0x4000, v93
	v_add_u32_e32 v82, 0x1000, v82
	s_waitcnt vmcnt(1)
	v_pk_fma_f32 v[18:19], v[54:55], v[18:19], v[34:35]
	v_mul_f32_e32 v34, 0xbfb8aa3b, v18
	v_mul_f32_e32 v35, 0xbfb8aa3b, v19
	v_exp_f32_e32 v34, v34
	v_exp_f32_e32 v35, v35
	v_pk_fma_f32 v[16:17], v[52:53], v[16:17], v[32:33]
	s_waitcnt vmcnt(0)
	v_pk_fma_f32 v[20:21], v[20:21], v[24:25], v[30:31]
	v_mul_f32_e32 v32, 0xbfb8aa3b, v16
	v_pk_add_f32 v[34:35], v[34:35], 1.0 op_sel_hi:[1,0]
	v_mul_f32_e32 v33, 0xbfb8aa3b, v17
	v_exp_f32_e32 v32, v32
	v_exp_f32_e32 v33, v33
	v_mul_f32_e32 v24, 0xbfb8aa3b, v20
	v_rcp_f32_e32 v35, v35
	v_pk_add_f32 v[32:33], v[32:33], 1.0 op_sel_hi:[1,0]
	v_exp_f32_e32 v30, v24
	v_mul_f32_e32 v24, 0xbfb8aa3b, v21
	v_rcp_f32_e32 v34, v34
	v_exp_f32_e32 v31, v24
	v_pk_fma_f32 v[22:23], v[22:23], v[26:27], v[28:29]
	v_pk_mul_f32 v[18:19], v[18:19], v[34:35]
	v_rcp_f32_e32 v33, v33
	v_pk_add_f32 v[26:27], v[30:31], 1.0 op_sel_hi:[1,0]
	v_mul_f32_e32 v24, 0xbfb8aa3b, v22
	v_rcp_f32_e32 v32, v32
	s_nop 0
	v_pk_mul_f32 v[16:17], v[16:17], v[32:33]
	v_rcp_f32_e32 v27, v27
	v_mul_f32_e32 v25, 0xbfb8aa3b, v23
	v_exp_f32_e32 v24, v24
	v_exp_f32_e32 v25, v25
	s_nop 0
	v_pk_add_f32 v[24:25], v[24:25], 1.0 op_sel_hi:[1,0]
	v_rcp_f32_e32 v26, v26
	s_nop 0
	v_pk_mul_f32 v[20:21], v[20:21], v[26:27]
	v_rcp_f32_e32 v25, v25
	s_movk_i32 s8, 0x7f
	v_rcp_f32_e32 v24, v24
	s_nop 0
	v_pk_mul_f32 v[22:23], v[22:23], v[24:25]
	ds_write_b128 v94, v[16:19]
	ds_write_b128 v94, v[20:23] offset:16
	v_add_u32_e32 v16, 0x200, v84
	v_cmp_lt_i32_e32 vcc, s8, v84
	s_or_b64 s[6:7], vcc, s[6:7]
	v_mov_b32_e32 v84, v16
	s_andn2_b64 exec, exec, s[6:7]
	s_cbranch_execz .LBB0_192

; DI float bf2f(bf16_t v) { return __uint_as_float((unsigned)v << 16); }
; DI void ssd_unit(const Args& a, bool sample, int b, int hd, LAS unsigned char* lds, const int tid) {
;     ...
;         if (tid < TC) { const float v = bf2f(HIN[(row0 + t0 + tid) * LDH + C_DT + hd]) + dtb; const float dt = v > 20.f ? v : log1pf(__expf(v)); dts[tid] = dt; dAs[tid] = __expf(dt * av); }
.LBB0_192:
	s_or_b64 exec, exec, s[4:5]
	v_lshlrev_b32_e32 v20, 4, v90
	v_cmp_gt_i32_e32 vcc, 16, v132
	s_and_saveexec_b64 s[4:5], vcc
	s_cbranch_execz .LBB0_196
	v_ashrrev_i32_e32 v133, 31, v132
	v_lshl_add_u64 v[16:17], v[132:133], 0, s[0:1]
	v_mov_b64_e32 v[18:19], s[82:83]
	v_mad_u64_u32 v[18:19], s[6:7], v16, s55, v[18:19]
	v_mad_i32_i24 v19, v17, s55, v19
	s_lshl_b32 s94, s3, 1
	v_lshl_add_u64 v[16:17], v[18:19], 0, s[94:95]
	v_add_co_u32_e32 v16, vcc, 0x1000, v16
	s_mov_b32 s3, 0x41a00000
	s_nop 0
	v_addc_co_u32_e32 v17, vcc, 0, v17, vcc
	global_load_ushort v16, v[16:17], off offset:2560
	s_waitcnt vmcnt(0)
	v_lshlrev_b32_e32 v16, 16, v16
	v_add_f32_e32 v16, v92, v16
	v_cmp_nlt_f32_e32 vcc, s3, v16
	s_and_saveexec_b64 s[6:7], vcc
	s_cbranch_execz .LBB0_195
	v_mul_f32_e32 v16, 0x3fb8aa3b, v16
	v_exp_f32_e32 v21, v16
	s_mov_b32 s3, 0x3f2aaaab
	v_add_f32_e32 v18, 1.0, v21
	v_frexp_mant_f32_e32 v22, v18
	v_cvt_f64_f32_e32 v[16:17], v18
	v_frexp_exp_i32_f64_e32 v16, v[16:17]
	v_cmp_gt_f32_e32 vcc, s3, v22
	v_add_f32_e32 v19, -1.0, v18
	v_sub_f32_e32 v23, v19, v18
	v_subbrev_co_u32_e32 v26, vcc, 0, v16, vcc
	v_sub_u32_e32 v16, 0, v26
	v_sub_f32_e32 v19, v21, v19
	v_add_f32_e32 v23, 1.0, v23
	v_ldexp_f32 v17, v18, v16
	v_add_f32_e32 v19, v19, v23
	v_add_f32_e32 v18, -1.0, v17
	v_add_f32_e32 v22, 1.0, v17
	v_ldexp_f32 v16, v19, v16
	v_add_f32_e32 v19, 1.0, v18
	v_add_f32_e32 v23, -1.0, v22
	v_sub_f32_e32 v19, v17, v19
	v_sub_f32_e32 v17, v17, v23
	v_add_f32_e32 v19, v16, v19
	v_add_f32_e32 v16, v16, v17
	v_add_f32_e32 v27, v22, v16
	v_rcp_f32_e32 v29, v27
	v_sub_f32_e32 v17, v27, v22
	v_sub_f32_e32 v28, v16, v17
	v_add_f32_e32 v17, v18, v19
	v_mul_f32_e32 v31, v17, v29
	v_sub_f32_e32 v16, v17, v18
	v_mul_f32_e32 v18, v27, v31
	v_fma_f32 v22, v31, v27, -v18
	v_fmac_f32_e32 v22, v31, v28
	v_sub_f32_e32 v30, v19, v16
	v_add_f32_e32 v16, v18, v22
	v_sub_f32_e32 v19, v17, v16
	v_pk_add_f32 v[24:25], v[16:17], v[18:19] neg_lo:[0,1] neg_hi:[0,1]
	v_mov_b32_e32 v23, v16
	v_pk_add_f32 v[16:17], v[24:25], v[22:23] neg_lo:[0,1] neg_hi:[0,1]
	s_mov_b32 s3, 0x3f317218
	v_add_f32_e32 v17, v30, v17
	v_add_f32_e32 v16, v16, v17
	v_add_f32_e32 v17, v19, v16
	v_mul_f32_e32 v30, v29, v17
	v_mul_f32_e32 v18, v27, v30
	v_fma_f32 v22, v30, v27, -v18
	v_fmac_f32_e32 v22, v30, v28
	v_sub_f32_e32 v19, v19, v17
	v_add_f32_e32 v27, v16, v19
	v_add_f32_e32 v16, v18, v22
	v_sub_f32_e32 v19, v17, v16
	v_pk_add_f32 v[24:25], v[16:17], v[18:19] neg_lo:[0,1] neg_hi:[0,1]
	v_mov_b32_e32 v23, v16
	v_pk_add_f32 v[16:17], v[24:25], v[22:23] neg_lo:[0,1] neg_hi:[0,1]
	v_add_f32_e32 v17, v27, v17
	v_add_f32_e32 v16, v16, v17
	v_add_f32_e32 v17, v31, v30
	v_add_f32_e32 v16, v19, v16
	v_sub_f32_e32 v18, v17, v31
	v_mul_f32_e32 v16, v29, v16
	v_sub_f32_e32 v18, v30, v18
	v_add_f32_e32 v18, v18, v16
	v_add_f32_e32 v22, v17, v18
	v_mul_f32_e32 v23, v22, v22
	v_mov_b32_e32 v16, 0x3ecc95a3
	v_fmamk_f32 v16, v23, 0x3e9b6dac, v16
	v_fmaak_f32 v183, v23, v16, 0x3f2aaada
	v_cvt_f32_i32_e32 v16, v26
	v_sub_f32_e32 v17, v22, v17
	v_sub_f32_e32 v17, v18, v17
	v_ldexp_f32 v24, v17, 1
	v_mul_f32_e32 v17, v22, v23
	v_ldexp_f32 v19, v22, 1
	v_pk_mul_f32 v[22:23], v[16:17], v[182:183]
	v_fma_f32 v18, v16, s3, -v22
	v_fmac_f32_e32 v18, 0xb102e308, v16
	v_pk_add_f32 v[16:17], v[22:23], v[18:19]
	s_mov_b32 s3, 0x7f800000
	v_sub_f32_e32 v19, v17, v19
	v_sub_f32_e32 v19, v23, v19
	v_add_f32_e32 v25, v24, v19
	v_mov_b32_e32 v24, v22
	v_pk_add_f32 v[22:23], v[16:17], v[22:23] neg_lo:[0,1] neg_hi:[0,1]
	v_pk_add_f32 v[26:27], v[16:17], v[24:25]
	v_mov_b32_e32 v19, v16
	v_mov_b32_e32 v23, v27
	v_pk_add_f32 v[28:29], v[18:19], v[22:23] neg_lo:[0,1] neg_hi:[0,1]
	v_pk_add_f32 v[18:19], v[18:19], v[22:23]
	v_mov_b32_e32 v24, v25
	v_pk_add_f32 v[22:23], v[18:19], v[16:17] op_sel:[1,0] op_sel_hi:[0,1] neg_lo:[0,1] neg_hi:[0,1]
	v_pk_add_f32 v[30:31], v[26:27], v[22:23] op_sel_hi:[1,0] neg_lo:[0,1] neg_hi:[0,1]
	v_mov_b32_e32 v26, v27
	v_mov_b32_e32 v27, v19
	v_pk_mov_b32 v[22:23], v[16:17], v[22:23] op_sel:[1,0]
	v_mov_b32_e32 v25, v16
	v_pk_add_f32 v[22:23], v[26:27], v[22:23] neg_lo:[0,1] neg_hi:[0,1]
	v_mov_b32_e32 v30, v28
	v_pk_add_f32 v[16:17], v[24:25], v[22:23] neg_lo:[0,1] neg_hi:[0,1]
	v_mov_b32_e32 v29, v19
	v_pk_add_f32 v[22:23], v[30:31], v[16:17]
	v_cmp_neq_f32_e32 vcc, s3, v21
	v_pk_add_f32 v[24:25], v[22:23], v[22:23] op_sel:[0,1] op_sel_hi:[1,0]
	s_mov_b32 s3, 0x33800000
	v_pk_add_f32 v[18:19], v[18:19], v[24:25] op_sel:[1,0] op_sel_hi:[0,1]
	v_mov_b32_e32 v23, v18
	v_pk_add_f32 v[26:27], v[22:23], v[28:29] neg_lo:[0,1] neg_hi:[0,1]
	v_mov_b32_e32 v17, v24
	v_sub_f32_e32 v19, v22, v26
	v_pk_add_f32 v[16:17], v[16:17], v[26:27] neg_lo:[0,1] neg_hi:[0,1]
	v_sub_f32_e32 v19, v28, v19
	v_add_f32_e32 v16, v16, v19
	v_add_f32_e32 v16, v16, v17
	v_add_f32_e32 v16, v18, v16
	v_mov_b32_e32 v17, 0x7f800000
	v_cndmask_b32_e32 v16, v17, v16, vcc
	v_cmp_ngt_f32_e32 vcc, -1.0, v21
	v_mov_b32_e32 v17, 0xff800000
	s_nop 0
	v_cndmask_b32_e32 v16, v206, v16, vcc
	v_cmp_neq_f32_e32 vcc, -1.0, v21
	s_nop 1
	v_cndmask_b32_e32 v16, v17, v16, vcc
	v_cmp_lt_f32_e64 vcc, |v21|, s3
	s_nop 1
	v_cndmask_b32_e32 v16, v16, v21, vcc

; #define LAS __attribute__((address_space(3)))
; DI void ssd_unit(const Args& a, bool sample, int b, int hd, LAS unsigned char* lds, const int tid) {
;     ...
;         for (int tt = 0; tt < TC; ++tt) {
;             const float dA = dAs[tt], xv = Xs[tt * 64 + pp], xdt = xv * dts[tt];
;             const LAS f32x4* bp = (const LAS f32x4*)(Bs + tt * 128 + ns * 16); const LAS f32x4* cp = (const LAS f32x4*)(Cs + tt * 128 + ns * 16);
;             float yp = 0.f;
; #pragma unroll
;             for (int q = 0; q < 4; ++q) { const f32x4 bv = bp[q], cv = cp[q];
; #pragma unroll
;                 for (int e = 0; e < 4; ++e) { h[4 * q + e] = dA * h[4 * q + e] + xdt * bv[e]; yp += h[4 * q + e] * cv[e]; } }
;             yp += __shfl_xor(yp, 1); yp += __shfl_xor(yp, 2); yp += __shfl_xor(yp, 4);
;             if (ns == 0) Ys[tt * 64 + pp] = yp + Dk * xv;
;         }
.LBB0_198:
	s_or_b64 exec, exec, s[4:5]
	v_readlane_b32 s3, v252, 49
	s_nop 1
	v_mov_b32_e32 v4, s3
	v_readlane_b32 s3, v252, 50
	ds_read_b32 v44, v4
	ds_read_b32 v26, v21 offset:256
	v_mov_b32_e32 v4, s3
	ds_read_b32 v4, v4
	s_waitcnt lgkmcnt(0)
	v_mul_f32_e32 v46, v26, v4
	ds_read_b128 v[4:7], v23 offset:16896
	ds_read_b128 v[28:31], v23 offset:16912
	ds_read_b128 v[32:35], v23 offset:16928
	ds_read_b128 v[36:39], v23 offset:16944
	ds_read_b128 v[40:43], v23 offset:49664
	s_waitcnt lgkmcnt(4)
	v_pk_mul_f32 v[4:5], v[46:47], v[4:5] op_sel_hi:[0,1]
	v_pk_mul_f32 v[6:7], v[46:47], v[6:7] op_sel_hi:[0,1]
	v_pk_fma_f32 v[4:5], v[16:17], v[44:45], v[4:5] op_sel_hi:[1,0,1]
	v_pk_fma_f32 v[6:7], v[18:19], v[44:45], v[6:7] op_sel_hi:[1,0,1]
	ds_read_b128 v[16:19], v23 offset:49680
	s_waitcnt lgkmcnt(1)
	v_fma_f32 v27, v40, v4, 0
	v_fmac_f32_e32 v27, v41, v5
	v_fmac_f32_e32 v27, v42, v6
	v_pk_mul_f32 v[28:29], v[46:47], v[28:29] op_sel_hi:[0,1]
	v_fmac_f32_e32 v27, v43, v7
	v_pk_fma_f32 v[8:9], v[8:9], v[44:45], v[28:29] op_sel_hi:[1,0,1]
	v_pk_mul_f32 v[28:29], v[46:47], v[32:33] op_sel_hi:[0,1]
	s_waitcnt lgkmcnt(0)
	v_fmac_f32_e32 v27, v16, v8
	v_fmac_f32_e32 v27, v17, v9
	v_pk_mul_f32 v[16:17], v[46:47], v[30:31] op_sel_hi:[0,1]
	v_pk_fma_f32 v[10:11], v[10:11], v[44:45], v[16:17] op_sel_hi:[1,0,1]
	v_pk_fma_f32 v[12:13], v[12:13], v[44:45], v[28:29] op_sel_hi:[1,0,1]
	v_fmac_f32_e32 v27, v18, v10
	v_fmac_f32_e32 v27, v19, v11
	ds_read_b128 v[16:19], v23 offset:49696
	v_pk_mul_f32 v[28:29], v[46:47], v[36:37] op_sel_hi:[0,1]
	v_pk_fma_f32 v[0:1], v[0:1], v[44:45], v[28:29] op_sel_hi:[1,0,1]
	s_waitcnt lgkmcnt(0)
	v_fmac_f32_e32 v27, v16, v12
	v_fmac_f32_e32 v27, v17, v13
	v_pk_mul_f32 v[16:17], v[46:47], v[34:35] op_sel_hi:[0,1]
	v_pk_fma_f32 v[14:15], v[14:15], v[44:45], v[16:17] op_sel_hi:[1,0,1]
	v_fmac_f32_e32 v27, v18, v14
	v_fmac_f32_e32 v27, v19, v15
	ds_read_b128 v[16:19], v23 offset:49712
	s_waitcnt lgkmcnt(0)
	v_fmac_f32_e32 v27, v16, v0
	v_fmac_f32_e32 v27, v17, v1
	v_pk_mul_f32 v[16:17], v[46:47], v[38:39] op_sel_hi:[0,1]
	v_pk_fma_f32 v[2:3], v[2:3], v[44:45], v[16:17] op_sel_hi:[1,0,1]
	v_fmac_f32_e32 v27, v18, v2
	v_fmac_f32_e32 v27, v19, v3
	ds_bpermute_b32 v16, v22, v27
	s_waitcnt lgkmcnt(0)
	v_add_f32_e32 v16, v27, v16
	ds_bpermute_b32 v17, v24, v16
	s_waitcnt lgkmcnt(0)
	v_add_f32_e32 v16, v16, v17
	ds_bpermute_b32 v17, v25, v16
	s_and_saveexec_b64 s[4:5], vcc
	s_cbranch_execz .LBB0_200
	s_waitcnt lgkmcnt(0)
	v_add_f32_e32 v16, v16, v17
	s_waitcnt vmcnt(0)
	v_fmac_f32_e32 v16, v85, v26
	v_add_u32_e32 v17, 0x14100, v21
	ds_write_b32 v17, v16
.LBB0_200:
	s_or_b64 exec, exec, s[4:5]
	v_readlane_b32 s3, v252, 51
	s_nop 1
	v_mov_b32_e32 v16, s3
	v_readlane_b32 s3, v252, 52
	ds_read_b32 v18, v16
	ds_read_b32 v16, v21 offset:512
	s_waitcnt lgkmcnt(2)
	v_mov_b32_e32 v17, s3
	ds_read_b32 v17, v17
	ds_read_b128 v[26:29], v23 offset:17408
	ds_read_b128 v[30:33], v23 offset:17424
	ds_read_b128 v[34:37], v23 offset:17440
	ds_read_b128 v[38:41], v23 offset:17456
	ds_read_b128 v[42:45], v23 offset:50176
	s_waitcnt lgkmcnt(5)
	v_mul_f32_e32 v46, v16, v17
	s_waitcnt lgkmcnt(4)
	v_pk_mul_f32 v[26:27], v[46:47], v[26:27] op_sel_hi:[0,1]
	v_pk_fma_f32 v[4:5], v[4:5], v[18:19], v[26:27] op_sel_hi:[1,0,1]
	v_pk_mul_f32 v[26:27], v[46:47], v[28:29] op_sel_hi:[0,1]
	v_pk_fma_f32 v[6:7], v[6:7], v[18:19], v[26:27] op_sel_hi:[1,0,1]
	ds_read_b128 v[26:29], v23 offset:50192
	s_waitcnt lgkmcnt(1)
	v_fma_f32 v17, v42, v4, 0
	v_fmac_f32_e32 v17, v43, v5
	v_fmac_f32_e32 v17, v44, v6
	v_pk_mul_f32 v[30:31], v[46:47], v[30:31] op_sel_hi:[0,1]
	v_fmac_f32_e32 v17, v45, v7
	v_pk_fma_f32 v[8:9], v[8:9], v[18:19], v[30:31] op_sel_hi:[1,0,1]
	v_pk_mul_f32 v[30:31], v[46:47], v[34:35] op_sel_hi:[0,1]
	s_waitcnt lgkmcnt(0)
	v_fmac_f32_e32 v17, v26, v8
	v_fmac_f32_e32 v17, v27, v9
	v_pk_mul_f32 v[26:27], v[46:47], v[32:33] op_sel_hi:[0,1]
	v_pk_fma_f32 v[10:11], v[10:11], v[18:19], v[26:27] op_sel_hi:[1,0,1]
	v_pk_fma_f32 v[12:13], v[12:13], v[18:19], v[30:31] op_sel_hi:[1,0,1]
	v_fmac_f32_e32 v17, v28, v10
	v_fmac_f32_e32 v17, v29, v11
	ds_read_b128 v[26:29], v23 offset:50208
	v_pk_mul_f32 v[30:31], v[46:47], v[38:39] op_sel_hi:[0,1]
	v_pk_fma_f32 v[0:1], v[0:1], v[18:19], v[30:31] op_sel_hi:[1,0,1]
	s_waitcnt lgkmcnt(0)
	v_fmac_f32_e32 v17, v26, v12
	v_fmac_f32_e32 v17, v27, v13
	v_pk_mul_f32 v[26:27], v[46:47], v[36:37] op_sel_hi:[0,1]
	v_pk_fma_f32 v[14:15], v[14:15], v[18:19], v[26:27] op_sel_hi:[1,0,1]
	v_fmac_f32_e32 v17, v28, v14
	v_fmac_f32_e32 v17, v29, v15
	ds_read_b128 v[26:29], v23 offset:50224
	s_waitcnt lgkmcnt(0)
	v_fmac_f32_e32 v17, v26, v0
	v_fmac_f32_e32 v17, v27, v1
	v_pk_mul_f32 v[26:27], v[46:47], v[40:41] op_sel_hi:[0,1]
	v_pk_fma_f32 v[2:3], v[2:3], v[18:19], v[26:27] op_sel_hi:[1,0,1]
	v_fmac_f32_e32 v17, v28, v2
	v_fmac_f32_e32 v17, v29, v3
	ds_bpermute_b32 v18, v22, v17
	s_waitcnt lgkmcnt(0)
	v_add_f32_e32 v17, v17, v18
	ds_bpermute_b32 v18, v24, v17
	s_waitcnt lgkmcnt(0)
	v_add_f32_e32 v17, v17, v18
	ds_bpermute_b32 v18, v25, v17
	s_and_saveexec_b64 s[4:5], vcc
	s_cbranch_execz .LBB0_202
	s_waitcnt lgkmcnt(0)
	v_add_f32_e32 v17, v17, v18
	s_waitcnt vmcnt(0)
	v_fmac_f32_e32 v17, v85, v16
	v_add_u32_e32 v16, 0x14200, v21
	ds_write_b32 v16, v17
; #define LAS __attribute__((address_space(3)))
; DI void ssd_unit(const Args& a, bool sample, int b, int hd, LAS unsigned char* lds, const int tid) {
;     ...
;         for (int tt = 0; tt < TC; ++tt) {
;             const float dA = dAs[tt], xv = Xs[tt * 64 + pp], xdt = xv * dts[tt];
;             const LAS f32x4* bp = (const LAS f32x4*)(Bs + tt * 128 + ns * 16); const LAS f32x4* cp = (const LAS f32x4*)(Cs + tt * 128 + ns * 16);
;             float yp = 0.f;
; #pragma unroll
;             for (int q = 0; q < 4; ++q) { const f32x4 bv = bp[q], cv = cp[q];
; #pragma unroll
;                 for (int e = 0; e < 4; ++e) { h[4 * q + e] = dA * h[4 * q + e] + xdt * bv[e]; yp += h[4 * q + e] * cv[e]; } }
;             yp += __shfl_xor(yp, 1); yp += __shfl_xor(yp, 2); yp += __shfl_xor(yp, 4);
;             if (ns == 0) Ys[tt * 64 + pp] = yp + Dk * xv;
;         }
.LBB0_202:
	s_or_b64 exec, exec, s[4:5]
	v_readlane_b32 s3, v252, 53
	s_nop 1
	v_mov_b32_e32 v16, s3
	v_readlane_b32 s3, v252, 54
	s_waitcnt lgkmcnt(0)
	ds_read_b32 v18, v16
	ds_read_b32 v16, v21 offset:768
	v_mov_b32_e32 v17, s3
	ds_read_b32 v17, v17
	ds_read_b128 v[26:29], v23 offset:17920
	ds_read_b128 v[30:33], v23 offset:17936
	ds_read_b128 v[34:37], v23 offset:17952
	ds_read_b128 v[38:41], v23 offset:17968
	ds_read_b128 v[42:45], v23 offset:50688
	s_waitcnt lgkmcnt(5)
	v_mul_f32_e32 v46, v16, v17
	s_waitcnt lgkmcnt(4)
	v_pk_mul_f32 v[26:27], v[46:47], v[26:27] op_sel_hi:[0,1]
	v_pk_fma_f32 v[4:5], v[4:5], v[18:19], v[26:27] op_sel_hi:[1,0,1]
	v_pk_mul_f32 v[26:27], v[46:47], v[28:29] op_sel_hi:[0,1]
	v_pk_fma_f32 v[6:7], v[6:7], v[18:19], v[26:27] op_sel_hi:[1,0,1]
	ds_read_b128 v[26:29], v23 offset:50704
	s_waitcnt lgkmcnt(1)
	v_fma_f32 v17, v42, v4, 0
	v_fmac_f32_e32 v17, v43, v5
	v_fmac_f32_e32 v17, v44, v6
	v_pk_mul_f32 v[30:31], v[46:47], v[30:31] op_sel_hi:[0,1]
	v_fmac_f32_e32 v17, v45, v7
	v_pk_fma_f32 v[8:9], v[8:9], v[18:19], v[30:31] op_sel_hi:[1,0,1]
	v_pk_mul_f32 v[30:31], v[46:47], v[34:35] op_sel_hi:[0,1]
	s_waitcnt lgkmcnt(0)
	v_fmac_f32_e32 v17, v26, v8
	v_fmac_f32_e32 v17, v27, v9
	v_pk_mul_f32 v[26:27], v[46:47], v[32:33] op_sel_hi:[0,1]
	v_pk_fma_f32 v[10:11], v[10:11], v[18:19], v[26:27] op_sel_hi:[1,0,1]
	v_pk_fma_f32 v[12:13], v[12:13], v[18:19], v[30:31] op_sel_hi:[1,0,1]
	v_fmac_f32_e32 v17, v28, v10
	v_fmac_f32_e32 v17, v29, v11
	ds_read_b128 v[26:29], v23 offset:50720
	v_pk_mul_f32 v[30:31], v[46:47], v[38:39] op_sel_hi:[0,1]
	v_pk_fma_f32 v[0:1], v[0:1], v[18:19], v[30:31] op_sel_hi:[1,0,1]
	s_waitcnt lgkmcnt(0)
	v_fmac_f32_e32 v17, v26, v12
	v_fmac_f32_e32 v17, v27, v13
	v_pk_mul_f32 v[26:27], v[46:47], v[36:37] op_sel_hi:[0,1]
	v_pk_fma_f32 v[14:15], v[14:15], v[18:19], v[26:27] op_sel_hi:[1,0,1]
	v_fmac_f32_e32 v17, v28, v14
	v_fmac_f32_e32 v17, v29, v15
	ds_read_b128 v[26:29], v23 offset:50736
	s_waitcnt lgkmcnt(0)
	v_fmac_f32_e32 v17, v26, v0
	v_fmac_f32_e32 v17, v27, v1
	v_pk_mul_f32 v[26:27], v[46:47], v[40:41] op_sel_hi:[0,1]
	v_pk_fma_f32 v[2:3], v[2:3], v[18:19], v[26:27] op_sel_hi:[1,0,1]
	v_fmac_f32_e32 v17, v28, v2
	v_fmac_f32_e32 v17, v29, v3
	ds_bpermute_b32 v18, v22, v17
	s_waitcnt lgkmcnt(0)
	v_add_f32_e32 v17, v17, v18
	ds_bpermute_b32 v18, v24, v17
	s_waitcnt lgkmcnt(0)
	v_add_f32_e32 v17, v17, v18
	ds_bpermute_b32 v18, v25, v17
	s_and_saveexec_b64 s[4:5], vcc
	s_cbranch_execz .LBB0_204
	s_waitcnt lgkmcnt(0)
	v_add_f32_e32 v17, v17, v18
	s_waitcnt vmcnt(0)
	v_fmac_f32_e32 v17, v85, v16
	v_add_u32_e32 v16, 0x14300, v21
	ds_write_b32 v16, v17
.LBB0_204:
	s_or_b64 exec, exec, s[4:5]
	v_readlane_b32 s3, v252, 55
	s_nop 1
	v_mov_b32_e32 v16, s3
	v_readlane_b32 s3, v252, 56
	s_waitcnt lgkmcnt(0)
	ds_read_b32 v18, v16
	ds_read_b32 v16, v21 offset:1024
	v_mov_b32_e32 v17, s3
	ds_read_b32 v17, v17
	ds_read_b128 v[26:29], v23 offset:18432
	ds_read_b128 v[30:33], v23 offset:18448
	ds_read_b128 v[34:37], v23 offset:18464
	ds_read_b128 v[38:41], v23 offset:18480
	ds_read_b128 v[42:45], v23 offset:51200
	s_waitcnt lgkmcnt(5)
	v_mul_f32_e32 v46, v16, v17
	s_waitcnt lgkmcnt(4)
	v_pk_mul_f32 v[26:27], v[46:47], v[26:27] op_sel_hi:[0,1]
	v_pk_fma_f32 v[4:5], v[4:5], v[18:19], v[26:27] op_sel_hi:[1,0,1]
	v_pk_mul_f32 v[26:27], v[46:47], v[28:29] op_sel_hi:[0,1]
	v_pk_fma_f32 v[6:7], v[6:7], v[18:19], v[26:27] op_sel_hi:[1,0,1]
	ds_read_b128 v[26:29], v23 offset:51216
	s_waitcnt lgkmcnt(1)
	v_fma_f32 v17, v42, v4, 0
	v_fmac_f32_e32 v17, v43, v5
	v_fmac_f32_e32 v17, v44, v6
	v_pk_mul_f32 v[30:31], v[46:47], v[30:31] op_sel_hi:[0,1]
	v_fmac_f32_e32 v17, v45, v7
	v_pk_fma_f32 v[8:9], v[8:9], v[18:19], v[30:31] op_sel_hi:[1,0,1]
	v_pk_mul_f32 v[30:31], v[46:47], v[34:35] op_sel_hi:[0,1]
	s_waitcnt lgkmcnt(0)
	v_fmac_f32_e32 v17, v26, v8
	v_fmac_f32_e32 v17, v27, v9
	v_pk_mul_f32 v[26:27], v[46:47], v[32:33] op_sel_hi:[0,1]
	v_pk_fma_f32 v[10:11], v[10:11], v[18:19], v[26:27] op_sel_hi:[1,0,1]
	v_pk_fma_f32 v[12:13], v[12:13], v[18:19], v[30:31] op_sel_hi:[1,0,1]
	v_fmac_f32_e32 v17, v28, v10
	v_fmac_f32_e32 v17, v29, v11
	ds_read_b128 v[26:29], v23 offset:51232
	v_pk_mul_f32 v[30:31], v[46:47], v[38:39] op_sel_hi:[0,1]
	v_pk_fma_f32 v[0:1], v[0:1], v[18:19], v[30:31] op_sel_hi:[1,0,1]
	s_waitcnt lgkmcnt(0)
	v_fmac_f32_e32 v17, v26, v12
	v_fmac_f32_e32 v17, v27, v13
	v_pk_mul_f32 v[26:27], v[46:47], v[36:37] op_sel_hi:[0,1]
	v_pk_fma_f32 v[14:15], v[14:15], v[18:19], v[26:27] op_sel_hi:[1,0,1]
	v_fmac_f32_e32 v17, v28, v14
	v_fmac_f32_e32 v17, v29, v15
	ds_read_b128 v[26:29], v23 offset:51248
	s_waitcnt lgkmcnt(0)
	v_fmac_f32_e32 v17, v26, v0
	v_fmac_f32_e32 v17, v27, v1
	v_pk_mul_f32 v[26:27], v[46:47], v[40:41] op_sel_hi:[0,1]
	v_pk_fma_f32 v[2:3], v[2:3], v[18:19], v[26:27] op_sel_hi:[1,0,1]
	v_fmac_f32_e32 v17, v28, v2
	v_fmac_f32_e32 v17, v29, v3
	ds_bpermute_b32 v18, v22, v17
	s_waitcnt lgkmcnt(0)
	v_add_f32_e32 v17, v17, v18
	ds_bpermute_b32 v18, v24, v17
	s_waitcnt lgkmcnt(0)
	v_add_f32_e32 v17, v17, v18
	ds_bpermute_b32 v18, v25, v17
	s_and_saveexec_b64 s[4:5], vcc
	s_cbranch_execz .LBB0_206
	s_waitcnt lgkmcnt(0)
	v_add_f32_e32 v17, v17, v18
	s_waitcnt vmcnt(0)
	v_fmac_f32_e32 v17, v85, v16
	v_add_u32_e32 v16, 0x14400, v21
	ds_write_b32 v16, v17
; #define LAS __attribute__((address_space(3)))
; DI void ssd_unit(const Args& a, bool sample, int b, int hd, LAS unsigned char* lds, const int tid) {
;     ...
;         for (int tt = 0; tt < TC; ++tt) {
;             const float dA = dAs[tt], xv = Xs[tt * 64 + pp], xdt = xv * dts[tt];
;             const LAS f32x4* bp = (const LAS f32x4*)(Bs + tt * 128 + ns * 16); const LAS f32x4* cp = (const LAS f32x4*)(Cs + tt * 128 + ns * 16);
;             float yp = 0.f;
; #pragma unroll
;             for (int q = 0; q < 4; ++q) { const f32x4 bv = bp[q], cv = cp[q];
; #pragma unroll
;                 for (int e = 0; e < 4; ++e) { h[4 * q + e] = dA * h[4 * q + e] + xdt * bv[e]; yp += h[4 * q + e] * cv[e]; } }
;             yp += __shfl_xor(yp, 1); yp += __shfl_xor(yp, 2); yp += __shfl_xor(yp, 4);
;             if (ns == 0) Ys[tt * 64 + pp] = yp + Dk * xv;
.LBB0_206:
	s_or_b64 exec, exec, s[4:5]
	v_readlane_b32 s3, v252, 57
	s_nop 1
	v_mov_b32_e32 v16, s3
	v_readlane_b32 s3, v252, 58
	s_waitcnt lgkmcnt(0)
	ds_read_b32 v18, v16
	ds_read_b32 v16, v21 offset:1280
	v_mov_b32_e32 v17, s3
	ds_read_b32 v17, v17
	ds_read_b128 v[26:29], v23 offset:18944
	ds_read_b128 v[30:33], v23 offset:18960
	ds_read_b128 v[34:37], v23 offset:18976
	ds_read_b128 v[38:41], v23 offset:18992
	ds_read_b128 v[42:45], v23 offset:51712
	s_waitcnt lgkmcnt(5)
	v_mul_f32_e32 v46, v16, v17
	s_waitcnt lgkmcnt(4)
	v_pk_mul_f32 v[26:27], v[46:47], v[26:27] op_sel_hi:[0,1]
	v_pk_fma_f32 v[4:5], v[4:5], v[18:19], v[26:27] op_sel_hi:[1,0,1]
	v_pk_mul_f32 v[26:27], v[46:47], v[28:29] op_sel_hi:[0,1]
	v_pk_fma_f32 v[6:7], v[6:7], v[18:19], v[26:27] op_sel_hi:[1,0,1]
	ds_read_b128 v[26:29], v23 offset:51728
	s_waitcnt lgkmcnt(1)
	v_fma_f32 v17, v42, v4, 0
	v_fmac_f32_e32 v17, v43, v5
	v_fmac_f32_e32 v17, v44, v6
	v_pk_mul_f32 v[30:31], v[46:47], v[30:31] op_sel_hi:[0,1]
	v_fmac_f32_e32 v17, v45, v7
	v_pk_fma_f32 v[8:9], v[8:9], v[18:19], v[30:31] op_sel_hi:[1,0,1]
	v_pk_mul_f32 v[30:31], v[46:47], v[34:35] op_sel_hi:[0,1]
	s_waitcnt lgkmcnt(0)
	v_fmac_f32_e32 v17, v26, v8
	v_fmac_f32_e32 v17, v27, v9
	v_pk_mul_f32 v[26:27], v[46:47], v[32:33] op_sel_hi:[0,1]
	v_pk_fma_f32 v[10:11], v[10:11], v[18:19], v[26:27] op_sel_hi:[1,0,1]
	v_pk_fma_f32 v[12:13], v[12:13], v[18:19], v[30:31] op_sel_hi:[1,0,1]
	v_fmac_f32_e32 v17, v28, v10
	v_fmac_f32_e32 v17, v29, v11
	ds_read_b128 v[26:29], v23 offset:51744
	v_pk_mul_f32 v[30:31], v[46:47], v[38:39] op_sel_hi:[0,1]
	v_pk_fma_f32 v[0:1], v[0:1], v[18:19], v[30:31] op_sel_hi:[1,0,1]
	s_waitcnt lgkmcnt(0)
	v_fmac_f32_e32 v17, v26, v12
	v_fmac_f32_e32 v17, v27, v13
	v_pk_mul_f32 v[26:27], v[46:47], v[36:37] op_sel_hi:[0,1]
	v_pk_fma_f32 v[14:15], v[14:15], v[18:19], v[26:27] op_sel_hi:[1,0,1]
	v_fmac_f32_e32 v17, v28, v14
	v_fmac_f32_e32 v17, v29, v15
	ds_read_b128 v[26:29], v23 offset:51760
	s_waitcnt lgkmcnt(0)
	v_fmac_f32_e32 v17, v26, v0
	v_fmac_f32_e32 v17, v27, v1
	v_pk_mul_f32 v[26:27], v[46:47], v[40:41] op_sel_hi:[0,1]
	v_pk_fma_f32 v[2:3], v[2:3], v[18:19], v[26:27] op_sel_hi:[1,0,1]
	v_fmac_f32_e32 v17, v28, v2
	v_fmac_f32_e32 v17, v29, v3
	ds_bpermute_b32 v18, v22, v17
	s_waitcnt lgkmcnt(0)
	v_add_f32_e32 v17, v17, v18
	ds_bpermute_b32 v18, v24, v17
	s_waitcnt lgkmcnt(0)
	v_add_f32_e32 v17, v17, v18
	ds_bpermute_b32 v18, v25, v17
	s_and_saveexec_b64 s[4:5], vcc
	s_cbranch_execz .LBB0_208
	s_waitcnt lgkmcnt(0)
	v_add_f32_e32 v17, v17, v18
	s_waitcnt vmcnt(0)
	v_fmac_f32_e32 v17, v85, v16
	v_add_u32_e32 v16, 0x14500, v21
	ds_write_b32 v16, v17
.LBB0_208:
	s_or_b64 exec, exec, s[4:5]
	v_readlane_b32 s3, v252, 59
	s_nop 1
	v_mov_b32_e32 v16, s3
	v_readlane_b32 s3, v252, 60
	s_waitcnt lgkmcnt(0)
	ds_read_b32 v18, v16
	ds_read_b32 v16, v21 offset:1536
	v_mov_b32_e32 v17, s3
	ds_read_b32 v17, v17
	ds_read_b128 v[26:29], v23 offset:19456
	ds_read_b128 v[30:33], v23 offset:19472
	ds_read_b128 v[34:37], v23 offset:19488
	ds_read_b128 v[38:41], v23 offset:19504
	ds_read_b128 v[42:45], v23 offset:52224
	s_waitcnt lgkmcnt(5)
	v_mul_f32_e32 v46, v16, v17
	s_waitcnt lgkmcnt(4)
	v_pk_mul_f32 v[26:27], v[46:47], v[26:27] op_sel_hi:[0,1]
	v_pk_fma_f32 v[4:5], v[4:5], v[18:19], v[26:27] op_sel_hi:[1,0,1]
	v_pk_mul_f32 v[26:27], v[46:47], v[28:29] op_sel_hi:[0,1]
	v_pk_fma_f32 v[6:7], v[6:7], v[18:19], v[26:27] op_sel_hi:[1,0,1]
	ds_read_b128 v[26:29], v23 offset:52240
	s_waitcnt lgkmcnt(1)
	v_fma_f32 v17, v42, v4, 0
	v_fmac_f32_e32 v17, v43, v5
	v_fmac_f32_e32 v17, v44, v6
	v_pk_mul_f32 v[30:31], v[46:47], v[30:31] op_sel_hi:[0,1]
	v_fmac_f32_e32 v17, v45, v7
	v_pk_fma_f32 v[8:9], v[8:9], v[18:19], v[30:31] op_sel_hi:[1,0,1]
	v_pk_mul_f32 v[30:31], v[46:47], v[34:35] op_sel_hi:[0,1]
	s_waitcnt lgkmcnt(0)
	v_fmac_f32_e32 v17, v26, v8
	v_fmac_f32_e32 v17, v27, v9
	v_pk_mul_f32 v[26:27], v[46:47], v[32:33] op_sel_hi:[0,1]
	v_pk_fma_f32 v[10:11], v[10:11], v[18:19], v[26:27] op_sel_hi:[1,0,1]
	v_pk_fma_f32 v[12:13], v[12:13], v[18:19], v[30:31] op_sel_hi:[1,0,1]
	v_fmac_f32_e32 v17, v28, v10
	v_fmac_f32_e32 v17, v29, v11
	ds_read_b128 v[26:29], v23 offset:52256
	v_pk_mul_f32 v[30:31], v[46:47], v[38:39] op_sel_hi:[0,1]
	v_pk_fma_f32 v[0:1], v[0:1], v[18:19], v[30:31] op_sel_hi:[1,0,1]
	s_waitcnt lgkmcnt(0)
	v_fmac_f32_e32 v17, v26, v12
	v_fmac_f32_e32 v17, v27, v13
	v_pk_mul_f32 v[26:27], v[46:47], v[36:37] op_sel_hi:[0,1]
	v_pk_fma_f32 v[14:15], v[14:15], v[18:19], v[26:27] op_sel_hi:[1,0,1]
	v_fmac_f32_e32 v17, v28, v14
	v_fmac_f32_e32 v17, v29, v15
	ds_read_b128 v[26:29], v23 offset:52272
	s_waitcnt lgkmcnt(0)
	v_fmac_f32_e32 v17, v26, v0
	v_fmac_f32_e32 v17, v27, v1
	v_pk_mul_f32 v[26:27], v[46:47], v[40:41] op_sel_hi:[0,1]
	v_pk_fma_f32 v[2:3], v[2:3], v[18:19], v[26:27] op_sel_hi:[1,0,1]
	v_fmac_f32_e32 v17, v28, v2
	v_fmac_f32_e32 v17, v29, v3
	ds_bpermute_b32 v18, v22, v17
	s_waitcnt lgkmcnt(0)
	v_add_f32_e32 v17, v17, v18
	ds_bpermute_b32 v18, v24, v17
	s_waitcnt lgkmcnt(0)
	v_add_f32_e32 v17, v17, v18
	ds_bpermute_b32 v18, v25, v17
	s_and_saveexec_b64 s[4:5], vcc
	s_cbranch_execz .LBB0_210
	s_waitcnt lgkmcnt(0)
	v_add_f32_e32 v17, v17, v18
	s_waitcnt vmcnt(0)
	v_fmac_f32_e32 v17, v85, v16
	v_add_u32_e32 v16, 0x14600, v21
	ds_write_b32 v16, v17
; #define LAS __attribute__((address_space(3)))
; DI void ssd_unit(const Args& a, bool sample, int b, int hd, LAS unsigned char* lds, const int tid) {
;     ...
;         for (int tt = 0; tt < TC; ++tt) {
;             const float dA = dAs[tt], xv = Xs[tt * 64 + pp], xdt = xv * dts[tt];
;             const LAS f32x4* bp = (const LAS f32x4*)(Bs + tt * 128 + ns * 16); const LAS f32x4* cp = (const LAS f32x4*)(Cs + tt * 128 + ns * 16);
;             float yp = 0.f;
; #pragma unroll
;             for (int q = 0; q < 4; ++q) { const f32x4 bv = bp[q], cv = cp[q];
; #pragma unroll
;                 for (int e = 0; e < 4; ++e) { h[4 * q + e] = dA * h[4 * q + e] + xdt * bv[e]; yp += h[4 * q + e] * cv[e]; } }
;             yp += __shfl_xor(yp, 1); yp += __shfl_xor(yp, 2); yp += __shfl_xor(yp, 4);
;             if (ns == 0) Ys[tt * 64 + pp] = yp + Dk * xv;
.LBB0_210:
	s_or_b64 exec, exec, s[4:5]
	v_readlane_b32 s3, v252, 61
	s_nop 1
	v_mov_b32_e32 v16, s3
	v_readlane_b32 s3, v252, 62
	s_waitcnt lgkmcnt(0)
	ds_read_b32 v18, v16
	ds_read_b32 v16, v21 offset:1792
	v_mov_b32_e32 v17, s3
	ds_read_b32 v17, v17
	ds_read_b128 v[26:29], v23 offset:19968
	ds_read_b128 v[30:33], v23 offset:19984
	ds_read_b128 v[34:37], v23 offset:20000
	ds_read_b128 v[38:41], v23 offset:20016
	ds_read_b128 v[42:45], v23 offset:52736
	s_waitcnt lgkmcnt(5)
	v_mul_f32_e32 v46, v16, v17
	s_waitcnt lgkmcnt(4)
	v_pk_mul_f32 v[26:27], v[46:47], v[26:27] op_sel_hi:[0,1]
	v_pk_fma_f32 v[4:5], v[4:5], v[18:19], v[26:27] op_sel_hi:[1,0,1]
	v_pk_mul_f32 v[26:27], v[46:47], v[28:29] op_sel_hi:[0,1]
	v_pk_fma_f32 v[6:7], v[6:7], v[18:19], v[26:27] op_sel_hi:[1,0,1]
	ds_read_b128 v[26:29], v23 offset:52752
	s_waitcnt lgkmcnt(1)
	v_fma_f32 v17, v42, v4, 0
	v_fmac_f32_e32 v17, v43, v5
	v_fmac_f32_e32 v17, v44, v6
	v_pk_mul_f32 v[30:31], v[46:47], v[30:31] op_sel_hi:[0,1]
	v_fmac_f32_e32 v17, v45, v7
	v_pk_fma_f32 v[8:9], v[8:9], v[18:19], v[30:31] op_sel_hi:[1,0,1]
	v_pk_mul_f32 v[30:31], v[46:47], v[34:35] op_sel_hi:[0,1]
	s_waitcnt lgkmcnt(0)
	v_fmac_f32_e32 v17, v26, v8
	v_fmac_f32_e32 v17, v27, v9
	v_pk_mul_f32 v[26:27], v[46:47], v[32:33] op_sel_hi:[0,1]
	v_pk_fma_f32 v[10:11], v[10:11], v[18:19], v[26:27] op_sel_hi:[1,0,1]
	v_pk_fma_f32 v[12:13], v[12:13], v[18:19], v[30:31] op_sel_hi:[1,0,1]
	v_fmac_f32_e32 v17, v28, v10
	v_fmac_f32_e32 v17, v29, v11
	ds_read_b128 v[26:29], v23 offset:52768
	v_pk_mul_f32 v[30:31], v[46:47], v[38:39] op_sel_hi:[0,1]
	v_pk_fma_f32 v[0:1], v[0:1], v[18:19], v[30:31] op_sel_hi:[1,0,1]
	s_waitcnt lgkmcnt(0)
	v_fmac_f32_e32 v17, v26, v12
	v_fmac_f32_e32 v17, v27, v13
	v_pk_mul_f32 v[26:27], v[46:47], v[36:37] op_sel_hi:[0,1]
	v_pk_fma_f32 v[14:15], v[14:15], v[18:19], v[26:27] op_sel_hi:[1,0,1]
	v_fmac_f32_e32 v17, v28, v14
	v_fmac_f32_e32 v17, v29, v15
	ds_read_b128 v[26:29], v23 offset:52784
	s_waitcnt lgkmcnt(0)
	v_fmac_f32_e32 v17, v26, v0
	v_fmac_f32_e32 v17, v27, v1
	v_pk_mul_f32 v[26:27], v[46:47], v[40:41] op_sel_hi:[0,1]
	v_pk_fma_f32 v[2:3], v[2:3], v[18:19], v[26:27] op_sel_hi:[1,0,1]
	v_fmac_f32_e32 v17, v28, v2
	v_fmac_f32_e32 v17, v29, v3
	ds_bpermute_b32 v18, v22, v17
	s_waitcnt lgkmcnt(0)
	v_add_f32_e32 v17, v17, v18
	ds_bpermute_b32 v18, v24, v17
	s_waitcnt lgkmcnt(0)
	v_add_f32_e32 v17, v17, v18
	ds_bpermute_b32 v18, v25, v17
	s_and_saveexec_b64 s[4:5], vcc
	s_cbranch_execz .LBB0_212
	s_waitcnt lgkmcnt(0)
	v_add_f32_e32 v17, v17, v18
	s_waitcnt vmcnt(0)
	v_fmac_f32_e32 v17, v85, v16
	v_add_u32_e32 v16, 0x14700, v21
	ds_write_b32 v16, v17
.LBB0_212:
	s_or_b64 exec, exec, s[4:5]
	v_readlane_b32 s3, v252, 63
	s_nop 1
	v_mov_b32_e32 v16, s3
	v_readlane_b32 s3, v253, 0
	s_waitcnt lgkmcnt(0)
	ds_read_b32 v18, v16
	ds_read_b32 v16, v21 offset:2048
	v_mov_b32_e32 v17, s3
	ds_read_b32 v17, v17
	ds_read_b128 v[26:29], v23 offset:20480
	ds_read_b128 v[30:33], v23 offset:20496
	ds_read_b128 v[34:37], v23 offset:20512
	ds_read_b128 v[38:41], v23 offset:20528
	ds_read_b128 v[42:45], v23 offset:53248
	s_waitcnt lgkmcnt(5)
	v_mul_f32_e32 v46, v16, v17
	s_waitcnt lgkmcnt(4)
	v_pk_mul_f32 v[26:27], v[46:47], v[26:27] op_sel_hi:[0,1]
	v_pk_fma_f32 v[4:5], v[4:5], v[18:19], v[26:27] op_sel_hi:[1,0,1]
	v_pk_mul_f32 v[26:27], v[46:47], v[28:29] op_sel_hi:[0,1]
	v_pk_fma_f32 v[6:7], v[6:7], v[18:19], v[26:27] op_sel_hi:[1,0,1]
	ds_read_b128 v[26:29], v23 offset:53264
	s_waitcnt lgkmcnt(1)
	v_fma_f32 v17, v42, v4, 0
	v_fmac_f32_e32 v17, v43, v5
	v_fmac_f32_e32 v17, v44, v6
	v_pk_mul_f32 v[30:31], v[46:47], v[30:31] op_sel_hi:[0,1]
	v_fmac_f32_e32 v17, v45, v7
	v_pk_fma_f32 v[8:9], v[8:9], v[18:19], v[30:31] op_sel_hi:[1,0,1]
	v_pk_mul_f32 v[30:31], v[46:47], v[34:35] op_sel_hi:[0,1]
	s_waitcnt lgkmcnt(0)
	v_fmac_f32_e32 v17, v26, v8
	v_fmac_f32_e32 v17, v27, v9
	v_pk_mul_f32 v[26:27], v[46:47], v[32:33] op_sel_hi:[0,1]
	v_pk_fma_f32 v[10:11], v[10:11], v[18:19], v[26:27] op_sel_hi:[1,0,1]
	v_pk_fma_f32 v[12:13], v[12:13], v[18:19], v[30:31] op_sel_hi:[1,0,1]
	v_fmac_f32_e32 v17, v28, v10
	v_fmac_f32_e32 v17, v29, v11
	ds_read_b128 v[26:29], v23 offset:53280
	v_pk_mul_f32 v[30:31], v[46:47], v[38:39] op_sel_hi:[0,1]
	v_pk_fma_f32 v[0:1], v[0:1], v[18:19], v[30:31] op_sel_hi:[1,0,1]
	s_waitcnt lgkmcnt(0)
	v_fmac_f32_e32 v17, v26, v12
	v_fmac_f32_e32 v17, v27, v13
	v_pk_mul_f32 v[26:27], v[46:47], v[36:37] op_sel_hi:[0,1]
	v_pk_fma_f32 v[14:15], v[14:15], v[18:19], v[26:27] op_sel_hi:[1,0,1]
	v_fmac_f32_e32 v17, v28, v14
	v_fmac_f32_e32 v17, v29, v15
	ds_read_b128 v[26:29], v23 offset:53296
	s_waitcnt lgkmcnt(0)
	v_fmac_f32_e32 v17, v26, v0
	v_fmac_f32_e32 v17, v27, v1
	v_pk_mul_f32 v[26:27], v[46:47], v[40:41] op_sel_hi:[0,1]
	v_pk_fma_f32 v[2:3], v[2:3], v[18:19], v[26:27] op_sel_hi:[1,0,1]
	v_fmac_f32_e32 v17, v28, v2
	v_fmac_f32_e32 v17, v29, v3
	ds_bpermute_b32 v18, v22, v17
	s_waitcnt lgkmcnt(0)
	v_add_f32_e32 v17, v17, v18
	ds_bpermute_b32 v18, v24, v17
	s_waitcnt lgkmcnt(0)
	v_add_f32_e32 v17, v17, v18
	ds_bpermute_b32 v18, v25, v17
	s_and_saveexec_b64 s[4:5], vcc
	s_cbranch_execz .LBB0_214
	s_waitcnt lgkmcnt(0)
	v_add_f32_e32 v17, v17, v18
	s_waitcnt vmcnt(0)
	v_fmac_f32_e32 v17, v85, v16
	v_add_u32_e32 v16, 0x14800, v21
	ds_write_b32 v16, v17
; #define LAS __attribute__((address_space(3)))
; DI void ssd_unit(const Args& a, bool sample, int b, int hd, LAS unsigned char* lds, const int tid) {
;     ...
;         for (int tt = 0; tt < TC; ++tt) {
;             const float dA = dAs[tt], xv = Xs[tt * 64 + pp], xdt = xv * dts[tt];
;             const LAS f32x4* bp = (const LAS f32x4*)(Bs + tt * 128 + ns * 16); const LAS f32x4* cp = (const LAS f32x4*)(Cs + tt * 128 + ns * 16);
;             float yp = 0.f;
; #pragma unroll
;             for (int q = 0; q < 4; ++q) { const f32x4 bv = bp[q], cv = cp[q];
; #pragma unroll
;                 for (int e = 0; e < 4; ++e) { h[4 * q + e] = dA * h[4 * q + e] + xdt * bv[e]; yp += h[4 * q + e] * cv[e]; } }
;             yp += __shfl_xor(yp, 1); yp += __shfl_xor(yp, 2); yp += __shfl_xor(yp, 4);
;             if (ns == 0) Ys[tt * 64 + pp] = yp + Dk * xv;
.LBB0_214:
	s_or_b64 exec, exec, s[4:5]
	v_readlane_b32 s3, v253, 1
	s_nop 1
	v_mov_b32_e32 v16, s3
	v_readlane_b32 s3, v253, 2
	s_waitcnt lgkmcnt(0)
	ds_read_b32 v18, v16
	ds_read_b32 v16, v21 offset:2304
	v_mov_b32_e32 v17, s3
	ds_read_b32 v17, v17
	ds_read_b128 v[26:29], v23 offset:20992
	ds_read_b128 v[30:33], v23 offset:21008
	ds_read_b128 v[34:37], v23 offset:21024
	ds_read_b128 v[38:41], v23 offset:21040
	ds_read_b128 v[42:45], v23 offset:53760
	s_waitcnt lgkmcnt(5)
	v_mul_f32_e32 v46, v16, v17
	s_waitcnt lgkmcnt(4)
	v_pk_mul_f32 v[26:27], v[46:47], v[26:27] op_sel_hi:[0,1]
	v_pk_fma_f32 v[4:5], v[4:5], v[18:19], v[26:27] op_sel_hi:[1,0,1]
	v_pk_mul_f32 v[26:27], v[46:47], v[28:29] op_sel_hi:[0,1]
	v_pk_fma_f32 v[6:7], v[6:7], v[18:19], v[26:27] op_sel_hi:[1,0,1]
	ds_read_b128 v[26:29], v23 offset:53776
	s_waitcnt lgkmcnt(1)
	v_fma_f32 v17, v42, v4, 0
	v_fmac_f32_e32 v17, v43, v5
	v_fmac_f32_e32 v17, v44, v6
	v_pk_mul_f32 v[30:31], v[46:47], v[30:31] op_sel_hi:[0,1]
	v_fmac_f32_e32 v17, v45, v7
	v_pk_fma_f32 v[8:9], v[8:9], v[18:19], v[30:31] op_sel_hi:[1,0,1]
	v_pk_mul_f32 v[30:31], v[46:47], v[34:35] op_sel_hi:[0,1]
	s_waitcnt lgkmcnt(0)
	v_fmac_f32_e32 v17, v26, v8
	v_fmac_f32_e32 v17, v27, v9
	v_pk_mul_f32 v[26:27], v[46:47], v[32:33] op_sel_hi:[0,1]
	v_pk_fma_f32 v[10:11], v[10:11], v[18:19], v[26:27] op_sel_hi:[1,0,1]
	v_pk_fma_f32 v[12:13], v[12:13], v[18:19], v[30:31] op_sel_hi:[1,0,1]
	v_fmac_f32_e32 v17, v28, v10
	v_fmac_f32_e32 v17, v29, v11
	ds_read_b128 v[26:29], v23 offset:53792
	v_pk_mul_f32 v[30:31], v[46:47], v[38:39] op_sel_hi:[0,1]
	v_pk_fma_f32 v[0:1], v[0:1], v[18:19], v[30:31] op_sel_hi:[1,0,1]
	s_waitcnt lgkmcnt(0)
	v_fmac_f32_e32 v17, v26, v12
	v_fmac_f32_e32 v17, v27, v13
	v_pk_mul_f32 v[26:27], v[46:47], v[36:37] op_sel_hi:[0,1]
	v_pk_fma_f32 v[14:15], v[14:15], v[18:19], v[26:27] op_sel_hi:[1,0,1]
	v_fmac_f32_e32 v17, v28, v14
	v_fmac_f32_e32 v17, v29, v15
	ds_read_b128 v[26:29], v23 offset:53808
	s_waitcnt lgkmcnt(0)
	v_fmac_f32_e32 v17, v26, v0
	v_fmac_f32_e32 v17, v27, v1
	v_pk_mul_f32 v[26:27], v[46:47], v[40:41] op_sel_hi:[0,1]
	v_pk_fma_f32 v[2:3], v[2:3], v[18:19], v[26:27] op_sel_hi:[1,0,1]
	v_fmac_f32_e32 v17, v28, v2
	v_fmac_f32_e32 v17, v29, v3
	ds_bpermute_b32 v18, v22, v17
	s_waitcnt lgkmcnt(0)
	v_add_f32_e32 v17, v17, v18
	ds_bpermute_b32 v18, v24, v17
	s_waitcnt lgkmcnt(0)
	v_add_f32_e32 v17, v17, v18
	ds_bpermute_b32 v18, v25, v17
	s_and_saveexec_b64 s[4:5], vcc
	s_cbranch_execz .LBB0_216
	s_waitcnt lgkmcnt(0)
	v_add_f32_e32 v17, v17, v18
	s_waitcnt vmcnt(0)
	v_fmac_f32_e32 v17, v85, v16
	v_add_u32_e32 v16, 0x14900, v21
	ds_write_b32 v16, v17
.LBB0_216:
	s_or_b64 exec, exec, s[4:5]
	v_readlane_b32 s3, v253, 3
	s_nop 1
	v_mov_b32_e32 v16, s3
	v_readlane_b32 s3, v253, 4
	s_waitcnt lgkmcnt(0)
	ds_read_b32 v18, v16
	ds_read_b32 v16, v21 offset:2560
	v_mov_b32_e32 v17, s3
	ds_read_b32 v17, v17
	ds_read_b128 v[26:29], v23 offset:21504
	ds_read_b128 v[30:33], v23 offset:21520
	ds_read_b128 v[34:37], v23 offset:21536
	ds_read_b128 v[38:41], v23 offset:21552
	ds_read_b128 v[42:45], v23 offset:54272
	s_waitcnt lgkmcnt(5)
	v_mul_f32_e32 v46, v16, v17
	s_waitcnt lgkmcnt(4)
	v_pk_mul_f32 v[26:27], v[46:47], v[26:27] op_sel_hi:[0,1]
	v_pk_fma_f32 v[4:5], v[4:5], v[18:19], v[26:27] op_sel_hi:[1,0,1]
	v_pk_mul_f32 v[26:27], v[46:47], v[28:29] op_sel_hi:[0,1]
	v_pk_fma_f32 v[6:7], v[6:7], v[18:19], v[26:27] op_sel_hi:[1,0,1]
	ds_read_b128 v[26:29], v23 offset:54288
	s_waitcnt lgkmcnt(1)
	v_fma_f32 v17, v42, v4, 0
	v_fmac_f32_e32 v17, v43, v5
	v_fmac_f32_e32 v17, v44, v6
	v_pk_mul_f32 v[30:31], v[46:47], v[30:31] op_sel_hi:[0,1]
	v_fmac_f32_e32 v17, v45, v7
	v_pk_fma_f32 v[8:9], v[8:9], v[18:19], v[30:31] op_sel_hi:[1,0,1]
	v_pk_mul_f32 v[30:31], v[46:47], v[34:35] op_sel_hi:[0,1]
	s_waitcnt lgkmcnt(0)
	v_fmac_f32_e32 v17, v26, v8
	v_fmac_f32_e32 v17, v27, v9
	v_pk_mul_f32 v[26:27], v[46:47], v[32:33] op_sel_hi:[0,1]
	v_pk_fma_f32 v[10:11], v[10:11], v[18:19], v[26:27] op_sel_hi:[1,0,1]
	v_pk_fma_f32 v[12:13], v[12:13], v[18:19], v[30:31] op_sel_hi:[1,0,1]
	v_fmac_f32_e32 v17, v28, v10
	v_fmac_f32_e32 v17, v29, v11
	ds_read_b128 v[26:29], v23 offset:54304
	v_pk_mul_f32 v[30:31], v[46:47], v[38:39] op_sel_hi:[0,1]
	v_pk_fma_f32 v[0:1], v[0:1], v[18:19], v[30:31] op_sel_hi:[1,0,1]
	s_waitcnt lgkmcnt(0)
	v_fmac_f32_e32 v17, v26, v12
	v_fmac_f32_e32 v17, v27, v13
	v_pk_mul_f32 v[26:27], v[46:47], v[36:37] op_sel_hi:[0,1]
	v_pk_fma_f32 v[14:15], v[14:15], v[18:19], v[26:27] op_sel_hi:[1,0,1]
	v_fmac_f32_e32 v17, v28, v14
	v_fmac_f32_e32 v17, v29, v15
	ds_read_b128 v[26:29], v23 offset:54320
	s_waitcnt lgkmcnt(0)
	v_fmac_f32_e32 v17, v26, v0
	v_fmac_f32_e32 v17, v27, v1
	v_pk_mul_f32 v[26:27], v[46:47], v[40:41] op_sel_hi:[0,1]
	v_pk_fma_f32 v[2:3], v[2:3], v[18:19], v[26:27] op_sel_hi:[1,0,1]
	v_fmac_f32_e32 v17, v28, v2
	v_fmac_f32_e32 v17, v29, v3
	ds_bpermute_b32 v18, v22, v17
	s_waitcnt lgkmcnt(0)
	v_add_f32_e32 v17, v17, v18
	ds_bpermute_b32 v18, v24, v17
	s_waitcnt lgkmcnt(0)
	v_add_f32_e32 v17, v17, v18
	ds_bpermute_b32 v18, v25, v17
	s_and_saveexec_b64 s[4:5], vcc
	s_cbranch_execz .LBB0_218
	s_waitcnt lgkmcnt(0)
	v_add_f32_e32 v17, v17, v18
	s_waitcnt vmcnt(0)
	v_fmac_f32_e32 v17, v85, v16
	v_add_u32_e32 v16, 0x14a00, v21
	ds_write_b32 v16, v17
; #define LAS __attribute__((address_space(3)))
; DI void ssd_unit(const Args& a, bool sample, int b, int hd, LAS unsigned char* lds, const int tid) {
;     ...
;         for (int tt = 0; tt < TC; ++tt) {
;             const float dA = dAs[tt], xv = Xs[tt * 64 + pp], xdt = xv * dts[tt];
;             const LAS f32x4* bp = (const LAS f32x4*)(Bs + tt * 128 + ns * 16); const LAS f32x4* cp = (const LAS f32x4*)(Cs + tt * 128 + ns * 16);
;             float yp = 0.f;
; #pragma unroll
;             for (int q = 0; q < 4; ++q) { const f32x4 bv = bp[q], cv = cp[q];
; #pragma unroll
;                 for (int e = 0; e < 4; ++e) { h[4 * q + e] = dA * h[4 * q + e] + xdt * bv[e]; yp += h[4 * q + e] * cv[e]; } }
;             yp += __shfl_xor(yp, 1); yp += __shfl_xor(yp, 2); yp += __shfl_xor(yp, 4);
;             if (ns == 0) Ys[tt * 64 + pp] = yp + Dk * xv;
.LBB0_218:
	s_or_b64 exec, exec, s[4:5]
	v_readlane_b32 s3, v253, 5
	s_nop 1
	v_mov_b32_e32 v16, s3
	v_readlane_b32 s3, v253, 6
	s_waitcnt lgkmcnt(0)
	ds_read_b32 v18, v16
	ds_read_b32 v16, v21 offset:2816
	v_mov_b32_e32 v17, s3
	ds_read_b32 v17, v17
	ds_read_b128 v[26:29], v23 offset:22016
	ds_read_b128 v[30:33], v23 offset:22032
	ds_read_b128 v[34:37], v23 offset:22048
	ds_read_b128 v[38:41], v23 offset:22064
	ds_read_b128 v[42:45], v23 offset:54784
	s_waitcnt lgkmcnt(5)
	v_mul_f32_e32 v46, v16, v17
	s_waitcnt lgkmcnt(4)
	v_pk_mul_f32 v[26:27], v[46:47], v[26:27] op_sel_hi:[0,1]
	v_pk_fma_f32 v[4:5], v[4:5], v[18:19], v[26:27] op_sel_hi:[1,0,1]
	v_pk_mul_f32 v[26:27], v[46:47], v[28:29] op_sel_hi:[0,1]
	v_pk_fma_f32 v[6:7], v[6:7], v[18:19], v[26:27] op_sel_hi:[1,0,1]
	ds_read_b128 v[26:29], v23 offset:54800
	s_waitcnt lgkmcnt(1)
	v_fma_f32 v17, v42, v4, 0
	v_fmac_f32_e32 v17, v43, v5
	v_fmac_f32_e32 v17, v44, v6
	v_pk_mul_f32 v[30:31], v[46:47], v[30:31] op_sel_hi:[0,1]
	v_fmac_f32_e32 v17, v45, v7
	v_pk_fma_f32 v[8:9], v[8:9], v[18:19], v[30:31] op_sel_hi:[1,0,1]
	v_pk_mul_f32 v[30:31], v[46:47], v[34:35] op_sel_hi:[0,1]
	s_waitcnt lgkmcnt(0)
	v_fmac_f32_e32 v17, v26, v8
	v_fmac_f32_e32 v17, v27, v9
	v_pk_mul_f32 v[26:27], v[46:47], v[32:33] op_sel_hi:[0,1]
	v_pk_fma_f32 v[10:11], v[10:11], v[18:19], v[26:27] op_sel_hi:[1,0,1]
	v_pk_fma_f32 v[12:13], v[12:13], v[18:19], v[30:31] op_sel_hi:[1,0,1]
	v_fmac_f32_e32 v17, v28, v10
	v_fmac_f32_e32 v17, v29, v11
	ds_read_b128 v[26:29], v23 offset:54816
	v_pk_mul_f32 v[30:31], v[46:47], v[38:39] op_sel_hi:[0,1]
	v_pk_fma_f32 v[0:1], v[0:1], v[18:19], v[30:31] op_sel_hi:[1,0,1]
	s_waitcnt lgkmcnt(0)
	v_fmac_f32_e32 v17, v26, v12
	v_fmac_f32_e32 v17, v27, v13
	v_pk_mul_f32 v[26:27], v[46:47], v[36:37] op_sel_hi:[0,1]
	v_pk_fma_f32 v[14:15], v[14:15], v[18:19], v[26:27] op_sel_hi:[1,0,1]
	v_fmac_f32_e32 v17, v28, v14
	v_fmac_f32_e32 v17, v29, v15
	ds_read_b128 v[26:29], v23 offset:54832
	s_waitcnt lgkmcnt(0)
	v_fmac_f32_e32 v17, v26, v0
	v_fmac_f32_e32 v17, v27, v1
	v_pk_mul_f32 v[26:27], v[46:47], v[40:41] op_sel_hi:[0,1]
	v_pk_fma_f32 v[2:3], v[2:3], v[18:19], v[26:27] op_sel_hi:[1,0,1]
	v_fmac_f32_e32 v17, v28, v2
	v_fmac_f32_e32 v17, v29, v3
	ds_bpermute_b32 v18, v22, v17
	s_waitcnt lgkmcnt(0)
	v_add_f32_e32 v17, v17, v18
	ds_bpermute_b32 v18, v24, v17
	s_waitcnt lgkmcnt(0)
	v_add_f32_e32 v17, v17, v18
	ds_bpermute_b32 v18, v25, v17
	s_and_saveexec_b64 s[4:5], vcc
	s_cbranch_execz .LBB0_220
	s_waitcnt lgkmcnt(0)
	v_add_f32_e32 v17, v17, v18
	s_waitcnt vmcnt(0)
	v_fmac_f32_e32 v17, v85, v16
	v_add_u32_e32 v16, 0x14b00, v21
	ds_write_b32 v16, v17
.LBB0_220:
	s_or_b64 exec, exec, s[4:5]
	v_readlane_b32 s3, v253, 7
	s_nop 1
	v_mov_b32_e32 v16, s3
	v_readlane_b32 s3, v253, 8
	s_waitcnt lgkmcnt(0)
	ds_read_b32 v18, v16
	ds_read_b32 v16, v21 offset:3072
	v_mov_b32_e32 v17, s3
	ds_read_b32 v17, v17
	ds_read_b128 v[26:29], v23 offset:22528
	ds_read_b128 v[30:33], v23 offset:22544
	ds_read_b128 v[34:37], v23 offset:22560
	ds_read_b128 v[38:41], v23 offset:22576
	ds_read_b128 v[42:45], v23 offset:55296
	s_waitcnt lgkmcnt(5)
	v_mul_f32_e32 v46, v16, v17
	s_waitcnt lgkmcnt(4)
	v_pk_mul_f32 v[26:27], v[46:47], v[26:27] op_sel_hi:[0,1]
	v_pk_fma_f32 v[4:5], v[4:5], v[18:19], v[26:27] op_sel_hi:[1,0,1]
	v_pk_mul_f32 v[26:27], v[46:47], v[28:29] op_sel_hi:[0,1]
	v_pk_fma_f32 v[6:7], v[6:7], v[18:19], v[26:27] op_sel_hi:[1,0,1]
	ds_read_b128 v[26:29], v23 offset:55312
	s_waitcnt lgkmcnt(1)
	v_fma_f32 v17, v42, v4, 0
	v_fmac_f32_e32 v17, v43, v5
	v_fmac_f32_e32 v17, v44, v6
	v_pk_mul_f32 v[30:31], v[46:47], v[30:31] op_sel_hi:[0,1]
	v_fmac_f32_e32 v17, v45, v7
	v_pk_fma_f32 v[8:9], v[8:9], v[18:19], v[30:31] op_sel_hi:[1,0,1]
	v_pk_mul_f32 v[30:31], v[46:47], v[34:35] op_sel_hi:[0,1]
	s_waitcnt lgkmcnt(0)
	v_fmac_f32_e32 v17, v26, v8
	v_fmac_f32_e32 v17, v27, v9
	v_pk_mul_f32 v[26:27], v[46:47], v[32:33] op_sel_hi:[0,1]
	v_pk_fma_f32 v[10:11], v[10:11], v[18:19], v[26:27] op_sel_hi:[1,0,1]
	v_pk_fma_f32 v[12:13], v[12:13], v[18:19], v[30:31] op_sel_hi:[1,0,1]
	v_fmac_f32_e32 v17, v28, v10
	v_fmac_f32_e32 v17, v29, v11
	ds_read_b128 v[26:29], v23 offset:55328
	v_pk_mul_f32 v[30:31], v[46:47], v[38:39] op_sel_hi:[0,1]
	v_pk_fma_f32 v[0:1], v[0:1], v[18:19], v[30:31] op_sel_hi:[1,0,1]
	s_waitcnt lgkmcnt(0)
	v_fmac_f32_e32 v17, v26, v12
	v_fmac_f32_e32 v17, v27, v13
	v_pk_mul_f32 v[26:27], v[46:47], v[36:37] op_sel_hi:[0,1]
	v_pk_fma_f32 v[14:15], v[14:15], v[18:19], v[26:27] op_sel_hi:[1,0,1]
	v_fmac_f32_e32 v17, v28, v14
	v_fmac_f32_e32 v17, v29, v15
	ds_read_b128 v[26:29], v23 offset:55344
	s_waitcnt lgkmcnt(0)
	v_fmac_f32_e32 v17, v26, v0
	v_fmac_f32_e32 v17, v27, v1
	v_pk_mul_f32 v[26:27], v[46:47], v[40:41] op_sel_hi:[0,1]
	v_pk_fma_f32 v[2:3], v[2:3], v[18:19], v[26:27] op_sel_hi:[1,0,1]
	v_fmac_f32_e32 v17, v28, v2
	v_fmac_f32_e32 v17, v29, v3
	ds_bpermute_b32 v18, v22, v17
	s_waitcnt lgkmcnt(0)
	v_add_f32_e32 v17, v17, v18
	ds_bpermute_b32 v18, v24, v17
	s_waitcnt lgkmcnt(0)
	v_add_f32_e32 v17, v17, v18
	ds_bpermute_b32 v18, v25, v17
	s_and_saveexec_b64 s[4:5], vcc
	s_cbranch_execz .LBB0_222
	s_waitcnt lgkmcnt(0)
	v_add_f32_e32 v17, v17, v18
	s_waitcnt vmcnt(0)
	v_fmac_f32_e32 v17, v85, v16
	v_add_u32_e32 v16, 0x14c00, v21
	ds_write_b32 v16, v17
; #define LAS __attribute__((address_space(3)))
; DI void ssd_unit(const Args& a, bool sample, int b, int hd, LAS unsigned char* lds, const int tid) {
;     ...
;         for (int tt = 0; tt < TC; ++tt) {
;             const float dA = dAs[tt], xv = Xs[tt * 64 + pp], xdt = xv * dts[tt];
;             const LAS f32x4* bp = (const LAS f32x4*)(Bs + tt * 128 + ns * 16); const LAS f32x4* cp = (const LAS f32x4*)(Cs + tt * 128 + ns * 16);
;             float yp = 0.f;
; #pragma unroll
;             for (int q = 0; q < 4; ++q) { const f32x4 bv = bp[q], cv = cp[q];
; #pragma unroll
;                 for (int e = 0; e < 4; ++e) { h[4 * q + e] = dA * h[4 * q + e] + xdt * bv[e]; yp += h[4 * q + e] * cv[e]; } }
;             yp += __shfl_xor(yp, 1); yp += __shfl_xor(yp, 2); yp += __shfl_xor(yp, 4);
;             if (ns == 0) Ys[tt * 64 + pp] = yp + Dk * xv;
.LBB0_222:
	s_or_b64 exec, exec, s[4:5]
	v_readlane_b32 s3, v253, 9
	s_nop 1
	v_mov_b32_e32 v16, s3
	v_readlane_b32 s3, v253, 10
	s_waitcnt lgkmcnt(0)
	ds_read_b32 v18, v16
	ds_read_b32 v16, v21 offset:3328
	v_mov_b32_e32 v17, s3
	ds_read_b32 v17, v17
	ds_read_b128 v[26:29], v23 offset:23040
	ds_read_b128 v[30:33], v23 offset:23056
	ds_read_b128 v[34:37], v23 offset:23072
	ds_read_b128 v[38:41], v23 offset:23088
	ds_read_b128 v[42:45], v23 offset:55808
	s_waitcnt lgkmcnt(5)
	v_mul_f32_e32 v46, v16, v17
	s_waitcnt lgkmcnt(4)
	v_pk_mul_f32 v[26:27], v[46:47], v[26:27] op_sel_hi:[0,1]
	v_pk_fma_f32 v[4:5], v[4:5], v[18:19], v[26:27] op_sel_hi:[1,0,1]
	v_pk_mul_f32 v[26:27], v[46:47], v[28:29] op_sel_hi:[0,1]
	v_pk_fma_f32 v[6:7], v[6:7], v[18:19], v[26:27] op_sel_hi:[1,0,1]
	ds_read_b128 v[26:29], v23 offset:55824
	s_waitcnt lgkmcnt(1)
	v_fma_f32 v17, v42, v4, 0
	v_fmac_f32_e32 v17, v43, v5
	v_fmac_f32_e32 v17, v44, v6
	v_pk_mul_f32 v[30:31], v[46:47], v[30:31] op_sel_hi:[0,1]
	v_fmac_f32_e32 v17, v45, v7
	v_pk_fma_f32 v[8:9], v[8:9], v[18:19], v[30:31] op_sel_hi:[1,0,1]
	v_pk_mul_f32 v[30:31], v[46:47], v[34:35] op_sel_hi:[0,1]
	s_waitcnt lgkmcnt(0)
	v_fmac_f32_e32 v17, v26, v8
	v_fmac_f32_e32 v17, v27, v9
	v_pk_mul_f32 v[26:27], v[46:47], v[32:33] op_sel_hi:[0,1]
	v_pk_fma_f32 v[10:11], v[10:11], v[18:19], v[26:27] op_sel_hi:[1,0,1]
	v_pk_fma_f32 v[12:13], v[12:13], v[18:19], v[30:31] op_sel_hi:[1,0,1]
	v_fmac_f32_e32 v17, v28, v10
	v_fmac_f32_e32 v17, v29, v11
	ds_read_b128 v[26:29], v23 offset:55840
	v_pk_mul_f32 v[30:31], v[46:47], v[38:39] op_sel_hi:[0,1]
	v_pk_fma_f32 v[0:1], v[0:1], v[18:19], v[30:31] op_sel_hi:[1,0,1]
	s_waitcnt lgkmcnt(0)
	v_fmac_f32_e32 v17, v26, v12
	v_fmac_f32_e32 v17, v27, v13
	v_pk_mul_f32 v[26:27], v[46:47], v[36:37] op_sel_hi:[0,1]
	v_pk_fma_f32 v[14:15], v[14:15], v[18:19], v[26:27] op_sel_hi:[1,0,1]
	v_fmac_f32_e32 v17, v28, v14
	v_fmac_f32_e32 v17, v29, v15
	ds_read_b128 v[26:29], v23 offset:55856
	s_waitcnt lgkmcnt(0)
	v_fmac_f32_e32 v17, v26, v0
	v_fmac_f32_e32 v17, v27, v1
	v_pk_mul_f32 v[26:27], v[46:47], v[40:41] op_sel_hi:[0,1]
	v_pk_fma_f32 v[2:3], v[2:3], v[18:19], v[26:27] op_sel_hi:[1,0,1]
	v_fmac_f32_e32 v17, v28, v2
	v_fmac_f32_e32 v17, v29, v3
	ds_bpermute_b32 v18, v22, v17
	s_waitcnt lgkmcnt(0)
	v_add_f32_e32 v17, v17, v18
	ds_bpermute_b32 v18, v24, v17
	s_waitcnt lgkmcnt(0)
	v_add_f32_e32 v17, v17, v18
	ds_bpermute_b32 v18, v25, v17
	s_and_saveexec_b64 s[4:5], vcc
	s_cbranch_execz .LBB0_224
	s_waitcnt lgkmcnt(0)
	v_add_f32_e32 v17, v17, v18
	s_waitcnt vmcnt(0)
	v_fmac_f32_e32 v17, v85, v16
	v_add_u32_e32 v16, 0x14d00, v21
	ds_write_b32 v16, v17
.LBB0_224:
	s_or_b64 exec, exec, s[4:5]
	v_readlane_b32 s3, v253, 11
	s_nop 1
	v_mov_b32_e32 v16, s3
	v_readlane_b32 s3, v253, 12
	ds_read_b32 v44, v16
	ds_read_b32 v26, v21 offset:3584
	v_mov_b32_e32 v16, s3
	ds_read_b32 v16, v16
	s_waitcnt lgkmcnt(0)
	v_mul_f32_e32 v46, v26, v16
	ds_read_b128 v[16:19], v23 offset:23552
	ds_read_b128 v[28:31], v23 offset:23568
	ds_read_b128 v[32:35], v23 offset:23584
	ds_read_b128 v[36:39], v23 offset:23600
	ds_read_b128 v[40:43], v23 offset:56320
	s_waitcnt lgkmcnt(4)
	v_pk_mul_f32 v[16:17], v[46:47], v[16:17] op_sel_hi:[0,1]
	v_pk_fma_f32 v[4:5], v[4:5], v[44:45], v[16:17] op_sel_hi:[1,0,1]
	v_pk_mul_f32 v[16:17], v[46:47], v[18:19] op_sel_hi:[0,1]
	v_pk_fma_f32 v[6:7], v[6:7], v[44:45], v[16:17] op_sel_hi:[1,0,1]
	ds_read_b128 v[16:19], v23 offset:56336
	s_waitcnt lgkmcnt(1)
	v_fma_f32 v27, v40, v4, 0
	v_fmac_f32_e32 v27, v41, v5
	v_fmac_f32_e32 v27, v42, v6
	v_pk_mul_f32 v[28:29], v[46:47], v[28:29] op_sel_hi:[0,1]
	v_fmac_f32_e32 v27, v43, v7
	v_pk_fma_f32 v[8:9], v[8:9], v[44:45], v[28:29] op_sel_hi:[1,0,1]
	v_pk_mul_f32 v[28:29], v[46:47], v[32:33] op_sel_hi:[0,1]
	s_waitcnt lgkmcnt(0)
	v_fmac_f32_e32 v27, v16, v8
	v_fmac_f32_e32 v27, v17, v9
	v_pk_mul_f32 v[16:17], v[46:47], v[30:31] op_sel_hi:[0,1]
	v_pk_fma_f32 v[10:11], v[10:11], v[44:45], v[16:17] op_sel_hi:[1,0,1]
	v_pk_fma_f32 v[12:13], v[12:13], v[44:45], v[28:29] op_sel_hi:[1,0,1]
	v_fmac_f32_e32 v27, v18, v10
	v_fmac_f32_e32 v27, v19, v11
	ds_read_b128 v[16:19], v23 offset:56352
	ds_read_b128 v[28:31], v23 offset:56368
	s_waitcnt lgkmcnt(1)
	v_fmac_f32_e32 v27, v16, v12
	v_fmac_f32_e32 v27, v17, v13
	v_pk_mul_f32 v[16:17], v[46:47], v[34:35] op_sel_hi:[0,1]
	v_pk_fma_f32 v[14:15], v[14:15], v[44:45], v[16:17] op_sel_hi:[1,0,1]
	v_pk_mul_f32 v[16:17], v[46:47], v[36:37] op_sel_hi:[0,1]
	v_fmac_f32_e32 v27, v18, v14
	v_fmac_f32_e32 v27, v19, v15
	v_pk_fma_f32 v[16:17], v[0:1], v[44:45], v[16:17] op_sel_hi:[1,0,1]
	v_pk_mul_f32 v[0:1], v[46:47], v[38:39] op_sel_hi:[0,1]
	s_waitcnt lgkmcnt(0)
	v_fmac_f32_e32 v27, v28, v16
	v_fmac_f32_e32 v27, v29, v17
	v_pk_fma_f32 v[18:19], v[2:3], v[44:45], v[0:1] op_sel_hi:[1,0,1]
	v_fmac_f32_e32 v27, v30, v18
	v_fmac_f32_e32 v27, v31, v19
	ds_bpermute_b32 v0, v22, v27
	s_waitcnt lgkmcnt(0)
	v_add_f32_e32 v0, v27, v0
	ds_bpermute_b32 v1, v24, v0
	s_waitcnt lgkmcnt(0)
	v_add_f32_e32 v0, v0, v1
	ds_bpermute_b32 v1, v25, v0
	s_and_saveexec_b64 s[4:5], vcc
	s_cbranch_execz .LBB0_226
	s_waitcnt lgkmcnt(0)
	v_add_f32_e32 v0, v0, v1
	s_waitcnt vmcnt(0)
	v_fmac_f32_e32 v0, v85, v26
	v_add_u32_e32 v1, 0x14e00, v21
	ds_write_b32 v1, v0

; #define LAS __attribute__((address_space(3)))
; DI unsigned ssd_dt_load(const bf16_t* HIN, size_t rowbase, int hd, int lane) { return (unsigned)HIN[(rowbase + lane) * LDH + C_DT + hd]; }
; DI void ssd_dt_scan(unsigned rawbits, float dtb, float av, int lane, LAS float* cumS, LAS float* dtS) {
;     const float v = __uint_as_float(rawbits << 16) + dtb; const float dt = v > 20.f ? v : log1pf(__expf(v));
; DI void ssd_prompt_unit(const Args& a, int b, int hd, LAS unsigned char* lds, const int tid) {
;     ...
;     if (wave == 7) { ssd_dt_scan(ssd_dt_load(HIN, row0, hd, lane), dtb, av, lane, cumS, dtS); dtraw = ssd_dt_load(HIN, row0 + 64, hd, lane); }
.LBB0_281:
	s_or_b64 exec, exec, s[0:1]
	s_waitcnt vmcnt(2)
	v_mul_f32_e32 v3, 0x3fb8aa3b, v10
	v_exp_f32_e32 v216, v3
	s_cmp_eq_u32 s70, 7
	s_cselect_b64 s[20:21], -1, 0
	v_mov_b32_e32 v217, 0
	s_and_b64 vcc, exec, s[20:21]
	s_cbranch_vccz .LBB0_285
	v_or_b32_e32 v3, s30, v8
	v_mov_b64_e32 v[4:5], s[82:83]
	v_mad_u64_u32 v[4:5], s[0:1], v3, s55, v[4:5]
	v_mov_b32_e32 v3, 0x1a80
	v_mad_i32_i24 v5, s31, v3, v5
	s_lshl_b32 s94, s60, 1
	v_lshl_add_u64 v[4:5], v[4:5], 0, s[94:95]
	v_add_co_u32_e32 v6, vcc, 0x1000, v4
	s_mov_b32 s0, 0x41a00000
	s_nop 0
	v_addc_co_u32_e32 v7, vcc, 0, v5, vcc
	global_load_ushort v3, v[6:7], off offset:2560
	s_waitcnt vmcnt(0)
	v_lshlrev_b32_e32 v3, 16, v3
	v_add_f32_e32 v3, v133, v3
	v_cmp_nlt_f32_e32 vcc, s0, v3
	s_and_saveexec_b64 s[0:1], vcc
	s_cbranch_execz .LBB0_284
	v_mul_f32_e32 v3, 0x3fb8aa3b, v3
	v_exp_f32_e32 v3, v3
	s_mov_b32 s2, 0x3f2aaaab
	v_add_f32_e32 v10, 1.0, v3
	v_frexp_mant_f32_e32 v12, v10
	v_cvt_f64_f32_e32 v[6:7], v10
	v_frexp_exp_i32_f64_e32 v6, v[6:7]
	v_cmp_gt_f32_e32 vcc, s2, v12
	v_add_f32_e32 v11, -1.0, v10
	v_sub_f32_e32 v13, v11, v10
	v_subbrev_co_u32_e32 v16, vcc, 0, v6, vcc
	v_sub_u32_e32 v6, 0, v16
	v_sub_f32_e32 v11, v3, v11
	v_add_f32_e32 v13, 1.0, v13
	v_ldexp_f32 v7, v10, v6
	v_add_f32_e32 v11, v11, v13
	v_add_f32_e32 v10, -1.0, v7
	v_add_f32_e32 v12, 1.0, v7
	v_ldexp_f32 v6, v11, v6
	v_add_f32_e32 v11, 1.0, v10
	v_add_f32_e32 v13, -1.0, v12
	v_sub_f32_e32 v11, v7, v11
	v_sub_f32_e32 v7, v7, v13
	v_add_f32_e32 v11, v6, v11
	v_add_f32_e32 v6, v6, v7
	v_add_f32_e32 v17, v12, v6
	v_rcp_f32_e32 v19, v17
	v_sub_f32_e32 v7, v17, v12
	v_sub_f32_e32 v18, v6, v7
	v_add_f32_e32 v7, v10, v11
	v_mul_f32_e32 v21, v7, v19
	v_sub_f32_e32 v6, v7, v10
	v_mul_f32_e32 v10, v17, v21
	v_fma_f32 v12, v21, v17, -v10
	v_fmac_f32_e32 v12, v21, v18
	v_sub_f32_e32 v20, v11, v6
	v_add_f32_e32 v6, v10, v12
	v_sub_f32_e32 v11, v7, v6
	v_pk_add_f32 v[14:15], v[6:7], v[10:11] neg_lo:[0,1] neg_hi:[0,1]
	v_mov_b32_e32 v13, v6
	v_pk_add_f32 v[6:7], v[14:15], v[12:13] neg_lo:[0,1] neg_hi:[0,1]
	s_mov_b32 s2, 0x3f317218
	v_add_f32_e32 v7, v20, v7
	v_add_f32_e32 v6, v6, v7
	v_add_f32_e32 v7, v11, v6
	v_mul_f32_e32 v20, v19, v7
	v_mul_f32_e32 v10, v17, v20
	v_fma_f32 v12, v20, v17, -v10
	v_fmac_f32_e32 v12, v20, v18
	v_sub_f32_e32 v11, v11, v7
	v_add_f32_e32 v17, v6, v11
	v_add_f32_e32 v6, v10, v12
	v_sub_f32_e32 v11, v7, v6
	v_pk_add_f32 v[14:15], v[6:7], v[10:11] neg_lo:[0,1] neg_hi:[0,1]
	v_mov_b32_e32 v13, v6
	v_pk_add_f32 v[6:7], v[14:15], v[12:13] neg_lo:[0,1] neg_hi:[0,1]
	v_add_f32_e32 v7, v17, v7
	v_add_f32_e32 v6, v6, v7
	v_add_f32_e32 v7, v21, v20
	v_add_f32_e32 v6, v11, v6
	v_sub_f32_e32 v10, v7, v21
	v_mul_f32_e32 v6, v19, v6
	v_sub_f32_e32 v10, v20, v10
	v_add_f32_e32 v10, v10, v6
	v_add_f32_e32 v12, v7, v10
	v_mul_f32_e32 v13, v12, v12
	v_mov_b32_e32 v6, 0x3ecc95a3
	v_fmamk_f32 v6, v13, 0x3e9b6dac, v6
	v_fmaak_f32 v183, v13, v6, 0x3f2aaada
	v_cvt_f32_i32_e32 v6, v16
	v_sub_f32_e32 v7, v12, v7
	v_sub_f32_e32 v7, v10, v7
	v_ldexp_f32 v14, v7, 1
	v_mul_f32_e32 v7, v12, v13
	v_ldexp_f32 v11, v12, 1
	v_pk_mul_f32 v[12:13], v[6:7], v[182:183]
	v_fma_f32 v10, v6, s2, -v12
	v_fmac_f32_e32 v10, 0xb102e308, v6
	v_pk_add_f32 v[6:7], v[12:13], v[10:11]
	s_mov_b32 s2, 0x7f800000
	v_sub_f32_e32 v11, v7, v11
	v_sub_f32_e32 v11, v13, v11
	v_add_f32_e32 v15, v14, v11
	v_mov_b32_e32 v14, v12
	v_pk_add_f32 v[12:13], v[6:7], v[12:13] neg_lo:[0,1] neg_hi:[0,1]
	v_pk_add_f32 v[16:17], v[6:7], v[14:15]
	v_mov_b32_e32 v11, v6
	v_mov_b32_e32 v13, v17
	v_pk_add_f32 v[18:19], v[10:11], v[12:13] neg_lo:[0,1] neg_hi:[0,1]
	v_pk_add_f32 v[10:11], v[10:11], v[12:13]
	v_mov_b32_e32 v14, v15
	v_pk_add_f32 v[12:13], v[10:11], v[6:7] op_sel:[1,0] op_sel_hi:[0,1] neg_lo:[0,1] neg_hi:[0,1]
	v_pk_add_f32 v[20:21], v[16:17], v[12:13] op_sel_hi:[1,0] neg_lo:[0,1] neg_hi:[0,1]
	v_mov_b32_e32 v16, v17
	v_mov_b32_e32 v17, v11
	v_pk_mov_b32 v[12:13], v[6:7], v[12:13] op_sel:[1,0]
	v_mov_b32_e32 v15, v6
	v_pk_add_f32 v[12:13], v[16:17], v[12:13] neg_lo:[0,1] neg_hi:[0,1]
	v_mov_b32_e32 v20, v18
	v_pk_add_f32 v[6:7], v[14:15], v[12:13] neg_lo:[0,1] neg_hi:[0,1]
	v_mov_b32_e32 v19, v11
	v_pk_add_f32 v[12:13], v[20:21], v[6:7]
	v_cmp_neq_f32_e32 vcc, s2, v3
	v_pk_add_f32 v[14:15], v[12:13], v[12:13] op_sel:[0,1] op_sel_hi:[1,0]
	s_mov_b32 s2, 0x33800000
	v_pk_add_f32 v[10:11], v[10:11], v[14:15] op_sel:[1,0] op_sel_hi:[0,1]
	v_mov_b32_e32 v13, v10
	v_pk_add_f32 v[16:17], v[12:13], v[18:19] neg_lo:[0,1] neg_hi:[0,1]
	v_mov_b32_e32 v7, v14
	v_sub_f32_e32 v11, v12, v16
	v_pk_add_f32 v[6:7], v[6:7], v[16:17] neg_lo:[0,1] neg_hi:[0,1]
	v_sub_f32_e32 v11, v18, v11
	v_add_f32_e32 v6, v6, v11
	v_add_f32_e32 v6, v6, v7
	v_add_f32_e32 v6, v10, v6
	v_mov_b32_e32 v7, 0x7f800000
	v_cndmask_b32_e32 v6, v7, v6, vcc
	v_cmp_ngt_f32_e32 vcc, -1.0, v3
	v_mov_b32_e32 v7, 0xff800000
	s_nop 0
	v_cndmask_b32_e32 v6, v206, v6, vcc
	v_cmp_neq_f32_e32 vcc, -1.0, v3
	s_nop 1
	v_cndmask_b32_e32 v6, v7, v6, vcc
	v_cmp_lt_f32_e64 vcc, |v3|, s2
	s_nop 1
	v_cndmask_b32_e32 v3, v6, v3, vcc

; #define LAS __attribute__((address_space(3)))
; DI float lo16(unsigned w) { return __uint_as_float(w << 16); }
; DI float hi16(unsigned w) { return __uint_as_float(w & 0xffff0000u); }
; DI void conv_row8(const u32x4 (&raw)[11], int i, const float (&w)[4][8], const float (&bias)[8], float (&v)[8]) {
; #pragma unroll
;     for (int e = 0; e < 8; ++e) v[e] = bias[e];
; #pragma unroll
;     for (int jj = 0; jj < 4; ++jj) {
; #pragma unroll
;         for (int e = 0; e < 4; ++e) { v[2 * e] += w[jj][2 * e] * lo16(raw[i + jj][e]); v[2 * e + 1] += w[jj][2 * e + 1] * hi16(raw[i + jj][e]); }
;     }
; #pragma unroll
;     for (int e = 0; e < 8; ++e) v[e] = v[e] * __frcp_rn(1.0f + __expf(-v[e]));
; }
; DI void ssd_prompt_unit(const Args& a, int b, int hd, LAS unsigned char* lds, const int tid) {
;     ...
;             const float cum63 = cumC[63];
;             float cwt[4][8], cbias[8];
; #pragma unroll
;             for (int jj = 0; jj < 4; ++jj) { const f32x4 w0 = *(const LAS f32x4*)(cwS + jj * 8), w1 = *(const LAS f32x4*)(cwS + jj * 8 + 4);
; #pragma unroll
;                 for (int e = 0; e < 4; ++e) { cwt[jj][e] = w0[e]; cwt[jj][4 + e] = w1[e]; } }
;             { const f32x4 b0 = *(const LAS f32x4*)(cwS + 32), b1 = *(const LAS f32x4*)(cwS + 36);
; #pragma unroll
;               for (int e = 0; e < 4; ++e) { cbias[e] = b0[e]; cbias[4 + e] = b1[e]; } }
;             const f32x4 cq0 = *(const LAS f32x4*)(cumC + seg * 8), cq1 = *(const LAS f32x4*)(cumC + seg * 8 + 4), dq0 = *(const LAS f32x4*)(dtC + seg * 8), dq1 = *(const LAS f32x4*)(dtC + seg * 8 + 4);
;             const float cqa[8] = {cq0[0], cq0[1], cq0[2], cq0[3], cq1[0], cq1[1], cq1[2], cq1[3]}, dqa[8] = {dq0[0], dq0[1], dq0[2], dq0[3], dq1[0], dq1[1], dq1[2], dq1[3]};
;             const int tn = (c + 1 < 32) ? t0 + 64 : t0;
;             const bf16_t* nsrc = HIN + (row0 + tn + seg * 8 - 3 + 2 * kq) * LDH + C_XBC + ch;
;     ...
; #pragma unroll
;             for (int k = 0; k < 4; ++k) {
;                 const bool act = stager || k == 0;
;                 float va[8], vb[8];
;                 if (act) { conv_row8(raw, 2 * k, cwt, cbias, va); conv_row8(raw, 2 * k + 1, cwt, cbias, vb); }
;                 raw[2 * k] = *(const u32x4*)(nsrc + SP_ROWOFF(2 * k)); raw[2 * k + 1] = *(const u32x4*)(nsrc + SP_ROWOFF(2 * k + 1));
.LBB0_286:
	s_and_b32 s58, s1, 1
	s_lshl_b32 s5, s58, 8
	s_add_i32 s66, s5, 0
	s_add_i32 s57, s66, 0x1c000
	s_add_i32 s66, s66, 0x1c200
	s_cmp_lg_u32 s92, 0x5d0000
	s_cselect_b64 s[12:13], -1, 0
	v_mov_b32_e32 v32, s57
	s_and_b64 s[14:15], s[12:13], exec
	ds_read_b32 v160, v32 offset:252
	ds_read_b128 v[100:103], v215
	ds_read_b128 v[44:47], v215 offset:16
	ds_read_b128 v[104:107], v215 offset:32
	ds_read_b128 v[48:51], v215 offset:48
	ds_read_b128 v[108:111], v215 offset:64
	ds_read_b128 v[52:55], v215 offset:80
	ds_read_b128 v[60:63], v215 offset:96
	ds_read_b128 v[40:43], v215 offset:112
	ds_read_b128 v[112:115], v215 offset:128
	ds_read_b128 v[56:59], v215 offset:144
	s_cselect_b32 s14, s62, 0x7c0
	s_mov_b32 s15, s95
	v_lshl_add_u64 v[144:145], v[136:137], 0, s[14:15]
	v_mad_u64_u32 v[142:143], s[14:15], v144, s55, v[138:139]
	v_mad_i32_i24 v143, v145, s55, v143
	s_waitcnt vmcnt(0)
	v_lshlrev_b32_e32 v144, 16, v72
	v_and_b32_e32 v145, 0xffff0000, v72
	v_lshlrev_b32_e32 v148, 16, v73
	v_and_b32_e32 v149, 0xffff0000, v73
	v_lshlrev_b32_e32 v146, 16, v76
	v_and_b32_e32 v147, 0xffff0000, v76
	v_lshlrev_b32_e32 v150, 16, v77
	v_and_b32_e32 v151, 0xffff0000, v77
	v_lshlrev_b32_e32 v76, 16, v78
	v_and_b32_e32 v77, 0xffff0000, v78
	v_lshlrev_b32_e32 v72, 16, v79
	v_and_b32_e32 v73, 0xffff0000, v79
	s_waitcnt lgkmcnt(1)
	v_pk_fma_f32 v[78:79], v[100:101], v[144:145], v[112:113]
	v_lshlrev_b32_e32 v190, 16, v92
	v_and_b32_e32 v191, 0xffff0000, v92
	v_pk_fma_f32 v[78:79], v[104:105], v[146:147], v[78:79]
	v_lshlrev_b32_e32 v186, 16, v96
	v_and_b32_e32 v187, 0xffff0000, v96
	v_pk_fma_f32 v[78:79], v[108:109], v[190:191], v[78:79]
	v_lshlrev_b32_e32 v174, 16, v93
	v_pk_fma_f32 v[78:79], v[60:61], v[186:187], v[78:79]
	v_and_b32_e32 v175, 0xffff0000, v93
	v_lshlrev_b32_e32 v170, 16, v97
	v_and_b32_e32 v171, 0xffff0000, v97
	v_lshlrev_b32_e32 v96, 16, v98
	v_and_b32_e32 v97, 0xffff0000, v98
	v_lshlrev_b32_e32 v92, 16, v99
	v_and_b32_e32 v93, 0xffff0000, v99
	v_mul_f32_e32 v98, 0xbfb8aa3b, v78
	v_mul_f32_e32 v99, 0xbfb8aa3b, v79
	v_exp_f32_e32 v98, v98
	v_exp_f32_e32 v99, v99
	v_lshlrev_b32_e32 v152, 16, v122
	v_and_b32_e32 v153, 0xffff0000, v122
	v_lshlrev_b32_e32 v156, 16, v120
	v_pk_add_f32 v[98:99], v[98:99], 1.0 op_sel_hi:[1,0]
	v_and_b32_e32 v157, 0xffff0000, v120
	v_lshlrev_b32_e32 v154, 16, v121
	v_and_b32_e32 v155, 0xffff0000, v121
	v_lshlrev_b32_e32 v120, 16, v123
	v_and_b32_e32 v121, 0xffff0000, v123
	v_lshlrev_b32_e32 v158, 16, v74
	v_and_b32_e32 v159, 0xffff0000, v74
	v_lshlrev_b32_e32 v168, 16, v94
	v_rcp_f32_e32 v99, v99
	v_and_b32_e32 v169, 0xffff0000, v94
	v_lshlrev_b32_e32 v74, 16, v75
	v_and_b32_e32 v75, 0xffff0000, v75
	v_rcp_f32_e32 v98, v98
	s_nop 0
	v_pk_mul_f32 v[144:145], v[78:79], v[98:99]
	v_pk_fma_f32 v[78:79], v[100:101], v[146:147], v[112:113]
	s_waitcnt lgkmcnt(0)
	v_pk_fma_f32 v[74:75], v[46:47], v[74:75], v[58:59]
	v_pk_fma_f32 v[78:79], v[104:105], v[190:191], v[78:79]
	v_lshlrev_b32_e32 v94, 16, v95
	v_pk_fma_f32 v[78:79], v[108:109], v[186:187], v[78:79]
	v_and_b32_e32 v95, 0xffff0000, v95
	v_pk_fma_f32 v[78:79], v[60:61], v[156:157], v[78:79]
	v_pk_fma_f32 v[74:75], v[50:51], v[72:73], v[74:75]
	v_mul_f32_e32 v98, 0xbfb8aa3b, v78
	v_mul_f32_e32 v99, 0xbfb8aa3b, v79
	v_exp_f32_e32 v98, v98
	v_exp_f32_e32 v99, v99
	v_pk_fma_f32 v[74:75], v[54:55], v[94:95], v[74:75]
	v_pk_fma_f32 v[72:73], v[46:47], v[72:73], v[58:59]
	v_pk_fma_f32 v[74:75], v[42:43], v[92:93], v[74:75]
	v_pk_add_f32 v[98:99], v[98:99], 1.0 op_sel_hi:[1,0]
	v_pk_fma_f32 v[72:73], v[50:51], v[94:95], v[72:73]
	v_pk_fma_f32 v[72:73], v[54:55], v[92:93], v[72:73]
	v_lshlrev_b32_e32 v32, 2, v134
	v_pk_fma_f32 v[72:73], v[42:43], v[120:121], v[72:73]
	v_rcp_f32_e32 v99, v99
	v_add_u32_e32 v162, s57, v32
	v_add_u32_e32 v32, s66, v32
	ds_read_b128 v[128:131], v162
	ds_read_b128 v[36:39], v162 offset:16
	v_rcp_f32_e32 v98, v98
	s_nop 0
	v_pk_mul_f32 v[146:147], v[78:79], v[98:99]
	v_pk_fma_f32 v[78:79], v[102:103], v[148:149], v[114:115]
	ds_read_b128 v[124:127], v32
	ds_read_b128 v[32:35], v32 offset:16
	v_pk_fma_f32 v[78:79], v[106:107], v[150:151], v[78:79]
	s_cmp_lt_i32 s67, 1
	v_pk_fma_f32 v[78:79], v[110:111], v[174:175], v[78:79]
	v_pk_fma_f32 v[78:79], v[62:63], v[170:171], v[78:79]
	v_mul_f32_e32 v98, 0xbfb8aa3b, v78
	v_mul_f32_e32 v99, 0xbfb8aa3b, v79
	v_exp_f32_e32 v98, v98
	v_exp_f32_e32 v99, v99
	s_nop 0
	v_pk_add_f32 v[98:99], v[98:99], 1.0 op_sel_hi:[1,0]
	v_rcp_f32_e32 v99, v99
	v_rcp_f32_e32 v98, v98
	s_nop 0
	v_pk_mul_f32 v[148:149], v[78:79], v[98:99]
	v_pk_fma_f32 v[78:79], v[102:103], v[150:151], v[114:115]
	v_pk_fma_f32 v[78:79], v[106:107], v[174:175], v[78:79]
	v_pk_fma_f32 v[78:79], v[110:111], v[170:171], v[78:79]
	v_pk_fma_f32 v[78:79], v[62:63], v[154:155], v[78:79]
	v_mul_f32_e32 v98, 0xbfb8aa3b, v78
	v_mul_f32_e32 v99, 0xbfb8aa3b, v79
	v_exp_f32_e32 v98, v98
	v_exp_f32_e32 v99, v99
	s_nop 0
	v_pk_add_f32 v[98:99], v[98:99], 1.0 op_sel_hi:[1,0]
	v_rcp_f32_e32 v99, v99
	v_rcp_f32_e32 v98, v98
	s_nop 0
	v_pk_mul_f32 v[150:151], v[78:79], v[98:99]
	v_pk_fma_f32 v[78:79], v[44:45], v[158:159], v[56:57]
	v_pk_fma_f32 v[78:79], v[48:49], v[76:77], v[78:79]
	v_pk_fma_f32 v[76:77], v[44:45], v[76:77], v[56:57]
	v_pk_fma_f32 v[78:79], v[52:53], v[168:169], v[78:79]
	v_pk_fma_f32 v[76:77], v[48:49], v[168:169], v[76:77]
	v_pk_fma_f32 v[78:79], v[40:41], v[96:97], v[78:79]
	v_pk_fma_f32 v[76:77], v[52:53], v[96:97], v[76:77]
	v_mul_f32_e32 v98, 0xbfb8aa3b, v78
	v_mul_f32_e32 v99, 0xbfb8aa3b, v79
	v_exp_f32_e32 v98, v98
	v_exp_f32_e32 v99, v99
	v_pk_fma_f32 v[76:77], v[40:41], v[152:153], v[76:77]
	v_pk_add_f32 v[98:99], v[98:99], 1.0 op_sel_hi:[1,0]
	v_rcp_f32_e32 v99, v99
	v_rcp_f32_e32 v98, v98
	s_nop 0
	v_pk_mul_f32 v[158:159], v[78:79], v[98:99]
	v_mul_f32_e32 v78, 0xbfb8aa3b, v76
	v_mul_f32_e32 v79, 0xbfb8aa3b, v77
	v_exp_f32_e32 v78, v78
	v_exp_f32_e32 v79, v79
	s_nop 0
	v_pk_add_f32 v[78:79], v[78:79], 1.0 op_sel_hi:[1,0]
	v_rcp_f32_e32 v79, v79
	v_rcp_f32_e32 v78, v78
	s_nop 0
	v_pk_mul_f32 v[166:167], v[76:77], v[78:79]
	v_mul_f32_e32 v76, 0xbfb8aa3b, v74
	v_mul_f32_e32 v77, 0xbfb8aa3b, v75
	v_exp_f32_e32 v76, v76
	v_exp_f32_e32 v77, v77
	s_nop 0
	v_pk_add_f32 v[76:77], v[76:77], 1.0 op_sel_hi:[1,0]
	v_rcp_f32_e32 v77, v77
	v_rcp_f32_e32 v76, v76
	s_nop 0
	v_pk_mul_f32 v[184:185], v[74:75], v[76:77]
	v_mul_f32_e32 v74, 0xbfb8aa3b, v72
	v_mul_f32_e32 v75, 0xbfb8aa3b, v73
	v_exp_f32_e32 v74, v74
	v_exp_f32_e32 v75, v75
	s_nop 0
	v_pk_add_f32 v[74:75], v[74:75], 1.0 op_sel_hi:[1,0]
	v_rcp_f32_e32 v75, v75
	s_mov_b64 s[14:15], -1
	v_rcp_f32_e32 v74, v74
	v_add_co_u32_e32 v76, vcc, 0x2000, v142
	v_pk_mul_f32 v[194:195], v[72:73], v[74:75]
	s_nop 0
	v_addc_co_u32_e32 v77, vcc, 0, v143, vcc
	global_load_dwordx4 v[72:75], v[142:143], off offset:3584
	s_nop 0
	global_load_dwordx4 v[76:79], v[76:77], off offset:2176
	s_cbranch_scc1 .LBB0_295
; #define LAS __attribute__((address_space(3)))
; DI unsigned pk2(float lo, float hi) { const f32x2_t v = {lo, hi}; const bf16x2_t b = __builtin_convertvector(v, bf16x2_t); return __builtin_bit_cast(unsigned, b); }
; DI void ssd_prompt_unit(const Args& a, int b, int hd, LAS unsigned char* lds, const int tid) {
;     ...
;                 const int ta = seg * 8 + 2 * (stager ? k : kq), tb = ta + 1;
;                 if (act) {
;                 if (typ == 0) {
; #pragma unroll
;                     for (int e = 0; e < 8; ++e) *(LAS unsigned*)(Xt + (cg * 8 + e) * SP_LDT + ta) = pk2(va[e], vb[e]);
;                 } else if (typ == 1) {
;                     const int nb = (cg - 8) * 8;
;                     u32x4 wa, wb;
; #pragma unroll
;                     for (int e = 0; e < 4; ++e) { wa[e] = pk2(va[2 * e], va[2 * e + 1]); wb[e] = pk2(vb[2 * e], vb[2 * e + 1]); }
;                     *(LAS u32x4*)(Bs + ta * SP_LDC + nb) = wa; *(LAS u32x4*)(Bs + tb * SP_LDC + nb) = wb;
;                     const float wsa = __expf(cum63 - cqa[2 * k]) * dqa[2 * k], wsb = __expf(cum63 - cqa[2 * k + 1]) * dqa[2 * k + 1];
; #pragma unroll
;                     for (int e = 0; e < 8; ++e) *(LAS unsigned*)(Bwt + (nb + e) * SP_LDT + ta) = pk2(va[e] * wsa, vb[e] * wsb);
;                 } else {
;                     const int nb = (cg - 24) * 8;
;                     float ca, cb2; if (stager) { ca = cqa[2 * k]; cb2 = cqa[2 * k + 1]; } else { ca = cumC[ta]; cb2 = cumC[tb]; }
;                     const float ea = __expf(ca), eb = __expf(cb2);
	s_cmp_lg_u32 s67, 1
	s_cbranch_scc0 .LBB0_292
	s_andn2_b64 vcc, exec, s[22:23]
	s_cbranch_vccnz .LBB0_290
	v_lshl_add_u32 v98, s64, 2, v162
	ds_read_b64 v[98:99], v98
	s_branch .LBB0_291

; #define LAS __attribute__((address_space(3)))
; DI unsigned pk2(float lo, float hi) { const f32x2_t v = {lo, hi}; const bf16x2_t b = __builtin_convertvector(v, bf16x2_t); return __builtin_bit_cast(unsigned, b); }
; DI void ssd_prompt_unit(const Args& a, int b, int hd, LAS unsigned char* lds, const int tid) {
;     ...
;                     const int nb = (cg - 8) * 8;
;                     u32x4 wa, wb;
; #pragma unroll
;                     for (int e = 0; e < 4; ++e) { wa[e] = pk2(va[2 * e], va[2 * e + 1]); wb[e] = pk2(vb[2 * e], vb[2 * e + 1]); }
;                     *(LAS u32x4*)(Bs + ta * SP_LDC + nb) = wa; *(LAS u32x4*)(Bs + tb * SP_LDC + nb) = wb;
;                     const float wsa = __expf(cum63 - cqa[2 * k]) * dqa[2 * k], wsb = __expf(cum63 - cqa[2 * k + 1]) * dqa[2 * k + 1];
; #pragma unroll
;                     for (int e = 0; e < 8; ++e) *(LAS unsigned*)(Bwt + (nb + e) * SP_LDT + ta) = pk2(va[e] * wsa, vb[e] * wsb);
.LBB0_292:
	s_and_b64 vcc, exec, s[14:15]
	s_cbranch_vccz .LBB0_294
	v_cvt_pk_bf16_f32 v162, v144, v145
	v_cvt_pk_bf16_f32 v163, v148, v149
	v_cvt_pk_bf16_f32 v164, v158, v159
	v_cvt_pk_bf16_f32 v165, v184, v185
	v_add_u32_e32 v98, v218, v221
	v_cvt_pk_bf16_f32 v208, v146, v147
	v_cvt_pk_bf16_f32 v209, v150, v151
	v_cvt_pk_bf16_f32 v210, v166, v167
	v_cvt_pk_bf16_f32 v211, v194, v195
	ds_write_b128 v98, v[162:165] offset:34688
	ds_write_b128 v98, v[208:211] offset:34960
	s_waitcnt lgkmcnt(5)
	v_sub_f32_e32 v98, v160, v128
	v_sub_f32_e32 v99, v160, v129
	v_mul_f32_e32 v98, 0x3fb8aa3b, v98
	v_mul_f32_e32 v99, 0x3fb8aa3b, v99
	v_exp_f32_e32 v98, v98
	v_exp_f32_e32 v99, v99
	v_mov_b32_e32 v122, v144
	v_mov_b32_e32 v123, v146
	s_waitcnt lgkmcnt(3)
	v_pk_mul_f32 v[98:99], v[124:125], v[98:99]
	v_pk_mul_f32 v[122:123], v[98:99], v[122:123]
	v_add_u32_e32 v125, v222, v223
	v_cvt_pk_bf16_f32 v122, v122, v123
	v_add_u32_e32 v123, v222, v224
	ds_write_b32 v123, v122 offset:52224
	v_mov_b32_e32 v122, v145
	v_mov_b32_e32 v123, v147
	v_pk_mul_f32 v[122:123], v[98:99], v[122:123]
	v_add_u32_e32 v128, 0xa800, v125
	v_cvt_pk_bf16_f32 v124, v122, v123
	v_mov_b32_e32 v122, v148
	v_mov_b32_e32 v123, v150
	v_pk_mul_f32 v[122:123], v[98:99], v[122:123]
	v_cvt_pk_bf16_f32 v122, v122, v123
	ds_write2_b32 v128, v124, v122 offset0:36 offset1:72
	v_mov_b32_e32 v122, v149
	v_mov_b32_e32 v123, v151
	v_pk_mul_f32 v[122:123], v[98:99], v[122:123]
	v_cvt_pk_bf16_f32 v124, v122, v123
	v_mov_b32_e32 v122, v158
	v_mov_b32_e32 v123, v166
	v_pk_mul_f32 v[122:123], v[98:99], v[122:123]
	v_cvt_pk_bf16_f32 v122, v122, v123
	ds_write2_b32 v128, v124, v122 offset0:108 offset1:144
	v_mov_b32_e32 v122, v159
	v_mov_b32_e32 v123, v167
	v_pk_mul_f32 v[122:123], v[98:99], v[122:123]
	v_cvt_pk_bf16_f32 v124, v122, v123
	v_mov_b32_e32 v122, v184
	v_mov_b32_e32 v123, v194
	v_pk_mul_f32 v[122:123], v[98:99], v[122:123]
	v_cvt_pk_bf16_f32 v122, v122, v123
	ds_write2_b32 v128, v124, v122 offset0:180 offset1:216
	v_mov_b32_e32 v122, v185
	v_mov_b32_e32 v123, v195
	v_pk_mul_f32 v[98:99], v[98:99], v[122:123]
	v_cvt_pk_bf16_f32 v98, v98, v99
	ds_write_b32 v125, v98 offset:44016

; DI float lo16(unsigned w) { return __uint_as_float(w << 16); }
; DI float hi16(unsigned w) { return __uint_as_float(w & 0xffff0000u); }
; DI void conv_row8(const u32x4 (&raw)[11], int i, const float (&w)[4][8], const float (&bias)[8], float (&v)[8]) {
; #pragma unroll
;     for (int e = 0; e < 8; ++e) v[e] = bias[e];
; #pragma unroll
;     for (int jj = 0; jj < 4; ++jj) {
; #pragma unroll
;         for (int e = 0; e < 4; ++e) { v[2 * e] += w[jj][2 * e] * lo16(raw[i + jj][e]); v[2 * e + 1] += w[jj][2 * e + 1] * hi16(raw[i + jj][e]); }
;     }
; #pragma unroll
;     for (int e = 0; e < 8; ++e) v[e] = v[e] * __frcp_rn(1.0f + __expf(-v[e]));
; }
; DI void ssd_prompt_unit(const Args& a, int b, int hd, LAS unsigned char* lds, const int tid) {
;     ...
;             for (int k = 0; k < 4; ++k) {
;                 const bool act = stager || k == 0;
;                 float va[8], vb[8];
;                 if (act) { conv_row8(raw, 2 * k, cwt, cbias, va); conv_row8(raw, 2 * k + 1, cwt, cbias, vb); }
.LBB0_297:
	v_cndmask_b32_e64 v98, 0, 1, s[26:27]
	v_cmp_ne_u32_e64 s[52:53], 1, v98
	s_andn2_b64 vcc, exec, s[26:27]
	v_lshlrev_b32_e32 v192, 16, v80
	v_and_b32_e32 v193, 0xffff0000, v80
	v_lshlrev_b32_e32 v164, 16, v116
	v_and_b32_e32 v165, 0xffff0000, v116
	v_lshlrev_b32_e32 v188, 16, v81
	v_and_b32_e32 v189, 0xffff0000, v81
	v_lshlrev_b32_e32 v162, 16, v117
	v_and_b32_e32 v163, 0xffff0000, v117
	v_lshlrev_b32_e32 v172, 16, v82
	v_and_b32_e32 v173, 0xffff0000, v82
	s_waitcnt lgkmcnt(3)
	v_lshlrev_b32_e32 v128, 16, v118
	v_and_b32_e32 v129, 0xffff0000, v118
	v_lshlrev_b32_e32 v122, 16, v83
	v_and_b32_e32 v123, 0xffff0000, v83
	s_waitcnt lgkmcnt(1)
	v_lshlrev_b32_e32 v124, 16, v119
	v_and_b32_e32 v125, 0xffff0000, v119
	s_cbranch_vccnz .LBB0_299
	v_pk_fma_f32 v[80:81], v[100:101], v[190:191], v[112:113]
	v_pk_fma_f32 v[80:81], v[104:105], v[186:187], v[80:81]
	v_pk_fma_f32 v[80:81], v[108:109], v[156:157], v[80:81]
	v_pk_fma_f32 v[80:81], v[60:61], v[192:193], v[80:81]
	v_mul_f32_e32 v82, 0xbfb8aa3b, v80
	v_mul_f32_e32 v83, 0xbfb8aa3b, v81
	v_exp_f32_e32 v82, v82
	v_exp_f32_e32 v83, v83
	s_nop 0
	v_pk_add_f32 v[82:83], v[82:83], 1.0 op_sel_hi:[1,0]
	v_rcp_f32_e32 v83, v83
	v_rcp_f32_e32 v82, v82
	s_nop 0
	v_pk_mul_f32 v[144:145], v[80:81], v[82:83]
	v_pk_fma_f32 v[80:81], v[100:101], v[186:187], v[112:113]
	v_pk_fma_f32 v[80:81], v[104:105], v[156:157], v[80:81]
	v_pk_fma_f32 v[80:81], v[108:109], v[192:193], v[80:81]
	v_pk_fma_f32 v[80:81], v[60:61], v[164:165], v[80:81]
	v_mul_f32_e32 v82, 0xbfb8aa3b, v80
	v_mul_f32_e32 v83, 0xbfb8aa3b, v81
	v_exp_f32_e32 v82, v82
	v_exp_f32_e32 v83, v83
	s_nop 0
	v_pk_add_f32 v[82:83], v[82:83], 1.0 op_sel_hi:[1,0]
	v_rcp_f32_e32 v83, v83
	v_rcp_f32_e32 v82, v82
	s_nop 0
	v_pk_mul_f32 v[146:147], v[80:81], v[82:83]
	v_pk_fma_f32 v[80:81], v[102:103], v[174:175], v[114:115]
	v_pk_fma_f32 v[80:81], v[106:107], v[170:171], v[80:81]
	v_pk_fma_f32 v[80:81], v[110:111], v[154:155], v[80:81]
	v_pk_fma_f32 v[80:81], v[62:63], v[188:189], v[80:81]
	v_mul_f32_e32 v82, 0xbfb8aa3b, v80
	v_mul_f32_e32 v83, 0xbfb8aa3b, v81
	v_exp_f32_e32 v82, v82
	v_exp_f32_e32 v83, v83
	s_nop 0
	v_pk_add_f32 v[82:83], v[82:83], 1.0 op_sel_hi:[1,0]
	v_rcp_f32_e32 v83, v83
	v_rcp_f32_e32 v82, v82
	s_nop 0
	v_pk_mul_f32 v[148:149], v[80:81], v[82:83]
	v_pk_fma_f32 v[80:81], v[102:103], v[170:171], v[114:115]
	v_pk_fma_f32 v[80:81], v[106:107], v[154:155], v[80:81]
	v_pk_fma_f32 v[80:81], v[110:111], v[188:189], v[80:81]
	v_pk_fma_f32 v[80:81], v[62:63], v[162:163], v[80:81]
	v_mul_f32_e32 v82, 0xbfb8aa3b, v80
	v_mul_f32_e32 v83, 0xbfb8aa3b, v81
	v_exp_f32_e32 v82, v82
	v_exp_f32_e32 v83, v83
	s_nop 0
	v_pk_add_f32 v[82:83], v[82:83], 1.0 op_sel_hi:[1,0]
	v_rcp_f32_e32 v83, v83
	v_rcp_f32_e32 v82, v82
	s_nop 0
	v_pk_mul_f32 v[150:151], v[80:81], v[82:83]
	v_pk_fma_f32 v[80:81], v[44:45], v[168:169], v[56:57]
	v_pk_fma_f32 v[80:81], v[48:49], v[96:97], v[80:81]
	v_pk_fma_f32 v[80:81], v[52:53], v[152:153], v[80:81]
	v_pk_fma_f32 v[80:81], v[40:41], v[172:173], v[80:81]
	v_mul_f32_e32 v82, 0xbfb8aa3b, v80
	v_mul_f32_e32 v83, 0xbfb8aa3b, v81
	v_exp_f32_e32 v82, v82
	v_exp_f32_e32 v83, v83
	s_nop 0
	v_pk_add_f32 v[82:83], v[82:83], 1.0 op_sel_hi:[1,0]
	v_rcp_f32_e32 v83, v83
	v_rcp_f32_e32 v82, v82
	s_nop 0
	v_pk_mul_f32 v[158:159], v[80:81], v[82:83]
	v_pk_fma_f32 v[80:81], v[44:45], v[96:97], v[56:57]
	v_pk_fma_f32 v[80:81], v[48:49], v[152:153], v[80:81]
	v_pk_fma_f32 v[80:81], v[52:53], v[172:173], v[80:81]
	v_pk_fma_f32 v[80:81], v[40:41], v[128:129], v[80:81]
	v_mul_f32_e32 v82, 0xbfb8aa3b, v80
	v_mul_f32_e32 v83, 0xbfb8aa3b, v81
	v_exp_f32_e32 v82, v82
	v_exp_f32_e32 v83, v83
	s_nop 0
	v_pk_add_f32 v[82:83], v[82:83], 1.0 op_sel_hi:[1,0]
	v_rcp_f32_e32 v83, v83
	v_rcp_f32_e32 v82, v82
	s_nop 0
	v_pk_mul_f32 v[166:167], v[80:81], v[82:83]
	v_pk_fma_f32 v[80:81], v[46:47], v[94:95], v[58:59]
	v_pk_fma_f32 v[80:81], v[50:51], v[92:93], v[80:81]
	v_pk_fma_f32 v[80:81], v[54:55], v[120:121], v[80:81]
	v_pk_fma_f32 v[80:81], v[42:43], v[122:123], v[80:81]
	v_mul_f32_e32 v82, 0xbfb8aa3b, v80
	v_mul_f32_e32 v83, 0xbfb8aa3b, v81
	v_exp_f32_e32 v82, v82
	v_exp_f32_e32 v83, v83
	s_nop 0
	v_pk_add_f32 v[82:83], v[82:83], 1.0 op_sel_hi:[1,0]
	v_rcp_f32_e32 v83, v83
	v_rcp_f32_e32 v82, v82
	s_nop 0
	v_pk_mul_f32 v[184:185], v[80:81], v[82:83]
	v_pk_fma_f32 v[80:81], v[46:47], v[92:93], v[58:59]
	v_pk_fma_f32 v[80:81], v[50:51], v[120:121], v[80:81]
	v_pk_fma_f32 v[80:81], v[54:55], v[122:123], v[80:81]
	v_pk_fma_f32 v[80:81], v[42:43], v[124:125], v[80:81]
	v_mul_f32_e32 v82, 0xbfb8aa3b, v80
	v_mul_f32_e32 v83, 0xbfb8aa3b, v81
	v_exp_f32_e32 v82, v82
	v_exp_f32_e32 v83, v83
	s_nop 0
	v_pk_add_f32 v[82:83], v[82:83], 1.0 op_sel_hi:[1,0]
	v_rcp_f32_e32 v83, v83
	v_rcp_f32_e32 v82, v82
	s_nop 0
	v_pk_mul_f32 v[194:195], v[80:81], v[82:83]

; #define LAS __attribute__((address_space(3)))
; DI unsigned pk2(float lo, float hi) { const f32x2_t v = {lo, hi}; const bf16x2_t b = __builtin_convertvector(v, bf16x2_t); return __builtin_bit_cast(unsigned, b); }
; DI void ssd_prompt_unit(const Args& a, int b, int hd, LAS unsigned char* lds, const int tid) {
;     ...
;                     const int nb = (cg - 8) * 8;
;                     u32x4 wa, wb;
; #pragma unroll
;                     for (int e = 0; e < 4; ++e) { wa[e] = pk2(va[2 * e], va[2 * e + 1]); wb[e] = pk2(vb[2 * e], vb[2 * e + 1]); }
;                     *(LAS u32x4*)(Bs + ta * SP_LDC + nb) = wa; *(LAS u32x4*)(Bs + tb * SP_LDC + nb) = wb;
;                     const float wsa = __expf(cum63 - cqa[2 * k]) * dqa[2 * k], wsb = __expf(cum63 - cqa[2 * k + 1]) * dqa[2 * k + 1];
; #pragma unroll
;                     for (int e = 0; e < 8; ++e) *(LAS unsigned*)(Bwt + (nb + e) * SP_LDT + ta) = pk2(va[e] * wsa, vb[e] * wsb);
.LBB0_303:
	s_andn2_b64 vcc, exec, s[14:15]
	s_cbranch_vccnz .LBB0_305
	ds_write_b128 v168, v[116:119] offset:34688
	ds_write_b128 v168, v[80:83] offset:34960
	v_sub_f32_e32 v80, v160, v130
	v_sub_f32_e32 v81, v160, v131
	v_mul_f32_e32 v80, 0x3fb8aa3b, v80
	v_mul_f32_e32 v81, 0x3fb8aa3b, v81
	v_exp_f32_e32 v80, v80
	v_exp_f32_e32 v81, v81
	v_mov_b32_e32 v82, v144
	v_mov_b32_e32 v83, v146
	v_add_u32_e32 v117, v227, v223
	v_pk_mul_f32 v[80:81], v[126:127], v[80:81]
	v_add_u32_e32 v118, 0xa800, v117
	v_pk_mul_f32 v[82:83], v[80:81], v[82:83]
	v_cvt_pk_bf16_f32 v82, v82, v83
	v_add_u32_e32 v83, v227, v224
	ds_write_b32 v83, v82 offset:52224
	v_mov_b32_e32 v82, v145
	v_mov_b32_e32 v83, v147
	v_pk_mul_f32 v[82:83], v[80:81], v[82:83]
	v_cvt_pk_bf16_f32 v116, v82, v83
	v_mov_b32_e32 v82, v148
	v_mov_b32_e32 v83, v150
	v_pk_mul_f32 v[82:83], v[80:81], v[82:83]
	v_cvt_pk_bf16_f32 v82, v82, v83
	ds_write2_b32 v118, v116, v82 offset0:36 offset1:72
	v_mov_b32_e32 v82, v149
	v_mov_b32_e32 v83, v151
	v_pk_mul_f32 v[82:83], v[80:81], v[82:83]
	v_cvt_pk_bf16_f32 v116, v82, v83
	v_mov_b32_e32 v82, v158
	v_mov_b32_e32 v83, v166
	v_pk_mul_f32 v[82:83], v[80:81], v[82:83]
	v_cvt_pk_bf16_f32 v82, v82, v83
	ds_write2_b32 v118, v116, v82 offset0:108 offset1:144
	v_mov_b32_e32 v82, v159
	v_mov_b32_e32 v83, v167
	v_pk_mul_f32 v[82:83], v[80:81], v[82:83]
	v_cvt_pk_bf16_f32 v116, v82, v83
	v_mov_b32_e32 v82, v184
	v_mov_b32_e32 v83, v194
	v_pk_mul_f32 v[82:83], v[80:81], v[82:83]
	v_cvt_pk_bf16_f32 v82, v82, v83
	ds_write2_b32 v118, v116, v82 offset0:180 offset1:216
	v_mov_b32_e32 v82, v185
	v_mov_b32_e32 v83, v195
	v_pk_mul_f32 v[80:81], v[80:81], v[82:83]
	v_cvt_pk_bf16_f32 v80, v80, v81
	ds_write_b32 v117, v80 offset:44016

; DI float lo16(unsigned w) { return __uint_as_float(w << 16); }
; DI float hi16(unsigned w) { return __uint_as_float(w & 0xffff0000u); }
; DI void conv_row8(const u32x4 (&raw)[11], int i, const float (&w)[4][8], const float (&bias)[8], float (&v)[8]) {
; #pragma unroll
;     for (int e = 0; e < 8; ++e) v[e] = bias[e];
; #pragma unroll
;     for (int jj = 0; jj < 4; ++jj) {
; #pragma unroll
;         for (int e = 0; e < 4; ++e) { v[2 * e] += w[jj][2 * e] * lo16(raw[i + jj][e]); v[2 * e + 1] += w[jj][2 * e + 1] * hi16(raw[i + jj][e]); }
;     }
; #pragma unroll
;     for (int e = 0; e < 8; ++e) v[e] = v[e] * __frcp_rn(1.0f + __expf(-v[e]));
; }
; DI void ssd_prompt_unit(const Args& a, int b, int hd, LAS unsigned char* lds, const int tid) {
;     ...
;             for (int k = 0; k < 4; ++k) {
;                 const bool act = stager || k == 0;
;                 float va[8], vb[8];
;                 if (act) { conv_row8(raw, 2 * k, cwt, cbias, va); conv_row8(raw, 2 * k + 1, cwt, cbias, vb); }
.LBB0_308:
	s_and_b64 vcc, exec, s[52:53]
	v_lshlrev_b32_e32 v174, 16, v84
	v_and_b32_e32 v175, 0xffff0000, v84
	v_lshlrev_b32_e32 v186, 16, v88
	v_and_b32_e32 v187, 0xffff0000, v88
	v_lshlrev_b32_e32 v168, 16, v85
	v_and_b32_e32 v169, 0xffff0000, v85
	v_lshlrev_b32_e32 v170, 16, v89
	v_and_b32_e32 v171, 0xffff0000, v89
	v_lshlrev_b32_e32 v126, 16, v86
	v_and_b32_e32 v127, 0xffff0000, v86
	v_lshlrev_b32_e32 v130, 16, v90
	v_and_b32_e32 v131, 0xffff0000, v90
	v_lshlrev_b32_e32 v116, 16, v87
	v_and_b32_e32 v117, 0xffff0000, v87
	v_lshlrev_b32_e32 v118, 16, v91
	v_and_b32_e32 v119, 0xffff0000, v91
	s_cbranch_vccnz .LBB0_310
	v_pk_fma_f32 v[80:81], v[100:101], v[156:157], v[112:113]
	v_pk_fma_f32 v[80:81], v[104:105], v[192:193], v[80:81]
	v_pk_fma_f32 v[80:81], v[108:109], v[164:165], v[80:81]
	v_pk_fma_f32 v[80:81], v[60:61], v[174:175], v[80:81]
	v_mul_f32_e32 v82, 0xbfb8aa3b, v80
	v_mul_f32_e32 v83, 0xbfb8aa3b, v81
	v_exp_f32_e32 v82, v82
	v_exp_f32_e32 v83, v83
	s_nop 0
	v_pk_add_f32 v[82:83], v[82:83], 1.0 op_sel_hi:[1,0]
	v_rcp_f32_e32 v83, v83
	v_rcp_f32_e32 v82, v82
	s_nop 0
	v_pk_mul_f32 v[144:145], v[80:81], v[82:83]
	v_pk_fma_f32 v[80:81], v[100:101], v[192:193], v[112:113]
	v_pk_fma_f32 v[80:81], v[104:105], v[164:165], v[80:81]
	v_pk_fma_f32 v[80:81], v[108:109], v[174:175], v[80:81]
	v_pk_fma_f32 v[80:81], v[60:61], v[186:187], v[80:81]
	v_mul_f32_e32 v82, 0xbfb8aa3b, v80
	v_mul_f32_e32 v83, 0xbfb8aa3b, v81
	v_exp_f32_e32 v82, v82
	v_exp_f32_e32 v83, v83
	s_nop 0
	v_pk_add_f32 v[82:83], v[82:83], 1.0 op_sel_hi:[1,0]
	v_rcp_f32_e32 v83, v83
	v_rcp_f32_e32 v82, v82
	s_nop 0
	v_pk_mul_f32 v[146:147], v[80:81], v[82:83]
	v_pk_fma_f32 v[80:81], v[102:103], v[154:155], v[114:115]
	v_pk_fma_f32 v[80:81], v[106:107], v[188:189], v[80:81]
	v_pk_fma_f32 v[80:81], v[110:111], v[162:163], v[80:81]
	v_pk_fma_f32 v[80:81], v[62:63], v[168:169], v[80:81]
	v_mul_f32_e32 v82, 0xbfb8aa3b, v80
	v_mul_f32_e32 v83, 0xbfb8aa3b, v81
	v_exp_f32_e32 v82, v82
	v_exp_f32_e32 v83, v83
	s_nop 0
	v_pk_add_f32 v[82:83], v[82:83], 1.0 op_sel_hi:[1,0]
	v_rcp_f32_e32 v83, v83
	v_rcp_f32_e32 v82, v82
	s_nop 0
	v_pk_mul_f32 v[148:149], v[80:81], v[82:83]
	v_pk_fma_f32 v[80:81], v[102:103], v[188:189], v[114:115]
	v_pk_fma_f32 v[80:81], v[106:107], v[162:163], v[80:81]
	v_pk_fma_f32 v[80:81], v[110:111], v[168:169], v[80:81]
	v_pk_fma_f32 v[80:81], v[62:63], v[170:171], v[80:81]
	v_mul_f32_e32 v82, 0xbfb8aa3b, v80
	v_mul_f32_e32 v83, 0xbfb8aa3b, v81
	v_exp_f32_e32 v82, v82
	v_exp_f32_e32 v83, v83
	s_nop 0
	v_pk_add_f32 v[82:83], v[82:83], 1.0 op_sel_hi:[1,0]
	v_rcp_f32_e32 v83, v83
	v_rcp_f32_e32 v82, v82
	s_nop 0
	v_pk_mul_f32 v[150:151], v[80:81], v[82:83]
	v_pk_fma_f32 v[80:81], v[44:45], v[152:153], v[56:57]
	v_pk_fma_f32 v[80:81], v[48:49], v[172:173], v[80:81]
	v_pk_fma_f32 v[80:81], v[52:53], v[128:129], v[80:81]
	v_pk_fma_f32 v[80:81], v[40:41], v[126:127], v[80:81]
	v_mul_f32_e32 v82, 0xbfb8aa3b, v80
	v_mul_f32_e32 v83, 0xbfb8aa3b, v81
	v_exp_f32_e32 v82, v82
	v_exp_f32_e32 v83, v83
	s_nop 0
	v_pk_add_f32 v[82:83], v[82:83], 1.0 op_sel_hi:[1,0]
	v_rcp_f32_e32 v83, v83
	v_rcp_f32_e32 v82, v82
	s_nop 0
	v_pk_mul_f32 v[158:159], v[80:81], v[82:83]
	v_pk_fma_f32 v[80:81], v[44:45], v[172:173], v[56:57]
	v_pk_fma_f32 v[80:81], v[48:49], v[128:129], v[80:81]
	v_pk_fma_f32 v[80:81], v[52:53], v[126:127], v[80:81]
	v_pk_fma_f32 v[80:81], v[40:41], v[130:131], v[80:81]
	v_mul_f32_e32 v82, 0xbfb8aa3b, v80
	v_mul_f32_e32 v83, 0xbfb8aa3b, v81
	v_exp_f32_e32 v82, v82
	v_exp_f32_e32 v83, v83
	s_nop 0
	v_pk_add_f32 v[82:83], v[82:83], 1.0 op_sel_hi:[1,0]
	v_rcp_f32_e32 v83, v83
	v_rcp_f32_e32 v82, v82
	s_nop 0
	v_pk_mul_f32 v[166:167], v[80:81], v[82:83]
	v_pk_fma_f32 v[80:81], v[46:47], v[120:121], v[58:59]
	v_pk_fma_f32 v[80:81], v[50:51], v[122:123], v[80:81]
	v_pk_fma_f32 v[80:81], v[54:55], v[124:125], v[80:81]
	v_pk_fma_f32 v[80:81], v[42:43], v[116:117], v[80:81]
	v_mul_f32_e32 v82, 0xbfb8aa3b, v80
	v_mul_f32_e32 v83, 0xbfb8aa3b, v81
	v_exp_f32_e32 v82, v82
	v_exp_f32_e32 v83, v83
	s_nop 0
	v_pk_add_f32 v[82:83], v[82:83], 1.0 op_sel_hi:[1,0]
	v_rcp_f32_e32 v83, v83
	v_rcp_f32_e32 v82, v82
	s_nop 0
	v_pk_mul_f32 v[184:185], v[80:81], v[82:83]
	v_pk_fma_f32 v[80:81], v[46:47], v[122:123], v[58:59]
	v_pk_fma_f32 v[80:81], v[50:51], v[124:125], v[80:81]
	v_pk_fma_f32 v[80:81], v[54:55], v[116:117], v[80:81]
	v_pk_fma_f32 v[80:81], v[42:43], v[118:119], v[80:81]
	v_mul_f32_e32 v82, 0xbfb8aa3b, v80
	v_mul_f32_e32 v83, 0xbfb8aa3b, v81
	v_exp_f32_e32 v82, v82
	v_exp_f32_e32 v83, v83
	s_nop 0
	v_pk_add_f32 v[82:83], v[82:83], 1.0 op_sel_hi:[1,0]
	v_rcp_f32_e32 v83, v83
	v_rcp_f32_e32 v82, v82
	s_nop 0
	v_pk_mul_f32 v[194:195], v[80:81], v[82:83]

; #define LAS __attribute__((address_space(3)))
; DI unsigned pk2(float lo, float hi) { const f32x2_t v = {lo, hi}; const bf16x2_t b = __builtin_convertvector(v, bf16x2_t); return __builtin_bit_cast(unsigned, b); }
; DI void ssd_prompt_unit(const Args& a, int b, int hd, LAS unsigned char* lds, const int tid) {
;     ...
;                     const int nb = (cg - 8) * 8;
;                     u32x4 wa, wb;
; #pragma unroll
;                     for (int e = 0; e < 4; ++e) { wa[e] = pk2(va[2 * e], va[2 * e + 1]); wb[e] = pk2(vb[2 * e], vb[2 * e + 1]); }
;                     *(LAS u32x4*)(Bs + ta * SP_LDC + nb) = wa; *(LAS u32x4*)(Bs + tb * SP_LDC + nb) = wb;
;                     const float wsa = __expf(cum63 - cqa[2 * k]) * dqa[2 * k], wsb = __expf(cum63 - cqa[2 * k + 1]) * dqa[2 * k + 1];
; #pragma unroll
;                     for (int e = 0; e < 8; ++e) *(LAS unsigned*)(Bwt + (nb + e) * SP_LDT + ta) = pk2(va[e] * wsa, vb[e] * wsb);
.LBB0_314:
	s_andn2_b64 vcc, exec, s[14:15]
	s_cbranch_vccnz .LBB0_316
	v_sub_f32_e32 v36, v160, v36
	v_sub_f32_e32 v37, v160, v37
	v_mul_f32_e32 v36, 0x3fb8aa3b, v36
	v_mul_f32_e32 v37, 0x3fb8aa3b, v37
	v_exp_f32_e32 v36, v36
	v_exp_f32_e32 v37, v37
	ds_write_b128 v152, v[88:91] offset:34688
	ds_write_b128 v152, v[84:87] offset:34960
	v_add_u32_e32 v85, v230, v223
	v_add_u32_e32 v86, 0xa800, v85
	s_waitcnt lgkmcnt(2)
	v_pk_mul_f32 v[32:33], v[32:33], v[36:37]
	v_mov_b32_e32 v36, v144
	v_mov_b32_e32 v37, v146
	v_pk_mul_f32 v[36:37], v[32:33], v[36:37]
	v_cvt_pk_bf16_f32 v36, v36, v37
	v_add_u32_e32 v37, v230, v224
	ds_write_b32 v37, v36 offset:52224
	v_mov_b32_e32 v36, v145
	v_mov_b32_e32 v37, v147
	v_pk_mul_f32 v[36:37], v[32:33], v[36:37]
	v_cvt_pk_bf16_f32 v84, v36, v37
	v_mov_b32_e32 v36, v148
	v_mov_b32_e32 v37, v150
	v_pk_mul_f32 v[36:37], v[32:33], v[36:37]
	v_cvt_pk_bf16_f32 v36, v36, v37
	ds_write2_b32 v86, v84, v36 offset0:36 offset1:72
	v_mov_b32_e32 v36, v149
	v_mov_b32_e32 v37, v151
	v_pk_mul_f32 v[36:37], v[32:33], v[36:37]
	v_cvt_pk_bf16_f32 v84, v36, v37
	v_mov_b32_e32 v36, v158
	v_mov_b32_e32 v37, v166
	v_pk_mul_f32 v[36:37], v[32:33], v[36:37]
	v_cvt_pk_bf16_f32 v36, v36, v37
	ds_write2_b32 v86, v84, v36 offset0:108 offset1:144
	v_mov_b32_e32 v36, v159
	v_mov_b32_e32 v37, v167
	v_pk_mul_f32 v[36:37], v[32:33], v[36:37]
	v_cvt_pk_bf16_f32 v84, v36, v37
	v_mov_b32_e32 v36, v184
	v_mov_b32_e32 v37, v194
	v_pk_mul_f32 v[36:37], v[32:33], v[36:37]
	v_cvt_pk_bf16_f32 v36, v36, v37
	ds_write2_b32 v86, v84, v36 offset0:180 offset1:216
	v_mov_b32_e32 v36, v185
	v_mov_b32_e32 v37, v195
	v_pk_mul_f32 v[32:33], v[32:33], v[36:37]
	v_cvt_pk_bf16_f32 v32, v32, v33
	ds_write_b32 v85, v32 offset:44016

; DI float lo16(unsigned w) { return __uint_as_float(w << 16); }
; DI float hi16(unsigned w) { return __uint_as_float(w & 0xffff0000u); }
; DI void conv_row8(const u32x4 (&raw)[11], int i, const float (&w)[4][8], const float (&bias)[8], float (&v)[8]) {
; #pragma unroll
;     for (int e = 0; e < 8; ++e) v[e] = bias[e];
; #pragma unroll
;     for (int jj = 0; jj < 4; ++jj) {
; #pragma unroll
;         for (int e = 0; e < 4; ++e) { v[2 * e] += w[jj][2 * e] * lo16(raw[i + jj][e]); v[2 * e + 1] += w[jj][2 * e + 1] * hi16(raw[i + jj][e]); }
;     }
; #pragma unroll
;     for (int e = 0; e < 8; ++e) v[e] = v[e] * __frcp_rn(1.0f + __expf(-v[e]));
; }
; DI void ssd_prompt_unit(const Args& a, int b, int hd, LAS unsigned char* lds, const int tid) {
;     ...
;             for (int k = 0; k < 4; ++k) {
;                 const bool act = stager || k == 0;
;                 float va[8], vb[8];
;                 if (act) { conv_row8(raw, 2 * k, cwt, cbias, va); conv_row8(raw, 2 * k + 1, cwt, cbias, vb); }
.LBB0_319:
	s_and_b64 vcc, exec, s[52:53]
	s_cbranch_vccnz .LBB0_321
	v_pk_fma_f32 v[36:37], v[100:101], v[164:165], v[112:113]
	s_waitcnt lgkmcnt(0)
	v_lshlrev_b32_e32 v32, 16, v68
	v_pk_fma_f32 v[36:37], v[104:105], v[174:175], v[36:37]
	v_and_b32_e32 v33, 0xffff0000, v68
	v_pk_fma_f32 v[36:37], v[108:109], v[186:187], v[36:37]
	v_pk_fma_f32 v[36:37], v[60:61], v[32:33], v[36:37]
	v_mul_f32_e32 v68, 0xbfb8aa3b, v36
	v_exp_f32_e32 v84, v68
	v_mul_f32_e32 v68, 0xbfb8aa3b, v37
	v_exp_f32_e32 v85, v68
	s_nop 0
	v_pk_add_f32 v[84:85], v[84:85], 1.0 op_sel_hi:[1,0]
	v_rcp_f32_e32 v85, v85
	v_rcp_f32_e32 v84, v84
	s_nop 0
	v_pk_mul_f32 v[144:145], v[36:37], v[84:85]
	v_pk_fma_f32 v[36:37], v[100:101], v[174:175], v[112:113]
	v_pk_fma_f32 v[36:37], v[104:105], v[186:187], v[36:37]
	v_pk_fma_f32 v[32:33], v[108:109], v[32:33], v[36:37]
	v_lshlrev_b32_e32 v36, 16, v64
	v_and_b32_e32 v37, 0xffff0000, v64
	v_pk_fma_f32 v[32:33], v[60:61], v[36:37], v[32:33]
	v_mul_f32_e32 v36, 0xbfb8aa3b, v32
	v_mul_f32_e32 v37, 0xbfb8aa3b, v33
	v_exp_f32_e32 v36, v36
	v_exp_f32_e32 v37, v37
	s_nop 0
	v_pk_add_f32 v[36:37], v[36:37], 1.0 op_sel_hi:[1,0]
	v_rcp_f32_e32 v37, v37
	v_rcp_f32_e32 v36, v36
	s_nop 0
	v_pk_mul_f32 v[146:147], v[32:33], v[36:37]
	v_pk_fma_f32 v[36:37], v[102:103], v[162:163], v[114:115]
	v_lshlrev_b32_e32 v32, 16, v69
	v_pk_fma_f32 v[36:37], v[106:107], v[168:169], v[36:37]
	v_and_b32_e32 v33, 0xffff0000, v69
	v_pk_fma_f32 v[36:37], v[110:111], v[170:171], v[36:37]
	v_pk_fma_f32 v[36:37], v[62:63], v[32:33], v[36:37]
	v_mul_f32_e32 v60, 0xbfb8aa3b, v36
	v_mul_f32_e32 v61, 0xbfb8aa3b, v37
	v_exp_f32_e32 v60, v60
	v_exp_f32_e32 v61, v61
	s_nop 0
	v_pk_add_f32 v[60:61], v[60:61], 1.0 op_sel_hi:[1,0]
	v_rcp_f32_e32 v61, v61
	v_rcp_f32_e32 v60, v60
	s_nop 0
	v_pk_mul_f32 v[148:149], v[36:37], v[60:61]
	v_pk_fma_f32 v[36:37], v[102:103], v[168:169], v[114:115]
	v_pk_fma_f32 v[36:37], v[106:107], v[170:171], v[36:37]
	v_pk_fma_f32 v[32:33], v[110:111], v[32:33], v[36:37]
	v_lshlrev_b32_e32 v36, 16, v65
	v_and_b32_e32 v37, 0xffff0000, v65
	v_pk_fma_f32 v[32:33], v[62:63], v[36:37], v[32:33]
	v_mul_f32_e32 v36, 0xbfb8aa3b, v32
	v_mul_f32_e32 v37, 0xbfb8aa3b, v33
	v_exp_f32_e32 v36, v36
	v_exp_f32_e32 v37, v37
	s_nop 0
	v_pk_add_f32 v[36:37], v[36:37], 1.0 op_sel_hi:[1,0]
	v_rcp_f32_e32 v37, v37
	v_rcp_f32_e32 v36, v36
	s_nop 0
	v_pk_mul_f32 v[150:151], v[32:33], v[36:37]
	v_pk_fma_f32 v[36:37], v[44:45], v[128:129], v[56:57]
	v_lshlrev_b32_e32 v32, 16, v70
	v_pk_fma_f32 v[36:37], v[48:49], v[126:127], v[36:37]
	v_and_b32_e32 v33, 0xffff0000, v70
	v_pk_fma_f32 v[36:37], v[52:53], v[130:131], v[36:37]
	v_pk_fma_f32 v[36:37], v[40:41], v[32:33], v[36:37]
	v_mul_f32_e32 v60, 0xbfb8aa3b, v36
	v_mul_f32_e32 v61, 0xbfb8aa3b, v37
	v_exp_f32_e32 v60, v60
	v_exp_f32_e32 v61, v61
	s_nop 0
	v_pk_add_f32 v[60:61], v[60:61], 1.0 op_sel_hi:[1,0]
	v_rcp_f32_e32 v61, v61
	v_rcp_f32_e32 v60, v60
	s_nop 0
	v_pk_mul_f32 v[158:159], v[36:37], v[60:61]
	v_pk_fma_f32 v[36:37], v[44:45], v[126:127], v[56:57]
	v_pk_fma_f32 v[36:37], v[48:49], v[130:131], v[36:37]
	v_pk_fma_f32 v[32:33], v[52:53], v[32:33], v[36:37]
	v_lshlrev_b32_e32 v36, 16, v66
	v_and_b32_e32 v37, 0xffff0000, v66
	v_pk_fma_f32 v[32:33], v[40:41], v[36:37], v[32:33]
	v_mul_f32_e32 v36, 0xbfb8aa3b, v32
	v_mul_f32_e32 v37, 0xbfb8aa3b, v33
	v_exp_f32_e32 v36, v36
	v_exp_f32_e32 v37, v37
	s_nop 0
	v_pk_add_f32 v[36:37], v[36:37], 1.0 op_sel_hi:[1,0]
	v_rcp_f32_e32 v37, v37
	v_rcp_f32_e32 v36, v36
	s_nop 0
	v_pk_mul_f32 v[166:167], v[32:33], v[36:37]
	v_pk_fma_f32 v[36:37], v[46:47], v[124:125], v[58:59]
	v_lshlrev_b32_e32 v32, 16, v71
	v_pk_fma_f32 v[36:37], v[50:51], v[116:117], v[36:37]
	v_and_b32_e32 v33, 0xffff0000, v71
	v_pk_fma_f32 v[36:37], v[54:55], v[118:119], v[36:37]
	v_pk_fma_f32 v[36:37], v[42:43], v[32:33], v[36:37]
	v_mul_f32_e32 v40, 0xbfb8aa3b, v36
	v_mul_f32_e32 v41, 0xbfb8aa3b, v37
	v_exp_f32_e32 v40, v40
	v_exp_f32_e32 v41, v41
	s_nop 0
	v_pk_add_f32 v[40:41], v[40:41], 1.0 op_sel_hi:[1,0]
	v_rcp_f32_e32 v41, v41
	v_rcp_f32_e32 v40, v40
	s_nop 0
	v_pk_mul_f32 v[184:185], v[36:37], v[40:41]
	v_pk_fma_f32 v[36:37], v[46:47], v[116:117], v[58:59]
	v_pk_fma_f32 v[36:37], v[50:51], v[118:119], v[36:37]
	v_pk_fma_f32 v[32:33], v[54:55], v[32:33], v[36:37]
	v_lshlrev_b32_e32 v36, 16, v67
	v_and_b32_e32 v37, 0xffff0000, v67
	v_pk_fma_f32 v[32:33], v[42:43], v[36:37], v[32:33]
	v_mul_f32_e32 v36, 0xbfb8aa3b, v32
	v_mul_f32_e32 v37, 0xbfb8aa3b, v33
	v_exp_f32_e32 v36, v36
	v_exp_f32_e32 v37, v37
	s_nop 0
	v_pk_add_f32 v[36:37], v[36:37], 1.0 op_sel_hi:[1,0]
	v_rcp_f32_e32 v37, v37
	v_rcp_f32_e32 v36, v36
	s_nop 0
	v_pk_mul_f32 v[194:195], v[32:33], v[36:37]

; #define LAS __attribute__((address_space(3)))
; DI unsigned pk2(float lo, float hi) { const f32x2_t v = {lo, hi}; const bf16x2_t b = __builtin_convertvector(v, bf16x2_t); return __builtin_bit_cast(unsigned, b); }
; DI void ssd_prompt_unit(const Args& a, int b, int hd, LAS unsigned char* lds, const int tid) {
;     ...
;                     const int nb = (cg - 8) * 8;
;                     u32x4 wa, wb;
; #pragma unroll
;                     for (int e = 0; e < 4; ++e) { wa[e] = pk2(va[2 * e], va[2 * e + 1]); wb[e] = pk2(vb[2 * e], vb[2 * e + 1]); }
;                     *(LAS u32x4*)(Bs + ta * SP_LDC + nb) = wa; *(LAS u32x4*)(Bs + tb * SP_LDC + nb) = wb;
;                     const float wsa = __expf(cum63 - cqa[2 * k]) * dqa[2 * k], wsb = __expf(cum63 - cqa[2 * k + 1]) * dqa[2 * k + 1];
; #pragma unroll
;                     for (int e = 0; e < 8; ++e) *(LAS unsigned*)(Bwt + (nb + e) * SP_LDT + ta) = pk2(va[e] * wsa, vb[e] * wsb);
.LBB0_325:
	s_andn2_b64 vcc, exec, s[14:15]
	s_cbranch_vccnz .LBB0_327
	ds_write_b128 v32, v[44:47] offset:34688
	ds_write_b128 v32, v[40:43] offset:34960
	v_sub_f32_e32 v32, v160, v38
	v_sub_f32_e32 v33, v160, v39
	v_mul_f32_e32 v32, 0x3fb8aa3b, v32
	v_mul_f32_e32 v33, 0x3fb8aa3b, v33
	v_exp_f32_e32 v32, v32
	v_exp_f32_e32 v33, v33
	v_add_u32_e32 v37, v233, v223
	v_add_u32_e32 v38, 0xa800, v37
	v_pk_mul_f32 v[32:33], v[34:35], v[32:33]
	v_mov_b32_e32 v34, v144
	v_mov_b32_e32 v35, v146
	v_pk_mul_f32 v[34:35], v[32:33], v[34:35]
	v_cvt_pk_bf16_f32 v34, v34, v35
	v_add_u32_e32 v35, v233, v224
	ds_write_b32 v35, v34 offset:52224
	v_mov_b32_e32 v34, v145
	v_mov_b32_e32 v35, v147
	v_pk_mul_f32 v[34:35], v[32:33], v[34:35]
	v_cvt_pk_bf16_f32 v36, v34, v35
	v_mov_b32_e32 v34, v148
	v_mov_b32_e32 v35, v150
	v_pk_mul_f32 v[34:35], v[32:33], v[34:35]
	v_cvt_pk_bf16_f32 v34, v34, v35
	ds_write2_b32 v38, v36, v34 offset0:36 offset1:72
	v_mov_b32_e32 v34, v149
	v_mov_b32_e32 v35, v151
	v_pk_mul_f32 v[34:35], v[32:33], v[34:35]
	v_cvt_pk_bf16_f32 v36, v34, v35
	v_mov_b32_e32 v34, v158
	v_mov_b32_e32 v35, v166
	v_pk_mul_f32 v[34:35], v[32:33], v[34:35]
	v_cvt_pk_bf16_f32 v34, v34, v35
	ds_write2_b32 v38, v36, v34 offset0:108 offset1:144
	v_mov_b32_e32 v34, v159
	v_mov_b32_e32 v35, v167
	v_pk_mul_f32 v[34:35], v[32:33], v[34:35]
	v_cvt_pk_bf16_f32 v36, v34, v35
	v_mov_b32_e32 v34, v184
	v_mov_b32_e32 v35, v194
	v_pk_mul_f32 v[34:35], v[32:33], v[34:35]
	v_cvt_pk_bf16_f32 v34, v34, v35
	ds_write2_b32 v38, v36, v34 offset0:180 offset1:216
	v_mov_b32_e32 v34, v185
	v_mov_b32_e32 v35, v195
	v_pk_mul_f32 v[32:33], v[32:33], v[34:35]
	v_cvt_pk_bf16_f32 v32, v32, v33
	ds_write_b32 v37, v32 offset:44016

; #define LAS __attribute__((address_space(3)))
; DI unsigned ssd_dt_load(const bf16_t* HIN, size_t rowbase, int hd, int lane) { return (unsigned)HIN[(rowbase + lane) * LDH + C_DT + hd]; }
; DI void ssd_dt_scan(unsigned rawbits, float dtb, float av, int lane, LAS float* cumS, LAS float* dtS) {
;     const float v = __uint_as_float(rawbits << 16) + dtb; const float dt = v > 20.f ? v : log1pf(__expf(v));
; DI void ssd_prompt_unit(const Args& a, int b, int hd, LAS unsigned char* lds, const int tid) {
;     ...
;         if (c + 1 < 32) {
;             if (wave == 7) { ssd_dt_scan(dtraw, dtb, av, lane, cumS + (buf ^ 1) * 64, dtS + (buf ^ 1) * 64); if (c + 2 < 32) dtraw = ssd_dt_load(HIN, row0 + t0 + 128, hd, lane); }
.LBB0_338:
	s_and_b64 s[12:13], s[20:21], s[12:13]
	s_andn2_b64 vcc, exec, s[12:13]
	s_cbranch_vccnz .LBB0_343
	v_lshlrev_b32_e32 v0, 16, v217
	v_add_f32_e32 v0, v133, v0
	s_mov_b32 s7, 0x41a00000
	v_cmp_nlt_f32_e32 vcc, s7, v0
	s_and_saveexec_b64 s[12:13], vcc
	s_cbranch_execz .LBB0_341
	v_mul_f32_e32 v0, 0x3fb8aa3b, v0
	v_exp_f32_e32 v14, v0
	s_mov_b32 s7, 0x3f2aaaab
	v_add_f32_e32 v2, 1.0, v14
	v_frexp_mant_f32_e32 v4, v2
	v_cvt_f64_f32_e32 v[0:1], v2
	v_frexp_exp_i32_f64_e32 v0, v[0:1]
	v_cmp_gt_f32_e32 vcc, s7, v4
	v_add_f32_e32 v3, -1.0, v2
	v_sub_f32_e32 v5, v3, v2
	v_subbrev_co_u32_e32 v8, vcc, 0, v0, vcc
	v_sub_u32_e32 v0, 0, v8
	v_sub_f32_e32 v3, v14, v3
	v_add_f32_e32 v5, 1.0, v5
	v_ldexp_f32 v1, v2, v0
	v_add_f32_e32 v3, v3, v5
	v_add_f32_e32 v2, -1.0, v1
	v_add_f32_e32 v4, 1.0, v1
	v_ldexp_f32 v0, v3, v0
	v_add_f32_e32 v3, 1.0, v2
	v_add_f32_e32 v5, -1.0, v4
	v_sub_f32_e32 v3, v1, v3
	v_sub_f32_e32 v1, v1, v5
	v_add_f32_e32 v3, v0, v3
	v_add_f32_e32 v0, v0, v1
	v_add_f32_e32 v9, v4, v0
	v_rcp_f32_e32 v11, v9
	v_sub_f32_e32 v1, v9, v4
	v_sub_f32_e32 v10, v0, v1
	v_add_f32_e32 v1, v2, v3
	v_mul_f32_e32 v13, v1, v11
	v_sub_f32_e32 v0, v1, v2
	v_mul_f32_e32 v2, v9, v13
	v_fma_f32 v4, v13, v9, -v2
	v_fmac_f32_e32 v4, v13, v10
	v_sub_f32_e32 v12, v3, v0
	v_add_f32_e32 v0, v2, v4
	v_sub_f32_e32 v3, v1, v0
	v_pk_add_f32 v[6:7], v[0:1], v[2:3] neg_lo:[0,1] neg_hi:[0,1]
	v_mov_b32_e32 v5, v0
	v_pk_add_f32 v[0:1], v[6:7], v[4:5] neg_lo:[0,1] neg_hi:[0,1]
	s_mov_b32 s7, 0x3f317218
	v_add_f32_e32 v1, v12, v1
	v_add_f32_e32 v0, v0, v1
	v_add_f32_e32 v1, v3, v0
	v_mul_f32_e32 v12, v11, v1
	v_mul_f32_e32 v2, v9, v12
	v_fma_f32 v4, v12, v9, -v2
	v_fmac_f32_e32 v4, v12, v10
	v_sub_f32_e32 v3, v3, v1
	v_add_f32_e32 v9, v0, v3
	v_add_f32_e32 v0, v2, v4
	v_sub_f32_e32 v3, v1, v0
	v_pk_add_f32 v[6:7], v[0:1], v[2:3] neg_lo:[0,1] neg_hi:[0,1]
	v_mov_b32_e32 v5, v0
	v_pk_add_f32 v[0:1], v[6:7], v[4:5] neg_lo:[0,1] neg_hi:[0,1]
	v_add_f32_e32 v1, v9, v1
	v_add_f32_e32 v0, v0, v1
	v_add_f32_e32 v1, v13, v12
	v_add_f32_e32 v0, v3, v0
	v_sub_f32_e32 v2, v1, v13
	v_mul_f32_e32 v0, v11, v0
	v_sub_f32_e32 v2, v12, v2
	v_add_f32_e32 v2, v2, v0
	v_add_f32_e32 v4, v1, v2
	v_mul_f32_e32 v5, v4, v4
	v_mov_b32_e32 v0, 0x3ecc95a3
	v_fmamk_f32 v0, v5, 0x3e9b6dac, v0
	v_fmaak_f32 v183, v5, v0, 0x3f2aaada
	v_cvt_f32_i32_e32 v0, v8
	v_sub_f32_e32 v1, v4, v1
	v_sub_f32_e32 v1, v2, v1
	v_ldexp_f32 v6, v1, 1
	v_mul_f32_e32 v1, v4, v5
	v_ldexp_f32 v3, v4, 1
	v_pk_mul_f32 v[4:5], v[0:1], v[182:183]
	v_fma_f32 v2, v0, s7, -v4
	v_fmac_f32_e32 v2, 0xb102e308, v0
	v_pk_add_f32 v[0:1], v[4:5], v[2:3]
	s_mov_b32 s7, 0x7f800000
	v_sub_f32_e32 v3, v1, v3
	v_sub_f32_e32 v3, v5, v3
	v_add_f32_e32 v7, v6, v3
	v_mov_b32_e32 v6, v4
	v_pk_add_f32 v[4:5], v[0:1], v[4:5] neg_lo:[0,1] neg_hi:[0,1]
	v_pk_add_f32 v[8:9], v[0:1], v[6:7]
	v_mov_b32_e32 v3, v0
	v_mov_b32_e32 v5, v9
	v_pk_add_f32 v[10:11], v[2:3], v[4:5] neg_lo:[0,1] neg_hi:[0,1]
	v_pk_add_f32 v[2:3], v[2:3], v[4:5]
	v_mov_b32_e32 v6, v7
	v_pk_add_f32 v[4:5], v[2:3], v[0:1] op_sel:[1,0] op_sel_hi:[0,1] neg_lo:[0,1] neg_hi:[0,1]
	v_pk_add_f32 v[12:13], v[8:9], v[4:5] op_sel_hi:[1,0] neg_lo:[0,1] neg_hi:[0,1]
	v_mov_b32_e32 v8, v9
	v_mov_b32_e32 v9, v3
	v_pk_mov_b32 v[4:5], v[0:1], v[4:5] op_sel:[1,0]
	v_mov_b32_e32 v7, v0
	v_pk_add_f32 v[4:5], v[8:9], v[4:5] neg_lo:[0,1] neg_hi:[0,1]
	v_mov_b32_e32 v12, v10
	v_pk_add_f32 v[0:1], v[6:7], v[4:5] neg_lo:[0,1] neg_hi:[0,1]
	v_mov_b32_e32 v11, v3
	v_pk_add_f32 v[4:5], v[12:13], v[0:1]
	v_cmp_neq_f32_e32 vcc, s7, v14
	v_pk_add_f32 v[6:7], v[4:5], v[4:5] op_sel:[0,1] op_sel_hi:[1,0]
	s_mov_b32 s7, 0x33800000
	v_pk_add_f32 v[2:3], v[2:3], v[6:7] op_sel:[1,0] op_sel_hi:[0,1]
	v_mov_b32_e32 v5, v2
	v_pk_add_f32 v[8:9], v[4:5], v[10:11] neg_lo:[0,1] neg_hi:[0,1]
	v_mov_b32_e32 v1, v6
	v_sub_f32_e32 v3, v4, v8
	v_pk_add_f32 v[0:1], v[0:1], v[8:9] neg_lo:[0,1] neg_hi:[0,1]
	v_sub_f32_e32 v3, v10, v3
	v_add_f32_e32 v0, v0, v3
	v_add_f32_e32 v0, v0, v1
	v_add_f32_e32 v0, v2, v0
	v_mov_b32_e32 v1, 0x7f800000
	v_cndmask_b32_e32 v0, v1, v0, vcc
	v_cmp_ngt_f32_e32 vcc, -1.0, v14
	v_mov_b32_e32 v1, 0xff800000
	s_nop 0
	v_cndmask_b32_e32 v0, v206, v0, vcc
	v_cmp_neq_f32_e32 vcc, -1.0, v14
	s_nop 1
	v_cndmask_b32_e32 v0, v1, v0, vcc
	v_cmp_lt_f32_e64 vcc, |v14|, s7
	s_nop 1
	v_cndmask_b32_e32 v0, v0, v14, vcc

; DI unsigned pk2(float lo, float hi) { const f32x2_t v = {lo, hi}; const bf16x2_t b = __builtin_convertvector(v, bf16x2_t); return __builtin_bit_cast(unsigned, b); }
; DI float lo16(unsigned w) { return __uint_as_float(w << 16); }
; DI float hi16(unsigned w) { return __uint_as_float(w & 0xffff0000u); }
; DI void shortconv_pass(const Args& a, int G, const int tid) {
;     ...
;         for (int tt = 0; tt < len; ++tt) {
;             const int t = t0 + tt; const bf16_t* rp = S + (row0 + t) * 2048; float g0[16];
; #pragma unroll
;             for (int q = 0; q < 2; ++q) { const u32x4 bw4 = *(const u32x4*)(rp + ch + 8 * q), gw4 = *(const u32x4*)(rp + 1024 + ch + 8 * q);
;                 u32x4 ow;
; #pragma unroll
;                 for (int e = 0; e < 4; ++e) { const int i0 = 8 * q + 2 * e; g0[i0] = lo16(gw4[e]); g0[i0 + 1] = hi16(gw4[e]);
;                     const float u0 = w0[i0] * g2[i0] + w1[i0] * g1[i0] + w2[i0] * g0[i0], u1 = w0[i0 + 1] * g2[i0 + 1] + w1[i0 + 1] * g1[i0 + 1] + w2[i0 + 1] * g0[i0 + 1];
;                     ow[e] = pk2(lo16(bw4[e]) * u0, hi16(bw4[e]) * u1); }
;                 *(u32x4*)(V1 + (row0 + t) * 1024 + ch + 8 * q) = ow; }
;             if (t >= L - 2) { float* so = a.out + (sample ? O_SSC : O_PSC) + ((size_t)b * 2 + (t - (L - 2))) * 1024 + ch;
; #pragma unroll
;                 for (int q = 0; q < 4; ++q) *(f32x4*)(so + 4 * q) = (f32x4){g0[4 * q], g0[4 * q + 1], g0[4 * q + 2], g0[4 * q + 3]}; }
; #pragma unroll
;             for (int e = 0; e < 16; ++e) { g2[e] = g1[e]; g1[e] = g0[e]; }
.LBB0_434:
	v_mov_b32_e32 v117, v53
	v_mov_b32_e32 v116, v52
	s_waitcnt vmcnt(1)
	v_mov_b32_e32 v53, v65
	v_mov_b32_e32 v52, v64
	v_lshl_add_u64 v[64:65], v[96:97], 0, v[160:161]
	v_mov_b32_e32 v115, v55
	v_mov_b32_e32 v114, v54
	v_mov_b32_e32 v55, v67
	v_mov_b32_e32 v54, v66
	v_lshlrev_b64 v[66:67], 12, v[64:65]
	v_lshl_add_u64 v[66:67], v[94:95], 0, v[66:67]
	v_mov_b32_e32 v50, v98
	v_mov_b32_e32 v103, v49
	v_mov_b32_e32 v102, v48
	v_mov_b32_e32 v109, v61
	v_mov_b32_e32 v108, v60
	v_mov_b32_e32 v111, v59
	v_mov_b32_e32 v110, v58
	s_waitcnt vmcnt(0)
	v_mov_b32_e32 v99, v83
	v_mov_b32_e32 v98, v82
	v_mov_b32_e32 v49, v81
	v_mov_b32_e32 v48, v80
	v_mov_b32_e32 v61, v73
	v_mov_b32_e32 v60, v72
	v_mov_b32_e32 v59, v71
	v_mov_b32_e32 v58, v70
	global_load_dwordx4 v[76:79], v[66:67], off offset:16
	global_load_dwordx4 v[70:73], v[66:67], off
	global_load_dwordx4 v[80:83], v[66:67], off offset:2064
	global_load_dwordx4 v[84:87], v[66:67], off offset:2048
	v_lshlrev_b64 v[64:65], 11, v[64:65]
	v_pk_mul_f32 v[66:67], v[24:25], v[52:53]
	v_lshl_add_u64 v[106:107], v[90:91], 0, v[64:65]
	v_pk_fma_f32 v[66:67], v[8:9], v[116:117], v[66:67]
	v_mov_b32_e32 v113, v57
	v_mov_b32_e32 v112, v56
	v_mov_b32_e32 v57, v69
	v_mov_b32_e32 v56, v68
	v_mov_b32_e32 v105, v63
	v_mov_b32_e32 v104, v62
	v_mov_b32_e32 v63, v75
	v_mov_b32_e32 v62, v74
	v_cmp_ge_u32_e32 vcc, v160, v118
	s_waitcnt vmcnt(2)
	v_lshlrev_b32_e32 v68, 16, v70
	v_and_b32_e32 v69, 0xffff0000, v70
	s_waitcnt vmcnt(0)
	v_lshlrev_b32_e32 v64, 16, v84
	v_and_b32_e32 v65, 0xffff0000, v84
	v_pk_fma_f32 v[66:67], v[28:29], v[64:65], v[66:67]
	v_lshlrev_b32_e32 v70, 16, v71
	v_pk_mul_f32 v[66:67], v[66:67], v[68:69]
	v_pk_mul_f32 v[68:69], v[26:27], v[54:55]
	v_cvt_pk_bf16_f32 v84, v66, v67
	v_lshlrev_b32_e32 v66, 16, v85
	v_and_b32_e32 v67, 0xffff0000, v85
	v_pk_fma_f32 v[68:69], v[10:11], v[114:115], v[68:69]
	v_and_b32_e32 v71, 0xffff0000, v71
	v_pk_fma_f32 v[68:69], v[30:31], v[66:67], v[68:69]
	v_lshlrev_b32_e32 v74, 16, v72
	v_pk_mul_f32 v[68:69], v[68:69], v[70:71]
	v_pk_mul_f32 v[70:71], v[20:21], v[56:57]
	v_cvt_pk_bf16_f32 v85, v68, v69
	v_lshlrev_b32_e32 v68, 16, v86
	v_and_b32_e32 v69, 0xffff0000, v86
	v_pk_fma_f32 v[70:71], v[12:13], v[112:113], v[70:71]
	v_and_b32_e32 v75, 0xffff0000, v72
	v_pk_fma_f32 v[70:71], v[44:45], v[68:69], v[70:71]
	v_lshlrev_b32_e32 v72, 16, v73
	v_pk_mul_f32 v[70:71], v[70:71], v[74:75]
	v_pk_mul_f32 v[74:75], v[22:23], v[58:59]
	v_cvt_pk_bf16_f32 v86, v70, v71
	v_lshlrev_b32_e32 v70, 16, v87
	v_and_b32_e32 v71, 0xffff0000, v87
	v_pk_fma_f32 v[74:75], v[14:15], v[110:111], v[74:75]
	v_and_b32_e32 v73, 0xffff0000, v73
	v_pk_fma_f32 v[74:75], v[46:47], v[70:71], v[74:75]
	v_pk_mul_f32 v[72:73], v[74:75], v[72:73]
	v_pk_mul_f32 v[74:75], v[16:17], v[60:61]
	v_cvt_pk_bf16_f32 v87, v72, v73
	v_lshlrev_b32_e32 v72, 16, v80
	v_and_b32_e32 v73, 0xffff0000, v80
	v_pk_fma_f32 v[74:75], v[0:1], v[108:109], v[74:75]
	global_store_dwordx4 v[106:107], v[84:87], off
	v_pk_fma_f32 v[74:75], v[32:33], v[72:73], v[74:75]
	s_nop 0
	v_lshlrev_b32_e32 v84, 16, v76
	v_and_b32_e32 v85, 0xffff0000, v76
	v_pk_mul_f32 v[74:75], v[74:75], v[84:85]
	v_lshlrev_b32_e32 v84, 16, v77
	v_cvt_pk_bf16_f32 v76, v74, v75
	v_lshlrev_b32_e32 v74, 16, v81
	v_and_b32_e32 v75, 0xffff0000, v81
	v_pk_mul_f32 v[80:81], v[18:19], v[62:63]
	v_and_b32_e32 v85, 0xffff0000, v77
	v_pk_fma_f32 v[80:81], v[2:3], v[104:105], v[80:81]
	v_lshlrev_b32_e32 v86, 16, v78
	v_pk_fma_f32 v[80:81], v[34:35], v[74:75], v[80:81]
	v_and_b32_e32 v87, 0xffff0000, v78
	v_pk_mul_f32 v[80:81], v[80:81], v[84:85]
	v_pk_mul_f32 v[84:85], v[40:41], v[48:49]
	v_cvt_pk_bf16_f32 v77, v80, v81
	v_lshlrev_b32_e32 v80, 16, v82
	v_and_b32_e32 v81, 0xffff0000, v82
	v_pk_fma_f32 v[84:85], v[4:5], v[102:103], v[84:85]
	v_lshlrev_b32_e32 v82, 16, v83
	v_pk_fma_f32 v[84:85], v[36:37], v[80:81], v[84:85]
	v_and_b32_e32 v83, 0xffff0000, v83
	v_pk_mul_f32 v[84:85], v[84:85], v[86:87]
	v_cvt_pk_bf16_f32 v78, v84, v85
	v_pk_mul_f32 v[84:85], v[42:43], v[98:99]
	v_pk_fma_f32 v[50:51], v[6:7], v[50:51], v[84:85]
	v_lshlrev_b32_e32 v84, 16, v79
	v_pk_fma_f32 v[50:51], v[38:39], v[82:83], v[50:51]
	v_and_b32_e32 v85, 0xffff0000, v79
	v_pk_mul_f32 v[50:51], v[50:51], v[84:85]
	v_cvt_pk_bf16_f32 v79, v50, v51
	global_store_dwordx4 v[106:107], v[76:79], off offset:16
	s_and_saveexec_b64 s[10:11], vcc
	s_cbranch_execz .LBB0_433
	v_add_u32_e32 v50, v120, v160
	v_mov_b32_e32 v51, v161
	v_lshlrev_b64 v[50:51], 12, v[50:51]
	v_lshl_add_u64 v[50:51], v[100:101], 0, v[50:51]
	global_store_dwordx4 v[50:51], v[64:67], off
	global_store_dwordx4 v[50:51], v[68:71], off offset:16
	global_store_dwordx4 v[50:51], v[72:75], off offset:32
	global_store_dwordx4 v[50:51], v[80:83], off offset:48
	s_branch .LBB0_433

; DI float lo16(unsigned w) { return __uint_as_float(w << 16); }
; DI float hi16(unsigned w) { return __uint_as_float(w & 0xffff0000u); }
; DI float rowscale(const float* ss, int row) {
;     const f32x4* p = (const f32x4*)(ss + (size_t)row * 16);
;     const f32x4 a = p[0], b = p[1], c = p[2], d = p[3];
;     const float s = (((a.x + a.y) + (a.z + a.w)) + ((b.x + b.y) + (b.z + b.w))) + (((c.x + c.y) + (c.z + c.w)) + ((d.x + d.y) + (d.z + d.w)));
;     return rsqrtf(s * (1.0f / 1024.0f) + EPS);
; }
; DI void rowscales8(const float* ss, int rowbase, int fr, int fq, float (&r)[2][4]) {
;     const int lane = fq * 16 + fr;
;     const float rA = rowscale(ss, rowbase + lane), rB = rowscale(ss, rowbase + 128 + lane);
; #pragma unroll
;     for (int m = 0; m < 4; ++m) { r[0][m] = __shfl(rA, m * 16 + fr); r[1][m] = __shfl(rB, m * 16 + fr); }
; }
;     DI void operator()(const pg8::f32x4 (&acc)[2][2][4][2], const pg8::Unit& u, int wr, int wc, int fr, int fq) const {
;         const int row0 = u.pm * 256 + wr * 64 + fr, col0 = u.pn * 256 + wc * 32 + 8 * fq;
;         float rs[2][4]; rowscales8(ss, u.pm * 256 + wr * 64, fr, fq, rs);
; #pragma unroll
;         for (int ai = 0; ai < 2; ++ai)
; #pragma unroll
;             for (int m = 0; m < 4; ++m) {
;                 const int row = row0 + ai * 128 + m * 16; const float r = rs[ai][m];
;                 float part = 0.f;
; #pragma unroll
;                 for (int bj = 0; bj < 2; ++bj) { const size_t off = (size_t)row * 1024 + col0 + bj * 128;
;                     const u32x4 tw = *(const u32x4*)(T + off); const u32x4 xw = *(const u32x4*)(xr + off);
;                     const pg8::f32x4 a0 = acc[ai][bj][m][0] * r, a1 = acc[ai][bj][m][1] * r;
;                     const float o0 = lo16(xw.x) + lo16(tw.x) * __frcp_rn(1.0f + __expf(-a0[0])), o1 = hi16(xw.x) + hi16(tw.x) * __frcp_rn(1.0f + __expf(-a0[1]));
.LBB0_470:
	s_lshl_b32 s1, s2, 8
	s_add_i32 s1, s1, s80
	v_or_b32_e32 v154, s1, v139
	v_ashrrev_i32_e32 v155, 31, v154
	v_lshlrev_b64 v[154:155], 6, v[154:155]
	v_lshl_add_u64 v[158:159], s[8:9], 0, v[154:155]
	global_load_dwordx4 v[154:157], v[158:159], off offset:16
	global_load_dwordx4 v[162:165], v[158:159], off offset:48
	global_load_dwordx4 v[166:169], v[158:159], off
	global_load_dwordx4 v[170:173], v[158:159], off offset:32
	s_mov_b32 s2, 0x3a800000
	v_or_b32_e32 v142, s1, v145
	v_lshl_or_b32 v140, s0, 8, v149
	s_waitcnt vmcnt(0)
	v_mov_b32_e32 v158, v166
	v_mov_b32_e32 v159, v170
	v_mov_b32_e32 v170, v167
	v_mov_b32_e32 v166, v168
	v_mov_b32_e32 v167, v172
	v_mov_b32_e32 v172, v169
	v_pk_add_f32 v[158:159], v[158:159], v[170:171]
	v_pk_add_f32 v[166:167], v[166:167], v[172:173]
	v_pk_add_f32 v[158:159], v[158:159], v[166:167]
	v_mov_b32_e32 v166, v154
	v_mov_b32_e32 v167, v162
	v_mov_b32_e32 v162, v155
	v_pk_add_f32 v[154:155], v[166:167], v[162:163]
	v_mov_b32_e32 v162, v156
	v_mov_b32_e32 v163, v164
	v_mov_b32_e32 v164, v157
	v_pk_add_f32 v[156:157], v[162:163], v[164:165]
	v_pk_add_f32 v[154:155], v[154:155], v[156:157]
	v_pk_add_f32 v[158:159], v[158:159], v[154:155]
	v_add_u32_e32 v154, s1, v151
	v_ashrrev_i32_e32 v155, 31, v154
	v_lshlrev_b64 v[154:155], 6, v[154:155]
	v_lshl_add_u64 v[170:171], s[8:9], 0, v[154:155]
	global_load_dwordx4 v[154:157], v[170:171], off offset:16
	global_load_dwordx4 v[162:165], v[170:171], off offset:48
	global_load_dwordx4 v[166:169], v[170:171], off
	s_nop 0
	global_load_dwordx4 v[170:173], v[170:171], off offset:32
	s_waitcnt vmcnt(1)
	v_mov_b32_e32 v174, v166
	s_waitcnt vmcnt(0)
	v_mov_b32_e32 v175, v170
	v_mov_b32_e32 v170, v167
	v_pk_add_f32 v[166:167], v[174:175], v[170:171]
	v_mov_b32_e32 v170, v168
	v_mov_b32_e32 v171, v172
	v_mov_b32_e32 v172, v169
	v_pk_add_f32 v[168:169], v[170:171], v[172:173]
	v_pk_add_f32 v[166:167], v[166:167], v[168:169]
	v_mov_b32_e32 v168, v154
	v_mov_b32_e32 v169, v162
	v_mov_b32_e32 v162, v155
	v_pk_add_f32 v[154:155], v[168:169], v[162:163]
	v_mov_b32_e32 v162, v156
	v_mov_b32_e32 v163, v164
	v_mov_b32_e32 v164, v157
	v_pk_add_f32 v[156:157], v[162:163], v[164:165]
	v_pk_add_f32 v[154:155], v[154:155], v[156:157]
	v_mov_b32_e32 v157, v158
	v_pk_add_f32 v[154:155], v[166:167], v[154:155]
	v_mov_b32_e32 v156, v154
	v_mov_b32_e32 v158, v155
	v_pk_add_f32 v[154:155], v[156:157], v[158:159]
	v_pk_fma_f32 v[154:155], v[154:155], s[2:3], v[176:177] op_sel_hi:[1,0,0]
	v_mul_f32_e32 v138, 0x4b800000, v155
	v_cmp_gt_f32_e64 s[42:43], s39, v155
	v_cmp_gt_f32_e32 vcc, s39, v154
	s_nop 0
	v_cndmask_b32_e64 v138, v155, v138, s[42:43]
	v_rsq_f32_e32 v138, v138
	s_nop 0
	v_mul_f32_e32 v141, 0x45800000, v138
	v_cndmask_b32_e64 v138, v138, v141, s[42:43]
	v_mul_f32_e32 v141, 0x4b800000, v154
	v_cndmask_b32_e32 v141, v154, v141, vcc
	v_rsq_f32_e32 v141, v141
	s_lshl_b32 s42, s0, 2
	s_ashr_i32 s43, s42, 31
	v_mul_f32_e32 v143, 0x45800000, v141
	v_cndmask_b32_e32 v141, v141, v143, vcc
	v_and_b32_e32 v143, 64, v177
	v_or_b32_e32 v144, v143, v145
	v_lshlrev_b32_e32 v155, 2, v144
	ds_bpermute_b32 v168, v155, v138
	ds_bpermute_b32 v148, v155, v141
	ds_bpermute_b32 v154, v155, v138 offset:64
	ds_bpermute_b32 v146, v155, v141 offset:64
	ds_bpermute_b32 v152, v155, v138 offset:128
	ds_bpermute_b32 v144, v155, v141 offset:128
	ds_bpermute_b32 v150, v155, v138 offset:192
	ds_bpermute_b32 v138, v155, v141 offset:192
	v_xor_b32_e32 v155, 16, v177
	v_add_u32_e32 v143, 64, v143
	v_cmp_lt_i32_e32 vcc, v155, v143
	v_ashrrev_i32_e32 v141, 31, v140
	s_nop 0
	v_cndmask_b32_e32 v155, v177, v155, vcc
	v_lshlrev_b32_e32 v169, 2, v155
	v_xor_b32_e32 v155, 32, v177
	v_cmp_lt_i32_e32 vcc, v155, v143
	s_waitcnt lgkmcnt(7)
	v_pk_mul_f32 v[124:125], v[124:125], v[168:169] op_sel_hi:[1,0]
	v_pk_mul_f32 v[126:127], v[126:127], v[168:169] op_sel_hi:[1,0]
	v_cndmask_b32_e32 v143, v177, v155, vcc
	v_lshlrev_b32_e32 v155, 2, v143
	v_ashrrev_i32_e32 v143, 31, v142
	v_lshlrev_b64 v[156:157], 10, v[142:143]
	v_lshl_add_u64 v[156:157], v[156:157], 0, v[140:141]
	v_lshlrev_b64 v[158:159], 1, v[156:157]
	v_lshl_add_u64 v[156:157], s[18:19], 0, v[158:159]
	global_load_dwordx4 v[162:165], v[156:157], off
	v_lshl_add_u64 v[170:171], s[12:13], 0, v[158:159]
	global_load_dwordx4 v[172:175], v[170:171], off
	v_mul_f32_e32 v124, 0xbfb8aa3b, v124
	v_mul_f32_e32 v125, 0xbfb8aa3b, v125
	v_exp_f32_e32 v124, v124
	v_exp_f32_e32 v125, v125
	v_mul_f32_e32 v126, 0xbfb8aa3b, v126
	v_mul_f32_e32 v127, 0xbfb8aa3b, v127
	v_exp_f32_e32 v126, v126
	v_pk_add_f32 v[124:125], v[124:125], 1.0 op_sel_hi:[1,0]
	v_exp_f32_e32 v127, v127
	v_pk_mul_f32 v[120:121], v[120:121], v[168:169] op_sel_hi:[1,0]
	v_pk_mul_f32 v[122:123], v[122:123], v[168:169] op_sel_hi:[1,0]
	v_mul_f32_e32 v120, 0xbfb8aa3b, v120
	v_pk_add_f32 v[126:127], v[126:127], 1.0 op_sel_hi:[1,0]
	v_mul_f32_e32 v121, 0xbfb8aa3b, v121
	v_exp_f32_e32 v120, v120
	v_exp_f32_e32 v121, v121
	v_pk_mul_f32 v[116:117], v[116:117], v[168:169] op_sel_hi:[1,0]
	v_pk_mul_f32 v[118:119], v[118:119], v[168:169] op_sel_hi:[1,0]
	v_pk_mul_f32 v[114:115], v[114:115], v[168:169] op_sel_hi:[1,0]
	v_pk_add_f32 v[120:121], v[120:121], 1.0 op_sel_hi:[1,0]
	v_mul_f32_e32 v114, 0xbfb8aa3b, v114
	v_mul_f32_e32 v115, 0xbfb8aa3b, v115
	v_exp_f32_e32 v114, v114
	v_exp_f32_e32 v115, v115
	s_waitcnt vmcnt(1)
	v_lshlrev_b32_e32 v166, 16, v162
	v_and_b32_e32 v167, 0xffff0000, v162
	s_waitcnt vmcnt(0)
; DI unsigned pk2(float lo, float hi) { const f32x2_t v = {lo, hi}; const bf16x2_t b = __builtin_convertvector(v, bf16x2_t); return __builtin_bit_cast(unsigned, b); }
; DI float lo16(unsigned w) { return __uint_as_float(w << 16); }
; DI float hi16(unsigned w) { return __uint_as_float(w & 0xffff0000u); }
;     DI void operator()(const pg8::f32x4 (&acc)[2][2][4][2], const pg8::Unit& u, int wr, int wc, int fr, int fq) const {
;     ...
;                 for (int bj = 0; bj < 2; ++bj) { const size_t off = (size_t)row * 1024 + col0 + bj * 128;
;                     const u32x4 tw = *(const u32x4*)(T + off); const u32x4 xw = *(const u32x4*)(xr + off);
;                     const pg8::f32x4 a0 = acc[ai][bj][m][0] * r, a1 = acc[ai][bj][m][1] * r;
;                     const float o0 = lo16(xw.x) + lo16(tw.x) * __frcp_rn(1.0f + __expf(-a0[0])), o1 = hi16(xw.x) + hi16(tw.x) * __frcp_rn(1.0f + __expf(-a0[1]));
;                     const float o2 = lo16(xw.y) + lo16(tw.y) * __frcp_rn(1.0f + __expf(-a0[2])), o3 = hi16(xw.y) + hi16(tw.y) * __frcp_rn(1.0f + __expf(-a0[3]));
;                     const float o4 = lo16(xw.z) + lo16(tw.z) * __frcp_rn(1.0f + __expf(-a1[0])), o5 = hi16(xw.z) + hi16(tw.z) * __frcp_rn(1.0f + __expf(-a1[1]));
;                     const float o6 = lo16(xw.w) + lo16(tw.w) * __frcp_rn(1.0f + __expf(-a1[2])), o7 = hi16(xw.w) + hi16(tw.w) * __frcp_rn(1.0f + __expf(-a1[3]));
;                     u32x4 w; w.x = pk2(o0, o1); w.y = pk2(o2, o3); w.z = pk2(o4, o5); w.w = pk2(o6, o7); *(u32x4*)(xbo + off) = w;
;                     part += ((o0 * o0 + o1 * o1) + (o2 * o2 + o3 * o3)) + ((o4 * o4 + o5 * o5) + (o6 * o6 + o7 * o7)); }
;                 part += __shfl_xor(part, 16); part += __shfl_xor(part, 32);
;                 if (ssout && fq == 0) ssout[(size_t)row * 16 + u.pn * 4 + wc] = part;
	v_lshlrev_b32_e32 v158, 16, v172
	v_and_b32_e32 v159, 0xffff0000, v172
	v_pk_add_f32 v[114:115], v[114:115], 1.0 op_sel_hi:[1,0]
	v_rcp_f32_e32 v125, v125
	v_rcp_f32_e32 v124, v124
	s_nop 0
	v_pk_fma_f32 v[124:125], v[124:125], v[166:167], v[158:159]
	v_lshlrev_b32_e32 v158, 16, v173
	v_and_b32_e32 v159, 0xffff0000, v173
	v_lshlrev_b32_e32 v162, 16, v163
	v_rcp_f32_e32 v127, v127
	v_and_b32_e32 v163, 0xffff0000, v163
	v_rcp_f32_e32 v126, v126
	s_nop 0
	v_pk_fma_f32 v[126:127], v[126:127], v[162:163], v[158:159]
	v_lshlrev_b32_e32 v162, 16, v164
	v_and_b32_e32 v163, 0xffff0000, v164
	v_lshlrev_b32_e32 v158, 16, v174
	v_and_b32_e32 v159, 0xffff0000, v174
	v_rcp_f32_e32 v121, v121
	v_rcp_f32_e32 v120, v120
	s_nop 0
	v_pk_fma_f32 v[166:167], v[120:121], v[162:163], v[158:159]
	v_mul_f32_e32 v120, 0xbfb8aa3b, v122
	v_mul_f32_e32 v121, 0xbfb8aa3b, v123
	v_exp_f32_e32 v120, v120
	v_exp_f32_e32 v121, v121
	v_lshlrev_b32_e32 v158, 16, v165
	v_and_b32_e32 v159, 0xffff0000, v165
	v_lshlrev_b32_e32 v122, 16, v175
	v_pk_add_f32 v[120:121], v[120:121], 1.0 op_sel_hi:[1,0]
	v_and_b32_e32 v123, 0xffff0000, v175
	v_rcp_f32_e32 v121, v121
	v_rcp_f32_e32 v120, v120
	s_nop 0
	v_pk_fma_f32 v[172:173], v[120:121], v[158:159], v[122:123]
	v_cvt_pk_bf16_f32 v120, v124, v125
	v_cvt_pk_bf16_f32 v121, v126, v127
	v_cvt_pk_bf16_f32 v122, v166, v167
	v_cvt_pk_bf16_f32 v123, v172, v173
	global_store_dwordx4 v[156:157], v[120:123], off
	v_pk_mul_f32 v[158:159], v[124:125], v[124:125]
	v_pk_mul_f32 v[162:163], v[126:127], v[126:127]
	global_load_dwordx4 v[120:123], v[156:157], off offset:256
	global_load_dwordx4 v[124:127], v[170:171], off offset:256
	v_pk_mul_f32 v[170:171], v[112:113], v[168:169] op_sel_hi:[1,0]
	v_mul_f32_e32 v112, 0xbfb8aa3b, v116
	v_mul_f32_e32 v113, 0xbfb8aa3b, v117
	v_exp_f32_e32 v112, v112
	v_exp_f32_e32 v113, v113
	v_pk_mul_f32 v[164:165], v[166:167], v[166:167]
	v_pk_mul_f32 v[166:167], v[172:173], v[172:173]
	v_pk_add_f32 v[112:113], v[112:113], 1.0 op_sel_hi:[1,0]
	s_waitcnt vmcnt(1)
	v_lshlrev_b32_e32 v172, 16, v120
	v_and_b32_e32 v173, 0xffff0000, v120
	s_waitcnt vmcnt(0)
	v_lshlrev_b32_e32 v116, 16, v124
	v_and_b32_e32 v117, 0xffff0000, v124
	v_rcp_f32_e32 v113, v113
	v_rcp_f32_e32 v112, v112
	s_nop 0
	v_pk_fma_f32 v[112:113], v[112:113], v[172:173], v[116:117]
	v_mul_f32_e32 v116, 0xbfb8aa3b, v118
	v_mul_f32_e32 v117, 0xbfb8aa3b, v119
	v_exp_f32_e32 v116, v116
	v_exp_f32_e32 v117, v117
	v_lshlrev_b32_e32 v118, 16, v125
	v_and_b32_e32 v119, 0xffff0000, v125
	v_lshlrev_b32_e32 v120, 16, v121
	v_pk_add_f32 v[116:117], v[116:117], 1.0 op_sel_hi:[1,0]
	v_and_b32_e32 v121, 0xffff0000, v121
	v_rcp_f32_e32 v117, v117
	v_rcp_f32_e32 v116, v116
	s_nop 0
	v_pk_fma_f32 v[116:117], v[116:117], v[120:121], v[118:119]
	v_mul_f32_e32 v118, 0xbfb8aa3b, v170
	v_mul_f32_e32 v119, 0xbfb8aa3b, v171
	v_exp_f32_e32 v118, v118
	v_exp_f32_e32 v119, v119
	v_lshlrev_b32_e32 v124, 16, v122
	v_and_b32_e32 v125, 0xffff0000, v122
	v_lshlrev_b32_e32 v120, 16, v126
	v_pk_add_f32 v[118:119], v[118:119], 1.0 op_sel_hi:[1,0]
	v_and_b32_e32 v121, 0xffff0000, v126
	v_rcp_f32_e32 v119, v119
	v_rcp_f32_e32 v118, v118
	s_nop 0
	v_pk_fma_f32 v[124:125], v[118:119], v[124:125], v[120:121]
	v_lshlrev_b32_e32 v120, 16, v123
	v_and_b32_e32 v121, 0xffff0000, v123
	v_lshlrev_b32_e32 v118, 16, v127
	v_and_b32_e32 v119, 0xffff0000, v127
	v_rcp_f32_e32 v115, v115
	v_rcp_f32_e32 v114, v114
	s_nop 0
	v_pk_fma_f32 v[114:115], v[114:115], v[120:121], v[118:119]
	v_cvt_pk_bf16_f32 v118, v112, v113
	v_cvt_pk_bf16_f32 v119, v116, v117
	v_cvt_pk_bf16_f32 v120, v124, v125
	v_cvt_pk_bf16_f32 v121, v114, v115
	global_store_dwordx4 v[156:157], v[118:121], off offset:256
	v_pk_mul_f32 v[114:115], v[114:115], v[114:115]
	v_pk_mul_f32 v[112:113], v[112:113], v[112:113]
	v_pk_mul_f32 v[118:119], v[124:125], v[124:125]
	v_pk_mul_f32 v[116:117], v[116:117], v[116:117]
	v_add_f32_e32 v120, v166, v167
	v_add_f32_e32 v121, v164, v165
	v_add_f32_e32 v114, v114, v115
	v_add_f32_e32 v115, v118, v119
	v_add_f32_e32 v120, v121, v120
	v_add_f32_e32 v121, v162, v163
	v_add_f32_e32 v122, v158, v159
	v_add_f32_e32 v114, v115, v114
	v_add_f32_e32 v115, v116, v117
	v_add_f32_e32 v112, v112, v113
	v_add_f32_e32 v121, v122, v121
	v_add_f32_e32 v112, v112, v115
	v_add_f32_e32 v120, v121, v120
	v_add_f32_e32 v112, v112, v114
	v_add_f32_e32 v112, v120, v112
	ds_bpermute_b32 v113, v169, v112
	s_waitcnt lgkmcnt(0)
	v_add_f32_e32 v112, v112, v113
	ds_bpermute_b32 v113, v155, v112
	s_and_saveexec_b64 s[0:1], s[46:47]
	s_cbranch_execz .LBB0_472
	s_waitcnt lgkmcnt(0)
	v_add_f32_e32 v114, v112, v113
	v_lshlrev_b64 v[112:113], 6, v[142:143]
	v_lshl_add_u64 v[112:113], s[6:7], 0, v[112:113]
	v_lshl_add_u64 v[112:113], s[42:43], 2, v[112:113]
	s_lshl_b32 s94, s35, 2
	v_lshl_add_u64 v[112:113], v[112:113], 0, s[94:95]
	global_store_dword v[112:113], v114, off
; DI unsigned pk2(float lo, float hi) { const f32x2_t v = {lo, hi}; const bf16x2_t b = __builtin_convertvector(v, bf16x2_t); return __builtin_bit_cast(unsigned, b); }
; DI float lo16(unsigned w) { return __uint_as_float(w << 16); }
; DI float hi16(unsigned w) { return __uint_as_float(w & 0xffff0000u); }
;     DI void operator()(const pg8::f32x4 (&acc)[2][2][4][2], const pg8::Unit& u, int wr, int wc, int fr, int fq) const {
;     ...
;             for (int m = 0; m < 4; ++m) {
;                 const int row = row0 + ai * 128 + m * 16; const float r = rs[ai][m];
;                 float part = 0.f;
; #pragma unroll
;                 for (int bj = 0; bj < 2; ++bj) { const size_t off = (size_t)row * 1024 + col0 + bj * 128;
;                     const u32x4 tw = *(const u32x4*)(T + off); const u32x4 xw = *(const u32x4*)(xr + off);
;                     const pg8::f32x4 a0 = acc[ai][bj][m][0] * r, a1 = acc[ai][bj][m][1] * r;
;                     const float o0 = lo16(xw.x) + lo16(tw.x) * __frcp_rn(1.0f + __expf(-a0[0])), o1 = hi16(xw.x) + hi16(tw.x) * __frcp_rn(1.0f + __expf(-a0[1]));
;                     const float o2 = lo16(xw.y) + lo16(tw.y) * __frcp_rn(1.0f + __expf(-a0[2])), o3 = hi16(xw.y) + hi16(tw.y) * __frcp_rn(1.0f + __expf(-a0[3]));
;                     const float o4 = lo16(xw.z) + lo16(tw.z) * __frcp_rn(1.0f + __expf(-a1[0])), o5 = hi16(xw.z) + hi16(tw.z) * __frcp_rn(1.0f + __expf(-a1[1]));
;                     const float o6 = lo16(xw.w) + lo16(tw.w) * __frcp_rn(1.0f + __expf(-a1[2])), o7 = hi16(xw.w) + hi16(tw.w) * __frcp_rn(1.0f + __expf(-a1[3]));
;                     u32x4 w; w.x = pk2(o0, o1); w.y = pk2(o2, o3); w.z = pk2(o4, o5); w.w = pk2(o6, o7); *(u32x4*)(xbo + off) = w;
;                     part += ((o0 * o0 + o1 * o1) + (o2 * o2 + o3 * o3)) + ((o4 * o4 + o5 * o5) + (o6 * o6 + o7 * o7)); }
;                 part += __shfl_xor(part, 16); part += __shfl_xor(part, 32);
;                 if (ssout && fq == 0) ssout[(size_t)row * 16 + u.pn * 4 + wc] = part;
.LBB0_472:
	s_or_b64 exec, exec, s[0:1]
	v_or_b32_e32 v120, 16, v142
	v_ashrrev_i32_e32 v121, 31, v120
	s_waitcnt lgkmcnt(0)
	v_lshlrev_b64 v[112:113], 10, v[120:121]
	v_lshl_add_u64 v[112:113], v[112:113], 0, v[140:141]
	v_lshlrev_b64 v[116:117], 1, v[112:113]
	v_lshl_add_u64 v[122:123], s[18:19], 0, v[116:117]
	global_load_dwordx4 v[112:115], v[122:123], off
	v_lshl_add_u64 v[124:125], s[12:13], 0, v[116:117]
	global_load_dwordx4 v[116:119], v[124:125], off
	v_pk_mul_f32 v[108:109], v[108:109], v[154:155] op_sel_hi:[1,0]
	v_pk_mul_f32 v[126:127], v[104:105], v[154:155] op_sel_hi:[1,0]
	v_mul_f32_e32 v104, 0xbfb8aa3b, v108
	v_mul_f32_e32 v105, 0xbfb8aa3b, v109
	v_exp_f32_e32 v104, v104
	v_exp_f32_e32 v105, v105
	v_pk_mul_f32 v[110:111], v[110:111], v[154:155] op_sel_hi:[1,0]
	v_pk_mul_f32 v[106:107], v[106:107], v[154:155] op_sel_hi:[1,0]
	v_pk_mul_f32 v[100:101], v[100:101], v[154:155] op_sel_hi:[1,0]
	v_pk_add_f32 v[104:105], v[104:105], 1.0 op_sel_hi:[1,0]
	v_mul_f32_e32 v106, 0xbfb8aa3b, v106
	v_mul_f32_e32 v107, 0xbfb8aa3b, v107
	v_exp_f32_e32 v106, v106
	v_exp_f32_e32 v107, v107
	v_pk_mul_f32 v[102:103], v[102:103], v[154:155] op_sel_hi:[1,0]
	v_pk_mul_f32 v[98:99], v[98:99], v[154:155] op_sel_hi:[1,0]
	v_pk_add_f32 v[106:107], v[106:107], 1.0 op_sel_hi:[1,0]
	v_mul_f32_e32 v98, 0xbfb8aa3b, v98
	v_mul_f32_e32 v99, 0xbfb8aa3b, v99
	v_exp_f32_e32 v98, v98
	v_exp_f32_e32 v99, v99
	s_waitcnt vmcnt(1)
	v_lshlrev_b32_e32 v156, 16, v112
	v_and_b32_e32 v157, 0xffff0000, v112
	s_waitcnt vmcnt(0)
	v_lshlrev_b32_e32 v108, 16, v116
	v_and_b32_e32 v109, 0xffff0000, v116
	v_pk_add_f32 v[98:99], v[98:99], 1.0 op_sel_hi:[1,0]
	v_rcp_f32_e32 v105, v105
	v_rcp_f32_e32 v104, v104
	s_nop 0
	v_pk_fma_f32 v[104:105], v[104:105], v[156:157], v[108:109]
	v_mul_f32_e32 v108, 0xbfb8aa3b, v110
	v_mul_f32_e32 v109, 0xbfb8aa3b, v111
	v_exp_f32_e32 v108, v108
	v_exp_f32_e32 v109, v109
	v_lshlrev_b32_e32 v110, 16, v117
	v_and_b32_e32 v111, 0xffff0000, v117
	v_lshlrev_b32_e32 v112, 16, v113
	v_pk_add_f32 v[108:109], v[108:109], 1.0 op_sel_hi:[1,0]
	v_and_b32_e32 v113, 0xffff0000, v113
	v_rcp_f32_e32 v109, v109
	v_rcp_f32_e32 v108, v108
	s_nop 0
	v_pk_fma_f32 v[110:111], v[108:109], v[112:113], v[110:111]
	v_mul_f32_e32 v108, 0xbfb8aa3b, v126
	v_mul_f32_e32 v109, 0xbfb8aa3b, v127
	v_exp_f32_e32 v108, v108
	v_exp_f32_e32 v109, v109
	v_lshlrev_b32_e32 v116, 16, v114
	v_and_b32_e32 v117, 0xffff0000, v114
	v_lshlrev_b32_e32 v112, 16, v118
	v_pk_add_f32 v[108:109], v[108:109], 1.0 op_sel_hi:[1,0]
	v_and_b32_e32 v113, 0xffff0000, v118
	v_rcp_f32_e32 v109, v109
	v_rcp_f32_e32 v108, v108
	s_nop 0
	v_pk_fma_f32 v[116:117], v[108:109], v[116:117], v[112:113]
	v_lshlrev_b32_e32 v112, 16, v115
	v_and_b32_e32 v113, 0xffff0000, v115
	v_lshlrev_b32_e32 v108, 16, v119
	v_and_b32_e32 v109, 0xffff0000, v119
	v_rcp_f32_e32 v107, v107
	v_rcp_f32_e32 v106, v106
	s_nop 0
	v_pk_fma_f32 v[118:119], v[106:107], v[112:113], v[108:109]
	v_cvt_pk_bf16_f32 v106, v104, v105
	v_cvt_pk_bf16_f32 v107, v110, v111
	v_cvt_pk_bf16_f32 v108, v116, v117
	v_cvt_pk_bf16_f32 v109, v118, v119
	global_store_dwordx4 v[122:123], v[106:109], off
	v_pk_mul_f32 v[112:113], v[104:105], v[104:105]
	v_pk_mul_f32 v[114:115], v[110:111], v[110:111]
	global_load_dwordx4 v[104:107], v[122:123], off offset:256
	global_load_dwordx4 v[108:111], v[124:125], off offset:256
	v_pk_mul_f32 v[124:125], v[96:97], v[154:155] op_sel_hi:[1,0]
	v_mul_f32_e32 v96, 0xbfb8aa3b, v100
	v_mul_f32_e32 v97, 0xbfb8aa3b, v101
	v_exp_f32_e32 v96, v96
	v_exp_f32_e32 v97, v97
	v_pk_mul_f32 v[116:117], v[116:117], v[116:117]
	v_pk_mul_f32 v[118:119], v[118:119], v[118:119]
	v_pk_add_f32 v[96:97], v[96:97], 1.0 op_sel_hi:[1,0]
	s_waitcnt vmcnt(1)
	v_lshlrev_b32_e32 v126, 16, v104
	v_and_b32_e32 v127, 0xffff0000, v104
	s_waitcnt vmcnt(0)
	v_lshlrev_b32_e32 v100, 16, v108
	v_and_b32_e32 v101, 0xffff0000, v108
	v_rcp_f32_e32 v97, v97
	v_rcp_f32_e32 v96, v96
	s_nop 0
	v_pk_fma_f32 v[96:97], v[96:97], v[126:127], v[100:101]
	v_mul_f32_e32 v100, 0xbfb8aa3b, v102
	v_mul_f32_e32 v101, 0xbfb8aa3b, v103
	v_exp_f32_e32 v100, v100
	v_exp_f32_e32 v101, v101
	v_lshlrev_b32_e32 v102, 16, v109
	v_and_b32_e32 v103, 0xffff0000, v109
	v_lshlrev_b32_e32 v104, 16, v105
	v_pk_add_f32 v[100:101], v[100:101], 1.0 op_sel_hi:[1,0]
	v_and_b32_e32 v105, 0xffff0000, v105
	v_rcp_f32_e32 v101, v101
	v_rcp_f32_e32 v100, v100
	s_nop 0
	v_pk_fma_f32 v[100:101], v[100:101], v[104:105], v[102:103]
	v_mul_f32_e32 v102, 0xbfb8aa3b, v124
	v_mul_f32_e32 v103, 0xbfb8aa3b, v125
	v_exp_f32_e32 v102, v102
	v_exp_f32_e32 v103, v103
	v_lshlrev_b32_e32 v108, 16, v106
	v_and_b32_e32 v109, 0xffff0000, v106
	v_lshlrev_b32_e32 v104, 16, v110
	v_pk_add_f32 v[102:103], v[102:103], 1.0 op_sel_hi:[1,0]
	v_and_b32_e32 v105, 0xffff0000, v110
	v_rcp_f32_e32 v103, v103
	v_rcp_f32_e32 v102, v102
	s_nop 0
	v_pk_fma_f32 v[108:109], v[102:103], v[108:109], v[104:105]
	v_lshlrev_b32_e32 v104, 16, v107
	v_and_b32_e32 v105, 0xffff0000, v107
	v_lshlrev_b32_e32 v102, 16, v111
	v_and_b32_e32 v103, 0xffff0000, v111
	v_rcp_f32_e32 v99, v99
	v_rcp_f32_e32 v98, v98
	s_nop 0
	v_pk_fma_f32 v[98:99], v[98:99], v[104:105], v[102:103]
	v_cvt_pk_bf16_f32 v102, v96, v97
	v_cvt_pk_bf16_f32 v103, v100, v101
	v_cvt_pk_bf16_f32 v104, v108, v109
	v_cvt_pk_bf16_f32 v105, v98, v99
	global_store_dwordx4 v[122:123], v[102:105], off offset:256
	v_pk_mul_f32 v[98:99], v[98:99], v[98:99]
	v_pk_mul_f32 v[96:97], v[96:97], v[96:97]
	v_pk_mul_f32 v[102:103], v[108:109], v[108:109]
	v_pk_mul_f32 v[100:101], v[100:101], v[100:101]
	v_add_f32_e32 v104, v118, v119
	v_add_f32_e32 v105, v116, v117
	v_add_f32_e32 v98, v98, v99
	v_add_f32_e32 v99, v102, v103
	v_add_f32_e32 v104, v105, v104
	v_add_f32_e32 v105, v114, v115
	v_add_f32_e32 v106, v112, v113
	v_add_f32_e32 v98, v99, v98
	v_add_f32_e32 v99, v100, v101
	v_add_f32_e32 v96, v96, v97
	v_add_f32_e32 v105, v106, v105
	v_add_f32_e32 v96, v96, v99
	v_add_f32_e32 v104, v105, v104
	v_add_f32_e32 v96, v96, v98
	v_add_f32_e32 v96, v104, v96
	ds_bpermute_b32 v97, v169, v96
	s_waitcnt lgkmcnt(0)
	v_add_f32_e32 v96, v96, v97
	ds_bpermute_b32 v97, v155, v96
	s_and_saveexec_b64 s[0:1], s[46:47]
	s_cbranch_execz .LBB0_474
	s_waitcnt lgkmcnt(0)
	v_add_f32_e32 v98, v96, v97
	v_lshlrev_b64 v[96:97], 6, v[120:121]
	v_lshl_add_u64 v[96:97], s[6:7], 0, v[96:97]
	v_lshl_add_u64 v[96:97], s[42:43], 2, v[96:97]
	s_lshl_b32 s94, s35, 2
	v_lshl_add_u64 v[96:97], v[96:97], 0, s[94:95]
	global_store_dword v[96:97], v98, off
; DI unsigned pk2(float lo, float hi) { const f32x2_t v = {lo, hi}; const bf16x2_t b = __builtin_convertvector(v, bf16x2_t); return __builtin_bit_cast(unsigned, b); }
; DI float lo16(unsigned w) { return __uint_as_float(w << 16); }
; DI float hi16(unsigned w) { return __uint_as_float(w & 0xffff0000u); }
;     DI void operator()(const pg8::f32x4 (&acc)[2][2][4][2], const pg8::Unit& u, int wr, int wc, int fr, int fq) const {
;     ...
;             for (int m = 0; m < 4; ++m) {
;                 const int row = row0 + ai * 128 + m * 16; const float r = rs[ai][m];
;                 float part = 0.f;
; #pragma unroll
;                 for (int bj = 0; bj < 2; ++bj) { const size_t off = (size_t)row * 1024 + col0 + bj * 128;
;                     const u32x4 tw = *(const u32x4*)(T + off); const u32x4 xw = *(const u32x4*)(xr + off);
;                     const pg8::f32x4 a0 = acc[ai][bj][m][0] * r, a1 = acc[ai][bj][m][1] * r;
;                     const float o0 = lo16(xw.x) + lo16(tw.x) * __frcp_rn(1.0f + __expf(-a0[0])), o1 = hi16(xw.x) + hi16(tw.x) * __frcp_rn(1.0f + __expf(-a0[1]));
;                     const float o2 = lo16(xw.y) + lo16(tw.y) * __frcp_rn(1.0f + __expf(-a0[2])), o3 = hi16(xw.y) + hi16(tw.y) * __frcp_rn(1.0f + __expf(-a0[3]));
;                     const float o4 = lo16(xw.z) + lo16(tw.z) * __frcp_rn(1.0f + __expf(-a1[0])), o5 = hi16(xw.z) + hi16(tw.z) * __frcp_rn(1.0f + __expf(-a1[1]));
;                     const float o6 = lo16(xw.w) + lo16(tw.w) * __frcp_rn(1.0f + __expf(-a1[2])), o7 = hi16(xw.w) + hi16(tw.w) * __frcp_rn(1.0f + __expf(-a1[3]));
;                     u32x4 w; w.x = pk2(o0, o1); w.y = pk2(o2, o3); w.z = pk2(o4, o5); w.w = pk2(o6, o7); *(u32x4*)(xbo + off) = w;
;                     part += ((o0 * o0 + o1 * o1) + (o2 * o2 + o3 * o3)) + ((o4 * o4 + o5 * o5) + (o6 * o6 + o7 * o7)); }
;                 part += __shfl_xor(part, 16); part += __shfl_xor(part, 32);
;                 if (ssout && fq == 0) ssout[(size_t)row * 16 + u.pn * 4 + wc] = part;
.LBB0_474:
	s_or_b64 exec, exec, s[0:1]
	v_or_b32_e32 v104, 32, v142
	v_ashrrev_i32_e32 v105, 31, v104
	s_waitcnt lgkmcnt(0)
	v_lshlrev_b64 v[96:97], 10, v[104:105]
	v_lshl_add_u64 v[96:97], v[96:97], 0, v[140:141]
	v_lshlrev_b64 v[100:101], 1, v[96:97]
	v_lshl_add_u64 v[106:107], s[18:19], 0, v[100:101]
	global_load_dwordx4 v[96:99], v[106:107], off
	v_lshl_add_u64 v[108:109], s[12:13], 0, v[100:101]
	global_load_dwordx4 v[100:103], v[108:109], off
	v_pk_mul_f32 v[92:93], v[92:93], v[152:153] op_sel_hi:[1,0]
	v_pk_mul_f32 v[110:111], v[88:89], v[152:153] op_sel_hi:[1,0]
	v_mul_f32_e32 v88, 0xbfb8aa3b, v92
	v_mul_f32_e32 v89, 0xbfb8aa3b, v93
	v_exp_f32_e32 v88, v88
	v_exp_f32_e32 v89, v89
	v_pk_mul_f32 v[94:95], v[94:95], v[152:153] op_sel_hi:[1,0]
	v_pk_mul_f32 v[90:91], v[90:91], v[152:153] op_sel_hi:[1,0]
	v_pk_mul_f32 v[84:85], v[84:85], v[152:153] op_sel_hi:[1,0]
	v_pk_add_f32 v[88:89], v[88:89], 1.0 op_sel_hi:[1,0]
	v_mul_f32_e32 v90, 0xbfb8aa3b, v90
	v_mul_f32_e32 v91, 0xbfb8aa3b, v91
	v_exp_f32_e32 v90, v90
	v_exp_f32_e32 v91, v91
	v_pk_mul_f32 v[86:87], v[86:87], v[152:153] op_sel_hi:[1,0]
	v_pk_mul_f32 v[82:83], v[82:83], v[152:153] op_sel_hi:[1,0]
	v_pk_add_f32 v[90:91], v[90:91], 1.0 op_sel_hi:[1,0]
	v_mul_f32_e32 v82, 0xbfb8aa3b, v82
	v_mul_f32_e32 v83, 0xbfb8aa3b, v83
	v_exp_f32_e32 v82, v82
	v_exp_f32_e32 v83, v83
	s_waitcnt vmcnt(1)
	v_lshlrev_b32_e32 v112, 16, v96
	v_and_b32_e32 v113, 0xffff0000, v96
	s_waitcnt vmcnt(0)
	v_lshlrev_b32_e32 v92, 16, v100
	v_and_b32_e32 v93, 0xffff0000, v100
	v_pk_add_f32 v[82:83], v[82:83], 1.0 op_sel_hi:[1,0]
	v_rcp_f32_e32 v89, v89
	v_rcp_f32_e32 v88, v88
	s_nop 0
	v_pk_fma_f32 v[88:89], v[88:89], v[112:113], v[92:93]
	v_mul_f32_e32 v92, 0xbfb8aa3b, v94
	v_mul_f32_e32 v93, 0xbfb8aa3b, v95
	v_exp_f32_e32 v92, v92
	v_exp_f32_e32 v93, v93
	v_lshlrev_b32_e32 v94, 16, v101
	v_and_b32_e32 v95, 0xffff0000, v101
	v_lshlrev_b32_e32 v96, 16, v97
	v_pk_add_f32 v[92:93], v[92:93], 1.0 op_sel_hi:[1,0]
	v_and_b32_e32 v97, 0xffff0000, v97
	v_rcp_f32_e32 v93, v93
	v_rcp_f32_e32 v92, v92
	s_nop 0
	v_pk_fma_f32 v[94:95], v[92:93], v[96:97], v[94:95]
	v_mul_f32_e32 v92, 0xbfb8aa3b, v110
	v_mul_f32_e32 v93, 0xbfb8aa3b, v111
	v_exp_f32_e32 v92, v92
	v_exp_f32_e32 v93, v93
	v_lshlrev_b32_e32 v100, 16, v98
	v_and_b32_e32 v101, 0xffff0000, v98
	v_lshlrev_b32_e32 v96, 16, v102
	v_pk_add_f32 v[92:93], v[92:93], 1.0 op_sel_hi:[1,0]
	v_and_b32_e32 v97, 0xffff0000, v102
	v_rcp_f32_e32 v93, v93
	v_rcp_f32_e32 v92, v92
	s_nop 0
	v_pk_fma_f32 v[100:101], v[92:93], v[100:101], v[96:97]
	v_lshlrev_b32_e32 v96, 16, v99
	v_and_b32_e32 v97, 0xffff0000, v99
	v_lshlrev_b32_e32 v92, 16, v103
	v_and_b32_e32 v93, 0xffff0000, v103
	v_rcp_f32_e32 v91, v91
	v_rcp_f32_e32 v90, v90
	s_nop 0
	v_pk_fma_f32 v[102:103], v[90:91], v[96:97], v[92:93]
	v_cvt_pk_bf16_f32 v90, v88, v89
	v_cvt_pk_bf16_f32 v91, v94, v95
	v_cvt_pk_bf16_f32 v92, v100, v101
	v_cvt_pk_bf16_f32 v93, v102, v103
	global_store_dwordx4 v[106:107], v[90:93], off
	v_pk_mul_f32 v[96:97], v[88:89], v[88:89]
	v_pk_mul_f32 v[98:99], v[94:95], v[94:95]
	global_load_dwordx4 v[88:91], v[106:107], off offset:256
	global_load_dwordx4 v[92:95], v[108:109], off offset:256
	v_pk_mul_f32 v[108:109], v[80:81], v[152:153] op_sel_hi:[1,0]
	v_mul_f32_e32 v80, 0xbfb8aa3b, v84
	v_mul_f32_e32 v81, 0xbfb8aa3b, v85
	v_exp_f32_e32 v80, v80
	v_exp_f32_e32 v81, v81
	v_pk_mul_f32 v[100:101], v[100:101], v[100:101]
	v_pk_mul_f32 v[102:103], v[102:103], v[102:103]
	v_pk_add_f32 v[80:81], v[80:81], 1.0 op_sel_hi:[1,0]
	s_waitcnt vmcnt(1)
	v_lshlrev_b32_e32 v110, 16, v88
	v_and_b32_e32 v111, 0xffff0000, v88
	s_waitcnt vmcnt(0)
	v_lshlrev_b32_e32 v84, 16, v92
	v_and_b32_e32 v85, 0xffff0000, v92
	v_rcp_f32_e32 v81, v81
	v_rcp_f32_e32 v80, v80
	s_nop 0
	v_pk_fma_f32 v[80:81], v[80:81], v[110:111], v[84:85]
	v_mul_f32_e32 v84, 0xbfb8aa3b, v86
	v_mul_f32_e32 v85, 0xbfb8aa3b, v87
	v_exp_f32_e32 v84, v84
	v_exp_f32_e32 v85, v85
	v_lshlrev_b32_e32 v86, 16, v93
	v_and_b32_e32 v87, 0xffff0000, v93
	v_lshlrev_b32_e32 v88, 16, v89
	v_pk_add_f32 v[84:85], v[84:85], 1.0 op_sel_hi:[1,0]
	v_and_b32_e32 v89, 0xffff0000, v89
	v_rcp_f32_e32 v85, v85
	v_rcp_f32_e32 v84, v84
	s_nop 0
	v_pk_fma_f32 v[84:85], v[84:85], v[88:89], v[86:87]
	v_mul_f32_e32 v86, 0xbfb8aa3b, v108
	v_mul_f32_e32 v87, 0xbfb8aa3b, v109
	v_exp_f32_e32 v86, v86
	v_exp_f32_e32 v87, v87
	v_lshlrev_b32_e32 v92, 16, v90
	v_and_b32_e32 v93, 0xffff0000, v90
	v_lshlrev_b32_e32 v88, 16, v94
	v_pk_add_f32 v[86:87], v[86:87], 1.0 op_sel_hi:[1,0]
	v_and_b32_e32 v89, 0xffff0000, v94
	v_rcp_f32_e32 v87, v87
	v_rcp_f32_e32 v86, v86
	s_nop 0
	v_pk_fma_f32 v[92:93], v[86:87], v[92:93], v[88:89]
	v_lshlrev_b32_e32 v88, 16, v91
	v_and_b32_e32 v89, 0xffff0000, v91
	v_lshlrev_b32_e32 v86, 16, v95
	v_and_b32_e32 v87, 0xffff0000, v95
	v_rcp_f32_e32 v83, v83
	v_rcp_f32_e32 v82, v82
	s_nop 0
	v_pk_fma_f32 v[82:83], v[82:83], v[88:89], v[86:87]
	v_cvt_pk_bf16_f32 v86, v80, v81
	v_cvt_pk_bf16_f32 v87, v84, v85
	v_cvt_pk_bf16_f32 v88, v92, v93
	v_cvt_pk_bf16_f32 v89, v82, v83
	global_store_dwordx4 v[106:107], v[86:89], off offset:256
	v_pk_mul_f32 v[82:83], v[82:83], v[82:83]
	v_pk_mul_f32 v[80:81], v[80:81], v[80:81]
	v_pk_mul_f32 v[86:87], v[92:93], v[92:93]
	v_pk_mul_f32 v[84:85], v[84:85], v[84:85]
	v_add_f32_e32 v88, v102, v103
	v_add_f32_e32 v89, v100, v101
	v_add_f32_e32 v82, v82, v83
	v_add_f32_e32 v83, v86, v87
	v_add_f32_e32 v88, v89, v88
	v_add_f32_e32 v89, v98, v99
	v_add_f32_e32 v90, v96, v97
	v_add_f32_e32 v82, v83, v82
	v_add_f32_e32 v83, v84, v85
	v_add_f32_e32 v80, v80, v81
	v_add_f32_e32 v89, v90, v89
	v_add_f32_e32 v80, v80, v83
	v_add_f32_e32 v88, v89, v88
	v_add_f32_e32 v80, v80, v82
	v_add_f32_e32 v80, v88, v80
	ds_bpermute_b32 v81, v169, v80
	s_waitcnt lgkmcnt(0)
	v_add_f32_e32 v80, v80, v81
	ds_bpermute_b32 v81, v155, v80
	s_and_saveexec_b64 s[0:1], s[46:47]
	s_cbranch_execz .LBB0_476
	s_waitcnt lgkmcnt(0)
	v_add_f32_e32 v82, v80, v81
	v_lshlrev_b64 v[80:81], 6, v[104:105]
	v_lshl_add_u64 v[80:81], s[6:7], 0, v[80:81]
	v_lshl_add_u64 v[80:81], s[42:43], 2, v[80:81]
	s_lshl_b32 s94, s35, 2
	v_lshl_add_u64 v[80:81], v[80:81], 0, s[94:95]
	global_store_dword v[80:81], v82, off
; DI unsigned pk2(float lo, float hi) { const f32x2_t v = {lo, hi}; const bf16x2_t b = __builtin_convertvector(v, bf16x2_t); return __builtin_bit_cast(unsigned, b); }
; DI float lo16(unsigned w) { return __uint_as_float(w << 16); }
; DI float hi16(unsigned w) { return __uint_as_float(w & 0xffff0000u); }
;     DI void operator()(const pg8::f32x4 (&acc)[2][2][4][2], const pg8::Unit& u, int wr, int wc, int fr, int fq) const {
;     ...
;             for (int m = 0; m < 4; ++m) {
;                 const int row = row0 + ai * 128 + m * 16; const float r = rs[ai][m];
;                 float part = 0.f;
; #pragma unroll
;                 for (int bj = 0; bj < 2; ++bj) { const size_t off = (size_t)row * 1024 + col0 + bj * 128;
;                     const u32x4 tw = *(const u32x4*)(T + off); const u32x4 xw = *(const u32x4*)(xr + off);
;                     const pg8::f32x4 a0 = acc[ai][bj][m][0] * r, a1 = acc[ai][bj][m][1] * r;
;                     const float o0 = lo16(xw.x) + lo16(tw.x) * __frcp_rn(1.0f + __expf(-a0[0])), o1 = hi16(xw.x) + hi16(tw.x) * __frcp_rn(1.0f + __expf(-a0[1]));
;                     const float o2 = lo16(xw.y) + lo16(tw.y) * __frcp_rn(1.0f + __expf(-a0[2])), o3 = hi16(xw.y) + hi16(tw.y) * __frcp_rn(1.0f + __expf(-a0[3]));
;                     const float o4 = lo16(xw.z) + lo16(tw.z) * __frcp_rn(1.0f + __expf(-a1[0])), o5 = hi16(xw.z) + hi16(tw.z) * __frcp_rn(1.0f + __expf(-a1[1]));
;                     const float o6 = lo16(xw.w) + lo16(tw.w) * __frcp_rn(1.0f + __expf(-a1[2])), o7 = hi16(xw.w) + hi16(tw.w) * __frcp_rn(1.0f + __expf(-a1[3]));
;                     u32x4 w; w.x = pk2(o0, o1); w.y = pk2(o2, o3); w.z = pk2(o4, o5); w.w = pk2(o6, o7); *(u32x4*)(xbo + off) = w;
;                     part += ((o0 * o0 + o1 * o1) + (o2 * o2 + o3 * o3)) + ((o4 * o4 + o5 * o5) + (o6 * o6 + o7 * o7)); }
;                 part += __shfl_xor(part, 16); part += __shfl_xor(part, 32);
;                 if (ssout && fq == 0) ssout[(size_t)row * 16 + u.pn * 4 + wc] = part;
.LBB0_476:
	s_or_b64 exec, exec, s[0:1]
	v_or_b32_e32 v88, 48, v142
	v_ashrrev_i32_e32 v89, 31, v88
	s_waitcnt lgkmcnt(0)
	v_lshlrev_b64 v[80:81], 10, v[88:89]
	v_lshl_add_u64 v[80:81], v[80:81], 0, v[140:141]
	v_lshlrev_b64 v[84:85], 1, v[80:81]
	v_lshl_add_u64 v[90:91], s[18:19], 0, v[84:85]
	global_load_dwordx4 v[80:83], v[90:91], off
	v_lshl_add_u64 v[92:93], s[12:13], 0, v[84:85]
	global_load_dwordx4 v[84:87], v[92:93], off
	v_pk_mul_f32 v[76:77], v[76:77], v[150:151] op_sel_hi:[1,0]
	v_pk_mul_f32 v[94:95], v[72:73], v[150:151] op_sel_hi:[1,0]
	v_mul_f32_e32 v72, 0xbfb8aa3b, v76
	v_mul_f32_e32 v73, 0xbfb8aa3b, v77
	v_exp_f32_e32 v72, v72
	v_exp_f32_e32 v73, v73
	v_pk_mul_f32 v[78:79], v[78:79], v[150:151] op_sel_hi:[1,0]
	v_pk_mul_f32 v[74:75], v[74:75], v[150:151] op_sel_hi:[1,0]
	v_pk_mul_f32 v[68:69], v[68:69], v[150:151] op_sel_hi:[1,0]
	v_pk_add_f32 v[72:73], v[72:73], 1.0 op_sel_hi:[1,0]
	v_mul_f32_e32 v74, 0xbfb8aa3b, v74
	v_mul_f32_e32 v75, 0xbfb8aa3b, v75
	v_exp_f32_e32 v74, v74
	v_exp_f32_e32 v75, v75
	v_pk_mul_f32 v[70:71], v[70:71], v[150:151] op_sel_hi:[1,0]
	v_pk_mul_f32 v[66:67], v[66:67], v[150:151] op_sel_hi:[1,0]
	v_pk_add_f32 v[74:75], v[74:75], 1.0 op_sel_hi:[1,0]
	v_mul_f32_e32 v66, 0xbfb8aa3b, v66
	v_mul_f32_e32 v67, 0xbfb8aa3b, v67
	v_exp_f32_e32 v66, v66
	v_exp_f32_e32 v67, v67
	s_waitcnt vmcnt(1)
	v_lshlrev_b32_e32 v96, 16, v80
	v_and_b32_e32 v97, 0xffff0000, v80
	s_waitcnt vmcnt(0)
	v_lshlrev_b32_e32 v76, 16, v84
	v_and_b32_e32 v77, 0xffff0000, v84
	v_pk_add_f32 v[66:67], v[66:67], 1.0 op_sel_hi:[1,0]
	v_rcp_f32_e32 v73, v73
	v_rcp_f32_e32 v72, v72
	s_nop 0
	v_pk_fma_f32 v[72:73], v[72:73], v[96:97], v[76:77]
	v_mul_f32_e32 v76, 0xbfb8aa3b, v78
	v_mul_f32_e32 v77, 0xbfb8aa3b, v79
	v_exp_f32_e32 v76, v76
	v_exp_f32_e32 v77, v77
	v_lshlrev_b32_e32 v78, 16, v85
	v_and_b32_e32 v79, 0xffff0000, v85
	v_lshlrev_b32_e32 v80, 16, v81
	v_pk_add_f32 v[76:77], v[76:77], 1.0 op_sel_hi:[1,0]
	v_and_b32_e32 v81, 0xffff0000, v81
	v_rcp_f32_e32 v77, v77
	v_rcp_f32_e32 v76, v76
	s_nop 0
	v_pk_fma_f32 v[78:79], v[76:77], v[80:81], v[78:79]
	v_mul_f32_e32 v76, 0xbfb8aa3b, v94
	v_mul_f32_e32 v77, 0xbfb8aa3b, v95
	v_exp_f32_e32 v76, v76
	v_exp_f32_e32 v77, v77
	v_lshlrev_b32_e32 v84, 16, v82
	v_and_b32_e32 v85, 0xffff0000, v82
	v_lshlrev_b32_e32 v80, 16, v86
	v_pk_add_f32 v[76:77], v[76:77], 1.0 op_sel_hi:[1,0]
	v_and_b32_e32 v81, 0xffff0000, v86
	v_rcp_f32_e32 v77, v77
	v_rcp_f32_e32 v76, v76
	s_nop 0
	v_pk_fma_f32 v[84:85], v[76:77], v[84:85], v[80:81]
	v_lshlrev_b32_e32 v80, 16, v83
	v_and_b32_e32 v81, 0xffff0000, v83
	v_lshlrev_b32_e32 v76, 16, v87
	v_and_b32_e32 v77, 0xffff0000, v87
	v_rcp_f32_e32 v75, v75
	v_rcp_f32_e32 v74, v74
	s_nop 0
	v_pk_fma_f32 v[86:87], v[74:75], v[80:81], v[76:77]
	v_cvt_pk_bf16_f32 v74, v72, v73
	v_cvt_pk_bf16_f32 v75, v78, v79
	v_cvt_pk_bf16_f32 v76, v84, v85
	v_cvt_pk_bf16_f32 v77, v86, v87
	global_store_dwordx4 v[90:91], v[74:77], off
	v_pk_mul_f32 v[80:81], v[72:73], v[72:73]
	v_pk_mul_f32 v[82:83], v[78:79], v[78:79]
	global_load_dwordx4 v[72:75], v[90:91], off offset:256
	global_load_dwordx4 v[76:79], v[92:93], off offset:256
	v_pk_mul_f32 v[92:93], v[64:65], v[150:151] op_sel_hi:[1,0]
	v_mul_f32_e32 v64, 0xbfb8aa3b, v68
	v_mul_f32_e32 v65, 0xbfb8aa3b, v69
	v_exp_f32_e32 v64, v64
	v_exp_f32_e32 v65, v65
	v_pk_mul_f32 v[84:85], v[84:85], v[84:85]
	v_pk_mul_f32 v[86:87], v[86:87], v[86:87]
	v_pk_add_f32 v[64:65], v[64:65], 1.0 op_sel_hi:[1,0]
	s_waitcnt vmcnt(1)
	v_lshlrev_b32_e32 v94, 16, v72
	v_and_b32_e32 v95, 0xffff0000, v72
	s_waitcnt vmcnt(0)
	v_lshlrev_b32_e32 v68, 16, v76
	v_and_b32_e32 v69, 0xffff0000, v76
	v_rcp_f32_e32 v65, v65
	v_rcp_f32_e32 v64, v64
	s_nop 0
	v_pk_fma_f32 v[64:65], v[64:65], v[94:95], v[68:69]
	v_mul_f32_e32 v68, 0xbfb8aa3b, v70
	v_mul_f32_e32 v69, 0xbfb8aa3b, v71
	v_exp_f32_e32 v68, v68
	v_exp_f32_e32 v69, v69
	v_lshlrev_b32_e32 v70, 16, v77
	v_and_b32_e32 v71, 0xffff0000, v77
	v_lshlrev_b32_e32 v72, 16, v73
	v_pk_add_f32 v[68:69], v[68:69], 1.0 op_sel_hi:[1,0]
	v_and_b32_e32 v73, 0xffff0000, v73
	v_rcp_f32_e32 v69, v69
	v_rcp_f32_e32 v68, v68
	s_nop 0
	v_pk_fma_f32 v[68:69], v[68:69], v[72:73], v[70:71]
	v_mul_f32_e32 v70, 0xbfb8aa3b, v92
	v_mul_f32_e32 v71, 0xbfb8aa3b, v93
	v_exp_f32_e32 v70, v70
	v_exp_f32_e32 v71, v71
	v_lshlrev_b32_e32 v76, 16, v74
	v_and_b32_e32 v77, 0xffff0000, v74
	v_lshlrev_b32_e32 v72, 16, v78
	v_pk_add_f32 v[70:71], v[70:71], 1.0 op_sel_hi:[1,0]
	v_and_b32_e32 v73, 0xffff0000, v78
	v_rcp_f32_e32 v71, v71
	v_rcp_f32_e32 v70, v70
	s_nop 0
	v_pk_fma_f32 v[76:77], v[70:71], v[76:77], v[72:73]
	v_lshlrev_b32_e32 v72, 16, v75
	v_and_b32_e32 v73, 0xffff0000, v75
	v_lshlrev_b32_e32 v70, 16, v79
	v_and_b32_e32 v71, 0xffff0000, v79
	v_rcp_f32_e32 v67, v67
	v_rcp_f32_e32 v66, v66
	s_nop 0
	v_pk_fma_f32 v[66:67], v[66:67], v[72:73], v[70:71]
	v_cvt_pk_bf16_f32 v70, v64, v65
	v_cvt_pk_bf16_f32 v71, v68, v69
	v_cvt_pk_bf16_f32 v72, v76, v77
	v_cvt_pk_bf16_f32 v73, v66, v67
	global_store_dwordx4 v[90:91], v[70:73], off offset:256
	v_pk_mul_f32 v[66:67], v[66:67], v[66:67]
	v_pk_mul_f32 v[64:65], v[64:65], v[64:65]
	v_pk_mul_f32 v[70:71], v[76:77], v[76:77]
	v_pk_mul_f32 v[68:69], v[68:69], v[68:69]
	v_add_f32_e32 v72, v86, v87
	v_add_f32_e32 v73, v84, v85
	v_add_f32_e32 v66, v66, v67
	v_add_f32_e32 v67, v70, v71
	v_add_f32_e32 v72, v73, v72
	v_add_f32_e32 v73, v82, v83
	v_add_f32_e32 v74, v80, v81
	v_add_f32_e32 v66, v67, v66
	v_add_f32_e32 v67, v68, v69
	v_add_f32_e32 v64, v64, v65
	v_add_f32_e32 v73, v74, v73
	v_add_f32_e32 v64, v64, v67
	v_add_f32_e32 v72, v73, v72
	v_add_f32_e32 v64, v64, v66
	v_add_f32_e32 v64, v72, v64
	ds_bpermute_b32 v65, v169, v64
	s_waitcnt lgkmcnt(0)
	v_add_f32_e32 v64, v64, v65
	ds_bpermute_b32 v65, v155, v64
	s_and_saveexec_b64 s[0:1], s[46:47]
	s_cbranch_execz .LBB0_478
	s_waitcnt lgkmcnt(0)
	v_add_f32_e32 v66, v64, v65
	v_lshlrev_b64 v[64:65], 6, v[88:89]
	v_lshl_add_u64 v[64:65], s[6:7], 0, v[64:65]
	v_lshl_add_u64 v[64:65], s[42:43], 2, v[64:65]
	s_lshl_b32 s94, s35, 2
	v_lshl_add_u64 v[64:65], v[64:65], 0, s[94:95]
	global_store_dword v[64:65], v66, off
; DI unsigned pk2(float lo, float hi) { const f32x2_t v = {lo, hi}; const bf16x2_t b = __builtin_convertvector(v, bf16x2_t); return __builtin_bit_cast(unsigned, b); }
; DI float lo16(unsigned w) { return __uint_as_float(w << 16); }
; DI float hi16(unsigned w) { return __uint_as_float(w & 0xffff0000u); }
;     DI void operator()(const pg8::f32x4 (&acc)[2][2][4][2], const pg8::Unit& u, int wr, int wc, int fr, int fq) const {
;     ...
;             for (int m = 0; m < 4; ++m) {
;                 const int row = row0 + ai * 128 + m * 16; const float r = rs[ai][m];
;                 float part = 0.f;
; #pragma unroll
;                 for (int bj = 0; bj < 2; ++bj) { const size_t off = (size_t)row * 1024 + col0 + bj * 128;
;                     const u32x4 tw = *(const u32x4*)(T + off); const u32x4 xw = *(const u32x4*)(xr + off);
;                     const pg8::f32x4 a0 = acc[ai][bj][m][0] * r, a1 = acc[ai][bj][m][1] * r;
;                     const float o0 = lo16(xw.x) + lo16(tw.x) * __frcp_rn(1.0f + __expf(-a0[0])), o1 = hi16(xw.x) + hi16(tw.x) * __frcp_rn(1.0f + __expf(-a0[1]));
;                     const float o2 = lo16(xw.y) + lo16(tw.y) * __frcp_rn(1.0f + __expf(-a0[2])), o3 = hi16(xw.y) + hi16(tw.y) * __frcp_rn(1.0f + __expf(-a0[3]));
;                     const float o4 = lo16(xw.z) + lo16(tw.z) * __frcp_rn(1.0f + __expf(-a1[0])), o5 = hi16(xw.z) + hi16(tw.z) * __frcp_rn(1.0f + __expf(-a1[1]));
;                     const float o6 = lo16(xw.w) + lo16(tw.w) * __frcp_rn(1.0f + __expf(-a1[2])), o7 = hi16(xw.w) + hi16(tw.w) * __frcp_rn(1.0f + __expf(-a1[3]));
;                     u32x4 w; w.x = pk2(o0, o1); w.y = pk2(o2, o3); w.z = pk2(o4, o5); w.w = pk2(o6, o7); *(u32x4*)(xbo + off) = w;
;                     part += ((o0 * o0 + o1 * o1) + (o2 * o2 + o3 * o3)) + ((o4 * o4 + o5 * o5) + (o6 * o6 + o7 * o7)); }
;                 part += __shfl_xor(part, 16); part += __shfl_xor(part, 32);
;                 if (ssout && fq == 0) ssout[(size_t)row * 16 + u.pn * 4 + wc] = part;
.LBB0_478:
	s_or_b64 exec, exec, s[0:1]
	v_add_u32_e32 v72, 0x80, v142
	v_ashrrev_i32_e32 v73, 31, v72
	s_waitcnt lgkmcnt(0)
	v_lshlrev_b64 v[64:65], 10, v[72:73]
	v_lshl_add_u64 v[64:65], v[64:65], 0, v[140:141]
	v_lshlrev_b64 v[68:69], 1, v[64:65]
	v_lshl_add_u64 v[74:75], s[18:19], 0, v[68:69]
	global_load_dwordx4 v[64:67], v[74:75], off
	v_lshl_add_u64 v[76:77], s[12:13], 0, v[68:69]
	global_load_dwordx4 v[68:71], v[76:77], off
	v_pk_mul_f32 v[60:61], v[60:61], v[148:149] op_sel_hi:[1,0]
	v_pk_mul_f32 v[78:79], v[56:57], v[148:149] op_sel_hi:[1,0]
	v_mul_f32_e32 v56, 0xbfb8aa3b, v60
	v_mul_f32_e32 v57, 0xbfb8aa3b, v61
	v_exp_f32_e32 v56, v56
	v_exp_f32_e32 v57, v57
	v_pk_mul_f32 v[62:63], v[62:63], v[148:149] op_sel_hi:[1,0]
	v_pk_mul_f32 v[58:59], v[58:59], v[148:149] op_sel_hi:[1,0]
	v_pk_mul_f32 v[52:53], v[52:53], v[148:149] op_sel_hi:[1,0]
	v_pk_add_f32 v[56:57], v[56:57], 1.0 op_sel_hi:[1,0]
	v_mul_f32_e32 v58, 0xbfb8aa3b, v58
	v_mul_f32_e32 v59, 0xbfb8aa3b, v59
	v_exp_f32_e32 v58, v58
	v_exp_f32_e32 v59, v59
	v_pk_mul_f32 v[54:55], v[54:55], v[148:149] op_sel_hi:[1,0]
	v_pk_mul_f32 v[50:51], v[50:51], v[148:149] op_sel_hi:[1,0]
	v_pk_add_f32 v[58:59], v[58:59], 1.0 op_sel_hi:[1,0]
	v_mul_f32_e32 v50, 0xbfb8aa3b, v50
	v_mul_f32_e32 v51, 0xbfb8aa3b, v51
	v_exp_f32_e32 v50, v50
	v_exp_f32_e32 v51, v51
	s_waitcnt vmcnt(1)
	v_lshlrev_b32_e32 v80, 16, v64
	v_and_b32_e32 v81, 0xffff0000, v64
	s_waitcnt vmcnt(0)
	v_lshlrev_b32_e32 v60, 16, v68
	v_and_b32_e32 v61, 0xffff0000, v68
	v_pk_add_f32 v[50:51], v[50:51], 1.0 op_sel_hi:[1,0]
	v_rcp_f32_e32 v57, v57
	v_rcp_f32_e32 v56, v56
	s_nop 0
	v_pk_fma_f32 v[56:57], v[56:57], v[80:81], v[60:61]
	v_mul_f32_e32 v60, 0xbfb8aa3b, v62
	v_mul_f32_e32 v61, 0xbfb8aa3b, v63
	v_exp_f32_e32 v60, v60
	v_exp_f32_e32 v61, v61
	v_lshlrev_b32_e32 v62, 16, v69
	v_and_b32_e32 v63, 0xffff0000, v69
	v_lshlrev_b32_e32 v64, 16, v65
	v_pk_add_f32 v[60:61], v[60:61], 1.0 op_sel_hi:[1,0]
	v_and_b32_e32 v65, 0xffff0000, v65
	v_rcp_f32_e32 v61, v61
	v_rcp_f32_e32 v60, v60
	s_nop 0
	v_pk_fma_f32 v[62:63], v[60:61], v[64:65], v[62:63]
	v_mul_f32_e32 v60, 0xbfb8aa3b, v78
	v_mul_f32_e32 v61, 0xbfb8aa3b, v79
	v_exp_f32_e32 v60, v60
	v_exp_f32_e32 v61, v61
	v_lshlrev_b32_e32 v68, 16, v66
	v_and_b32_e32 v69, 0xffff0000, v66
	v_lshlrev_b32_e32 v64, 16, v70
	v_pk_add_f32 v[60:61], v[60:61], 1.0 op_sel_hi:[1,0]
	v_and_b32_e32 v65, 0xffff0000, v70
	v_rcp_f32_e32 v61, v61
	v_rcp_f32_e32 v60, v60
	s_nop 0
	v_pk_fma_f32 v[68:69], v[60:61], v[68:69], v[64:65]
	v_lshlrev_b32_e32 v64, 16, v67
	v_and_b32_e32 v65, 0xffff0000, v67
	v_lshlrev_b32_e32 v60, 16, v71
	v_and_b32_e32 v61, 0xffff0000, v71
	v_rcp_f32_e32 v59, v59
	v_rcp_f32_e32 v58, v58
	s_nop 0
	v_pk_fma_f32 v[70:71], v[58:59], v[64:65], v[60:61]
	v_cvt_pk_bf16_f32 v58, v56, v57
	v_cvt_pk_bf16_f32 v59, v62, v63
	v_cvt_pk_bf16_f32 v60, v68, v69
	v_cvt_pk_bf16_f32 v61, v70, v71
	global_store_dwordx4 v[74:75], v[58:61], off
	v_pk_mul_f32 v[64:65], v[56:57], v[56:57]
	v_pk_mul_f32 v[66:67], v[62:63], v[62:63]
	global_load_dwordx4 v[56:59], v[74:75], off offset:256
	global_load_dwordx4 v[60:63], v[76:77], off offset:256
	v_pk_mul_f32 v[76:77], v[48:49], v[148:149] op_sel_hi:[1,0]
	v_mul_f32_e32 v48, 0xbfb8aa3b, v52
	v_mul_f32_e32 v49, 0xbfb8aa3b, v53
	v_exp_f32_e32 v48, v48
	v_exp_f32_e32 v49, v49
	v_pk_mul_f32 v[68:69], v[68:69], v[68:69]
	v_pk_mul_f32 v[70:71], v[70:71], v[70:71]
	v_pk_add_f32 v[48:49], v[48:49], 1.0 op_sel_hi:[1,0]
	s_waitcnt vmcnt(1)
	v_lshlrev_b32_e32 v78, 16, v56
	v_and_b32_e32 v79, 0xffff0000, v56
	s_waitcnt vmcnt(0)
	v_lshlrev_b32_e32 v52, 16, v60
	v_and_b32_e32 v53, 0xffff0000, v60
	v_rcp_f32_e32 v49, v49
	v_rcp_f32_e32 v48, v48
	s_nop 0
	v_pk_fma_f32 v[48:49], v[48:49], v[78:79], v[52:53]
	v_mul_f32_e32 v52, 0xbfb8aa3b, v54
	v_mul_f32_e32 v53, 0xbfb8aa3b, v55
	v_exp_f32_e32 v52, v52
	v_exp_f32_e32 v53, v53
	v_lshlrev_b32_e32 v54, 16, v61
	v_and_b32_e32 v55, 0xffff0000, v61
	v_lshlrev_b32_e32 v56, 16, v57
	v_pk_add_f32 v[52:53], v[52:53], 1.0 op_sel_hi:[1,0]
	v_and_b32_e32 v57, 0xffff0000, v57
	v_rcp_f32_e32 v53, v53
	v_rcp_f32_e32 v52, v52
	s_nop 0
	v_pk_fma_f32 v[52:53], v[52:53], v[56:57], v[54:55]
	v_mul_f32_e32 v54, 0xbfb8aa3b, v76
	v_mul_f32_e32 v55, 0xbfb8aa3b, v77
	v_exp_f32_e32 v54, v54
	v_exp_f32_e32 v55, v55
	v_lshlrev_b32_e32 v60, 16, v58
	v_and_b32_e32 v61, 0xffff0000, v58
	v_lshlrev_b32_e32 v56, 16, v62
	v_pk_add_f32 v[54:55], v[54:55], 1.0 op_sel_hi:[1,0]
	v_and_b32_e32 v57, 0xffff0000, v62
	v_rcp_f32_e32 v55, v55
	v_rcp_f32_e32 v54, v54
	s_nop 0
	v_pk_fma_f32 v[60:61], v[54:55], v[60:61], v[56:57]
	v_lshlrev_b32_e32 v56, 16, v59
	v_and_b32_e32 v57, 0xffff0000, v59
	v_lshlrev_b32_e32 v54, 16, v63
	v_and_b32_e32 v55, 0xffff0000, v63
	v_rcp_f32_e32 v51, v51
	v_rcp_f32_e32 v50, v50
	s_nop 0
	v_pk_fma_f32 v[50:51], v[50:51], v[56:57], v[54:55]
	v_cvt_pk_bf16_f32 v54, v48, v49
	v_cvt_pk_bf16_f32 v55, v52, v53
	v_cvt_pk_bf16_f32 v56, v60, v61
	v_cvt_pk_bf16_f32 v57, v50, v51
	global_store_dwordx4 v[74:75], v[54:57], off offset:256
	v_pk_mul_f32 v[50:51], v[50:51], v[50:51]
	v_pk_mul_f32 v[48:49], v[48:49], v[48:49]
	v_pk_mul_f32 v[54:55], v[60:61], v[60:61]
	v_pk_mul_f32 v[52:53], v[52:53], v[52:53]
	v_add_f32_e32 v56, v70, v71
	v_add_f32_e32 v57, v68, v69
	v_add_f32_e32 v50, v50, v51
	v_add_f32_e32 v51, v54, v55
	v_add_f32_e32 v56, v57, v56
	v_add_f32_e32 v57, v66, v67
	v_add_f32_e32 v58, v64, v65
	v_add_f32_e32 v50, v51, v50
	v_add_f32_e32 v51, v52, v53
	v_add_f32_e32 v48, v48, v49
	v_add_f32_e32 v57, v58, v57
	v_add_f32_e32 v48, v48, v51
	v_add_f32_e32 v56, v57, v56
	v_add_f32_e32 v48, v48, v50
	v_add_f32_e32 v48, v56, v48
	ds_bpermute_b32 v49, v169, v48
	s_waitcnt lgkmcnt(0)
	v_add_f32_e32 v48, v48, v49
	ds_bpermute_b32 v49, v155, v48
	s_and_saveexec_b64 s[0:1], s[46:47]
	s_cbranch_execz .LBB0_480
	s_waitcnt lgkmcnt(0)
	v_add_f32_e32 v50, v48, v49
	v_lshlrev_b64 v[48:49], 6, v[72:73]
	v_lshl_add_u64 v[48:49], s[6:7], 0, v[48:49]
	v_lshl_add_u64 v[48:49], s[42:43], 2, v[48:49]
	s_lshl_b32 s94, s35, 2
	v_lshl_add_u64 v[48:49], v[48:49], 0, s[94:95]
	global_store_dword v[48:49], v50, off
; DI unsigned pk2(float lo, float hi) { const f32x2_t v = {lo, hi}; const bf16x2_t b = __builtin_convertvector(v, bf16x2_t); return __builtin_bit_cast(unsigned, b); }
; DI float lo16(unsigned w) { return __uint_as_float(w << 16); }
; DI float hi16(unsigned w) { return __uint_as_float(w & 0xffff0000u); }
;     DI void operator()(const pg8::f32x4 (&acc)[2][2][4][2], const pg8::Unit& u, int wr, int wc, int fr, int fq) const {
;     ...
;             for (int m = 0; m < 4; ++m) {
;                 const int row = row0 + ai * 128 + m * 16; const float r = rs[ai][m];
;                 float part = 0.f;
; #pragma unroll
;                 for (int bj = 0; bj < 2; ++bj) { const size_t off = (size_t)row * 1024 + col0 + bj * 128;
;                     const u32x4 tw = *(const u32x4*)(T + off); const u32x4 xw = *(const u32x4*)(xr + off);
;                     const pg8::f32x4 a0 = acc[ai][bj][m][0] * r, a1 = acc[ai][bj][m][1] * r;
;                     const float o0 = lo16(xw.x) + lo16(tw.x) * __frcp_rn(1.0f + __expf(-a0[0])), o1 = hi16(xw.x) + hi16(tw.x) * __frcp_rn(1.0f + __expf(-a0[1]));
;                     const float o2 = lo16(xw.y) + lo16(tw.y) * __frcp_rn(1.0f + __expf(-a0[2])), o3 = hi16(xw.y) + hi16(tw.y) * __frcp_rn(1.0f + __expf(-a0[3]));
;                     const float o4 = lo16(xw.z) + lo16(tw.z) * __frcp_rn(1.0f + __expf(-a1[0])), o5 = hi16(xw.z) + hi16(tw.z) * __frcp_rn(1.0f + __expf(-a1[1]));
;                     const float o6 = lo16(xw.w) + lo16(tw.w) * __frcp_rn(1.0f + __expf(-a1[2])), o7 = hi16(xw.w) + hi16(tw.w) * __frcp_rn(1.0f + __expf(-a1[3]));
;                     u32x4 w; w.x = pk2(o0, o1); w.y = pk2(o2, o3); w.z = pk2(o4, o5); w.w = pk2(o6, o7); *(u32x4*)(xbo + off) = w;
;                     part += ((o0 * o0 + o1 * o1) + (o2 * o2 + o3 * o3)) + ((o4 * o4 + o5 * o5) + (o6 * o6 + o7 * o7)); }
;                 part += __shfl_xor(part, 16); part += __shfl_xor(part, 32);
;                 if (ssout && fq == 0) ssout[(size_t)row * 16 + u.pn * 4 + wc] = part;
.LBB0_480:
	s_or_b64 exec, exec, s[0:1]
	v_add_u32_e32 v56, 0x90, v142
	v_ashrrev_i32_e32 v57, 31, v56
	s_waitcnt lgkmcnt(0)
	v_lshlrev_b64 v[48:49], 10, v[56:57]
	v_lshl_add_u64 v[48:49], v[48:49], 0, v[140:141]
	v_lshlrev_b64 v[52:53], 1, v[48:49]
	v_lshl_add_u64 v[58:59], s[18:19], 0, v[52:53]
	global_load_dwordx4 v[48:51], v[58:59], off
	v_lshl_add_u64 v[60:61], s[12:13], 0, v[52:53]
	global_load_dwordx4 v[52:55], v[60:61], off
	v_pk_mul_f32 v[44:45], v[44:45], v[146:147] op_sel_hi:[1,0]
	v_pk_mul_f32 v[62:63], v[40:41], v[146:147] op_sel_hi:[1,0]
	v_mul_f32_e32 v40, 0xbfb8aa3b, v44
	v_mul_f32_e32 v41, 0xbfb8aa3b, v45
	v_exp_f32_e32 v40, v40
	v_exp_f32_e32 v41, v41
	v_pk_mul_f32 v[46:47], v[46:47], v[146:147] op_sel_hi:[1,0]
	v_pk_mul_f32 v[42:43], v[42:43], v[146:147] op_sel_hi:[1,0]
	v_pk_mul_f32 v[36:37], v[36:37], v[146:147] op_sel_hi:[1,0]
	v_pk_add_f32 v[40:41], v[40:41], 1.0 op_sel_hi:[1,0]
	v_mul_f32_e32 v42, 0xbfb8aa3b, v42
	v_mul_f32_e32 v43, 0xbfb8aa3b, v43
	v_exp_f32_e32 v42, v42
	v_exp_f32_e32 v43, v43
	v_pk_mul_f32 v[38:39], v[38:39], v[146:147] op_sel_hi:[1,0]
	v_pk_mul_f32 v[34:35], v[34:35], v[146:147] op_sel_hi:[1,0]
	v_pk_add_f32 v[42:43], v[42:43], 1.0 op_sel_hi:[1,0]
	v_mul_f32_e32 v34, 0xbfb8aa3b, v34
	v_mul_f32_e32 v35, 0xbfb8aa3b, v35
	v_exp_f32_e32 v34, v34
	v_exp_f32_e32 v35, v35
	s_waitcnt vmcnt(1)
	v_lshlrev_b32_e32 v64, 16, v48
	v_and_b32_e32 v65, 0xffff0000, v48
	s_waitcnt vmcnt(0)
	v_lshlrev_b32_e32 v44, 16, v52
	v_and_b32_e32 v45, 0xffff0000, v52
	v_pk_add_f32 v[34:35], v[34:35], 1.0 op_sel_hi:[1,0]
	v_rcp_f32_e32 v41, v41
	v_rcp_f32_e32 v40, v40
	s_nop 0
	v_pk_fma_f32 v[40:41], v[40:41], v[64:65], v[44:45]
	v_mul_f32_e32 v44, 0xbfb8aa3b, v46
	v_mul_f32_e32 v45, 0xbfb8aa3b, v47
	v_exp_f32_e32 v44, v44
	v_exp_f32_e32 v45, v45
	v_lshlrev_b32_e32 v46, 16, v53
	v_and_b32_e32 v47, 0xffff0000, v53
	v_lshlrev_b32_e32 v48, 16, v49
	v_pk_add_f32 v[44:45], v[44:45], 1.0 op_sel_hi:[1,0]
	v_and_b32_e32 v49, 0xffff0000, v49
	v_rcp_f32_e32 v45, v45
	v_rcp_f32_e32 v44, v44
	s_nop 0
	v_pk_fma_f32 v[46:47], v[44:45], v[48:49], v[46:47]
	v_mul_f32_e32 v44, 0xbfb8aa3b, v62
	v_mul_f32_e32 v45, 0xbfb8aa3b, v63
	v_exp_f32_e32 v44, v44
	v_exp_f32_e32 v45, v45
	v_lshlrev_b32_e32 v52, 16, v50
	v_and_b32_e32 v53, 0xffff0000, v50
	v_lshlrev_b32_e32 v48, 16, v54
	v_pk_add_f32 v[44:45], v[44:45], 1.0 op_sel_hi:[1,0]
	v_and_b32_e32 v49, 0xffff0000, v54
	v_rcp_f32_e32 v45, v45
	v_rcp_f32_e32 v44, v44
	s_nop 0
	v_pk_fma_f32 v[52:53], v[44:45], v[52:53], v[48:49]
	v_lshlrev_b32_e32 v48, 16, v51
	v_and_b32_e32 v49, 0xffff0000, v51
	v_lshlrev_b32_e32 v44, 16, v55
	v_and_b32_e32 v45, 0xffff0000, v55
	v_rcp_f32_e32 v43, v43
	v_rcp_f32_e32 v42, v42
	s_nop 0
	v_pk_fma_f32 v[54:55], v[42:43], v[48:49], v[44:45]
	v_cvt_pk_bf16_f32 v42, v40, v41
	v_cvt_pk_bf16_f32 v43, v46, v47
	v_cvt_pk_bf16_f32 v44, v52, v53
	v_cvt_pk_bf16_f32 v45, v54, v55
	global_store_dwordx4 v[58:59], v[42:45], off
	v_pk_mul_f32 v[48:49], v[40:41], v[40:41]
	v_pk_mul_f32 v[50:51], v[46:47], v[46:47]
	global_load_dwordx4 v[40:43], v[58:59], off offset:256
	global_load_dwordx4 v[44:47], v[60:61], off offset:256
	v_pk_mul_f32 v[60:61], v[32:33], v[146:147] op_sel_hi:[1,0]
	v_mul_f32_e32 v32, 0xbfb8aa3b, v36
	v_mul_f32_e32 v33, 0xbfb8aa3b, v37
	v_exp_f32_e32 v32, v32
	v_exp_f32_e32 v33, v33
	v_pk_mul_f32 v[52:53], v[52:53], v[52:53]
	v_pk_mul_f32 v[54:55], v[54:55], v[54:55]
	v_pk_add_f32 v[32:33], v[32:33], 1.0 op_sel_hi:[1,0]
	s_waitcnt vmcnt(1)
	v_lshlrev_b32_e32 v62, 16, v40
	v_and_b32_e32 v63, 0xffff0000, v40
	s_waitcnt vmcnt(0)
	v_lshlrev_b32_e32 v36, 16, v44
	v_and_b32_e32 v37, 0xffff0000, v44
	v_rcp_f32_e32 v33, v33
	v_rcp_f32_e32 v32, v32
	s_nop 0
	v_pk_fma_f32 v[32:33], v[32:33], v[62:63], v[36:37]
	v_mul_f32_e32 v36, 0xbfb8aa3b, v38
	v_mul_f32_e32 v37, 0xbfb8aa3b, v39
	v_exp_f32_e32 v36, v36
	v_exp_f32_e32 v37, v37
	v_lshlrev_b32_e32 v38, 16, v45
	v_and_b32_e32 v39, 0xffff0000, v45
	v_lshlrev_b32_e32 v40, 16, v41
	v_pk_add_f32 v[36:37], v[36:37], 1.0 op_sel_hi:[1,0]
	v_and_b32_e32 v41, 0xffff0000, v41
	v_rcp_f32_e32 v37, v37
	v_rcp_f32_e32 v36, v36
	s_nop 0
	v_pk_fma_f32 v[36:37], v[36:37], v[40:41], v[38:39]
	v_mul_f32_e32 v38, 0xbfb8aa3b, v60
	v_mul_f32_e32 v39, 0xbfb8aa3b, v61
	v_exp_f32_e32 v38, v38
	v_exp_f32_e32 v39, v39
	v_lshlrev_b32_e32 v44, 16, v42
	v_and_b32_e32 v45, 0xffff0000, v42
	v_lshlrev_b32_e32 v40, 16, v46
	v_pk_add_f32 v[38:39], v[38:39], 1.0 op_sel_hi:[1,0]
	v_and_b32_e32 v41, 0xffff0000, v46
	v_rcp_f32_e32 v39, v39
	v_rcp_f32_e32 v38, v38
	s_nop 0
	v_pk_fma_f32 v[44:45], v[38:39], v[44:45], v[40:41]
	v_lshlrev_b32_e32 v40, 16, v43
	v_and_b32_e32 v41, 0xffff0000, v43
	v_lshlrev_b32_e32 v38, 16, v47
	v_and_b32_e32 v39, 0xffff0000, v47
	v_rcp_f32_e32 v35, v35
	v_rcp_f32_e32 v34, v34
	s_nop 0
	v_pk_fma_f32 v[34:35], v[34:35], v[40:41], v[38:39]
	v_cvt_pk_bf16_f32 v38, v32, v33
	v_cvt_pk_bf16_f32 v39, v36, v37
	v_cvt_pk_bf16_f32 v40, v44, v45
	v_cvt_pk_bf16_f32 v41, v34, v35
	global_store_dwordx4 v[58:59], v[38:41], off offset:256
	v_pk_mul_f32 v[34:35], v[34:35], v[34:35]
	v_pk_mul_f32 v[32:33], v[32:33], v[32:33]
	v_pk_mul_f32 v[38:39], v[44:45], v[44:45]
	v_pk_mul_f32 v[36:37], v[36:37], v[36:37]
	v_add_f32_e32 v40, v54, v55
	v_add_f32_e32 v41, v52, v53
	v_add_f32_e32 v34, v34, v35
	v_add_f32_e32 v35, v38, v39
	v_add_f32_e32 v40, v41, v40
	v_add_f32_e32 v41, v50, v51
	v_add_f32_e32 v42, v48, v49
	v_add_f32_e32 v34, v35, v34
	v_add_f32_e32 v35, v36, v37
	v_add_f32_e32 v32, v32, v33
	v_add_f32_e32 v41, v42, v41
	v_add_f32_e32 v32, v32, v35
	v_add_f32_e32 v40, v41, v40
	v_add_f32_e32 v32, v32, v34
	v_add_f32_e32 v32, v40, v32
	ds_bpermute_b32 v33, v169, v32
	s_waitcnt lgkmcnt(0)
	v_add_f32_e32 v32, v32, v33
	ds_bpermute_b32 v33, v155, v32
	s_and_saveexec_b64 s[0:1], s[46:47]
	s_cbranch_execz .LBB0_482
	s_waitcnt lgkmcnt(0)
	v_add_f32_e32 v34, v32, v33
	v_lshlrev_b64 v[32:33], 6, v[56:57]
	v_lshl_add_u64 v[32:33], s[6:7], 0, v[32:33]
	v_lshl_add_u64 v[32:33], s[42:43], 2, v[32:33]
	s_lshl_b32 s94, s35, 2
	v_lshl_add_u64 v[32:33], v[32:33], 0, s[94:95]
	global_store_dword v[32:33], v34, off
; DI unsigned pk2(float lo, float hi) { const f32x2_t v = {lo, hi}; const bf16x2_t b = __builtin_convertvector(v, bf16x2_t); return __builtin_bit_cast(unsigned, b); }
; DI float lo16(unsigned w) { return __uint_as_float(w << 16); }
; DI float hi16(unsigned w) { return __uint_as_float(w & 0xffff0000u); }
;     DI void operator()(const pg8::f32x4 (&acc)[2][2][4][2], const pg8::Unit& u, int wr, int wc, int fr, int fq) const {
;     ...
;             for (int m = 0; m < 4; ++m) {
;                 const int row = row0 + ai * 128 + m * 16; const float r = rs[ai][m];
;                 float part = 0.f;
; #pragma unroll
;                 for (int bj = 0; bj < 2; ++bj) { const size_t off = (size_t)row * 1024 + col0 + bj * 128;
;                     const u32x4 tw = *(const u32x4*)(T + off); const u32x4 xw = *(const u32x4*)(xr + off);
;                     const pg8::f32x4 a0 = acc[ai][bj][m][0] * r, a1 = acc[ai][bj][m][1] * r;
;                     const float o0 = lo16(xw.x) + lo16(tw.x) * __frcp_rn(1.0f + __expf(-a0[0])), o1 = hi16(xw.x) + hi16(tw.x) * __frcp_rn(1.0f + __expf(-a0[1]));
;                     const float o2 = lo16(xw.y) + lo16(tw.y) * __frcp_rn(1.0f + __expf(-a0[2])), o3 = hi16(xw.y) + hi16(tw.y) * __frcp_rn(1.0f + __expf(-a0[3]));
;                     const float o4 = lo16(xw.z) + lo16(tw.z) * __frcp_rn(1.0f + __expf(-a1[0])), o5 = hi16(xw.z) + hi16(tw.z) * __frcp_rn(1.0f + __expf(-a1[1]));
;                     const float o6 = lo16(xw.w) + lo16(tw.w) * __frcp_rn(1.0f + __expf(-a1[2])), o7 = hi16(xw.w) + hi16(tw.w) * __frcp_rn(1.0f + __expf(-a1[3]));
;                     u32x4 w; w.x = pk2(o0, o1); w.y = pk2(o2, o3); w.z = pk2(o4, o5); w.w = pk2(o6, o7); *(u32x4*)(xbo + off) = w;
;                     part += ((o0 * o0 + o1 * o1) + (o2 * o2 + o3 * o3)) + ((o4 * o4 + o5 * o5) + (o6 * o6 + o7 * o7)); }
;                 part += __shfl_xor(part, 16); part += __shfl_xor(part, 32);
;                 if (ssout && fq == 0) ssout[(size_t)row * 16 + u.pn * 4 + wc] = part;
.LBB0_482:
	s_or_b64 exec, exec, s[0:1]
	v_add_u32_e32 v40, 0xa0, v142
	v_ashrrev_i32_e32 v41, 31, v40
	s_waitcnt lgkmcnt(0)
	v_lshlrev_b64 v[32:33], 10, v[40:41]
	v_lshl_add_u64 v[32:33], v[32:33], 0, v[140:141]
	v_lshlrev_b64 v[36:37], 1, v[32:33]
	v_lshl_add_u64 v[42:43], s[18:19], 0, v[36:37]
	global_load_dwordx4 v[32:35], v[42:43], off
	v_lshl_add_u64 v[44:45], s[12:13], 0, v[36:37]
	global_load_dwordx4 v[36:39], v[44:45], off
	v_pk_mul_f32 v[28:29], v[28:29], v[144:145] op_sel_hi:[1,0]
	v_pk_mul_f32 v[46:47], v[24:25], v[144:145] op_sel_hi:[1,0]
	v_mul_f32_e32 v24, 0xbfb8aa3b, v28
	v_mul_f32_e32 v25, 0xbfb8aa3b, v29
	v_exp_f32_e32 v24, v24
	v_exp_f32_e32 v25, v25
	v_pk_mul_f32 v[30:31], v[30:31], v[144:145] op_sel_hi:[1,0]
	v_pk_mul_f32 v[26:27], v[26:27], v[144:145] op_sel_hi:[1,0]
	v_pk_mul_f32 v[20:21], v[20:21], v[144:145] op_sel_hi:[1,0]
	v_pk_add_f32 v[24:25], v[24:25], 1.0 op_sel_hi:[1,0]
	v_mul_f32_e32 v26, 0xbfb8aa3b, v26
	v_mul_f32_e32 v27, 0xbfb8aa3b, v27
	v_exp_f32_e32 v26, v26
	v_exp_f32_e32 v27, v27
	v_pk_mul_f32 v[22:23], v[22:23], v[144:145] op_sel_hi:[1,0]
	v_pk_mul_f32 v[18:19], v[18:19], v[144:145] op_sel_hi:[1,0]
	v_pk_add_f32 v[26:27], v[26:27], 1.0 op_sel_hi:[1,0]
	v_mul_f32_e32 v18, 0xbfb8aa3b, v18
	v_mul_f32_e32 v19, 0xbfb8aa3b, v19
	v_exp_f32_e32 v18, v18
	v_exp_f32_e32 v19, v19
	s_waitcnt vmcnt(1)
	v_lshlrev_b32_e32 v48, 16, v32
	v_and_b32_e32 v49, 0xffff0000, v32
	s_waitcnt vmcnt(0)
	v_lshlrev_b32_e32 v28, 16, v36
	v_and_b32_e32 v29, 0xffff0000, v36
	v_pk_add_f32 v[18:19], v[18:19], 1.0 op_sel_hi:[1,0]
	v_rcp_f32_e32 v25, v25
	v_rcp_f32_e32 v24, v24
	s_nop 0
	v_pk_fma_f32 v[24:25], v[24:25], v[48:49], v[28:29]
	v_mul_f32_e32 v28, 0xbfb8aa3b, v30
	v_mul_f32_e32 v29, 0xbfb8aa3b, v31
	v_exp_f32_e32 v28, v28
	v_exp_f32_e32 v29, v29
	v_lshlrev_b32_e32 v30, 16, v37
	v_and_b32_e32 v31, 0xffff0000, v37
	v_lshlrev_b32_e32 v32, 16, v33
	v_pk_add_f32 v[28:29], v[28:29], 1.0 op_sel_hi:[1,0]
	v_and_b32_e32 v33, 0xffff0000, v33
	v_rcp_f32_e32 v29, v29
	v_rcp_f32_e32 v28, v28
	s_nop 0
	v_pk_fma_f32 v[30:31], v[28:29], v[32:33], v[30:31]
	v_mul_f32_e32 v28, 0xbfb8aa3b, v46
	v_mul_f32_e32 v29, 0xbfb8aa3b, v47
	v_exp_f32_e32 v28, v28
	v_exp_f32_e32 v29, v29
	v_lshlrev_b32_e32 v36, 16, v34
	v_and_b32_e32 v37, 0xffff0000, v34
	v_lshlrev_b32_e32 v32, 16, v38
	v_pk_add_f32 v[28:29], v[28:29], 1.0 op_sel_hi:[1,0]
	v_and_b32_e32 v33, 0xffff0000, v38
	v_rcp_f32_e32 v29, v29
	v_rcp_f32_e32 v28, v28
	s_nop 0
	v_pk_fma_f32 v[36:37], v[28:29], v[36:37], v[32:33]
	v_lshlrev_b32_e32 v32, 16, v35
	v_and_b32_e32 v33, 0xffff0000, v35
	v_lshlrev_b32_e32 v28, 16, v39
	v_and_b32_e32 v29, 0xffff0000, v39
	v_rcp_f32_e32 v27, v27
	v_rcp_f32_e32 v26, v26
	s_nop 0
	v_pk_fma_f32 v[38:39], v[26:27], v[32:33], v[28:29]
	v_cvt_pk_bf16_f32 v26, v24, v25
	v_cvt_pk_bf16_f32 v27, v30, v31
	v_cvt_pk_bf16_f32 v28, v36, v37
	v_cvt_pk_bf16_f32 v29, v38, v39
	global_store_dwordx4 v[42:43], v[26:29], off
	v_pk_mul_f32 v[32:33], v[24:25], v[24:25]
	v_pk_mul_f32 v[34:35], v[30:31], v[30:31]
	global_load_dwordx4 v[24:27], v[42:43], off offset:256
	global_load_dwordx4 v[28:31], v[44:45], off offset:256
	v_pk_mul_f32 v[44:45], v[16:17], v[144:145] op_sel_hi:[1,0]
	v_mul_f32_e32 v16, 0xbfb8aa3b, v20
	v_mul_f32_e32 v17, 0xbfb8aa3b, v21
	v_exp_f32_e32 v16, v16
	v_exp_f32_e32 v17, v17
	v_pk_mul_f32 v[36:37], v[36:37], v[36:37]
	v_pk_mul_f32 v[38:39], v[38:39], v[38:39]
	v_pk_add_f32 v[16:17], v[16:17], 1.0 op_sel_hi:[1,0]
	s_waitcnt vmcnt(1)
	v_lshlrev_b32_e32 v46, 16, v24
	v_and_b32_e32 v47, 0xffff0000, v24
	s_waitcnt vmcnt(0)
	v_lshlrev_b32_e32 v20, 16, v28
	v_and_b32_e32 v21, 0xffff0000, v28
	v_rcp_f32_e32 v17, v17
	v_rcp_f32_e32 v16, v16
	s_nop 0
	v_pk_fma_f32 v[16:17], v[16:17], v[46:47], v[20:21]
	v_mul_f32_e32 v20, 0xbfb8aa3b, v22
	v_mul_f32_e32 v21, 0xbfb8aa3b, v23
	v_exp_f32_e32 v20, v20
	v_exp_f32_e32 v21, v21
	v_lshlrev_b32_e32 v22, 16, v29
	v_and_b32_e32 v23, 0xffff0000, v29
	v_lshlrev_b32_e32 v24, 16, v25
	v_pk_add_f32 v[20:21], v[20:21], 1.0 op_sel_hi:[1,0]
	v_and_b32_e32 v25, 0xffff0000, v25
	v_rcp_f32_e32 v21, v21
	v_rcp_f32_e32 v20, v20
	s_nop 0
	v_pk_fma_f32 v[20:21], v[20:21], v[24:25], v[22:23]
	v_mul_f32_e32 v22, 0xbfb8aa3b, v44
	v_mul_f32_e32 v23, 0xbfb8aa3b, v45
	v_exp_f32_e32 v22, v22
	v_exp_f32_e32 v23, v23
	v_lshlrev_b32_e32 v28, 16, v26
	v_and_b32_e32 v29, 0xffff0000, v26
	v_lshlrev_b32_e32 v24, 16, v30
	v_pk_add_f32 v[22:23], v[22:23], 1.0 op_sel_hi:[1,0]
	v_and_b32_e32 v25, 0xffff0000, v30
	v_rcp_f32_e32 v23, v23
	v_rcp_f32_e32 v22, v22
	s_nop 0
	v_pk_fma_f32 v[28:29], v[22:23], v[28:29], v[24:25]
	v_lshlrev_b32_e32 v24, 16, v27
	v_and_b32_e32 v25, 0xffff0000, v27
	v_lshlrev_b32_e32 v22, 16, v31
	v_and_b32_e32 v23, 0xffff0000, v31
	v_rcp_f32_e32 v19, v19
	v_rcp_f32_e32 v18, v18
	s_nop 0
	v_pk_fma_f32 v[18:19], v[18:19], v[24:25], v[22:23]
	v_cvt_pk_bf16_f32 v22, v16, v17
	v_cvt_pk_bf16_f32 v23, v20, v21
	v_cvt_pk_bf16_f32 v24, v28, v29
	v_cvt_pk_bf16_f32 v25, v18, v19
	global_store_dwordx4 v[42:43], v[22:25], off offset:256
	v_pk_mul_f32 v[18:19], v[18:19], v[18:19]
	v_pk_mul_f32 v[16:17], v[16:17], v[16:17]
	v_pk_mul_f32 v[22:23], v[28:29], v[28:29]
	v_pk_mul_f32 v[20:21], v[20:21], v[20:21]
	v_add_f32_e32 v24, v38, v39
	v_add_f32_e32 v25, v36, v37
	v_add_f32_e32 v18, v18, v19
	v_add_f32_e32 v19, v22, v23
	v_add_f32_e32 v24, v25, v24
	v_add_f32_e32 v25, v34, v35
	v_add_f32_e32 v26, v32, v33
	v_add_f32_e32 v18, v19, v18
	v_add_f32_e32 v19, v20, v21
	v_add_f32_e32 v16, v16, v17
	v_add_f32_e32 v25, v26, v25
	v_add_f32_e32 v16, v16, v19
	v_add_f32_e32 v24, v25, v24
	v_add_f32_e32 v16, v16, v18
	v_add_f32_e32 v16, v24, v16
	ds_bpermute_b32 v17, v169, v16
	s_waitcnt lgkmcnt(0)
	v_add_f32_e32 v16, v16, v17
	ds_bpermute_b32 v17, v155, v16
	s_and_saveexec_b64 s[0:1], s[46:47]
	s_cbranch_execz .LBB0_484
	s_waitcnt lgkmcnt(0)
	v_add_f32_e32 v18, v16, v17
	v_lshlrev_b64 v[16:17], 6, v[40:41]
	v_lshl_add_u64 v[16:17], s[6:7], 0, v[16:17]
	v_lshl_add_u64 v[16:17], s[42:43], 2, v[16:17]
	s_lshl_b32 s94, s35, 2
	v_lshl_add_u64 v[16:17], v[16:17], 0, s[94:95]
	global_store_dword v[16:17], v18, off
; DI unsigned pk2(float lo, float hi) { const f32x2_t v = {lo, hi}; const bf16x2_t b = __builtin_convertvector(v, bf16x2_t); return __builtin_bit_cast(unsigned, b); }
; DI float lo16(unsigned w) { return __uint_as_float(w << 16); }
; DI float hi16(unsigned w) { return __uint_as_float(w & 0xffff0000u); }
;     DI void operator()(const pg8::f32x4 (&acc)[2][2][4][2], const pg8::Unit& u, int wr, int wc, int fr, int fq) const {
;     ...
;         for (int ai = 0; ai < 2; ++ai)
; #pragma unroll
;             for (int m = 0; m < 4; ++m) {
;                 const int row = row0 + ai * 128 + m * 16; const float r = rs[ai][m];
;                 float part = 0.f;
; #pragma unroll
;                 for (int bj = 0; bj < 2; ++bj) { const size_t off = (size_t)row * 1024 + col0 + bj * 128;
;                     const u32x4 tw = *(const u32x4*)(T + off); const u32x4 xw = *(const u32x4*)(xr + off);
;                     const pg8::f32x4 a0 = acc[ai][bj][m][0] * r, a1 = acc[ai][bj][m][1] * r;
;                     const float o0 = lo16(xw.x) + lo16(tw.x) * __frcp_rn(1.0f + __expf(-a0[0])), o1 = hi16(xw.x) + hi16(tw.x) * __frcp_rn(1.0f + __expf(-a0[1]));
;                     const float o2 = lo16(xw.y) + lo16(tw.y) * __frcp_rn(1.0f + __expf(-a0[2])), o3 = hi16(xw.y) + hi16(tw.y) * __frcp_rn(1.0f + __expf(-a0[3]));
;                     const float o4 = lo16(xw.z) + lo16(tw.z) * __frcp_rn(1.0f + __expf(-a1[0])), o5 = hi16(xw.z) + hi16(tw.z) * __frcp_rn(1.0f + __expf(-a1[1]));
;                     const float o6 = lo16(xw.w) + lo16(tw.w) * __frcp_rn(1.0f + __expf(-a1[2])), o7 = hi16(xw.w) + hi16(tw.w) * __frcp_rn(1.0f + __expf(-a1[3]));
;                     u32x4 w; w.x = pk2(o0, o1); w.y = pk2(o2, o3); w.z = pk2(o4, o5); w.w = pk2(o6, o7); *(u32x4*)(xbo + off) = w;
;                     part += ((o0 * o0 + o1 * o1) + (o2 * o2 + o3 * o3)) + ((o4 * o4 + o5 * o5) + (o6 * o6 + o7 * o7)); }
;                 part += __shfl_xor(part, 16); part += __shfl_xor(part, 32);
;                 if (ssout && fq == 0) ssout[(size_t)row * 16 + u.pn * 4 + wc] = part;
.LBB0_484:
	s_or_b64 exec, exec, s[0:1]
	v_add_u32_e32 v24, 0xb0, v142
	v_ashrrev_i32_e32 v25, 31, v24
	s_waitcnt lgkmcnt(0)
	v_lshlrev_b64 v[16:17], 10, v[24:25]
	v_lshl_add_u64 v[16:17], v[16:17], 0, v[140:141]
	v_lshlrev_b64 v[20:21], 1, v[16:17]
	v_lshl_add_u64 v[26:27], s[18:19], 0, v[20:21]
	global_load_dwordx4 v[16:19], v[26:27], off
	v_lshl_add_u64 v[28:29], s[12:13], 0, v[20:21]
	global_load_dwordx4 v[20:23], v[28:29], off
	v_pk_mul_f32 v[12:13], v[12:13], v[138:139] op_sel_hi:[1,0]
	v_pk_mul_f32 v[30:31], v[8:9], v[138:139] op_sel_hi:[1,0]
	v_mul_f32_e32 v8, 0xbfb8aa3b, v12
	v_mul_f32_e32 v9, 0xbfb8aa3b, v13
	v_exp_f32_e32 v8, v8
	v_exp_f32_e32 v9, v9
	v_pk_mul_f32 v[14:15], v[14:15], v[138:139] op_sel_hi:[1,0]
	v_pk_mul_f32 v[10:11], v[10:11], v[138:139] op_sel_hi:[1,0]
	v_pk_mul_f32 v[4:5], v[4:5], v[138:139] op_sel_hi:[1,0]
	v_pk_add_f32 v[8:9], v[8:9], 1.0 op_sel_hi:[1,0]
	v_mul_f32_e32 v10, 0xbfb8aa3b, v10
	v_mul_f32_e32 v11, 0xbfb8aa3b, v11
	v_exp_f32_e32 v10, v10
	v_exp_f32_e32 v11, v11
	v_pk_mul_f32 v[6:7], v[6:7], v[138:139] op_sel_hi:[1,0]
	v_pk_mul_f32 v[2:3], v[2:3], v[138:139] op_sel_hi:[1,0]
	v_pk_add_f32 v[10:11], v[10:11], 1.0 op_sel_hi:[1,0]
	v_mul_f32_e32 v2, 0xbfb8aa3b, v2
	v_mul_f32_e32 v3, 0xbfb8aa3b, v3
	v_exp_f32_e32 v2, v2
	v_exp_f32_e32 v3, v3
	s_waitcnt vmcnt(1)
	v_lshlrev_b32_e32 v32, 16, v16
	v_and_b32_e32 v33, 0xffff0000, v16
	s_waitcnt vmcnt(0)
	v_lshlrev_b32_e32 v12, 16, v20
	v_and_b32_e32 v13, 0xffff0000, v20
	v_pk_add_f32 v[2:3], v[2:3], 1.0 op_sel_hi:[1,0]
	v_rcp_f32_e32 v9, v9
	v_rcp_f32_e32 v8, v8
	s_nop 0
	v_pk_fma_f32 v[8:9], v[8:9], v[32:33], v[12:13]
	v_mul_f32_e32 v12, 0xbfb8aa3b, v14
	v_mul_f32_e32 v13, 0xbfb8aa3b, v15
	v_exp_f32_e32 v12, v12
	v_exp_f32_e32 v13, v13
	v_lshlrev_b32_e32 v14, 16, v21
	v_and_b32_e32 v15, 0xffff0000, v21
	v_lshlrev_b32_e32 v16, 16, v17
	v_pk_add_f32 v[12:13], v[12:13], 1.0 op_sel_hi:[1,0]
	v_and_b32_e32 v17, 0xffff0000, v17
	v_rcp_f32_e32 v13, v13
	v_rcp_f32_e32 v12, v12
	s_nop 0
	v_pk_fma_f32 v[14:15], v[12:13], v[16:17], v[14:15]
	v_mul_f32_e32 v12, 0xbfb8aa3b, v30
	v_mul_f32_e32 v13, 0xbfb8aa3b, v31
	v_exp_f32_e32 v12, v12
	v_exp_f32_e32 v13, v13
	v_lshlrev_b32_e32 v20, 16, v18
	v_and_b32_e32 v21, 0xffff0000, v18
	v_lshlrev_b32_e32 v16, 16, v22
	v_pk_add_f32 v[12:13], v[12:13], 1.0 op_sel_hi:[1,0]
	v_and_b32_e32 v17, 0xffff0000, v22
	v_rcp_f32_e32 v13, v13
	v_rcp_f32_e32 v12, v12
	s_nop 0
	v_pk_fma_f32 v[20:21], v[12:13], v[20:21], v[16:17]
	v_lshlrev_b32_e32 v16, 16, v19
	v_and_b32_e32 v17, 0xffff0000, v19
	v_lshlrev_b32_e32 v12, 16, v23
	v_and_b32_e32 v13, 0xffff0000, v23
	v_rcp_f32_e32 v11, v11
	v_rcp_f32_e32 v10, v10
	s_nop 0
	v_pk_fma_f32 v[22:23], v[10:11], v[16:17], v[12:13]
	v_cvt_pk_bf16_f32 v10, v8, v9
	v_cvt_pk_bf16_f32 v11, v14, v15
	v_cvt_pk_bf16_f32 v12, v20, v21
	v_cvt_pk_bf16_f32 v13, v22, v23
	global_store_dwordx4 v[26:27], v[10:13], off
	v_pk_mul_f32 v[16:17], v[8:9], v[8:9]
	v_pk_mul_f32 v[18:19], v[14:15], v[14:15]
	global_load_dwordx4 v[8:11], v[26:27], off offset:256
	global_load_dwordx4 v[12:15], v[28:29], off offset:256
	v_pk_mul_f32 v[28:29], v[0:1], v[138:139] op_sel_hi:[1,0]
	v_mul_f32_e32 v0, 0xbfb8aa3b, v4
	v_mul_f32_e32 v1, 0xbfb8aa3b, v5
	v_exp_f32_e32 v0, v0
	v_exp_f32_e32 v1, v1
	v_pk_mul_f32 v[20:21], v[20:21], v[20:21]
	v_pk_mul_f32 v[22:23], v[22:23], v[22:23]
	v_pk_add_f32 v[0:1], v[0:1], 1.0 op_sel_hi:[1,0]
	s_waitcnt vmcnt(1)
	v_lshlrev_b32_e32 v30, 16, v8
	v_and_b32_e32 v31, 0xffff0000, v8
	s_waitcnt vmcnt(0)
	v_lshlrev_b32_e32 v4, 16, v12
	v_and_b32_e32 v5, 0xffff0000, v12
	v_rcp_f32_e32 v1, v1
	v_rcp_f32_e32 v0, v0
	s_nop 0
	v_pk_fma_f32 v[0:1], v[0:1], v[30:31], v[4:5]
	v_mul_f32_e32 v4, 0xbfb8aa3b, v6
	v_mul_f32_e32 v5, 0xbfb8aa3b, v7
	v_exp_f32_e32 v4, v4
	v_exp_f32_e32 v5, v5
	v_lshlrev_b32_e32 v6, 16, v13
	v_and_b32_e32 v7, 0xffff0000, v13
	v_lshlrev_b32_e32 v8, 16, v9
	v_pk_add_f32 v[4:5], v[4:5], 1.0 op_sel_hi:[1,0]
	v_and_b32_e32 v9, 0xffff0000, v9
	v_rcp_f32_e32 v5, v5
	v_rcp_f32_e32 v4, v4
	s_nop 0
	v_pk_fma_f32 v[4:5], v[4:5], v[8:9], v[6:7]
	v_mul_f32_e32 v6, 0xbfb8aa3b, v28
	v_mul_f32_e32 v7, 0xbfb8aa3b, v29
	v_exp_f32_e32 v6, v6
	v_exp_f32_e32 v7, v7
	v_lshlrev_b32_e32 v12, 16, v10
	v_and_b32_e32 v13, 0xffff0000, v10
	v_lshlrev_b32_e32 v8, 16, v14
	v_pk_add_f32 v[6:7], v[6:7], 1.0 op_sel_hi:[1,0]
	v_and_b32_e32 v9, 0xffff0000, v14
	v_rcp_f32_e32 v7, v7
	v_rcp_f32_e32 v6, v6
	s_nop 0
	v_pk_fma_f32 v[12:13], v[6:7], v[12:13], v[8:9]
	v_lshlrev_b32_e32 v8, 16, v11
	v_and_b32_e32 v9, 0xffff0000, v11
	v_lshlrev_b32_e32 v6, 16, v15
	v_and_b32_e32 v7, 0xffff0000, v15
	v_rcp_f32_e32 v3, v3
	v_rcp_f32_e32 v2, v2
	s_nop 0
	v_pk_fma_f32 v[2:3], v[2:3], v[8:9], v[6:7]
	v_cvt_pk_bf16_f32 v6, v0, v1
	v_cvt_pk_bf16_f32 v7, v4, v5
	v_cvt_pk_bf16_f32 v8, v12, v13
	v_cvt_pk_bf16_f32 v9, v2, v3
	global_store_dwordx4 v[26:27], v[6:9], off offset:256
	v_pk_mul_f32 v[2:3], v[2:3], v[2:3]
	v_pk_mul_f32 v[0:1], v[0:1], v[0:1]
	v_pk_mul_f32 v[6:7], v[12:13], v[12:13]
	v_pk_mul_f32 v[4:5], v[4:5], v[4:5]
	v_add_f32_e32 v8, v22, v23
	v_add_f32_e32 v9, v20, v21
	v_add_f32_e32 v2, v2, v3
	v_add_f32_e32 v3, v6, v7
	v_add_f32_e32 v8, v9, v8
	v_add_f32_e32 v9, v18, v19
	v_add_f32_e32 v10, v16, v17
	v_add_f32_e32 v2, v3, v2
	v_add_f32_e32 v3, v4, v5
	v_add_f32_e32 v0, v0, v1
	v_add_f32_e32 v9, v10, v9
	v_add_f32_e32 v0, v0, v3
	v_add_f32_e32 v8, v9, v8
	v_add_f32_e32 v0, v0, v2
	v_add_f32_e32 v0, v8, v0
	ds_bpermute_b32 v1, v169, v0
	s_waitcnt lgkmcnt(0)
	v_add_f32_e32 v0, v0, v1
	ds_bpermute_b32 v1, v155, v0
	s_and_saveexec_b64 s[0:1], s[46:47]
	s_cbranch_execz .LBB0_486
	s_waitcnt lgkmcnt(0)
	v_add_f32_e32 v2, v0, v1
	v_lshlrev_b64 v[0:1], 6, v[24:25]
	v_lshl_add_u64 v[0:1], s[6:7], 0, v[0:1]
	v_lshl_add_u64 v[0:1], s[42:43], 2, v[0:1]
	s_lshl_b32 s94, s35, 2
	v_lshl_add_u64 v[0:1], v[0:1], 0, s[94:95]
	global_store_dword v[0:1], v2, off

; #define LAS __attribute__((address_space(3)))
; #define BX mk_bx()
; DI void lds_barrier() { asm volatile("s_waitcnt lgkmcnt(0)\n\ts_barrier" ::: "memory"); }
; template <class Epi> DI void small_gemm(LAS unsigned char* lds, const bf16_t* A, const bf16_t* Bt, int K, const Epi& E, int G, const int tid) {
;     ...
;     for (int u = BX; u < 256; u += G) {
;         const int rg = u & 15, slot = u >> 4, cA = (slot >> 2) * 256 + (slot & 3) * 32;
;         const bf16_t* ap = A + (size_t)(RP + 32 * rg + r) * K + w * kw + 8 * h;
;         const bf16_t* b0 = Bt + (size_t)(cA + r) * K + w * kw + 8 * h;
;         const bf16_t* b1 = b0 + (size_t)128 * K;
;         f32x16 acc0, acc1;
; #pragma unroll
;         for (int i = 0; i < 16; ++i) { acc0[i] = 0.f; acc1[i] = 0.f; }
;         for (int ks = 0; ks < nks; ks += 2) {
;             const bf16x8 a0 = *(const bf16x8*)(ap + 16 * ks), a1 = *(const bf16x8*)(ap + 16 * ks + 16);
;             const bf16x8 w00 = *(const bf16x8*)(b0 + 16 * ks), w01 = *(const bf16x8*)(b0 + 16 * ks + 16);
;             const bf16x8 w10 = *(const bf16x8*)(b1 + 16 * ks), w11 = *(const bf16x8*)(b1 + 16 * ks + 16);
;             acc0 = __builtin_amdgcn_mfma_f32_32x32x16_bf16(w00, a0, acc0, 0, 0, 0); acc1 = __builtin_amdgcn_mfma_f32_32x32x16_bf16(w10, a0, acc1, 0, 0, 0);
;             acc0 = __builtin_amdgcn_mfma_f32_32x32x16_bf16(w01, a1, acc0, 0, 0, 0); acc1 = __builtin_amdgcn_mfma_f32_32x32x16_bf16(w11, a1, acc1, 0, 0, 0);
;         }
; #pragma unroll
;         for (int g = 0; g < 4; ++g) {
;             *(LAS f32x4*)(red + (((w * 2 + 0) * 4 + g) * 64 + lane) * 4) = (f32x4){acc0[4 * g], acc0[4 * g + 1], acc0[4 * g + 2], acc0[4 * g + 3]};
;             *(LAS f32x4*)(red + (((w * 2 + 1) * 4 + g) * 64 + lane) * 4) = (f32x4){acc1[4 * g], acc1[4 * g + 1], acc1[4 * g + 2], acc1[4 * g + 3]};
;         }
;         lds_barrier();
.LBB0_493:
	s_ashr_i32 s2, s16, 4
	s_lshl_b32 s14, s2, 5
	s_and_b32 s3, s21, 0xffffff00
	s_and_b32 s14, s14, 0x60
	s_or_b32 s14, s14, s3
	v_or_b32_e32 v0, s14, v36
	s_and_b32 s3, s20, 0x1e0
	s_waitcnt lgkmcnt(0)
	v_ashrrev_i32_e32 v1, 31, v0
	s_bitset1_b32 s3, 16
	v_lshlrev_b64 v[0:1], 11, v[0:1]
	v_or_b32_e32 v42, s3, v36
	s_waitcnt vmcnt(0)
	v_lshl_add_u64 v[68:69], v[34:35], 0, v[0:1]
	s_mov_b32 s15, 0x40000
	v_lshlrev_b32_e32 v0, 11, v42
	v_mov_b32_e32 v1, v161
	v_add_co_u32_e32 v72, vcc, s15, v68
	v_lshl_add_u64 v[70:71], v[32:33], 0, v[0:1]
	s_nop 0
	v_addc_co_u32_e32 v73, vcc, 0, v69, vcc
	global_load_dwordx4 v[16:19], v[70:71], off
	global_load_dwordx4 v[44:47], v[70:71], off offset:32
	global_load_dwordx4 v[0:3], v[68:69], off
	global_load_dwordx4 v[48:51], v[68:69], off offset:32
	global_load_dwordx4 v[20:23], v[72:73], off
	global_load_dwordx4 v[52:55], v[72:73], off offset:32
	v_add_u32_e32 v43, s17, v37
	v_lshlrev_b32_e32 v160, 10, v42
	s_waitcnt vmcnt(3)
	v_mfma_f32_32x32x16_bf16 v[0:15], v[0:3], v[16:19], 0
	s_waitcnt vmcnt(1)
	v_mfma_f32_32x32x16_bf16 v[16:31], v[20:23], v[16:19], 0
	v_mfma_f32_32x32x16_bf16 v[0:15], v[48:51], v[44:47], v[0:15]
	s_waitcnt vmcnt(0)
	v_mfma_f32_32x32x16_bf16 v[16:31], v[52:55], v[44:47], v[16:31]
	global_load_dwordx4 v[44:47], v[70:71], off offset:64
	global_load_dwordx4 v[48:51], v[70:71], off offset:96
	global_load_dwordx4 v[52:55], v[68:69], off offset:64
	global_load_dwordx4 v[56:59], v[68:69], off offset:96
	global_load_dwordx4 v[60:63], v[72:73], off offset:64
	global_load_dwordx4 v[64:67], v[72:73], off offset:96
	s_waitcnt vmcnt(3)
	v_mfma_f32_32x32x16_bf16 v[0:15], v[52:55], v[44:47], v[0:15]
	s_waitcnt vmcnt(1)
	v_mfma_f32_32x32x16_bf16 v[16:31], v[60:63], v[44:47], v[16:31]
	v_mfma_f32_32x32x16_bf16 v[0:15], v[56:59], v[48:51], v[0:15]
	s_waitcnt vmcnt(0)
	v_mfma_f32_32x32x16_bf16 v[16:31], v[64:67], v[48:51], v[16:31]
	global_load_dwordx4 v[44:47], v[70:71], off offset:128
	global_load_dwordx4 v[48:51], v[70:71], off offset:160
	global_load_dwordx4 v[52:55], v[68:69], off offset:128
	global_load_dwordx4 v[56:59], v[68:69], off offset:160
	global_load_dwordx4 v[60:63], v[72:73], off offset:128
	global_load_dwordx4 v[64:67], v[72:73], off offset:160
	s_waitcnt vmcnt(3)
	v_mfma_f32_32x32x16_bf16 v[0:15], v[52:55], v[44:47], v[0:15]
	s_waitcnt vmcnt(1)
	v_mfma_f32_32x32x16_bf16 v[16:31], v[60:63], v[44:47], v[16:31]
	v_mfma_f32_32x32x16_bf16 v[0:15], v[56:59], v[48:51], v[0:15]
	s_waitcnt vmcnt(0)
	v_mfma_f32_32x32x16_bf16 v[16:31], v[64:67], v[48:51], v[16:31]
	global_load_dwordx4 v[44:47], v[70:71], off offset:192
	global_load_dwordx4 v[48:51], v[70:71], off offset:224
	global_load_dwordx4 v[52:55], v[68:69], off offset:192
	global_load_dwordx4 v[56:59], v[68:69], off offset:224
	global_load_dwordx4 v[60:63], v[72:73], off offset:192
	global_load_dwordx4 v[64:67], v[72:73], off offset:224
	s_waitcnt vmcnt(3)
	v_mfma_f32_32x32x16_bf16 v[0:15], v[52:55], v[44:47], v[0:15]
	s_waitcnt vmcnt(1)
	v_mfma_f32_32x32x16_bf16 v[16:31], v[60:63], v[44:47], v[16:31]
	v_mfma_f32_32x32x16_bf16 v[0:15], v[56:59], v[48:51], v[0:15]
	s_waitcnt vmcnt(0)
	v_mfma_f32_32x32x16_bf16 v[16:31], v[64:67], v[48:51], v[16:31]
	s_nop 9
	ds_write_b128 v43, v[0:3]
	s_nop 0
	ds_write_b128 v43, v[16:19] offset:4096
	ds_write_b128 v43, v[4:7] offset:1024
	ds_write_b128 v43, v[20:23] offset:5120
	ds_write_b128 v43, v[8:11] offset:2048
	ds_write_b128 v43, v[24:27] offset:6144
	ds_write_b128 v43, v[12:15] offset:3072
	ds_write_b128 v43, v[28:31] offset:7168
	s_waitcnt lgkmcnt(0)
	s_barrier
; #define LAS __attribute__((address_space(3)))
; DI unsigned pk2(float lo, float hi) { const f32x2_t v = {lo, hi}; const bf16x2_t b = __builtin_convertvector(v, bf16x2_t); return __builtin_bit_cast(unsigned, b); }
; DI float lo16(unsigned w) { return __uint_as_float(w << 16); }
; DI float hi16(unsigned w) { return __uint_as_float(w & 0xffff0000u); }
;     DI float small(int row, int col, const pg8::f32x4& v) const {
;         const float r = rowscale(ss, row); const size_t off = (size_t)row * 1024 + col;
;         const u32x2 tw = *(const u32x2*)(T + off); const u32x2 xw = *(const u32x2*)(xr + off);
;         const float o0 = lo16(xw.x) + lo16(tw.x) * __frcp_rn(1.0f + __expf(-v[0] * r)), o1 = hi16(xw.x) + hi16(tw.x) * __frcp_rn(1.0f + __expf(-v[1] * r));
;         const float o2 = lo16(xw.y) + lo16(tw.y) * __frcp_rn(1.0f + __expf(-v[2] * r)), o3 = hi16(xw.y) + hi16(tw.y) * __frcp_rn(1.0f + __expf(-v[3] * r));
;         u32x2 w; w.x = pk2(o0, o1); w.y = pk2(o2, o3); *(u32x2*)(xbo + off) = w;
;         return (o0 * o0 + o1 * o1) + (o2 * o2 + o3 * o3);
; template <class Epi> DI void small_gemm(LAS unsigned char* lds, const bf16_t* A, const bf16_t* Bt, int K, const Epi& E, int G, const int tid) {
;     ...
;         const int tile = w >> 2, g = w & 3;
;         f32x4 v = (f32x4){0.f, 0.f, 0.f, 0.f};
; #pragma unroll
;         for (int ww = 0; ww < 8; ++ww) v += *(const LAS f32x4*)(red + (((ww * 2 + tile) * 4 + g) * 64 + lane) * 4);
;         const int row = RP + 32 * rg + r, col = cA + tile * 128 + 8 * g + 4 * h;
;         float part = E.small(row, col, pg8::f32x4{v[0], v[1], v[2], v[3]});
;         part += __shfl_xor(part, 32);
;         if (h == 0) ssred[w * 32 + r] = part;
	ds_read_b128 v[0:3], v40
	s_waitcnt lgkmcnt(0)
	v_pk_add_f32 v[4:5], v[2:3], 0 op_sel_hi:[1,0]
	v_pk_add_f32 v[6:7], v[0:1], 0 op_sel_hi:[1,0]
	ds_read_b128 v[0:3], v40 offset:8192
	s_waitcnt lgkmcnt(0)
	v_pk_add_f32 v[4:5], v[4:5], v[2:3]
	v_pk_add_f32 v[6:7], v[6:7], v[0:1]
	ds_read_b128 v[0:3], v40 offset:16384
	s_waitcnt lgkmcnt(0)
	v_pk_add_f32 v[4:5], v[4:5], v[2:3]
	v_pk_add_f32 v[6:7], v[6:7], v[0:1]
	ds_read_b128 v[0:3], v40 offset:24576
	s_waitcnt lgkmcnt(0)
	v_pk_add_f32 v[4:5], v[4:5], v[2:3]
	v_pk_add_f32 v[6:7], v[6:7], v[0:1]
	ds_read_b128 v[0:3], v40 offset:32768
	s_waitcnt lgkmcnt(0)
	v_pk_add_f32 v[4:5], v[4:5], v[2:3]
	v_pk_add_f32 v[6:7], v[6:7], v[0:1]
	ds_read_b128 v[0:3], v40 offset:40960
	s_waitcnt lgkmcnt(0)
	v_pk_add_f32 v[4:5], v[4:5], v[2:3]
	v_pk_add_f32 v[6:7], v[6:7], v[0:1]
	ds_read_b128 v[0:3], v40 offset:49152
	s_waitcnt lgkmcnt(0)
	v_pk_add_f32 v[8:9], v[4:5], v[2:3]
	ds_read_b128 v[2:5], v40 offset:57344
	v_pk_add_f32 v[6:7], v[6:7], v[0:1]
	s_waitcnt lgkmcnt(0)
	v_pk_add_f32 v[0:1], v[8:9], v[4:5]
	v_lshlrev_b32_e32 v5, 6, v42
	v_pk_add_f32 v[2:3], v[6:7], v[2:3]
	global_load_dwordx4 v[6:9], v5, s[8:9] offset:16
	global_load_dwordx4 v[10:13], v5, s[8:9] offset:48
	global_load_dwordx4 v[14:17], v5, s[8:9]
	global_load_dwordx4 v[18:21], v5, s[8:9] offset:32
	v_add_u32_e32 v4, s14, v39
	s_waitcnt vmcnt(1)
	v_mov_b32_e32 v22, v14
	s_waitcnt vmcnt(0)
	v_mov_b32_e32 v23, v18
	v_mov_b32_e32 v18, v15
	v_pk_add_f32 v[14:15], v[22:23], v[18:19]
	v_mov_b32_e32 v18, v16
	v_mov_b32_e32 v19, v20
	v_mov_b32_e32 v20, v17
	v_pk_add_f32 v[16:17], v[18:19], v[20:21]
	v_pk_add_f32 v[14:15], v[14:15], v[16:17]
	v_mov_b32_e32 v16, v6
	v_mov_b32_e32 v17, v10
	v_mov_b32_e32 v10, v7
	v_pk_add_f32 v[6:7], v[16:17], v[10:11]
	v_mov_b32_e32 v10, v8
	v_mov_b32_e32 v11, v12
	v_mov_b32_e32 v12, v9
	v_pk_add_f32 v[8:9], v[10:11], v[12:13]
	v_pk_add_f32 v[6:7], v[6:7], v[8:9]
	v_pk_add_f32 v[6:7], v[14:15], v[6:7]
	v_add_f32_e32 v5, v6, v7
	v_fmamk_f32 v5, v5, 0x3a800000, v176
	v_cmp_gt_f32_e32 vcc, s39, v5
	v_mul_f32_e32 v6, 0x4b800000, v5
	s_nop 0
	v_cndmask_b32_e32 v5, v5, v6, vcc
	v_rsq_f32_e32 v5, v5
	s_nop 0
	v_mul_f32_e32 v6, 0x45800000, v5
	v_cndmask_b32_e32 v14, v5, v6, vcc
	v_ashrrev_i32_e32 v5, 31, v4
	v_lshl_add_u64 v[4:5], v[4:5], 0, v[160:161]
	v_lshlrev_b64 v[4:5], 1, v[4:5]
	v_lshl_add_u64 v[6:7], s[18:19], 0, v[4:5]
	v_lshl_add_u64 v[4:5], s[12:13], 0, v[4:5]
	global_load_dwordx2 v[4:5], v[4:5], off
	v_mul_f32_e64 v2, v14, -v2
	global_load_dwordx2 v[8:9], v[6:7], off
	v_mul_f32_e64 v3, v14, -v3
	v_mul_f32_e32 v2, 0x3fb8aa3b, v2
	v_mul_f32_e32 v3, 0x3fb8aa3b, v3
	v_exp_f32_e32 v2, v2
	v_exp_f32_e32 v3, v3
	v_mul_f32_e64 v0, v14, -v0
	v_mul_f32_e64 v1, v14, -v1
	v_mul_f32_e32 v0, 0x3fb8aa3b, v0
	v_pk_add_f32 v[2:3], v[2:3], 1.0 op_sel_hi:[1,0]
	v_mul_f32_e32 v1, 0x3fb8aa3b, v1
	v_exp_f32_e32 v0, v0
	v_exp_f32_e32 v1, v1
	s_waitcnt vmcnt(1)
	v_lshlrev_b32_e32 v10, 16, v4
	v_and_b32_e32 v11, 0xffff0000, v4
	s_waitcnt vmcnt(0)
	v_lshlrev_b32_e32 v12, 16, v8
	v_and_b32_e32 v13, 0xffff0000, v8
	v_pk_add_f32 v[0:1], v[0:1], 1.0 op_sel_hi:[1,0]
	v_rcp_f32_e32 v3, v3
	v_rcp_f32_e32 v2, v2
	s_nop 0
	v_pk_fma_f32 v[2:3], v[2:3], v[12:13], v[10:11]
	v_lshlrev_b32_e32 v4, 16, v5
	v_and_b32_e32 v5, 0xffff0000, v5
	v_lshlrev_b32_e32 v8, 16, v9
	v_rcp_f32_e32 v1, v1
	v_and_b32_e32 v9, 0xffff0000, v9
	v_rcp_f32_e32 v0, v0
	s_nop 0
	v_pk_fma_f32 v[0:1], v[0:1], v[8:9], v[4:5]
	v_cvt_pk_bf16_f32 v4, v2, v3
	v_cvt_pk_bf16_f32 v5, v0, v1
	v_pk_mul_f32 v[2:3], v[2:3], v[2:3]
	v_pk_mul_f32 v[0:1], v[0:1], v[0:1]
	global_store_dwordx2 v[6:7], v[4:5], off
	v_add_f32_e32 v0, v0, v1
	v_add_f32_e32 v1, v2, v3
	v_and_b32_e32 v2, 64, v177
	v_add_f32_e32 v0, v1, v0
	v_xor_b32_e32 v1, 32, v177
	v_add_u32_e32 v2, 64, v2
	v_cmp_lt_i32_e32 vcc, v1, v2
	s_nop 1
	v_cndmask_b32_e32 v1, v177, v1, vcc
	v_lshlrev_b32_e32 v1, 2, v1
	ds_bpermute_b32 v1, v1, v0
	s_and_saveexec_b64 s[14:15], s[40:41]
	s_cbranch_execz .LBB0_495
	s_waitcnt lgkmcnt(0)
	v_add_f32_e32 v0, v0, v1
	ds_write_b32 v41, v0

; DI float rowscale(const float* ss, int row) {
;     const f32x4* p = (const f32x4*)(ss + (size_t)row * 16);
;     const f32x4 a = p[0], b = p[1], c = p[2], d = p[3];
;     const float s = (((a.x + a.y) + (a.z + a.w)) + ((b.x + b.y) + (b.z + b.w))) + (((c.x + c.y) + (c.z + c.w)) + ((d.x + d.y) + (d.z + d.w)));
;     return rsqrtf(s * (1.0f / 1024.0f) + EPS);
; }
; DI void rowscales8(const float* ss, int rowbase, int fr, int fq, float (&r)[2][4]) {
;     const int lane = fq * 16 + fr;
;     const float rA = rowscale(ss, rowbase + lane), rB = rowscale(ss, rowbase + 128 + lane);
; #pragma unroll
;     for (int m = 0; m < 4; ++m) { r[0][m] = __shfl(rA, m * 16 + fr); r[1][m] = __shfl(rB, m * 16 + fr); }
; }
;     DI void operator()(const pg8::f32x4 (&acc)[2][2][4][2], const pg8::Unit& u, int wr, int wc, int fr, int fq) const {
;         const int row0 = u.pm * 256 + wr * 64 + fr, col0 = u.pn * 128 + wc * 32 + 8 * fq;
;         float rs[2][4]; rowscales8(ss, u.pm * 256 + wr * 64, fr, fq, rs);
; #pragma unroll
;         for (int ai = 0; ai < 2; ++ai)
; #pragma unroll
;             for (int m = 0; m < 4; ++m) {
;                 const int row = row0 + ai * 128 + m * 16; const float r = rs[ai][m];
;                 float hv[8];
; #pragma unroll
;                 for (int n = 0; n < 2; ++n) { const pg8::f32x4 g = acc[ai][0][m][n] * r, uu = acc[ai][1][m][n] * r;
; #pragma unroll
;                     for (int e = 0; e < 4; ++e) hv[4 * n + e] = g[e] * __frcp_rn(1.0f + __expf(-g[e])) * uu[e]; }
.LBB0_520:
	s_lshl_b32 s9, s16, 8
	s_add_i32 s9, s9, s48
	v_or_b32_e32 v154, s9, v143
	v_ashrrev_i32_e32 v155, 31, v154
	v_lshlrev_b64 v[154:155], 6, v[154:155]
	v_lshl_add_u64 v[158:159], s[4:5], 0, v[154:155]
	global_load_dwordx4 v[154:157], v[158:159], off offset:16
	global_load_dwordx4 v[162:165], v[158:159], off offset:48
	global_load_dwordx4 v[166:169], v[158:159], off
	global_load_dwordx4 v[170:173], v[158:159], off offset:32
	s_mov_b32 s16, 0x3a800000
	v_lshl_or_b32 v152, s17, 7, v147
	v_or_b32_e32 v151, s9, v139
	s_mul_i32 s11, s88, 56
	s_waitcnt vmcnt(0)
	v_mov_b32_e32 v158, v166
	v_mov_b32_e32 v159, v170
	v_mov_b32_e32 v170, v167
	v_mov_b32_e32 v166, v168
	v_mov_b32_e32 v167, v172
	v_mov_b32_e32 v172, v169
	v_pk_add_f32 v[158:159], v[158:159], v[170:171]
	v_pk_add_f32 v[166:167], v[166:167], v[172:173]
	v_pk_add_f32 v[158:159], v[158:159], v[166:167]
	v_mov_b32_e32 v166, v154
	v_mov_b32_e32 v167, v162
	v_mov_b32_e32 v162, v155
	v_pk_add_f32 v[154:155], v[166:167], v[162:163]
	v_mov_b32_e32 v162, v156
	v_mov_b32_e32 v163, v164
	v_mov_b32_e32 v164, v157
	v_pk_add_f32 v[156:157], v[162:163], v[164:165]
	v_pk_add_f32 v[154:155], v[154:155], v[156:157]
	v_pk_add_f32 v[158:159], v[158:159], v[154:155]
	v_add_u32_e32 v154, s9, v145
	v_ashrrev_i32_e32 v155, 31, v154
	v_lshlrev_b64 v[154:155], 6, v[154:155]
	v_lshl_add_u64 v[170:171], s[4:5], 0, v[154:155]
	global_load_dwordx4 v[154:157], v[170:171], off offset:16
	global_load_dwordx4 v[162:165], v[170:171], off offset:48
	global_load_dwordx4 v[166:169], v[170:171], off
	s_nop 0
	global_load_dwordx4 v[170:173], v[170:171], off offset:32
	s_movk_i32 s9, 0x1600
	s_waitcnt vmcnt(1)
	v_mov_b32_e32 v174, v166
	s_waitcnt vmcnt(0)
	v_mov_b32_e32 v175, v170
	v_mov_b32_e32 v170, v167
	v_pk_add_f32 v[166:167], v[174:175], v[170:171]
	v_mov_b32_e32 v170, v168
	v_mov_b32_e32 v171, v172
	v_mov_b32_e32 v172, v169
	v_pk_add_f32 v[168:169], v[170:171], v[172:173]
	v_pk_add_f32 v[166:167], v[166:167], v[168:169]
	v_mov_b32_e32 v168, v154
	v_mov_b32_e32 v169, v162
	v_mov_b32_e32 v162, v155
	v_pk_add_f32 v[154:155], v[168:169], v[162:163]
	v_mov_b32_e32 v162, v156
	v_mov_b32_e32 v163, v164
	v_mov_b32_e32 v164, v157
	v_pk_add_f32 v[156:157], v[162:163], v[164:165]
	v_pk_add_f32 v[154:155], v[154:155], v[156:157]
	v_mov_b32_e32 v157, v158
	v_pk_add_f32 v[154:155], v[166:167], v[154:155]
	v_mov_b32_e32 v156, v154
	v_mov_b32_e32 v158, v155
	v_pk_add_f32 v[154:155], v[156:157], v[158:159]
	v_pk_fma_f32 v[154:155], v[154:155], s[16:17], v[176:177] op_sel_hi:[1,0,0]
	v_mul_f32_e32 v138, 0x4b800000, v155
	v_cmp_gt_f32_e64 s[42:43], s39, v155
	v_cmp_gt_f32_e32 vcc, s39, v154
	s_nop 0
	v_cndmask_b32_e64 v138, v155, v138, s[42:43]
	v_rsq_f32_e32 v138, v138
	s_nop 0
	v_mul_f32_e32 v140, 0x45800000, v138
	v_cndmask_b32_e64 v138, v138, v140, s[42:43]
	v_mul_f32_e32 v140, 0x4b800000, v154
	v_cndmask_b32_e32 v140, v154, v140, vcc
	v_rsq_f32_e32 v140, v140
	s_nop 0
	v_mul_f32_e32 v142, 0x45800000, v140
	v_cndmask_b32_e32 v153, v140, v142, vcc
	v_and_or_b32 v140, v177, 64, v139
	v_lshlrev_b32_e32 v155, 2, v140
	ds_bpermute_b32 v154, v155, v138
	ds_bpermute_b32 v144, v155, v153
	ds_bpermute_b32 v150, v155, v138 offset:64
	ds_bpermute_b32 v142, v155, v153 offset:64
	ds_bpermute_b32 v148, v155, v138 offset:128
	s_waitcnt lgkmcnt(4)
	v_pk_mul_f32 v[124:125], v[124:125], v[154:155] op_sel_hi:[1,0]
	ds_bpermute_b32 v140, v155, v153 offset:128
	ds_bpermute_b32 v146, v155, v138 offset:192
	ds_bpermute_b32 v138, v155, v153 offset:192
	v_mul_f32_e32 v155, 0xbfb8aa3b, v124
	v_exp_f32_e32 v156, v155
	v_mul_f32_e32 v155, 0xbfb8aa3b, v125
	v_exp_f32_e32 v157, v155
	v_ashrrev_i32_e32 v153, 31, v152
	s_waitcnt lgkmcnt(5)
	v_pk_mul_f32 v[108:109], v[108:109], v[150:151] op_sel_hi:[1,0]
	v_pk_mul_f32 v[104:105], v[104:105], v[150:151] op_sel_hi:[1,0]
	v_pk_add_f32 v[156:157], v[156:157], 1.0 op_sel_hi:[1,0]
	v_pk_mul_f32 v[106:107], v[106:107], v[150:151] op_sel_hi:[1,0]
	v_pk_mul_f32 v[100:101], v[100:101], v[150:151] op_sel_hi:[1,0]
	v_pk_mul_f32 v[96:97], v[96:97], v[150:151] op_sel_hi:[1,0]
	v_pk_mul_f32 v[98:99], v[98:99], v[150:151] op_sel_hi:[1,0]
	v_rcp_f32_e32 v157, v157
	s_waitcnt lgkmcnt(3)
	v_pk_mul_f32 v[92:93], v[92:93], v[148:149] op_sel_hi:[1,0]
	v_pk_mul_f32 v[88:89], v[88:89], v[148:149] op_sel_hi:[1,0]
	v_pk_mul_f32 v[90:91], v[90:91], v[148:149] op_sel_hi:[1,0]
	v_rcp_f32_e32 v156, v156
	s_nop 0
	v_pk_mul_f32 v[124:125], v[124:125], v[156:157]
	v_pk_mul_f32 v[120:121], v[120:121], v[154:155] op_sel_hi:[1,0]
	v_pk_mul_f32 v[84:85], v[84:85], v[148:149] op_sel_hi:[1,0]
	v_pk_mul_f32 v[120:121], v[120:121], v[124:125]
	v_pk_mul_f32 v[124:125], v[126:127], v[154:155] op_sel_hi:[1,0]
	v_pk_mul_f32 v[80:81], v[80:81], v[148:149] op_sel_hi:[1,0]
	v_mul_f32_e32 v126, 0xbfb8aa3b, v124
	v_mul_f32_e32 v127, 0xbfb8aa3b, v125
	v_exp_f32_e32 v126, v126
	v_exp_f32_e32 v127, v127
	v_pk_mul_f32 v[82:83], v[82:83], v[148:149] op_sel_hi:[1,0]
	s_waitcnt lgkmcnt(1)
; DI unsigned pk2(float lo, float hi) { const f32x2_t v = {lo, hi}; const bf16x2_t b = __builtin_convertvector(v, bf16x2_t); return __builtin_bit_cast(unsigned, b); }
;     DI void operator()(const pg8::f32x4 (&acc)[2][2][4][2], const pg8::Unit& u, int wr, int wc, int fr, int fq) const {
;     ...
; #pragma unroll
;         for (int ai = 0; ai < 2; ++ai)
; #pragma unroll
;             for (int m = 0; m < 4; ++m) {
;                 const int row = row0 + ai * 128 + m * 16; const float r = rs[ai][m];
;                 float hv[8];
; #pragma unroll
;                 for (int n = 0; n < 2; ++n) { const pg8::f32x4 g = acc[ai][0][m][n] * r, uu = acc[ai][1][m][n] * r;
; #pragma unroll
;                     for (int e = 0; e < 4; ++e) hv[4 * n + e] = g[e] * __frcp_rn(1.0f + __expf(-g[e])) * uu[e]; }
;                 u32x4 w; w.x = pk2(hv[0], hv[1]); w.y = pk2(hv[2], hv[3]); w.z = pk2(hv[4], hv[5]); w.w = pk2(hv[6], hv[7]);
;                 *(u32x4*)(H + (size_t)row * DFF + col0) = w;
	v_pk_mul_f32 v[76:77], v[76:77], v[146:147] op_sel_hi:[1,0]
	v_pk_mul_f32 v[72:73], v[72:73], v[146:147] op_sel_hi:[1,0]
	v_pk_add_f32 v[126:127], v[126:127], 1.0 op_sel_hi:[1,0]
	v_pk_mul_f32 v[74:75], v[74:75], v[146:147] op_sel_hi:[1,0]
	v_pk_mul_f32 v[68:69], v[68:69], v[146:147] op_sel_hi:[1,0]
	v_pk_mul_f32 v[64:65], v[64:65], v[146:147] op_sel_hi:[1,0]
	v_pk_mul_f32 v[66:67], v[66:67], v[146:147] op_sel_hi:[1,0]
	v_rcp_f32_e32 v127, v127
	v_pk_mul_f32 v[60:61], v[60:61], v[144:145] op_sel_hi:[1,0]
	v_pk_mul_f32 v[56:57], v[56:57], v[144:145] op_sel_hi:[1,0]
	v_pk_mul_f32 v[58:59], v[58:59], v[144:145] op_sel_hi:[1,0]
	v_rcp_f32_e32 v126, v126
	s_nop 0
	v_pk_mul_f32 v[124:125], v[124:125], v[126:127]
	v_pk_mul_f32 v[122:123], v[122:123], v[154:155] op_sel_hi:[1,0]
	v_pk_mul_f32 v[116:117], v[116:117], v[154:155] op_sel_hi:[1,0]
	v_pk_mul_f32 v[122:123], v[122:123], v[124:125]
	v_mul_f32_e32 v124, 0xbfb8aa3b, v116
	v_mul_f32_e32 v125, 0xbfb8aa3b, v117
	v_exp_f32_e32 v124, v124
	v_exp_f32_e32 v125, v125
	v_pk_mul_f32 v[52:53], v[52:53], v[144:145] op_sel_hi:[1,0]
	v_pk_mul_f32 v[48:49], v[48:49], v[144:145] op_sel_hi:[1,0]
	v_pk_mul_f32 v[50:51], v[50:51], v[144:145] op_sel_hi:[1,0]
	v_pk_add_f32 v[124:125], v[124:125], 1.0 op_sel_hi:[1,0]
	v_pk_mul_f32 v[44:45], v[44:45], v[142:143] op_sel_hi:[1,0]
	v_pk_mul_f32 v[40:41], v[40:41], v[142:143] op_sel_hi:[1,0]
	v_pk_mul_f32 v[42:43], v[42:43], v[142:143] op_sel_hi:[1,0]
	v_pk_mul_f32 v[36:37], v[36:37], v[142:143] op_sel_hi:[1,0]
	v_rcp_f32_e32 v125, v125
	v_pk_mul_f32 v[32:33], v[32:33], v[142:143] op_sel_hi:[1,0]
	v_pk_mul_f32 v[34:35], v[34:35], v[142:143] op_sel_hi:[1,0]
	v_pk_mul_f32 v[28:29], v[28:29], v[140:141] op_sel_hi:[1,0]
	v_rcp_f32_e32 v124, v124
	s_nop 0
	v_pk_mul_f32 v[116:117], v[116:117], v[124:125]
	v_pk_mul_f32 v[112:113], v[112:113], v[154:155] op_sel_hi:[1,0]
	v_pk_mul_f32 v[24:25], v[24:25], v[140:141] op_sel_hi:[1,0]
	v_pk_mul_f32 v[112:113], v[112:113], v[116:117]
	v_pk_mul_f32 v[116:117], v[118:119], v[154:155] op_sel_hi:[1,0]
	v_pk_mul_f32 v[26:27], v[26:27], v[140:141] op_sel_hi:[1,0]
	v_mul_f32_e32 v118, 0xbfb8aa3b, v116
	v_mul_f32_e32 v119, 0xbfb8aa3b, v117
	v_exp_f32_e32 v118, v118
	v_exp_f32_e32 v119, v119
	v_pk_mul_f32 v[20:21], v[20:21], v[140:141] op_sel_hi:[1,0]
	v_pk_mul_f32 v[16:17], v[16:17], v[140:141] op_sel_hi:[1,0]
	v_pk_mul_f32 v[18:19], v[18:19], v[140:141] op_sel_hi:[1,0]
	v_pk_add_f32 v[118:119], v[118:119], 1.0 op_sel_hi:[1,0]
	s_waitcnt lgkmcnt(0)
	v_pk_mul_f32 v[12:13], v[12:13], v[138:139] op_sel_hi:[1,0]
	v_pk_mul_f32 v[8:9], v[8:9], v[138:139] op_sel_hi:[1,0]
	v_pk_mul_f32 v[10:11], v[10:11], v[138:139] op_sel_hi:[1,0]
	v_pk_mul_f32 v[4:5], v[4:5], v[138:139] op_sel_hi:[1,0]
	v_rcp_f32_e32 v119, v119
	v_pk_mul_f32 v[0:1], v[0:1], v[138:139] op_sel_hi:[1,0]
	v_pk_mul_f32 v[2:3], v[2:3], v[138:139] op_sel_hi:[1,0]
	v_rcp_f32_e32 v118, v118
	s_nop 0
	v_pk_mul_f32 v[116:117], v[116:117], v[118:119]
	v_pk_mul_f32 v[114:115], v[114:115], v[154:155] op_sel_hi:[1,0]
	v_cvt_pk_bf16_f32 v118, v112, v113
	v_pk_mul_f32 v[114:115], v[114:115], v[116:117]
	v_mov_b64_e32 v[112:113], s[82:83]
	v_cvt_pk_bf16_f32 v116, v120, v121
	v_cvt_pk_bf16_f32 v119, v114, v115
	v_mad_i64_i32 v[120:121], s[16:17], v151, s9, v[112:113]
	v_lshlrev_b64 v[114:115], 1, v[152:153]
	v_cvt_pk_bf16_f32 v117, v122, v123
	v_lshl_add_u64 v[120:121], v[120:121], 0, v[114:115]
	global_store_dwordx4 v[120:121], v[116:119], off
	s_nop 1
	v_mul_f32_e32 v116, 0xbfb8aa3b, v108
	v_mul_f32_e32 v117, 0xbfb8aa3b, v109
	v_exp_f32_e32 v116, v116
	v_exp_f32_e32 v117, v117
	s_nop 0
	v_pk_add_f32 v[116:117], v[116:117], 1.0 op_sel_hi:[1,0]
	v_rcp_f32_e32 v117, v117
	v_rcp_f32_e32 v116, v116
	s_nop 0
	v_pk_mul_f32 v[108:109], v[108:109], v[116:117]
	v_pk_mul_f32 v[104:105], v[104:105], v[108:109]
	v_pk_mul_f32 v[108:109], v[110:111], v[150:151] op_sel_hi:[1,0]
	v_mul_f32_e32 v110, 0xbfb8aa3b, v108
	v_mul_f32_e32 v111, 0xbfb8aa3b, v109
	v_exp_f32_e32 v110, v110
	v_exp_f32_e32 v111, v111
	s_nop 0
	v_pk_add_f32 v[110:111], v[110:111], 1.0 op_sel_hi:[1,0]
	v_rcp_f32_e32 v111, v111
	v_rcp_f32_e32 v110, v110
	s_nop 0
	v_pk_mul_f32 v[108:109], v[108:109], v[110:111]
	v_pk_mul_f32 v[106:107], v[106:107], v[108:109]
	v_mul_f32_e32 v108, 0xbfb8aa3b, v100
	v_mul_f32_e32 v109, 0xbfb8aa3b, v101
	v_exp_f32_e32 v108, v108
	v_exp_f32_e32 v109, v109
	s_nop 0
	v_pk_add_f32 v[108:109], v[108:109], 1.0 op_sel_hi:[1,0]
	v_rcp_f32_e32 v109, v109
	v_rcp_f32_e32 v108, v108
	s_nop 0
	v_pk_mul_f32 v[100:101], v[100:101], v[108:109]
	v_pk_mul_f32 v[100:101], v[96:97], v[100:101]
	v_pk_mul_f32 v[96:97], v[102:103], v[150:151] op_sel_hi:[1,0]
	v_mul_f32_e32 v102, 0xbfb8aa3b, v96
	v_mul_f32_e32 v103, 0xbfb8aa3b, v97
	v_exp_f32_e32 v102, v102
	v_exp_f32_e32 v103, v103
	s_nop 0
	v_pk_add_f32 v[102:103], v[102:103], 1.0 op_sel_hi:[1,0]
	v_rcp_f32_e32 v103, v103
	v_rcp_f32_e32 v102, v102
	s_nop 0
	v_pk_mul_f32 v[96:97], v[96:97], v[102:103]
	v_or_b32_e32 v108, 16, v151
	v_pk_mul_f32 v[102:103], v[98:99], v[96:97]
	v_cvt_pk_bf16_f32 v98, v100, v101
	v_mad_i64_i32 v[100:101], s[16:17], v108, s9, v[112:113]
	v_cvt_pk_bf16_f32 v96, v104, v105
	v_cvt_pk_bf16_f32 v97, v106, v107
	v_cvt_pk_bf16_f32 v99, v102, v103
	v_lshl_add_u64 v[100:101], v[100:101], 0, v[114:115]
	global_store_dwordx4 v[100:101], v[96:99], off
	s_nop 1
	v_mul_f32_e32 v96, 0xbfb8aa3b, v92
	v_mul_f32_e32 v97, 0xbfb8aa3b, v93
	v_exp_f32_e32 v96, v96
	v_exp_f32_e32 v97, v97
	s_nop 0
	v_pk_add_f32 v[96:97], v[96:97], 1.0 op_sel_hi:[1,0]
	v_rcp_f32_e32 v97, v97
	v_rcp_f32_e32 v96, v96
	s_nop 0
	v_pk_mul_f32 v[92:93], v[92:93], v[96:97]
	v_pk_mul_f32 v[88:89], v[88:89], v[92:93]
; DI unsigned pk2(float lo, float hi) { const f32x2_t v = {lo, hi}; const bf16x2_t b = __builtin_convertvector(v, bf16x2_t); return __builtin_bit_cast(unsigned, b); }
;     DI void operator()(const pg8::f32x4 (&acc)[2][2][4][2], const pg8::Unit& u, int wr, int wc, int fr, int fq) const {
;     ...
; #pragma unroll
;         for (int ai = 0; ai < 2; ++ai)
; #pragma unroll
;             for (int m = 0; m < 4; ++m) {
;                 const int row = row0 + ai * 128 + m * 16; const float r = rs[ai][m];
;                 float hv[8];
; #pragma unroll
;                 for (int n = 0; n < 2; ++n) { const pg8::f32x4 g = acc[ai][0][m][n] * r, uu = acc[ai][1][m][n] * r;
; #pragma unroll
;                     for (int e = 0; e < 4; ++e) hv[4 * n + e] = g[e] * __frcp_rn(1.0f + __expf(-g[e])) * uu[e]; }
;                 u32x4 w; w.x = pk2(hv[0], hv[1]); w.y = pk2(hv[2], hv[3]); w.z = pk2(hv[4], hv[5]); w.w = pk2(hv[6], hv[7]);
;                 *(u32x4*)(H + (size_t)row * DFF + col0) = w;
	v_pk_mul_f32 v[92:93], v[94:95], v[148:149] op_sel_hi:[1,0]
	v_mul_f32_e32 v94, 0xbfb8aa3b, v92
	v_mul_f32_e32 v95, 0xbfb8aa3b, v93
	v_exp_f32_e32 v94, v94
	v_exp_f32_e32 v95, v95
	s_nop 0
	v_pk_add_f32 v[94:95], v[94:95], 1.0 op_sel_hi:[1,0]
	v_rcp_f32_e32 v95, v95
	v_rcp_f32_e32 v94, v94
	s_nop 0
	v_pk_mul_f32 v[92:93], v[92:93], v[94:95]
	v_pk_mul_f32 v[90:91], v[90:91], v[92:93]
	v_mul_f32_e32 v92, 0xbfb8aa3b, v84
	v_mul_f32_e32 v93, 0xbfb8aa3b, v85
	v_exp_f32_e32 v92, v92
	v_exp_f32_e32 v93, v93
	s_nop 0
	v_pk_add_f32 v[92:93], v[92:93], 1.0 op_sel_hi:[1,0]
	v_rcp_f32_e32 v93, v93
	v_rcp_f32_e32 v92, v92
	s_nop 0
	v_pk_mul_f32 v[84:85], v[84:85], v[92:93]
	v_pk_mul_f32 v[84:85], v[80:81], v[84:85]
	v_pk_mul_f32 v[80:81], v[86:87], v[148:149] op_sel_hi:[1,0]
	v_mul_f32_e32 v86, 0xbfb8aa3b, v80
	v_mul_f32_e32 v87, 0xbfb8aa3b, v81
	v_exp_f32_e32 v86, v86
	v_exp_f32_e32 v87, v87
	s_nop 0
	v_pk_add_f32 v[86:87], v[86:87], 1.0 op_sel_hi:[1,0]
	v_rcp_f32_e32 v87, v87
	v_rcp_f32_e32 v86, v86
	s_nop 0
	v_pk_mul_f32 v[80:81], v[80:81], v[86:87]
	v_or_b32_e32 v92, 32, v151
	v_pk_mul_f32 v[86:87], v[82:83], v[80:81]
	v_cvt_pk_bf16_f32 v82, v84, v85
	v_mad_i64_i32 v[84:85], s[16:17], v92, s9, v[112:113]
	v_cvt_pk_bf16_f32 v80, v88, v89
	v_cvt_pk_bf16_f32 v81, v90, v91
	v_cvt_pk_bf16_f32 v83, v86, v87
	v_lshl_add_u64 v[84:85], v[84:85], 0, v[114:115]
	global_store_dwordx4 v[84:85], v[80:83], off
	s_nop 1
	v_mul_f32_e32 v80, 0xbfb8aa3b, v76
	v_mul_f32_e32 v81, 0xbfb8aa3b, v77
	v_exp_f32_e32 v80, v80
	v_exp_f32_e32 v81, v81
	s_nop 0
	v_pk_add_f32 v[80:81], v[80:81], 1.0 op_sel_hi:[1,0]
	v_rcp_f32_e32 v81, v81
	v_rcp_f32_e32 v80, v80
	s_nop 0
	v_pk_mul_f32 v[76:77], v[76:77], v[80:81]
	v_pk_mul_f32 v[72:73], v[72:73], v[76:77]
	v_pk_mul_f32 v[76:77], v[78:79], v[146:147] op_sel_hi:[1,0]
	v_mul_f32_e32 v78, 0xbfb8aa3b, v76
	v_mul_f32_e32 v79, 0xbfb8aa3b, v77
	v_exp_f32_e32 v78, v78
	v_exp_f32_e32 v79, v79
	s_nop 0
	v_pk_add_f32 v[78:79], v[78:79], 1.0 op_sel_hi:[1,0]
	v_rcp_f32_e32 v79, v79
	v_rcp_f32_e32 v78, v78
	s_nop 0
	v_pk_mul_f32 v[76:77], v[76:77], v[78:79]
	v_pk_mul_f32 v[74:75], v[74:75], v[76:77]
	v_mul_f32_e32 v76, 0xbfb8aa3b, v68
	v_mul_f32_e32 v77, 0xbfb8aa3b, v69
	v_exp_f32_e32 v76, v76
	v_exp_f32_e32 v77, v77
	s_nop 0
	v_pk_add_f32 v[76:77], v[76:77], 1.0 op_sel_hi:[1,0]
	v_rcp_f32_e32 v77, v77
	v_rcp_f32_e32 v76, v76
	s_nop 0
	v_pk_mul_f32 v[68:69], v[68:69], v[76:77]
	v_pk_mul_f32 v[68:69], v[64:65], v[68:69]
	v_pk_mul_f32 v[64:65], v[70:71], v[146:147] op_sel_hi:[1,0]
	v_mul_f32_e32 v70, 0xbfb8aa3b, v64
	v_mul_f32_e32 v71, 0xbfb8aa3b, v65
	v_exp_f32_e32 v70, v70
	v_exp_f32_e32 v71, v71
	s_nop 0
	v_pk_add_f32 v[70:71], v[70:71], 1.0 op_sel_hi:[1,0]
	v_rcp_f32_e32 v71, v71
	v_rcp_f32_e32 v70, v70
	s_nop 0
	v_pk_mul_f32 v[64:65], v[64:65], v[70:71]
	v_or_b32_e32 v76, 48, v151
	v_pk_mul_f32 v[70:71], v[66:67], v[64:65]
	v_cvt_pk_bf16_f32 v66, v68, v69
	v_mad_i64_i32 v[68:69], s[16:17], v76, s9, v[112:113]
	v_cvt_pk_bf16_f32 v64, v72, v73
	v_cvt_pk_bf16_f32 v65, v74, v75
	v_cvt_pk_bf16_f32 v67, v70, v71
	v_lshl_add_u64 v[68:69], v[68:69], 0, v[114:115]
	global_store_dwordx4 v[68:69], v[64:67], off
	s_nop 1
	v_mul_f32_e32 v64, 0xbfb8aa3b, v60
	v_mul_f32_e32 v65, 0xbfb8aa3b, v61
	v_exp_f32_e32 v64, v64
	v_exp_f32_e32 v65, v65
	v_add_u32_e32 v66, 0x80, v151
	v_pk_add_f32 v[64:65], v[64:65], 1.0 op_sel_hi:[1,0]
	v_rcp_f32_e32 v65, v65
	v_rcp_f32_e32 v64, v64
	s_nop 0
	v_pk_mul_f32 v[60:61], v[60:61], v[64:65]
	v_pk_mul_f32 v[56:57], v[56:57], v[60:61]
	v_pk_mul_f32 v[60:61], v[62:63], v[144:145] op_sel_hi:[1,0]
	v_mul_f32_e32 v62, 0xbfb8aa3b, v60
	v_mul_f32_e32 v63, 0xbfb8aa3b, v61
	v_exp_f32_e32 v62, v62
	v_exp_f32_e32 v63, v63
	s_nop 0
	v_pk_add_f32 v[62:63], v[62:63], 1.0 op_sel_hi:[1,0]
	v_rcp_f32_e32 v63, v63
	v_rcp_f32_e32 v62, v62
	s_nop 0
	v_pk_mul_f32 v[60:61], v[60:61], v[62:63]
	v_pk_mul_f32 v[58:59], v[58:59], v[60:61]
	v_mul_f32_e32 v60, 0xbfb8aa3b, v52
	v_mul_f32_e32 v61, 0xbfb8aa3b, v53
	v_exp_f32_e32 v60, v60
	v_exp_f32_e32 v61, v61
	s_nop 0
	v_pk_add_f32 v[60:61], v[60:61], 1.0 op_sel_hi:[1,0]
	v_rcp_f32_e32 v61, v61
	v_rcp_f32_e32 v60, v60
	s_nop 0
	v_pk_mul_f32 v[52:53], v[52:53], v[60:61]
	v_pk_mul_f32 v[52:53], v[48:49], v[52:53]
	v_pk_mul_f32 v[48:49], v[54:55], v[144:145] op_sel_hi:[1,0]
	v_mul_f32_e32 v54, 0xbfb8aa3b, v48
	v_mul_f32_e32 v55, 0xbfb8aa3b, v49
	v_exp_f32_e32 v54, v54
	v_exp_f32_e32 v55, v55
	s_nop 0
	v_pk_add_f32 v[54:55], v[54:55], 1.0 op_sel_hi:[1,0]
	v_rcp_f32_e32 v55, v55
	v_rcp_f32_e32 v54, v54
	s_nop 0
	v_pk_mul_f32 v[48:49], v[48:49], v[54:55]
	v_pk_mul_f32 v[54:55], v[50:51], v[48:49]
	v_cvt_pk_bf16_f32 v50, v52, v53
	v_mad_i64_i32 v[52:53], s[16:17], v66, s9, v[112:113]
	v_cvt_pk_bf16_f32 v48, v56, v57
	v_cvt_pk_bf16_f32 v49, v58, v59
	v_cvt_pk_bf16_f32 v51, v54, v55
	v_lshl_add_u64 v[52:53], v[52:53], 0, v[114:115]
	global_store_dwordx4 v[52:53], v[48:51], off
	s_nop 1
	v_mul_f32_e32 v48, 0xbfb8aa3b, v44
	v_mul_f32_e32 v49, 0xbfb8aa3b, v45
	v_exp_f32_e32 v48, v48
	v_exp_f32_e32 v49, v49
	s_nop 0
	v_pk_add_f32 v[48:49], v[48:49], 1.0 op_sel_hi:[1,0]
	v_rcp_f32_e32 v49, v49
; #define PG8_BAR __builtin_amdgcn_s_barrier()
; DI unsigned pk2(float lo, float hi) { const f32x2_t v = {lo, hi}; const bf16x2_t b = __builtin_convertvector(v, bf16x2_t); return __builtin_bit_cast(unsigned, b); }
; template <class Epi, class Sched, bool ALIGN_EPI = false, bool SP2 = false>
; __device__ __forceinline__ void gemm_phase(PG8_LAS unsigned char* lds, const Gemm g, const Sched& S, const Epi& E, const int tid) {
;     ...
;         if constexpr (ALIGN_EPI) { if (wr == 0) PG8_BAR; }
;         if constexpr (!Epi::AFTER_DRAIN) { E(acc, cur, wr, wc, fr, fq); S.done(cur); }
;         if (!has_next) break;
; #pragma unroll
;         for (int a = 0; a < 2; ++a)
; #pragma unroll
;             for (int b = 0; b < 2; ++b)
; #pragma unroll
;                 for (int m = 0; m < 4; ++m)
; #pragma unroll
;                     for (int n = 0; n < 2; ++n) acc[a][b][m][n] = (f32x4){0.f, 0.f, 0.f, 0.f};
;         cur = nxt; cA = nA; cB = nB; ++ui;
;         if constexpr (ALIGN_EPI) { if (wr == 1) PG8_BAR; }
;     DI void operator()(const pg8::f32x4 (&acc)[2][2][4][2], const pg8::Unit& u, int wr, int wc, int fr, int fq) const {
;     ...
; #pragma unroll
;         for (int ai = 0; ai < 2; ++ai)
; #pragma unroll
;             for (int m = 0; m < 4; ++m) {
;                 const int row = row0 + ai * 128 + m * 16; const float r = rs[ai][m];
;                 float hv[8];
; #pragma unroll
;                 for (int n = 0; n < 2; ++n) { const pg8::f32x4 g = acc[ai][0][m][n] * r, uu = acc[ai][1][m][n] * r;
; #pragma unroll
;                     for (int e = 0; e < 4; ++e) hv[4 * n + e] = g[e] * __frcp_rn(1.0f + __expf(-g[e])) * uu[e]; }
;                 u32x4 w; w.x = pk2(hv[0], hv[1]); w.y = pk2(hv[2], hv[3]); w.z = pk2(hv[4], hv[5]); w.w = pk2(hv[6], hv[7]);
;                 *(u32x4*)(H + (size_t)row * DFF + col0) = w;
	v_rcp_f32_e32 v48, v48
	s_nop 0
	v_pk_mul_f32 v[44:45], v[44:45], v[48:49]
	v_pk_mul_f32 v[40:41], v[40:41], v[44:45]
	v_pk_mul_f32 v[44:45], v[46:47], v[142:143] op_sel_hi:[1,0]
	v_mul_f32_e32 v46, 0xbfb8aa3b, v44
	v_mul_f32_e32 v47, 0xbfb8aa3b, v45
	v_exp_f32_e32 v46, v46
	v_exp_f32_e32 v47, v47
	s_nop 0
	v_pk_add_f32 v[46:47], v[46:47], 1.0 op_sel_hi:[1,0]
	v_rcp_f32_e32 v47, v47
	v_rcp_f32_e32 v46, v46
	s_nop 0
	v_pk_mul_f32 v[44:45], v[44:45], v[46:47]
	v_pk_mul_f32 v[42:43], v[42:43], v[44:45]
	v_mul_f32_e32 v44, 0xbfb8aa3b, v36
	v_mul_f32_e32 v45, 0xbfb8aa3b, v37
	v_exp_f32_e32 v44, v44
	v_exp_f32_e32 v45, v45
	s_nop 0
	v_pk_add_f32 v[44:45], v[44:45], 1.0 op_sel_hi:[1,0]
	v_rcp_f32_e32 v45, v45
	v_rcp_f32_e32 v44, v44
	s_nop 0
	v_pk_mul_f32 v[36:37], v[36:37], v[44:45]
	v_pk_mul_f32 v[36:37], v[32:33], v[36:37]
	v_pk_mul_f32 v[32:33], v[38:39], v[142:143] op_sel_hi:[1,0]
	v_mul_f32_e32 v38, 0xbfb8aa3b, v32
	v_mul_f32_e32 v39, 0xbfb8aa3b, v33
	v_exp_f32_e32 v38, v38
	v_exp_f32_e32 v39, v39
	s_nop 0
	v_pk_add_f32 v[38:39], v[38:39], 1.0 op_sel_hi:[1,0]
	v_rcp_f32_e32 v39, v39
	v_rcp_f32_e32 v38, v38
	s_nop 0
	v_pk_mul_f32 v[32:33], v[32:33], v[38:39]
	v_add_u32_e32 v44, 0x90, v151
	v_pk_mul_f32 v[38:39], v[34:35], v[32:33]
	v_cvt_pk_bf16_f32 v34, v36, v37
	v_mad_i64_i32 v[36:37], s[16:17], v44, s9, v[112:113]
	v_cvt_pk_bf16_f32 v32, v40, v41
	v_cvt_pk_bf16_f32 v33, v42, v43
	v_cvt_pk_bf16_f32 v35, v38, v39
	v_lshl_add_u64 v[36:37], v[36:37], 0, v[114:115]
	global_store_dwordx4 v[36:37], v[32:35], off
	s_nop 1
	v_mul_f32_e32 v32, 0xbfb8aa3b, v28
	v_mul_f32_e32 v33, 0xbfb8aa3b, v29
	v_exp_f32_e32 v32, v32
	v_exp_f32_e32 v33, v33
	s_nop 0
	v_pk_add_f32 v[32:33], v[32:33], 1.0 op_sel_hi:[1,0]
	v_rcp_f32_e32 v33, v33
	v_rcp_f32_e32 v32, v32
	s_nop 0
	v_pk_mul_f32 v[28:29], v[28:29], v[32:33]
	v_pk_mul_f32 v[24:25], v[24:25], v[28:29]
	v_pk_mul_f32 v[28:29], v[30:31], v[140:141] op_sel_hi:[1,0]
	v_mul_f32_e32 v30, 0xbfb8aa3b, v28
	v_mul_f32_e32 v31, 0xbfb8aa3b, v29
	v_exp_f32_e32 v30, v30
	v_exp_f32_e32 v31, v31
	s_nop 0
	v_pk_add_f32 v[30:31], v[30:31], 1.0 op_sel_hi:[1,0]
	v_rcp_f32_e32 v31, v31
	v_rcp_f32_e32 v30, v30
	s_nop 0
	v_pk_mul_f32 v[28:29], v[28:29], v[30:31]
	v_pk_mul_f32 v[26:27], v[26:27], v[28:29]
	v_mul_f32_e32 v28, 0xbfb8aa3b, v20
	v_mul_f32_e32 v29, 0xbfb8aa3b, v21
	v_exp_f32_e32 v28, v28
	v_exp_f32_e32 v29, v29
	s_nop 0
	v_pk_add_f32 v[28:29], v[28:29], 1.0 op_sel_hi:[1,0]
	v_rcp_f32_e32 v29, v29
	v_rcp_f32_e32 v28, v28
	s_nop 0
	v_pk_mul_f32 v[20:21], v[20:21], v[28:29]
	v_pk_mul_f32 v[20:21], v[16:17], v[20:21]
	v_pk_mul_f32 v[16:17], v[22:23], v[140:141] op_sel_hi:[1,0]
	v_mul_f32_e32 v22, 0xbfb8aa3b, v16
	v_mul_f32_e32 v23, 0xbfb8aa3b, v17
	v_exp_f32_e32 v22, v22
	v_exp_f32_e32 v23, v23
	s_nop 0
	v_pk_add_f32 v[22:23], v[22:23], 1.0 op_sel_hi:[1,0]
	v_rcp_f32_e32 v23, v23
	v_rcp_f32_e32 v22, v22
	s_nop 0
	v_pk_mul_f32 v[16:17], v[16:17], v[22:23]
	v_add_u32_e32 v28, 0xa0, v151
	v_pk_mul_f32 v[22:23], v[18:19], v[16:17]
	v_cvt_pk_bf16_f32 v18, v20, v21
	v_mad_i64_i32 v[20:21], s[16:17], v28, s9, v[112:113]
	v_cvt_pk_bf16_f32 v16, v24, v25
	v_cvt_pk_bf16_f32 v17, v26, v27
	v_cvt_pk_bf16_f32 v19, v22, v23
	v_lshl_add_u64 v[20:21], v[20:21], 0, v[114:115]
	global_store_dwordx4 v[20:21], v[16:19], off
	s_nop 1
	v_mul_f32_e32 v16, 0xbfb8aa3b, v12
	v_mul_f32_e32 v17, 0xbfb8aa3b, v13
	v_exp_f32_e32 v16, v16
	v_exp_f32_e32 v17, v17
	s_nop 0
	v_pk_add_f32 v[16:17], v[16:17], 1.0 op_sel_hi:[1,0]
	v_rcp_f32_e32 v17, v17
	v_rcp_f32_e32 v16, v16
	s_nop 0
	v_pk_mul_f32 v[12:13], v[12:13], v[16:17]
	v_pk_mul_f32 v[8:9], v[8:9], v[12:13]
	v_pk_mul_f32 v[12:13], v[14:15], v[138:139] op_sel_hi:[1,0]
	v_mul_f32_e32 v14, 0xbfb8aa3b, v12
	v_mul_f32_e32 v15, 0xbfb8aa3b, v13
	v_exp_f32_e32 v14, v14
	v_exp_f32_e32 v15, v15
	s_nop 0
	v_pk_add_f32 v[14:15], v[14:15], 1.0 op_sel_hi:[1,0]
	v_rcp_f32_e32 v15, v15
	v_rcp_f32_e32 v14, v14
	s_nop 0
	v_pk_mul_f32 v[12:13], v[12:13], v[14:15]
	v_pk_mul_f32 v[10:11], v[10:11], v[12:13]
	v_mul_f32_e32 v12, 0xbfb8aa3b, v4
	v_mul_f32_e32 v13, 0xbfb8aa3b, v5
	v_exp_f32_e32 v12, v12
	v_exp_f32_e32 v13, v13
	s_nop 0
	v_pk_add_f32 v[12:13], v[12:13], 1.0 op_sel_hi:[1,0]
	v_rcp_f32_e32 v13, v13
	v_rcp_f32_e32 v12, v12
	s_nop 0
	v_pk_mul_f32 v[4:5], v[4:5], v[12:13]
	v_pk_mul_f32 v[4:5], v[0:1], v[4:5]
	v_pk_mul_f32 v[0:1], v[6:7], v[138:139] op_sel_hi:[1,0]
	v_mul_f32_e32 v6, 0xbfb8aa3b, v0
	v_mul_f32_e32 v7, 0xbfb8aa3b, v1
	v_exp_f32_e32 v6, v6
	v_exp_f32_e32 v7, v7
	s_nop 0
	v_pk_add_f32 v[6:7], v[6:7], 1.0 op_sel_hi:[1,0]
	v_rcp_f32_e32 v7, v7
	v_rcp_f32_e32 v6, v6
	s_nop 0
	v_pk_mul_f32 v[0:1], v[0:1], v[6:7]
	v_add_u32_e32 v12, 0xb0, v151
	v_pk_mul_f32 v[6:7], v[2:3], v[0:1]
	v_cvt_pk_bf16_f32 v2, v4, v5
	v_mad_i64_i32 v[4:5], s[16:17], v12, s9, v[112:113]
	v_cvt_pk_bf16_f32 v0, v8, v9
	v_cvt_pk_bf16_f32 v1, v10, v11
	v_cvt_pk_bf16_f32 v3, v6, v7
	v_lshl_add_u64 v[4:5], v[4:5], 0, v[114:115]
	s_mov_b64 s[16:17], -1
	s_andn2_b64 vcc, exec, s[40:41]
	global_store_dwordx4 v[4:5], v[0:3], off
	s_cbranch_vccnz .LBB0_509
	s_andn2_b64 vcc, exec, s[2:3]
	s_cbranch_vccnz .LBB0_508
	s_barrier
	s_branch .LBB0_508

; DI float rowscale(const float* ss, int row) {
;     const f32x4* p = (const f32x4*)(ss + (size_t)row * 16);
;     const f32x4 a = p[0], b = p[1], c = p[2], d = p[3];
;     const float s = (((a.x + a.y) + (a.z + a.w)) + ((b.x + b.y) + (b.z + b.w))) + (((c.x + c.y) + (c.z + c.w)) + ((d.x + d.y) + (d.z + d.w)));
;     return rsqrtf(s * (1.0f / 1024.0f) + EPS);
; }
; DI void rowscales8(const float* ss, int rowbase, int fr, int fq, float (&r)[2][4]) {
;     const int lane = fq * 16 + fr;
;     const float rA = rowscale(ss, rowbase + lane), rB = rowscale(ss, rowbase + 128 + lane);
; #pragma unroll
;     for (int m = 0; m < 4; ++m) { r[0][m] = __shfl(rA, m * 16 + fr); r[1][m] = __shfl(rB, m * 16 + fr); }
; }
;     DI void operator()(const pg8::f32x4 (&acc)[2][2][4][2], const pg8::Unit& u, int wr, int wc, int fr, int fq) const {
;         const int row0 = u.pm * 256 + wr * 64 + fr, col0 = u.pn * 256 + wc * 32 + 8 * fq;
;         float rs[2][4];
;         if (ss) rowscales8(ss, u.pm * 256 + wr * 64, fr, fq, rs);
.LBB0_624:
	s_lshl_b32 s37, s97, 8
	s_andn2_b64 vcc, exec, s[30:31]
	s_add_i32 s37, s37, s81
	s_cbranch_vccnz .LBB0_626
	v_or_b32_e32 v144, s37, v170
	v_ashrrev_i32_e32 v145, 31, v144
	v_lshlrev_b64 v[144:145], 6, v[144:145]
	v_lshl_add_u64 v[156:157], s[4:5], 0, v[144:145]
	global_load_dwordx4 v[144:147], v[156:157], off offset:16
	global_load_dwordx4 v[148:151], v[156:157], off offset:48
	global_load_dwordx4 v[152:155], v[156:157], off
	global_load_dwordx4 v[184:187], v[156:157], off offset:32
	s_mov_b32 s44, 0x3a800000
	s_waitcnt vmcnt(0)
	v_mov_b32_e32 v156, v152
	v_mov_b32_e32 v157, v184
	v_mov_b32_e32 v184, v153
	v_pk_add_f32 v[152:153], v[156:157], v[184:185]
	v_mov_b32_e32 v156, v154
	v_mov_b32_e32 v157, v186
	v_mov_b32_e32 v186, v155
	v_pk_add_f32 v[154:155], v[156:157], v[186:187]
	v_pk_add_f32 v[152:153], v[152:153], v[154:155]
	v_mov_b32_e32 v154, v144
	v_mov_b32_e32 v155, v148
	v_mov_b32_e32 v148, v145
	v_pk_add_f32 v[144:145], v[154:155], v[148:149]
	v_mov_b32_e32 v148, v146
	v_mov_b32_e32 v149, v150
	v_mov_b32_e32 v150, v147
	v_pk_add_f32 v[146:147], v[148:149], v[150:151]
	v_pk_add_f32 v[144:145], v[144:145], v[146:147]
	v_or_b32_e32 v146, 0x80, v170
	v_add_u32_e32 v146, s37, v146
	v_ashrrev_i32_e32 v147, 31, v146
	v_lshlrev_b64 v[146:147], 6, v[146:147]
	v_lshl_add_u64 v[178:179], s[4:5], 0, v[146:147]
	v_pk_add_f32 v[144:145], v[152:153], v[144:145]
	global_load_dwordx4 v[146:149], v[178:179], off offset:16
	global_load_dwordx4 v[150:153], v[178:179], off offset:48
	global_load_dwordx4 v[154:157], v[178:179], off
	global_load_dwordx4 v[184:187], v[178:179], off offset:32
	s_waitcnt vmcnt(1)
	v_mov_b32_e32 v178, v154
	s_waitcnt vmcnt(0)
	v_mov_b32_e32 v179, v184
	v_mov_b32_e32 v184, v155
	v_pk_add_f32 v[154:155], v[178:179], v[184:185]
	v_mov_b32_e32 v178, v156
	v_mov_b32_e32 v179, v186
	v_mov_b32_e32 v186, v157
	v_pk_add_f32 v[156:157], v[178:179], v[186:187]
	v_pk_add_f32 v[154:155], v[154:155], v[156:157]
	v_mov_b32_e32 v156, v146
	v_mov_b32_e32 v157, v150
	v_mov_b32_e32 v150, v147
	v_pk_add_f32 v[146:147], v[156:157], v[150:151]
	v_mov_b32_e32 v150, v148
	v_mov_b32_e32 v151, v152
	v_mov_b32_e32 v152, v149
	v_pk_add_f32 v[148:149], v[150:151], v[152:153]
	v_pk_add_f32 v[146:147], v[146:147], v[148:149]
	v_mov_b32_e32 v149, v144
	v_pk_add_f32 v[146:147], v[154:155], v[146:147]
	v_mov_b32_e32 v148, v146
	v_mov_b32_e32 v144, v147
	v_pk_add_f32 v[144:145], v[148:149], v[144:145]
	v_pk_fma_f32 v[144:145], v[144:145], s[44:45], v[176:177] op_sel_hi:[1,0,0]
	v_mul_f32_e32 v146, 0x4b800000, v145
	v_cmp_gt_f32_e64 s[44:45], s39, v145
	v_cmp_gt_f32_e32 vcc, s39, v144
	s_nop 0
	v_cndmask_b32_e64 v145, v145, v146, s[44:45]
	v_rsq_f32_e32 v145, v145
	s_nop 0
	v_mul_f32_e32 v146, 0x45800000, v145
	v_cndmask_b32_e64 v145, v145, v146, s[44:45]
	v_mul_f32_e32 v146, 0x4b800000, v144
	v_cndmask_b32_e32 v144, v144, v146, vcc
	v_rsq_f32_e32 v144, v144
	s_nop 0
	v_mul_f32_e32 v146, 0x45800000, v144
	v_cndmask_b32_e32 v150, v144, v146, vcc
	v_and_or_b32 v144, v177, 64, v166
	v_lshlrev_b32_e32 v151, 2, v144
	ds_bpermute_b32 v152, v151, v145
	ds_bpermute_b32 v146, v151, v150
	ds_bpermute_b32 v153, v151, v145 offset:64
	ds_bpermute_b32 v147, v151, v150 offset:64
	ds_bpermute_b32 v148, v151, v145 offset:128
	ds_bpermute_b32 v144, v151, v150 offset:128
	ds_bpermute_b32 v149, v151, v145 offset:192
	ds_bpermute_b32 v145, v151, v150 offset:192
	s_branch .LBB0_627

; #define LAS __attribute__((address_space(3)))
; DI void lds_barrier() { asm volatile("s_waitcnt lgkmcnt(0)\n\ts_barrier" ::: "memory"); }
; DI float rowscale(const float* ss, int row) {
;     const f32x4* p = (const f32x4*)(ss + (size_t)row * 16);
;     const f32x4 a = p[0], b = p[1], c = p[2], d = p[3];
;     const float s = (((a.x + a.y) + (a.z + a.w)) + ((b.x + b.y) + (b.z + b.w))) + (((c.x + c.y) + (c.z + c.w)) + ((d.x + d.y) + (d.z + d.w)));
;     return rsqrtf(s * (1.0f / 1024.0f) + EPS);
; template <class Epi> DI void small_gemm(LAS unsigned char* lds, const bf16_t* A, const bf16_t* Bt, int K, const Epi& E, int G, const int tid) {
;     ...
;         for (int ks = 0; ks < nks; ks += 2) {
;             const bf16x8 a0 = *(const bf16x8*)(ap + 16 * ks), a1 = *(const bf16x8*)(ap + 16 * ks + 16);
;             const bf16x8 w00 = *(const bf16x8*)(b0 + 16 * ks), w01 = *(const bf16x8*)(b0 + 16 * ks + 16);
;             const bf16x8 w10 = *(const bf16x8*)(b1 + 16 * ks), w11 = *(const bf16x8*)(b1 + 16 * ks + 16);
;             acc0 = __builtin_amdgcn_mfma_f32_32x32x16_bf16(w00, a0, acc0, 0, 0, 0); acc1 = __builtin_amdgcn_mfma_f32_32x32x16_bf16(w10, a0, acc1, 0, 0, 0);
;             acc0 = __builtin_amdgcn_mfma_f32_32x32x16_bf16(w01, a1, acc0, 0, 0, 0); acc1 = __builtin_amdgcn_mfma_f32_32x32x16_bf16(w11, a1, acc1, 0, 0, 0);
;         }
; #pragma unroll
;         for (int g = 0; g < 4; ++g) {
;             *(LAS f32x4*)(red + (((w * 2 + 0) * 4 + g) * 64 + lane) * 4) = (f32x4){acc0[4 * g], acc0[4 * g + 1], acc0[4 * g + 2], acc0[4 * g + 3]};
;             *(LAS f32x4*)(red + (((w * 2 + 1) * 4 + g) * 64 + lane) * 4) = (f32x4){acc1[4 * g], acc1[4 * g + 1], acc1[4 * g + 2], acc1[4 * g + 3]};
;         }
;         lds_barrier();
;         const int tile = w >> 2, g = w & 3;
;         f32x4 v = (f32x4){0.f, 0.f, 0.f, 0.f};
; #pragma unroll
;         for (int ww = 0; ww < 8; ++ww) v += *(const LAS f32x4*)(red + (((ww * 2 + tile) * 4 + g) * 64 + lane) * 4);
.LBB0_671:
	global_load_dwordx4 v[46:49], v[38:39], off offset:-32
	global_load_dwordx4 v[50:53], v[40:41], off offset:-32
	s_add_i32 s7, s7, 2
	s_cmp_ge_u32 s7, s18
	s_waitcnt vmcnt(0)
	v_mfma_f32_32x32x16_bf16 v[0:15], v[46:49], v[50:53], v[0:15]
	global_load_dwordx4 v[46:49], v[36:37], off offset:-32
	global_load_dwordx4 v[54:57], v[38:39], off
	v_lshl_add_u64 v[38:39], v[38:39], 0, 64
	s_waitcnt vmcnt(1)
	v_mfma_f32_32x32x16_bf16 v[16:31], v[46:49], v[50:53], v[16:31]
	global_load_dwordx4 v[50:53], v[36:37], off
	global_load_dwordx4 v[46:49], v[40:41], off
	v_lshl_add_u64 v[36:37], v[36:37], 0, 64
	v_lshl_add_u64 v[40:41], v[40:41], 0, 64
	s_waitcnt vmcnt(0)
	v_mfma_f32_32x32x16_bf16 v[0:15], v[54:57], v[46:49], v[0:15]
	v_mfma_f32_32x32x16_bf16 v[16:31], v[50:53], v[46:49], v[16:31]
	s_cbranch_scc0 .LBB0_671
	v_add_u32_e32 v36, s19, v172
	s_nop 8
	ds_write_b128 v36, v[0:3]
	ds_write_b128 v36, v[16:19] offset:4096
	ds_write_b128 v36, v[4:7] offset:1024
	ds_write_b128 v36, v[20:23] offset:5120
	ds_write_b128 v36, v[8:11] offset:2048
	ds_write_b128 v36, v[24:27] offset:6144
	ds_write_b128 v36, v[12:15] offset:3072
	ds_write_b128 v36, v[28:31] offset:7168
	s_waitcnt lgkmcnt(0)
	s_barrier
	ds_read_b128 v[28:31], v43
	ds_read_b128 v[24:27], v43 offset:8192
	ds_read_b128 v[20:23], v43 offset:16384
	ds_read_b128 v[16:19], v43 offset:24576
	ds_read_b128 v[12:15], v43 offset:32768
	ds_read_b128 v[8:11], v43 offset:40960
	ds_read_b128 v[4:7], v43 offset:49152
	ds_read_b128 v[0:3], v43 offset:57344
	s_and_b64 vcc, exec, s[12:13]
	s_cbranch_vccz .LBB0_674
	v_lshlrev_b32_e32 v40, 6, v45
	global_load_dwordx4 v[36:39], v40, s[4:5]
	global_load_dwordx4 v[46:49], v40, s[4:5] offset:32
	global_load_dwordx4 v[50:53], v40, s[4:5] offset:16
	global_load_dwordx4 v[54:57], v40, s[4:5] offset:48
	s_waitcnt vmcnt(3)
	v_mov_b32_e32 v40, v36
	s_waitcnt vmcnt(2)
	v_mov_b32_e32 v41, v46
	v_mov_b32_e32 v46, v37
	v_mov_b32_e32 v36, v38
	v_mov_b32_e32 v37, v48
	v_mov_b32_e32 v48, v39
	s_waitcnt vmcnt(1)
	v_mov_b32_e32 v38, v50
	s_waitcnt vmcnt(0)
	v_mov_b32_e32 v39, v54
	v_mov_b32_e32 v54, v51
	v_mov_b32_e32 v50, v52
	v_mov_b32_e32 v51, v56
	v_mov_b32_e32 v56, v53
	v_pk_add_f32 v[40:41], v[40:41], v[46:47]
	v_pk_add_f32 v[36:37], v[36:37], v[48:49]
	v_pk_add_f32 v[38:39], v[38:39], v[54:55]
	v_pk_add_f32 v[46:47], v[50:51], v[56:57]
	v_pk_add_f32 v[36:37], v[40:41], v[36:37]
	v_pk_add_f32 v[38:39], v[38:39], v[46:47]
	v_pk_add_f32 v[36:37], v[36:37], v[38:39]
	v_add_f32_e32 v36, v36, v37
	v_fmamk_f32 v36, v36, 0x3a800000, v176
	v_mul_f32_e32 v37, 0x4b800000, v36
	v_cmp_gt_f32_e32 vcc, s39, v36
	s_nop 1
	v_cndmask_b32_e32 v36, v36, v37, vcc
	v_rsq_f32_e32 v36, v36
	s_nop 0
	v_mul_f32_e32 v37, 0x45800000, v36
	v_cndmask_b32_e32 v38, v36, v37, vcc
	s_branch .LBB0_675
